# noprio
# speedup vs baseline: 1.0215x; 1.0215x over previous
; #define STAGE(P, BASE, LD, br, kt) do { const char* _g = (const char*)((BASE) + (size_t)(br) * (LD) + (size_t)(kt) * 64); \
;     for (int _i = 0; _i < 2; ++_i) { int _b = tidx * 16 + _i * 8192; int _r, _c; stage_rc(_b, _r, _c); \
;       __builtin_amdgcn_global_load_lds((const unsigned*)(_g + (unsigned)((_r * (LD) + _c) * 2)), (unsigned*)((char*)(P) + _b), 16, 0, 0); } } while (0)
; #define LDA(dst, b, h) for (int m = 0; m < 4; ++m) for (int k = 0; k < 2; ++k) \
;     dst[m][k] = *reinterpret_cast<const bf16x8*>((char*)SA(b, h) + lds_byte(wr * 64 + m * 16 + fr, k * 32 + fq * 8))
; #define LDB(dst, b, h) for (int n = 0; n < 2; ++n) for (int k = 0; k < 2; ++k) \
;     dst[n][k] = *reinterpret_cast<const bf16x8*>((char*)SB(b, h) + lds_byte(wc * 32 + n * 16 + fr, k * 32 + fq * 8))
; #define MMA(ai, bj, At_, Bt_) do { __builtin_amdgcn_s_setprio(1); \
;     for (int k = 0; k < 2; ++k) for (int m = 0; m < 4; ++m) for (int n = 0; n < 2; ++n) \
;       acc[ai][bj][m][n] = __builtin_amdgcn_mfma_f32_16x16x32_bf16(At_[m][k], Bt_[n][k], acc[ai][bj][m][n], 0, 0, 0); \
;     __builtin_amdgcn_s_setprio(0); } while (0)
; #define WAIT_L(n) asm volatile("s_waitcnt lgkmcnt(" #n ")" ::: "memory")
; #define BAR __builtin_amdgcn_s_barrier()
; #define SCHED __builtin_amdgcn_sched_barrier(0)
; template <int EPI, int lda, int ldb, int N, int K>
; __device__ __forceinline__ void gemm_phase(const u16* __restrict__ A, const u16* __restrict__ Bt, const GemmEpi ep, int wv) {
;     ...
;     for (int t = 0; t < nt - 2; t += 2) {
;       LDB(B0, 0, 0); SCHED; LDA(At, 0, 0); STAGE(SA(1, 1), Ab, lda, brow + HALF, t + 1);
;       WAIT_L(8); BAR; WAIT_L(0); MMA(0, 0, At, B0); BAR; SCHED;
;       LDB(B1, 0, 1); STAGE(SB(0, 0), Bt, ldb, bcol, t + 2);
;       BAR; WAIT_L(0); MMA(0, 1, At, B1); BAR;
;       LDA(At, 0, 1); STAGE(SA(0, 0), Ab, lda, brow, t + 2);
;       BAR; WAIT_L(0); MMA(1, 0, At, B0); BAR; SCHED;
.LBB0_53:
	ds_read_b128 v[172:175], v161
	ds_read_b128 v[176:179], v161 offset:1024
	ds_read_b128 v[180:183], v161 offset:2048
	ds_read_b128 v[184:187], v161 offset:3072
	v_add_u32_e32 v169, 0xc000, v148
	v_lshl_add_u64 v[236:237], v[136:137], 0, s[42:43]
	v_readfirstlane_b32 s45, v169
	v_add_u32_e32 v170, 0xe000, v148
	v_lshl_add_u64 v[162:163], v[236:237], 0, s[14:15]
	s_mov_b32 m0, s45
	v_lshl_add_u64 v[238:239], v[134:135], 0, s[42:43]
	v_readfirstlane_b32 s45, v170
	ds_read_b128 v[164:167], v152
	ds_read_b128 v[188:191], v152 offset:1024
	ds_read_b128 v[192:195], v151
	ds_read_b128 v[196:199], v151 offset:1024
	ds_read_b128 v[200:203], v150
	ds_read_b128 v[204:207], v150 offset:1024
	ds_read_b128 v[208:211], v149
	ds_read_b128 v[212:215], v149 offset:1024
	global_load_lds_dwordx4 v[162:163], off
	v_lshl_add_u64 v[162:163], v[238:239], 0, s[14:15]
	s_mov_b32 m0, s45
	s_nop 0
	global_load_lds_dwordx4 v[162:163], off
	s_waitcnt lgkmcnt(8)
	s_barrier
	s_waitcnt lgkmcnt(0)
	s_waitcnt lgkmcnt(0)
	v_mfma_f32_16x16x32_bf16 v[124:127], v[172:175], v[164:167], v[124:127]
	v_mfma_f32_16x16x32_bf16 v[120:123], v[180:183], v[164:167], v[120:123]
	v_mfma_f32_16x16x32_bf16 v[116:119], v[172:175], v[192:195], v[116:119]
	v_mfma_f32_16x16x32_bf16 v[112:115], v[180:183], v[192:195], v[112:115]
	v_mfma_f32_16x16x32_bf16 v[108:111], v[172:175], v[200:203], v[108:111]
	v_mfma_f32_16x16x32_bf16 v[104:107], v[180:183], v[200:203], v[104:107]
	v_mfma_f32_16x16x32_bf16 v[100:103], v[172:175], v[208:211], v[100:103]
	v_mfma_f32_16x16x32_bf16 v[96:99], v[180:183], v[208:211], v[96:99]
	v_mfma_f32_16x16x32_bf16 v[124:127], v[176:179], v[188:191], v[124:127]
	v_mfma_f32_16x16x32_bf16 v[120:123], v[184:187], v[188:191], v[120:123]
	v_mfma_f32_16x16x32_bf16 v[116:119], v[176:179], v[196:199], v[116:119]
	v_mfma_f32_16x16x32_bf16 v[112:115], v[184:187], v[196:199], v[112:115]
	v_mfma_f32_16x16x32_bf16 v[108:111], v[176:179], v[204:207], v[108:111]
	v_mfma_f32_16x16x32_bf16 v[104:107], v[184:187], v[204:207], v[104:107]
	v_mfma_f32_16x16x32_bf16 v[100:103], v[176:179], v[212:215], v[100:103]
	v_mfma_f32_16x16x32_bf16 v[96:99], v[184:187], v[212:215], v[96:99]
	s_barrier
	v_add_u32_e32 v162, s54, v153
	v_lshl_add_u64 v[240:241], v[140:141], 0, s[42:43]
	v_readfirstlane_b32 s45, v162
	v_add_u32_e32 v163, 0x2000, v162
	v_lshl_add_u64 v[232:233], v[240:241], 0, s[16:17]
	s_mov_b32 m0, s45
	v_lshl_add_u64 v[242:243], v[138:139], 0, s[42:43]
	v_readfirstlane_b32 s45, v163
	ds_read_b128 v[216:219], v160
	ds_read_b128 v[220:223], v160 offset:1024
	ds_read_b128 v[224:227], v160 offset:2048
	ds_read_b128 v[228:231], v160 offset:3072
	global_load_lds_dwordx4 v[232:233], off
	v_lshl_add_u64 v[232:233], v[242:243], 0, s[16:17]
	s_mov_b32 m0, s45
	s_nop 0
	global_load_lds_dwordx4 v[232:233], off
	s_barrier
	s_waitcnt lgkmcnt(0)
	s_waitcnt lgkmcnt(0)
	v_mfma_f32_16x16x32_bf16 v[92:95], v[216:219], v[164:167], v[92:95]
	v_mfma_f32_16x16x32_bf16 v[88:91], v[224:227], v[164:167], v[88:91]
	v_mfma_f32_16x16x32_bf16 v[84:87], v[216:219], v[192:195], v[84:87]
	v_mfma_f32_16x16x32_bf16 v[80:83], v[224:227], v[192:195], v[80:83]
	v_mfma_f32_16x16x32_bf16 v[76:79], v[216:219], v[200:203], v[76:79]
	v_mfma_f32_16x16x32_bf16 v[72:75], v[224:227], v[200:203], v[72:75]
	v_mfma_f32_16x16x32_bf16 v[68:71], v[216:219], v[208:211], v[68:71]
	v_mfma_f32_16x16x32_bf16 v[64:67], v[224:227], v[208:211], v[64:67]
	v_mfma_f32_16x16x32_bf16 v[92:95], v[220:223], v[188:191], v[92:95]
	v_mfma_f32_16x16x32_bf16 v[88:91], v[228:231], v[188:191], v[88:91]
	v_mfma_f32_16x16x32_bf16 v[84:87], v[220:223], v[196:199], v[84:87]
	v_mfma_f32_16x16x32_bf16 v[80:83], v[228:231], v[196:199], v[80:83]
	v_mfma_f32_16x16x32_bf16 v[76:79], v[220:223], v[204:207], v[76:79]
	v_mfma_f32_16x16x32_bf16 v[72:75], v[228:231], v[204:207], v[72:75]
	v_mfma_f32_16x16x32_bf16 v[68:71], v[220:223], v[212:215], v[68:71]
	v_mfma_f32_16x16x32_bf16 v[64:67], v[228:231], v[212:215], v[64:67]
	v_readfirstlane_b32 s45, v148
	v_lshl_add_u64 v[164:165], v[236:237], 0, s[18:19]
	s_mov_b32 m0, s45
	s_barrier
	ds_read_b128 v[188:191], v152 offset:16384
	ds_read_b128 v[192:195], v152 offset:17408
	ds_read_b128 v[196:199], v151 offset:16384
	ds_read_b128 v[200:203], v151 offset:17408
	ds_read_b128 v[204:207], v150 offset:16384
	ds_read_b128 v[208:211], v150 offset:17408
	ds_read_b128 v[212:215], v149 offset:16384
	ds_read_b128 v[232:235], v149 offset:17408
	global_load_lds_dwordx4 v[164:165], off
	v_add_u32_e32 v164, 0x2000, v148
	v_lshl_add_u64 v[166:167], v[238:239], 0, s[18:19]
	v_readfirstlane_b32 s45, v164
	s_mov_b32 m0, s45
	s_nop 0
	global_load_lds_dwordx4 v[166:167], off
	s_barrier
	s_waitcnt lgkmcnt(0)
	s_waitcnt lgkmcnt(0)
	v_mfma_f32_16x16x32_bf16 v[60:63], v[172:175], v[188:191], v[60:63]
	v_mfma_f32_16x16x32_bf16 v[56:59], v[180:183], v[188:191], v[56:59]
	v_mfma_f32_16x16x32_bf16 v[52:55], v[172:175], v[196:199], v[52:55]
	v_mfma_f32_16x16x32_bf16 v[48:51], v[180:183], v[196:199], v[48:51]
	v_mfma_f32_16x16x32_bf16 v[44:47], v[172:175], v[204:207], v[44:47]
	v_mfma_f32_16x16x32_bf16 v[40:43], v[180:183], v[204:207], v[40:43]
	v_mfma_f32_16x16x32_bf16 v[36:39], v[172:175], v[212:215], v[36:39]
	v_mfma_f32_16x16x32_bf16 v[32:35], v[180:183], v[212:215], v[32:35]
	v_mfma_f32_16x16x32_bf16 v[60:63], v[176:179], v[192:195], v[60:63]
	v_mfma_f32_16x16x32_bf16 v[56:59], v[184:187], v[192:195], v[56:59]
	v_mfma_f32_16x16x32_bf16 v[52:55], v[176:179], v[200:203], v[52:55]
	v_mfma_f32_16x16x32_bf16 v[48:51], v[184:187], v[200:203], v[48:51]
	v_mfma_f32_16x16x32_bf16 v[44:47], v[176:179], v[208:211], v[44:47]
	v_mfma_f32_16x16x32_bf16 v[40:43], v[184:187], v[208:211], v[40:43]
	v_mfma_f32_16x16x32_bf16 v[36:39], v[176:179], v[232:235], v[36:39]
	v_mfma_f32_16x16x32_bf16 v[32:35], v[184:187], v[232:235], v[32:35]
	s_barrier
; #define STAGE(P, BASE, LD, br, kt) do { const char* _g = (const char*)((BASE) + (size_t)(br) * (LD) + (size_t)(kt) * 64); \
;     for (int _i = 0; _i < 2; ++_i) { int _b = tidx * 16 + _i * 8192; int _r, _c; stage_rc(_b, _r, _c); \
;       __builtin_amdgcn_global_load_lds((const unsigned*)(_g + (unsigned)((_r * (LD) + _c) * 2)), (unsigned*)((char*)(P) + _b), 16, 0, 0); } } while (0)
; #define LDA(dst, b, h) for (int m = 0; m < 4; ++m) for (int k = 0; k < 2; ++k) \
;     dst[m][k] = *reinterpret_cast<const bf16x8*>((char*)SA(b, h) + lds_byte(wr * 64 + m * 16 + fr, k * 32 + fq * 8))
; #define LDB(dst, b, h) for (int n = 0; n < 2; ++n) for (int k = 0; k < 2; ++k) \
;     dst[n][k] = *reinterpret_cast<const bf16x8*>((char*)SB(b, h) + lds_byte(wc * 32 + n * 16 + fr, k * 32 + fq * 8))
; #define MMA(ai, bj, At_, Bt_) do { __builtin_amdgcn_s_setprio(1); \
;     for (int k = 0; k < 2; ++k) for (int m = 0; m < 4; ++m) for (int n = 0; n < 2; ++n) \
;       acc[ai][bj][m][n] = __builtin_amdgcn_mfma_f32_16x16x32_bf16(At_[m][k], Bt_[n][k], acc[ai][bj][m][n], 0, 0, 0); \
;     __builtin_amdgcn_s_setprio(0); } while (0)
; #define WAIT_V(n) asm volatile("s_waitcnt vmcnt(" #n ")" ::: "memory")
; #define WAIT_L(n) asm volatile("s_waitcnt lgkmcnt(" #n ")" ::: "memory")
; #define BAR __builtin_amdgcn_s_barrier()
; #define SCHED __builtin_amdgcn_sched_barrier(0)
; template <int EPI, int lda, int ldb, int N, int K>
; __device__ __forceinline__ void gemm_phase(const u16* __restrict__ A, const u16* __restrict__ Bt, const GemmEpi ep, int wv) {
;     ...
;       STAGE(SB(0, 1), Bt, ldb, bcol + HALF, t + 2);
;       WAIT_V(6); BAR; MMA(1, 1, At, B1); BAR;
;       LDB(B0, 1, 0); SCHED; LDA(At, 1, 0); STAGE(SA(0, 1), Ab, lda, brow + HALF, t + 2);
;       WAIT_L(8); BAR; WAIT_L(0); MMA(0, 0, At, B0); BAR; SCHED;
;       LDB(B1, 1, 1); STAGE(SB(1, 0), Bt, ldb, bcol, t + 3);
;       BAR; WAIT_L(0); MMA(0, 1, At, B1); BAR;
	v_add_u32_e32 v165, s55, v153
	v_lshl_add_u64 v[166:167], v[240:241], 0, s[20:21]
	v_readfirstlane_b32 s45, v165
	s_mov_b32 m0, s45
	v_lshl_add_u64 v[172:173], v[242:243], 0, s[20:21]
	global_load_lds_dwordx4 v[166:167], off
	v_add_u32_e32 v166, 0x2000, v165
	s_nop 0
	v_readfirstlane_b32 s45, v166
	s_mov_b32 m0, s45
	s_nop 0
	global_load_lds_dwordx4 v[172:173], off
	s_waitcnt vmcnt(6)
	s_barrier
	v_mfma_f32_16x16x32_bf16 v[28:31], v[216:219], v[188:191], v[28:31]
	v_mfma_f32_16x16x32_bf16 v[24:27], v[224:227], v[188:191], v[24:27]
	v_mfma_f32_16x16x32_bf16 v[20:23], v[216:219], v[196:199], v[20:23]
	v_mfma_f32_16x16x32_bf16 v[16:19], v[224:227], v[196:199], v[16:19]
	v_mfma_f32_16x16x32_bf16 v[12:15], v[216:219], v[204:207], v[12:15]
	v_mfma_f32_16x16x32_bf16 v[8:11], v[224:227], v[204:207], v[8:11]
	v_mfma_f32_16x16x32_bf16 v[4:7], v[216:219], v[212:215], v[4:7]
	v_mfma_f32_16x16x32_bf16 v[0:3], v[224:227], v[212:215], v[0:3]
	v_mfma_f32_16x16x32_bf16 v[28:31], v[220:223], v[192:195], v[28:31]
	v_mfma_f32_16x16x32_bf16 v[24:27], v[228:231], v[192:195], v[24:27]
	v_mfma_f32_16x16x32_bf16 v[20:23], v[220:223], v[200:203], v[20:23]
	v_mfma_f32_16x16x32_bf16 v[16:19], v[228:231], v[200:203], v[16:19]
	v_mfma_f32_16x16x32_bf16 v[12:15], v[220:223], v[208:211], v[12:15]
	v_mfma_f32_16x16x32_bf16 v[8:11], v[228:231], v[208:211], v[8:11]
	v_mfma_f32_16x16x32_bf16 v[4:7], v[220:223], v[232:235], v[4:7]
	v_mfma_f32_16x16x32_bf16 v[0:3], v[228:231], v[232:235], v[0:3]
	s_barrier
	ds_read_b128 v[172:175], v156
	ds_read_b128 v[176:179], v156 offset:1024
	ds_read_b128 v[180:183], v156 offset:2048
	ds_read_b128 v[184:187], v156 offset:3072
	v_add_u32_e32 v167, 0x4000, v148
	v_add_u32_e32 v168, 0x6000, v148
	v_readfirstlane_b32 s45, v167
	v_lshl_add_u64 v[220:221], v[236:237], 0, s[22:23]
	s_mov_b32 m0, s45
	v_readfirstlane_b32 s45, v168
	ds_read_b128 v[188:191], v152 offset:32768
	ds_read_b128 v[192:195], v152 offset:33792
	ds_read_b128 v[196:199], v151 offset:32768
	ds_read_b128 v[200:203], v151 offset:33792
	ds_read_b128 v[204:207], v150 offset:32768
	ds_read_b128 v[208:211], v150 offset:33792
	ds_read_b128 v[212:215], v149 offset:32768
	ds_read_b128 v[216:219], v149 offset:33792
	global_load_lds_dwordx4 v[220:221], off
	v_lshl_add_u64 v[220:221], v[238:239], 0, s[22:23]
	s_mov_b32 m0, s45
	s_nop 0
	global_load_lds_dwordx4 v[220:221], off
	s_waitcnt lgkmcnt(8)
	s_barrier
	s_waitcnt lgkmcnt(0)
	s_waitcnt lgkmcnt(0)
	v_mfma_f32_16x16x32_bf16 v[124:127], v[172:175], v[188:191], v[124:127]
	v_mfma_f32_16x16x32_bf16 v[120:123], v[180:183], v[188:191], v[120:123]
	v_mfma_f32_16x16x32_bf16 v[116:119], v[172:175], v[196:199], v[116:119]
	v_mfma_f32_16x16x32_bf16 v[112:115], v[180:183], v[196:199], v[112:115]
	v_mfma_f32_16x16x32_bf16 v[108:111], v[172:175], v[204:207], v[108:111]
	v_mfma_f32_16x16x32_bf16 v[104:107], v[180:183], v[204:207], v[104:107]
	v_mfma_f32_16x16x32_bf16 v[100:103], v[172:175], v[212:215], v[100:103]
	v_mfma_f32_16x16x32_bf16 v[96:99], v[180:183], v[212:215], v[96:99]
	v_mfma_f32_16x16x32_bf16 v[124:127], v[176:179], v[192:195], v[124:127]
	v_mfma_f32_16x16x32_bf16 v[120:123], v[184:187], v[192:195], v[120:123]
	v_mfma_f32_16x16x32_bf16 v[116:119], v[176:179], v[200:203], v[116:119]
	v_mfma_f32_16x16x32_bf16 v[112:115], v[184:187], v[200:203], v[112:115]
	v_mfma_f32_16x16x32_bf16 v[108:111], v[176:179], v[208:211], v[108:111]
	v_mfma_f32_16x16x32_bf16 v[104:107], v[184:187], v[208:211], v[104:107]
	v_mfma_f32_16x16x32_bf16 v[100:103], v[176:179], v[216:219], v[100:103]
	v_mfma_f32_16x16x32_bf16 v[96:99], v[184:187], v[216:219], v[96:99]
	s_barrier
	v_readfirstlane_b32 s45, v155
	v_add_u32_e32 v171, 0x2000, v155
	v_lshl_add_u64 v[244:245], v[240:241], 0, s[24:25]
	s_mov_b32 m0, s45
	v_readfirstlane_b32 s45, v171
	ds_read_b128 v[220:223], v154
	ds_read_b128 v[224:227], v154 offset:1024
	ds_read_b128 v[228:231], v154 offset:2048
	ds_read_b128 v[232:235], v154 offset:3072
	global_load_lds_dwordx4 v[244:245], off
	v_lshl_add_u64 v[244:245], v[242:243], 0, s[24:25]
	s_mov_b32 m0, s45
	s_nop 0
	global_load_lds_dwordx4 v[244:245], off
	s_barrier
	s_waitcnt lgkmcnt(0)
	s_waitcnt lgkmcnt(0)
	v_mfma_f32_16x16x32_bf16 v[92:95], v[220:223], v[188:191], v[92:95]
	v_mfma_f32_16x16x32_bf16 v[88:91], v[228:231], v[188:191], v[88:91]
	v_mfma_f32_16x16x32_bf16 v[84:87], v[220:223], v[196:199], v[84:87]
	v_mfma_f32_16x16x32_bf16 v[80:83], v[228:231], v[196:199], v[80:83]
	v_mfma_f32_16x16x32_bf16 v[76:79], v[220:223], v[204:207], v[76:79]
	v_mfma_f32_16x16x32_bf16 v[72:75], v[228:231], v[204:207], v[72:75]
	v_mfma_f32_16x16x32_bf16 v[68:71], v[220:223], v[212:215], v[68:71]
	v_mfma_f32_16x16x32_bf16 v[64:67], v[228:231], v[212:215], v[64:67]
	v_mfma_f32_16x16x32_bf16 v[92:95], v[224:227], v[192:195], v[92:95]
	v_mfma_f32_16x16x32_bf16 v[88:91], v[232:235], v[192:195], v[88:91]
	v_mfma_f32_16x16x32_bf16 v[84:87], v[224:227], v[200:203], v[84:87]
	v_mfma_f32_16x16x32_bf16 v[80:83], v[232:235], v[200:203], v[80:83]
	v_mfma_f32_16x16x32_bf16 v[76:79], v[224:227], v[208:211], v[76:79]
	v_mfma_f32_16x16x32_bf16 v[72:75], v[232:235], v[208:211], v[72:75]
	v_mfma_f32_16x16x32_bf16 v[68:71], v[224:227], v[216:219], v[68:71]
	v_mfma_f32_16x16x32_bf16 v[64:67], v[232:235], v[216:219], v[64:67]
	v_readfirstlane_b32 s45, v157
	v_lshl_add_u64 v[236:237], v[236:237], 0, s[26:27]
	s_mov_b32 m0, s45
	v_readfirstlane_b32 s45, v158
	s_barrier
; #define STAGE(P, BASE, LD, br, kt) do { const char* _g = (const char*)((BASE) + (size_t)(br) * (LD) + (size_t)(kt) * 64); \
;     for (int _i = 0; _i < 2; ++_i) { int _b = tidx * 16 + _i * 8192; int _r, _c; stage_rc(_b, _r, _c); \
;       __builtin_amdgcn_global_load_lds((const unsigned*)(_g + (unsigned)((_r * (LD) + _c) * 2)), (unsigned*)((char*)(P) + _b), 16, 0, 0); } } while (0)
; #define LDA(dst, b, h) for (int m = 0; m < 4; ++m) for (int k = 0; k < 2; ++k) \
;     dst[m][k] = *reinterpret_cast<const bf16x8*>((char*)SA(b, h) + lds_byte(wr * 64 + m * 16 + fr, k * 32 + fq * 8))
; #define LDB(dst, b, h) for (int n = 0; n < 2; ++n) for (int k = 0; k < 2; ++k) \
;     dst[n][k] = *reinterpret_cast<const bf16x8*>((char*)SB(b, h) + lds_byte(wc * 32 + n * 16 + fr, k * 32 + fq * 8))
; #define MMA(ai, bj, At_, Bt_) do { __builtin_amdgcn_s_setprio(1); \
;     for (int k = 0; k < 2; ++k) for (int m = 0; m < 4; ++m) for (int n = 0; n < 2; ++n) \
;       acc[ai][bj][m][n] = __builtin_amdgcn_mfma_f32_16x16x32_bf16(At_[m][k], Bt_[n][k], acc[ai][bj][m][n], 0, 0, 0); \
;     __builtin_amdgcn_s_setprio(0); } while (0)
; #define WAIT_V(n) asm volatile("s_waitcnt vmcnt(" #n ")" ::: "memory")
; #define WAIT_L(n) asm volatile("s_waitcnt lgkmcnt(" #n ")" ::: "memory")
; #define BAR __builtin_amdgcn_s_barrier()
; #define SCHED __builtin_amdgcn_sched_barrier(0)
; template <int EPI, int lda, int ldb, int N, int K>
; __device__ __forceinline__ void gemm_phase(const u16* __restrict__ A, const u16* __restrict__ Bt, const GemmEpi ep, int wv) {
;     ...
;       LDA(At, 1, 1); STAGE(SA(1, 0), Ab, lda, brow, t + 3);
;       BAR; WAIT_L(0); MMA(1, 0, At, B0); BAR; SCHED;
;       STAGE(SB(1, 1), Bt, ldb, bcol + HALF, t + 3);
;       WAIT_V(6); BAR; MMA(1, 1, At, B1); BAR;
;     }
;     { LDB(B0, 0, 0); LDA(At, 0, 0); STAGE(SA(1, 1), Ab, lda, brow + HALF, nt - 1);
;       BAR; WAIT_L(0); MMA(0, 0, At, B0); BAR;
;       LDB(B1, 0, 1); BAR; WAIT_L(0); MMA(0, 1, At, B1); BAR;
	ds_read_b128 v[188:191], v152 offset:49152
	ds_read_b128 v[192:195], v152 offset:50176
	ds_read_b128 v[196:199], v151 offset:49152
	ds_read_b128 v[200:203], v151 offset:50176
	ds_read_b128 v[204:207], v150 offset:49152
	ds_read_b128 v[208:211], v150 offset:50176
	ds_read_b128 v[212:215], v149 offset:49152
	ds_read_b128 v[216:219], v149 offset:50176
	global_load_lds_dwordx4 v[236:237], off
	v_lshl_add_u64 v[236:237], v[238:239], 0, s[26:27]
	s_mov_b32 m0, s45
	s_nop 0
	global_load_lds_dwordx4 v[236:237], off
	s_barrier
	s_waitcnt lgkmcnt(0)
	s_waitcnt lgkmcnt(0)
	v_mfma_f32_16x16x32_bf16 v[60:63], v[172:175], v[188:191], v[60:63]
	v_mfma_f32_16x16x32_bf16 v[56:59], v[180:183], v[188:191], v[56:59]
	v_mfma_f32_16x16x32_bf16 v[52:55], v[172:175], v[196:199], v[52:55]
	v_mfma_f32_16x16x32_bf16 v[48:51], v[180:183], v[196:199], v[48:51]
	v_mfma_f32_16x16x32_bf16 v[44:47], v[172:175], v[204:207], v[44:47]
	v_mfma_f32_16x16x32_bf16 v[40:43], v[180:183], v[204:207], v[40:43]
	v_mfma_f32_16x16x32_bf16 v[36:39], v[172:175], v[212:215], v[36:39]
	v_mfma_f32_16x16x32_bf16 v[32:35], v[180:183], v[212:215], v[32:35]
	v_mfma_f32_16x16x32_bf16 v[60:63], v[176:179], v[192:195], v[60:63]
	v_mfma_f32_16x16x32_bf16 v[56:59], v[184:187], v[192:195], v[56:59]
	v_mfma_f32_16x16x32_bf16 v[52:55], v[176:179], v[200:203], v[52:55]
	v_mfma_f32_16x16x32_bf16 v[48:51], v[184:187], v[200:203], v[48:51]
	v_mfma_f32_16x16x32_bf16 v[44:47], v[176:179], v[208:211], v[44:47]
	v_mfma_f32_16x16x32_bf16 v[40:43], v[184:187], v[208:211], v[40:43]
	v_mfma_f32_16x16x32_bf16 v[36:39], v[176:179], v[216:219], v[36:39]
	v_mfma_f32_16x16x32_bf16 v[32:35], v[184:187], v[216:219], v[32:35]
	s_barrier
	v_readfirstlane_b32 s45, v159
	v_add_u32_e32 v171, 0x2000, v159
	v_lshl_add_u64 v[172:173], v[240:241], 0, s[34:35]
	s_mov_b32 m0, s45
	v_readfirstlane_b32 s45, v171
	global_load_lds_dwordx4 v[172:173], off
	v_lshl_add_u64 v[172:173], v[242:243], 0, s[34:35]
	s_mov_b32 m0, s45
	s_nop 0
	global_load_lds_dwordx4 v[172:173], off
	s_waitcnt vmcnt(6)
	s_barrier
	v_mfma_f32_16x16x32_bf16 v[28:31], v[220:223], v[188:191], v[28:31]
	v_mfma_f32_16x16x32_bf16 v[24:27], v[228:231], v[188:191], v[24:27]
	v_mfma_f32_16x16x32_bf16 v[20:23], v[220:223], v[196:199], v[20:23]
	v_mfma_f32_16x16x32_bf16 v[16:19], v[228:231], v[196:199], v[16:19]
	v_mfma_f32_16x16x32_bf16 v[12:15], v[220:223], v[204:207], v[12:15]
	v_mfma_f32_16x16x32_bf16 v[8:11], v[228:231], v[204:207], v[8:11]
	v_mfma_f32_16x16x32_bf16 v[4:7], v[220:223], v[212:215], v[4:7]
	v_mfma_f32_16x16x32_bf16 v[0:3], v[228:231], v[212:215], v[0:3]
	v_mfma_f32_16x16x32_bf16 v[28:31], v[224:227], v[192:195], v[28:31]
	v_mfma_f32_16x16x32_bf16 v[24:27], v[232:235], v[192:195], v[24:27]
	v_mfma_f32_16x16x32_bf16 v[20:23], v[224:227], v[200:203], v[20:23]
	v_mfma_f32_16x16x32_bf16 v[16:19], v[232:235], v[200:203], v[16:19]
	v_mfma_f32_16x16x32_bf16 v[12:15], v[224:227], v[208:211], v[12:15]
	v_mfma_f32_16x16x32_bf16 v[8:11], v[232:235], v[208:211], v[8:11]
	v_mfma_f32_16x16x32_bf16 v[4:7], v[224:227], v[216:219], v[4:7]
	v_mfma_f32_16x16x32_bf16 v[0:3], v[232:235], v[216:219], v[0:3]
	s_add_i32 s44, s44, 2
	s_add_u32 s42, s42, 0x100
	s_addc_u32 s43, s43, 0
	s_cmp_gt_u32 s44, 27
	s_barrier
	s_cbranch_scc0 .LBB0_53
	s_add_i32 s42, s38, 0x80
	s_mul_hi_i32 s43, s42, 0x1080
	s_mulk_i32 s42, 0x1080
	s_add_u32 s42, s51, s42
	s_addc_u32 s43, s52, s43
	v_lshl_add_u64 v[158:159], s[42:43], 0, v[128:129]
	v_readfirstlane_b32 s44, v169
	v_lshl_add_u64 v[158:159], v[158:159], 0, s[36:37]
	s_mov_b32 m0, s44
	ds_read_b128 v[134:137], v161
	ds_read_b128 v[138:141], v161 offset:1024
	ds_read_b128 v[172:175], v161 offset:2048
	ds_read_b128 v[176:179], v161 offset:3072
	ds_read_b128 v[180:183], v152
	ds_read_b128 v[184:187], v152 offset:1024
	ds_read_b128 v[188:191], v151
	ds_read_b128 v[192:195], v151 offset:1024
	ds_read_b128 v[196:199], v150
	ds_read_b128 v[200:203], v150 offset:1024
	ds_read_b128 v[204:207], v149
	ds_read_b128 v[208:211], v149 offset:1024
	global_load_lds_dwordx4 v[158:159], off
	v_lshl_add_u64 v[158:159], s[42:43], 0, v[132:133]
	v_readfirstlane_b32 s42, v170
	v_lshl_add_u64 v[158:159], v[158:159], 0, s[36:37]
	s_mov_b32 m0, s42
	s_nop 0
	global_load_lds_dwordx4 v[158:159], off
	s_barrier
	s_waitcnt lgkmcnt(0)
	s_waitcnt lgkmcnt(0)
	v_mfma_f32_16x16x32_bf16 v[124:127], v[134:137], v[180:183], v[124:127]
	v_mfma_f32_16x16x32_bf16 v[120:123], v[172:175], v[180:183], v[120:123]
	v_mfma_f32_16x16x32_bf16 v[116:119], v[134:137], v[188:191], v[116:119]
	v_mfma_f32_16x16x32_bf16 v[112:115], v[172:175], v[188:191], v[112:115]
	v_mfma_f32_16x16x32_bf16 v[108:111], v[134:137], v[196:199], v[108:111]
	v_mfma_f32_16x16x32_bf16 v[104:107], v[172:175], v[196:199], v[104:107]
	v_mfma_f32_16x16x32_bf16 v[100:103], v[134:137], v[204:207], v[100:103]
	v_mfma_f32_16x16x32_bf16 v[96:99], v[172:175], v[204:207], v[96:99]
	v_mfma_f32_16x16x32_bf16 v[124:127], v[138:141], v[184:187], v[124:127]
	v_mfma_f32_16x16x32_bf16 v[120:123], v[176:179], v[184:187], v[120:123]
	v_mfma_f32_16x16x32_bf16 v[116:119], v[138:141], v[192:195], v[116:119]
	v_mfma_f32_16x16x32_bf16 v[112:115], v[176:179], v[192:195], v[112:115]
	v_mfma_f32_16x16x32_bf16 v[108:111], v[138:141], v[200:203], v[108:111]
	v_mfma_f32_16x16x32_bf16 v[104:107], v[176:179], v[200:203], v[104:107]
	v_mfma_f32_16x16x32_bf16 v[100:103], v[138:141], v[208:211], v[100:103]
	v_mfma_f32_16x16x32_bf16 v[96:99], v[176:179], v[208:211], v[96:99]
	s_barrier
	ds_read_b128 v[212:215], v160
	ds_read_b128 v[216:219], v160 offset:1024
	ds_read_b128 v[220:223], v160 offset:2048
	ds_read_b128 v[158:161], v160 offset:3072
	s_barrier
; #define LDA(dst, b, h) for (int m = 0; m < 4; ++m) for (int k = 0; k < 2; ++k) \
;     dst[m][k] = *reinterpret_cast<const bf16x8*>((char*)SA(b, h) + lds_byte(wr * 64 + m * 16 + fr, k * 32 + fq * 8))
; #define LDB(dst, b, h) for (int n = 0; n < 2; ++n) for (int k = 0; k < 2; ++k) \
;     dst[n][k] = *reinterpret_cast<const bf16x8*>((char*)SB(b, h) + lds_byte(wc * 32 + n * 16 + fr, k * 32 + fq * 8))
; #define MMA(ai, bj, At_, Bt_) do { __builtin_amdgcn_s_setprio(1); \
;     for (int k = 0; k < 2; ++k) for (int m = 0; m < 4; ++m) for (int n = 0; n < 2; ++n) \
;       acc[ai][bj][m][n] = __builtin_amdgcn_mfma_f32_16x16x32_bf16(At_[m][k], Bt_[n][k], acc[ai][bj][m][n], 0, 0, 0); \
;     __builtin_amdgcn_s_setprio(0); } while (0)
; #define WAIT_V(n) asm volatile("s_waitcnt vmcnt(" #n ")" ::: "memory")
; #define WAIT_L(n) asm volatile("s_waitcnt lgkmcnt(" #n ")" ::: "memory")
; #define BAR __builtin_amdgcn_s_barrier()
; template <int EPI, int lda, int ldb, int N, int K>
; __device__ __forceinline__ void gemm_phase(const u16* __restrict__ A, const u16* __restrict__ Bt, const GemmEpi ep, int wv) {
;     ...
;       LDB(B1, 0, 1); BAR; WAIT_L(0); MMA(0, 1, At, B1); BAR;
;       LDA(At, 0, 1); WAIT_V(4); BAR; WAIT_L(0); MMA(1, 0, At, B0); MMA(1, 1, At, B1); BAR; }
;     { LDB(B0, 1, 0); LDA(At, 1, 0); WAIT_V(2); BAR; WAIT_L(0); MMA(0, 0, At, B0); BAR;
	s_waitcnt lgkmcnt(0)
	s_waitcnt lgkmcnt(0)
	v_mfma_f32_16x16x32_bf16 v[92:95], v[212:215], v[180:183], v[92:95]
	v_mfma_f32_16x16x32_bf16 v[88:91], v[220:223], v[180:183], v[88:91]
	v_mfma_f32_16x16x32_bf16 v[76:79], v[212:215], v[196:199], v[76:79]
	v_mfma_f32_16x16x32_bf16 v[72:75], v[220:223], v[196:199], v[72:75]
	v_mfma_f32_16x16x32_bf16 v[84:87], v[212:215], v[188:191], v[84:87]
	v_mfma_f32_16x16x32_bf16 v[80:83], v[220:223], v[188:191], v[80:83]
	v_mfma_f32_16x16x32_bf16 v[68:71], v[212:215], v[204:207], v[68:71]
	v_mfma_f32_16x16x32_bf16 v[64:67], v[220:223], v[204:207], v[64:67]
	v_mfma_f32_16x16x32_bf16 v[92:95], v[216:219], v[184:187], v[92:95]
	v_mfma_f32_16x16x32_bf16 v[88:91], v[158:161], v[184:187], v[88:91]
	v_mfma_f32_16x16x32_bf16 v[76:79], v[216:219], v[200:203], v[76:79]
	v_mfma_f32_16x16x32_bf16 v[72:75], v[158:161], v[200:203], v[72:75]
	v_mfma_f32_16x16x32_bf16 v[180:183], v[216:219], v[192:195], v[84:87]
	v_mfma_f32_16x16x32_bf16 v[184:187], v[158:161], v[192:195], v[80:83]
	v_mfma_f32_16x16x32_bf16 v[188:191], v[216:219], v[208:211], v[68:71]
	v_mfma_f32_16x16x32_bf16 v[192:195], v[158:161], v[208:211], v[64:67]
	s_barrier
	s_nop 0
	ds_read_b128 v[64:67], v152 offset:16384
	ds_read_b128 v[68:71], v152 offset:17408
	ds_read_b128 v[80:83], v151 offset:16384
	ds_read_b128 v[84:87], v151 offset:17408
	ds_read_b128 v[196:199], v150 offset:16384
	ds_read_b128 v[200:203], v150 offset:17408
	ds_read_b128 v[204:207], v149 offset:16384
	ds_read_b128 v[208:211], v149 offset:17408
	s_waitcnt vmcnt(4)
	s_barrier
	s_waitcnt lgkmcnt(0)
	s_waitcnt lgkmcnt(0)
	v_mfma_f32_16x16x32_bf16 v[60:63], v[134:137], v[64:67], v[60:63]
	v_mfma_f32_16x16x32_bf16 v[56:59], v[172:175], v[64:67], v[56:59]
	v_mfma_f32_16x16x32_bf16 v[52:55], v[134:137], v[80:83], v[52:55]
	v_mfma_f32_16x16x32_bf16 v[48:51], v[172:175], v[80:83], v[48:51]
	v_mfma_f32_16x16x32_bf16 v[44:47], v[134:137], v[196:199], v[44:47]
	v_mfma_f32_16x16x32_bf16 v[40:43], v[172:175], v[196:199], v[40:43]
	v_mfma_f32_16x16x32_bf16 v[36:39], v[134:137], v[204:207], v[36:39]
	v_mfma_f32_16x16x32_bf16 v[32:35], v[172:175], v[204:207], v[32:35]
	v_mfma_f32_16x16x32_bf16 v[60:63], v[138:141], v[68:71], v[60:63]
	v_mfma_f32_16x16x32_bf16 v[56:59], v[176:179], v[68:71], v[56:59]
	v_mfma_f32_16x16x32_bf16 v[52:55], v[138:141], v[84:87], v[52:55]
	v_mfma_f32_16x16x32_bf16 v[48:51], v[176:179], v[84:87], v[48:51]
	v_mfma_f32_16x16x32_bf16 v[44:47], v[138:141], v[200:203], v[44:47]
	v_mfma_f32_16x16x32_bf16 v[40:43], v[176:179], v[200:203], v[40:43]
	v_mfma_f32_16x16x32_bf16 v[36:39], v[138:141], v[208:211], v[36:39]
	v_mfma_f32_16x16x32_bf16 v[32:35], v[176:179], v[208:211], v[32:35]
	v_mfma_f32_16x16x32_bf16 v[28:31], v[212:215], v[64:67], v[28:31]
	v_mfma_f32_16x16x32_bf16 v[24:27], v[220:223], v[64:67], v[24:27]
	v_mfma_f32_16x16x32_bf16 v[12:15], v[212:215], v[196:199], v[12:15]
	v_mfma_f32_16x16x32_bf16 v[8:11], v[220:223], v[196:199], v[8:11]
	v_mfma_f32_16x16x32_bf16 v[20:23], v[212:215], v[80:83], v[20:23]
	v_mfma_f32_16x16x32_bf16 v[16:19], v[220:223], v[80:83], v[16:19]
	v_mfma_f32_16x16x32_bf16 v[4:7], v[212:215], v[204:207], v[4:7]
	v_mfma_f32_16x16x32_bf16 v[0:3], v[220:223], v[204:207], v[0:3]
	v_mfma_f32_16x16x32_bf16 v[28:31], v[216:219], v[68:71], v[28:31]
	v_mfma_f32_16x16x32_bf16 v[24:27], v[158:161], v[68:71], v[24:27]
	v_mfma_f32_16x16x32_bf16 v[12:15], v[216:219], v[200:203], v[12:15]
	v_mfma_f32_16x16x32_bf16 v[8:11], v[158:161], v[200:203], v[8:11]
	v_mfma_f32_16x16x32_bf16 v[134:137], v[216:219], v[84:87], v[20:23]
	v_mfma_f32_16x16x32_bf16 v[138:141], v[158:161], v[84:87], v[16:19]
	v_mfma_f32_16x16x32_bf16 v[170:173], v[216:219], v[208:211], v[4:7]
	v_mfma_f32_16x16x32_bf16 v[158:161], v[158:161], v[208:211], v[0:3]
	s_barrier
	s_nop 0
	ds_read_b128 v[0:3], v156
	ds_read_b128 v[4:7], v156 offset:1024
	ds_read_b128 v[16:19], v156 offset:2048
	ds_read_b128 v[174:177], v156 offset:3072
	ds_read_b128 v[20:23], v152 offset:32768
	ds_read_b128 v[196:199], v152 offset:33792
	ds_read_b128 v[200:203], v151 offset:32768
	ds_read_b128 v[204:207], v151 offset:33792
	ds_read_b128 v[208:211], v150 offset:32768
	ds_read_b128 v[212:215], v150 offset:33792
	ds_read_b128 v[216:219], v149 offset:32768
	ds_read_b128 v[220:223], v149 offset:33792
	s_waitcnt vmcnt(2)
	s_barrier
; #define LDA(dst, b, h) for (int m = 0; m < 4; ++m) for (int k = 0; k < 2; ++k) \
;     dst[m][k] = *reinterpret_cast<const bf16x8*>((char*)SA(b, h) + lds_byte(wr * 64 + m * 16 + fr, k * 32 + fq * 8))
; #define LDB(dst, b, h) for (int n = 0; n < 2; ++n) for (int k = 0; k < 2; ++k) \
;     dst[n][k] = *reinterpret_cast<const bf16x8*>((char*)SB(b, h) + lds_byte(wc * 32 + n * 16 + fr, k * 32 + fq * 8))
; #define MMA(ai, bj, At_, Bt_) do { __builtin_amdgcn_s_setprio(1); \
;     for (int k = 0; k < 2; ++k) for (int m = 0; m < 4; ++m) for (int n = 0; n < 2; ++n) \
;       acc[ai][bj][m][n] = __builtin_amdgcn_mfma_f32_16x16x32_bf16(At_[m][k], Bt_[n][k], acc[ai][bj][m][n], 0, 0, 0); \
;     __builtin_amdgcn_s_setprio(0); } while (0)
; #define WAIT_V(n) asm volatile("s_waitcnt vmcnt(" #n ")" ::: "memory")
; #define WAIT_L(n) asm volatile("s_waitcnt lgkmcnt(" #n ")" ::: "memory")
; #define BAR __builtin_amdgcn_s_barrier()
; #define STAGE4(BROW, BCOL, PN) do { const u16* Ab_ = A + (EPI == EPI_RG ? ((PN) >> 1) * 256 : 0); \
;     STAGE(SB(0, 0), Bt, ldb, (BCOL), 0); STAGE(SA(0, 0), Ab_, lda, (BROW), 0); \
;     STAGE(SB(0, 1), Bt, ldb, (BCOL) + HALF, 0); STAGE(SA(0, 1), Ab_, lda, (BROW) + HALF, 0); } while (0)
; template <int EPI, int lda, int ldb, int N, int K>
; __device__ __forceinline__ void gemm_phase(const u16* __restrict__ A, const u16* __restrict__ Bt, const GemmEpi ep, int wv) {
;     ...
;     { LDB(B0, 1, 0); LDA(At, 1, 0); WAIT_V(2); BAR; WAIT_L(0); MMA(0, 0, At, B0); BAR;
;       LDB(B1, 1, 1); WAIT_V(0); BAR; WAIT_L(0); MMA(0, 1, At, B1); BAR;
;       LDA(At, 1, 1); BAR; WAIT_L(0); MMA(1, 0, At, B0); MMA(1, 1, At, B1); BAR; }
;     if (wr == 0) BAR;
;     int ntile = 0, nbrow = 0, nbcol = 0, npn = 0; bool more = false;
;     if constexpr (PF) { ntile = tile + gridDim.x; more = ntile < nwg; if (more) { TILE_COORDS(ntile, nbrow, nbcol, npn); STAGE4(nbrow, nbcol, npn); } }
	s_waitcnt lgkmcnt(0)
	s_waitcnt lgkmcnt(0)
	v_mfma_f32_16x16x32_bf16 v[64:67], v[0:3], v[20:23], v[124:127]
	v_mfma_f32_16x16x32_bf16 v[68:71], v[16:19], v[20:23], v[120:123]
	v_mfma_f32_16x16x32_bf16 v[80:83], v[0:3], v[200:203], v[116:119]
	v_mfma_f32_16x16x32_bf16 v[84:87], v[16:19], v[200:203], v[112:115]
	v_mfma_f32_16x16x32_bf16 v[108:111], v[0:3], v[208:211], v[108:111]
	v_mfma_f32_16x16x32_bf16 v[104:107], v[16:19], v[208:211], v[104:107]
	v_mfma_f32_16x16x32_bf16 v[120:123], v[0:3], v[216:219], v[100:103]
	v_mfma_f32_16x16x32_bf16 v[124:127], v[16:19], v[216:219], v[96:99]
	v_mfma_f32_16x16x32_bf16 v[116:119], v[4:7], v[196:199], v[64:67]
	v_mfma_f32_16x16x32_bf16 v[112:115], v[174:177], v[196:199], v[68:71]
	v_mfma_f32_16x16x32_bf16 v[100:103], v[4:7], v[204:207], v[80:83]
	v_mfma_f32_16x16x32_bf16 v[96:99], v[174:177], v[204:207], v[84:87]
	v_mfma_f32_16x16x32_bf16 v[84:87], v[4:7], v[212:215], v[108:111]
	v_mfma_f32_16x16x32_bf16 v[80:83], v[174:177], v[212:215], v[104:107]
	v_mfma_f32_16x16x32_bf16 v[68:71], v[4:7], v[220:223], v[120:123]
	v_mfma_f32_16x16x32_bf16 v[64:67], v[174:177], v[220:223], v[124:127]
	s_barrier
	ds_read_b128 v[224:227], v154
	ds_read_b128 v[228:231], v154 offset:1024
	ds_read_b128 v[232:235], v154 offset:2048
	ds_read_b128 v[154:157], v154 offset:3072
	s_waitcnt vmcnt(0)
	s_barrier
	s_waitcnt lgkmcnt(0)
	s_waitcnt lgkmcnt(0)
	v_mfma_f32_16x16x32_bf16 v[92:95], v[224:227], v[20:23], v[92:95]
	v_mfma_f32_16x16x32_bf16 v[20:23], v[232:235], v[20:23], v[88:91]
	v_mfma_f32_16x16x32_bf16 v[88:91], v[224:227], v[200:203], v[180:183]
	v_mfma_f32_16x16x32_bf16 v[104:107], v[232:235], v[200:203], v[184:187]
	v_mfma_f32_16x16x32_bf16 v[76:79], v[224:227], v[208:211], v[76:79]
	v_mfma_f32_16x16x32_bf16 v[72:75], v[232:235], v[208:211], v[72:75]
	v_mfma_f32_16x16x32_bf16 v[178:181], v[224:227], v[216:219], v[188:191]
	v_mfma_f32_16x16x32_bf16 v[182:185], v[232:235], v[216:219], v[192:195]
	v_mfma_f32_16x16x32_bf16 v[124:127], v[228:231], v[196:199], v[92:95]
	v_mfma_f32_16x16x32_bf16 v[120:123], v[154:157], v[196:199], v[20:23]
	v_mfma_f32_16x16x32_bf16 v[108:111], v[228:231], v[204:207], v[88:91]
	v_mfma_f32_16x16x32_bf16 v[104:107], v[154:157], v[204:207], v[104:107]
	v_mfma_f32_16x16x32_bf16 v[92:95], v[228:231], v[212:215], v[76:79]
	v_mfma_f32_16x16x32_bf16 v[88:91], v[154:157], v[212:215], v[72:75]
	v_mfma_f32_16x16x32_bf16 v[76:79], v[228:231], v[220:223], v[178:181]
	v_mfma_f32_16x16x32_bf16 v[72:75], v[154:157], v[220:223], v[182:185]
	s_barrier
	ds_read_b128 v[178:181], v152 offset:49152
	ds_read_b128 v[182:185], v152 offset:50176
	ds_read_b128 v[186:189], v151 offset:49152
	ds_read_b128 v[190:193], v151 offset:50176
	ds_read_b128 v[194:197], v150 offset:49152
	ds_read_b128 v[150:153], v150 offset:50176
	ds_read_b128 v[198:201], v149 offset:49152
	ds_read_b128 v[202:205], v149 offset:50176
	s_barrier
	s_waitcnt lgkmcnt(0)
	s_waitcnt lgkmcnt(0)
	v_mfma_f32_16x16x32_bf16 v[20:23], v[0:3], v[178:181], v[60:63]
	v_mfma_f32_16x16x32_bf16 v[56:59], v[16:19], v[178:181], v[56:59]
	v_mfma_f32_16x16x32_bf16 v[60:63], v[0:3], v[186:189], v[52:55]
	v_mfma_f32_16x16x32_bf16 v[206:209], v[16:19], v[186:189], v[48:51]
	v_mfma_f32_16x16x32_bf16 v[44:47], v[0:3], v[194:197], v[44:47]
	v_mfma_f32_16x16x32_bf16 v[40:43], v[16:19], v[194:197], v[40:43]
	v_mfma_f32_16x16x32_bf16 v[0:3], v[0:3], v[198:201], v[36:39]
	v_mfma_f32_16x16x32_bf16 v[210:213], v[16:19], v[198:201], v[32:35]
	v_mfma_f32_16x16x32_bf16 v[52:55], v[4:7], v[182:185], v[20:23]
	v_mfma_f32_16x16x32_bf16 v[48:51], v[174:177], v[182:185], v[56:59]
	v_mfma_f32_16x16x32_bf16 v[36:39], v[4:7], v[190:193], v[60:63]
	v_mfma_f32_16x16x32_bf16 v[32:35], v[174:177], v[190:193], v[206:209]
	v_mfma_f32_16x16x32_bf16 v[20:23], v[4:7], v[150:153], v[44:47]
	v_mfma_f32_16x16x32_bf16 v[16:19], v[174:177], v[150:153], v[40:43]
	v_mfma_f32_16x16x32_bf16 v[4:7], v[4:7], v[202:205], v[0:3]
	v_mfma_f32_16x16x32_bf16 v[0:3], v[174:177], v[202:205], v[210:213]
	v_mfma_f32_16x16x32_bf16 v[28:31], v[224:227], v[178:181], v[28:31]
	v_mfma_f32_16x16x32_bf16 v[24:27], v[232:235], v[178:181], v[24:27]
	v_mfma_f32_16x16x32_bf16 v[40:43], v[224:227], v[186:189], v[134:137]
	v_mfma_f32_16x16x32_bf16 v[134:137], v[232:235], v[186:189], v[138:141]
	v_mfma_f32_16x16x32_bf16 v[12:15], v[224:227], v[194:197], v[12:15]
	v_mfma_f32_16x16x32_bf16 v[8:11], v[232:235], v[194:197], v[8:11]
	v_mfma_f32_16x16x32_bf16 v[138:141], v[224:227], v[198:201], v[170:173]
	v_mfma_f32_16x16x32_bf16 v[158:161], v[232:235], v[198:201], v[158:161]
	v_mfma_f32_16x16x32_bf16 v[60:63], v[228:231], v[182:185], v[28:31]
	v_mfma_f32_16x16x32_bf16 v[56:59], v[154:157], v[182:185], v[24:27]
	v_mfma_f32_16x16x32_bf16 v[44:47], v[228:231], v[190:193], v[40:43]
	v_mfma_f32_16x16x32_bf16 v[40:43], v[154:157], v[190:193], v[134:137]
	v_mfma_f32_16x16x32_bf16 v[28:31], v[228:231], v[150:153], v[12:15]
	v_mfma_f32_16x16x32_bf16 v[24:27], v[154:157], v[150:153], v[8:11]
	v_mfma_f32_16x16x32_bf16 v[12:15], v[228:231], v[202:205], v[138:141]
	v_mfma_f32_16x16x32_bf16 v[8:11], v[154:157], v[202:205], v[158:161]
	v_cmp_gt_u32_e32 vcc, s56, v130
	s_barrier
	s_and_saveexec_b64 s[42:43], vcc
	s_cbranch_execz .LBB0_56
	s_barrier

; #define STAGE(P, BASE, LD, br, kt) do { const char* _g = (const char*)((BASE) + (size_t)(br) * (LD) + (size_t)(kt) * 64); \
;     for (int _i = 0; _i < 2; ++_i) { int _b = tidx * 16 + _i * 8192; int _r, _c; stage_rc(_b, _r, _c); \
;       __builtin_amdgcn_global_load_lds((const unsigned*)(_g + (unsigned)((_r * (LD) + _c) * 2)), (unsigned*)((char*)(P) + _b), 16, 0, 0); } } while (0)
; #define LDA(dst, b, h) for (int m = 0; m < 4; ++m) for (int k = 0; k < 2; ++k) \
;     dst[m][k] = *reinterpret_cast<const bf16x8*>((char*)SA(b, h) + lds_byte(wr * 64 + m * 16 + fr, k * 32 + fq * 8))
; #define LDB(dst, b, h) for (int n = 0; n < 2; ++n) for (int k = 0; k < 2; ++k) \
;     dst[n][k] = *reinterpret_cast<const bf16x8*>((char*)SB(b, h) + lds_byte(wc * 32 + n * 16 + fr, k * 32 + fq * 8))
; #define MMA(ai, bj, At_, Bt_) do { __builtin_amdgcn_s_setprio(1); \
;     for (int k = 0; k < 2; ++k) for (int m = 0; m < 4; ++m) for (int n = 0; n < 2; ++n) \
;       acc[ai][bj][m][n] = __builtin_amdgcn_mfma_f32_16x16x32_bf16(At_[m][k], Bt_[n][k], acc[ai][bj][m][n], 0, 0, 0); \
;     __builtin_amdgcn_s_setprio(0); } while (0)
; #define WAIT_L(n) asm volatile("s_waitcnt lgkmcnt(" #n ")" ::: "memory")
; #define BAR __builtin_amdgcn_s_barrier()
; #define SCHED __builtin_amdgcn_sched_barrier(0)
; template <int EPI, int lda, int ldb, int N, int K>
; __device__ __forceinline__ void gemm_phase(const u16* __restrict__ A, const u16* __restrict__ Bt, const GemmEpi ep, int wv) {
;     ...
;     for (int t = 0; t < nt - 2; t += 2) {
;       LDB(B0, 0, 0); SCHED; LDA(At, 0, 0); STAGE(SA(1, 1), Ab, lda, brow + HALF, t + 1);
;       WAIT_L(8); BAR; WAIT_L(0); MMA(0, 0, At, B0); BAR; SCHED;
;       LDB(B1, 0, 1); STAGE(SB(0, 0), Bt, ldb, bcol, t + 2);
;       BAR; WAIT_L(0); MMA(0, 1, At, B1); BAR;
;       LDA(At, 0, 1); STAGE(SA(0, 0), Ab, lda, brow, t + 2);
;       BAR; WAIT_L(0); MMA(1, 0, At, B0); BAR; SCHED;
.LBB0_224:
	ds_read_b128 v[168:171], v164
	ds_read_b128 v[174:177], v164 offset:1024
	ds_read_b128 v[178:181], v164 offset:2048
	ds_read_b128 v[182:185], v164 offset:3072
	v_add_u32_e32 v172, 0xc000, v147
	v_lshl_add_u64 v[238:239], v[136:137], 0, s[44:45]
	v_readfirstlane_b32 s66, v172
	v_add_u32_e32 v173, 0xe000, v147
	v_lshl_add_u64 v[166:167], v[238:239], 0, s[18:19]
	s_mov_b32 m0, s66
	v_lshl_add_u64 v[240:241], v[134:135], 0, s[44:45]
	v_readfirstlane_b32 s66, v173
	ds_read_b128 v[186:189], v155
	ds_read_b128 v[190:193], v155 offset:1024
	ds_read_b128 v[194:197], v154
	ds_read_b128 v[198:201], v154 offset:1024
	ds_read_b128 v[202:205], v153
	ds_read_b128 v[206:209], v153 offset:1024
	ds_read_b128 v[210:213], v152
	ds_read_b128 v[214:217], v152 offset:1024
	global_load_lds_dwordx4 v[166:167], off
	v_lshl_add_u64 v[166:167], v[240:241], 0, s[18:19]
	s_mov_b32 m0, s66
	s_nop 0
	global_load_lds_dwordx4 v[166:167], off
	s_waitcnt lgkmcnt(8)
	s_barrier
	s_waitcnt lgkmcnt(0)
	s_waitcnt lgkmcnt(0)
	v_mfma_f32_16x16x32_bf16 v[124:127], v[168:171], v[186:189], v[124:127]
	v_mfma_f32_16x16x32_bf16 v[120:123], v[178:181], v[186:189], v[120:123]
	v_mfma_f32_16x16x32_bf16 v[116:119], v[168:171], v[194:197], v[116:119]
	v_mfma_f32_16x16x32_bf16 v[112:115], v[178:181], v[194:197], v[112:115]
	v_mfma_f32_16x16x32_bf16 v[108:111], v[168:171], v[202:205], v[108:111]
	v_mfma_f32_16x16x32_bf16 v[104:107], v[178:181], v[202:205], v[104:107]
	v_mfma_f32_16x16x32_bf16 v[100:103], v[168:171], v[210:213], v[100:103]
	v_mfma_f32_16x16x32_bf16 v[96:99], v[178:181], v[210:213], v[96:99]
	v_mfma_f32_16x16x32_bf16 v[124:127], v[174:177], v[190:193], v[124:127]
	v_mfma_f32_16x16x32_bf16 v[120:123], v[182:185], v[190:193], v[120:123]
	v_mfma_f32_16x16x32_bf16 v[116:119], v[174:177], v[198:201], v[116:119]
	v_mfma_f32_16x16x32_bf16 v[112:115], v[182:185], v[198:201], v[112:115]
	v_mfma_f32_16x16x32_bf16 v[108:111], v[174:177], v[206:209], v[108:111]
	v_mfma_f32_16x16x32_bf16 v[104:107], v[182:185], v[206:209], v[104:107]
	v_mfma_f32_16x16x32_bf16 v[100:103], v[174:177], v[214:217], v[100:103]
	v_mfma_f32_16x16x32_bf16 v[96:99], v[182:185], v[214:217], v[96:99]
	s_barrier
	v_add_u32_e32 v165, s55, v156
	v_lshl_add_u64 v[242:243], v[144:145], 0, s[44:45]
	v_readfirstlane_b32 s66, v165
	v_lshl_add_u64 v[166:167], v[242:243], 0, s[20:21]
	s_mov_b32 m0, s66
	ds_read_b128 v[218:221], v163
	ds_read_b128 v[222:225], v163 offset:1024
	ds_read_b128 v[226:229], v163 offset:2048
	ds_read_b128 v[230:233], v163 offset:3072
	global_load_lds_dwordx4 v[166:167], off
	v_add_u32_e32 v166, 0x2000, v165
	v_lshl_add_u64 v[244:245], v[142:143], 0, s[44:45]
	v_readfirstlane_b32 s66, v166
	v_lshl_add_u64 v[234:235], v[244:245], 0, s[20:21]
	s_mov_b32 m0, s66
	s_nop 0
	global_load_lds_dwordx4 v[234:235], off
	s_barrier
	s_waitcnt lgkmcnt(0)
	s_waitcnt lgkmcnt(0)
	v_mfma_f32_16x16x32_bf16 v[92:95], v[218:221], v[186:189], v[92:95]
	v_mfma_f32_16x16x32_bf16 v[88:91], v[226:229], v[186:189], v[88:91]
	v_mfma_f32_16x16x32_bf16 v[84:87], v[218:221], v[194:197], v[84:87]
	v_mfma_f32_16x16x32_bf16 v[80:83], v[226:229], v[194:197], v[80:83]
	v_mfma_f32_16x16x32_bf16 v[76:79], v[218:221], v[202:205], v[76:79]
	v_mfma_f32_16x16x32_bf16 v[72:75], v[226:229], v[202:205], v[72:75]
	v_mfma_f32_16x16x32_bf16 v[68:71], v[218:221], v[210:213], v[68:71]
	v_mfma_f32_16x16x32_bf16 v[64:67], v[226:229], v[210:213], v[64:67]
	v_mfma_f32_16x16x32_bf16 v[92:95], v[222:225], v[190:193], v[92:95]
	v_mfma_f32_16x16x32_bf16 v[88:91], v[230:233], v[190:193], v[88:91]
	v_mfma_f32_16x16x32_bf16 v[84:87], v[222:225], v[198:201], v[84:87]
	v_mfma_f32_16x16x32_bf16 v[80:83], v[230:233], v[198:201], v[80:83]
	v_mfma_f32_16x16x32_bf16 v[76:79], v[222:225], v[206:209], v[76:79]
	v_mfma_f32_16x16x32_bf16 v[72:75], v[230:233], v[206:209], v[72:75]
	v_mfma_f32_16x16x32_bf16 v[68:71], v[222:225], v[214:217], v[68:71]
	v_mfma_f32_16x16x32_bf16 v[64:67], v[230:233], v[214:217], v[64:67]
	v_readfirstlane_b32 s66, v147
	v_add_u32_e32 v167, 0x2000, v147
	v_lshl_add_u64 v[234:235], v[238:239], 0, s[22:23]
	s_mov_b32 m0, s66
	v_readfirstlane_b32 s66, v167
	s_barrier
	ds_read_b128 v[186:189], v155 offset:16384
	ds_read_b128 v[190:193], v155 offset:17408
	ds_read_b128 v[194:197], v154 offset:16384
	ds_read_b128 v[198:201], v154 offset:17408
	ds_read_b128 v[202:205], v153 offset:16384
	ds_read_b128 v[206:209], v153 offset:17408
	ds_read_b128 v[210:213], v152 offset:16384
	ds_read_b128 v[214:217], v152 offset:17408
	global_load_lds_dwordx4 v[234:235], off
	v_lshl_add_u64 v[234:235], v[240:241], 0, s[22:23]
	s_mov_b32 m0, s66
	s_nop 0
	global_load_lds_dwordx4 v[234:235], off
	s_barrier
	s_waitcnt lgkmcnt(0)
	s_waitcnt lgkmcnt(0)
	v_mfma_f32_16x16x32_bf16 v[60:63], v[168:171], v[186:189], v[60:63]
	v_mfma_f32_16x16x32_bf16 v[56:59], v[178:181], v[186:189], v[56:59]
	v_mfma_f32_16x16x32_bf16 v[52:55], v[168:171], v[194:197], v[52:55]
	v_mfma_f32_16x16x32_bf16 v[48:51], v[178:181], v[194:197], v[48:51]
	v_mfma_f32_16x16x32_bf16 v[44:47], v[168:171], v[202:205], v[44:47]
	v_mfma_f32_16x16x32_bf16 v[40:43], v[178:181], v[202:205], v[40:43]
	v_mfma_f32_16x16x32_bf16 v[36:39], v[168:171], v[210:213], v[36:39]
	v_mfma_f32_16x16x32_bf16 v[32:35], v[178:181], v[210:213], v[32:35]
	v_mfma_f32_16x16x32_bf16 v[60:63], v[174:177], v[190:193], v[60:63]
	v_mfma_f32_16x16x32_bf16 v[56:59], v[182:185], v[190:193], v[56:59]
	v_mfma_f32_16x16x32_bf16 v[52:55], v[174:177], v[198:201], v[52:55]
	v_mfma_f32_16x16x32_bf16 v[48:51], v[182:185], v[198:201], v[48:51]
	v_mfma_f32_16x16x32_bf16 v[44:47], v[174:177], v[206:209], v[44:47]
	v_mfma_f32_16x16x32_bf16 v[40:43], v[182:185], v[206:209], v[40:43]
	v_mfma_f32_16x16x32_bf16 v[36:39], v[174:177], v[214:217], v[36:39]
	v_mfma_f32_16x16x32_bf16 v[32:35], v[182:185], v[214:217], v[32:35]
	s_barrier
; #define STAGE(P, BASE, LD, br, kt) do { const char* _g = (const char*)((BASE) + (size_t)(br) * (LD) + (size_t)(kt) * 64); \
;     for (int _i = 0; _i < 2; ++_i) { int _b = tidx * 16 + _i * 8192; int _r, _c; stage_rc(_b, _r, _c); \
;       __builtin_amdgcn_global_load_lds((const unsigned*)(_g + (unsigned)((_r * (LD) + _c) * 2)), (unsigned*)((char*)(P) + _b), 16, 0, 0); } } while (0)
; #define LDA(dst, b, h) for (int m = 0; m < 4; ++m) for (int k = 0; k < 2; ++k) \
;     dst[m][k] = *reinterpret_cast<const bf16x8*>((char*)SA(b, h) + lds_byte(wr * 64 + m * 16 + fr, k * 32 + fq * 8))
; #define LDB(dst, b, h) for (int n = 0; n < 2; ++n) for (int k = 0; k < 2; ++k) \
;     dst[n][k] = *reinterpret_cast<const bf16x8*>((char*)SB(b, h) + lds_byte(wc * 32 + n * 16 + fr, k * 32 + fq * 8))
; #define MMA(ai, bj, At_, Bt_) do { __builtin_amdgcn_s_setprio(1); \
;     for (int k = 0; k < 2; ++k) for (int m = 0; m < 4; ++m) for (int n = 0; n < 2; ++n) \
;       acc[ai][bj][m][n] = __builtin_amdgcn_mfma_f32_16x16x32_bf16(At_[m][k], Bt_[n][k], acc[ai][bj][m][n], 0, 0, 0); \
;     __builtin_amdgcn_s_setprio(0); } while (0)
; #define WAIT_V(n) asm volatile("s_waitcnt vmcnt(" #n ")" ::: "memory")
; #define WAIT_L(n) asm volatile("s_waitcnt lgkmcnt(" #n ")" ::: "memory")
; #define BAR __builtin_amdgcn_s_barrier()
; #define SCHED __builtin_amdgcn_sched_barrier(0)
; template <int EPI, int lda, int ldb, int N, int K>
; __device__ __forceinline__ void gemm_phase(const u16* __restrict__ A, const u16* __restrict__ Bt, const GemmEpi ep, int wv) {
;     ...
;       STAGE(SB(0, 1), Bt, ldb, bcol + HALF, t + 2);
;       WAIT_V(6); BAR; MMA(1, 1, At, B1); BAR;
;       LDB(B0, 1, 0); SCHED; LDA(At, 1, 0); STAGE(SA(0, 1), Ab, lda, brow + HALF, t + 2);
;       WAIT_L(8); BAR; WAIT_L(0); MMA(0, 0, At, B0); BAR; SCHED;
;       LDB(B1, 1, 1); STAGE(SB(1, 0), Bt, ldb, bcol, t + 3);
;       BAR; WAIT_L(0); MMA(0, 1, At, B1); BAR;
	v_add_u32_e32 v168, s56, v156
	v_lshl_add_u64 v[246:247], v[140:141], 0, s[44:45]
	v_readfirstlane_b32 s66, v168
	v_add_u32_e32 v169, 0x2000, v168
	v_lshl_add_u64 v[170:171], v[246:247], 0, s[24:25]
	s_mov_b32 m0, s66
	v_lshl_add_u64 v[248:249], v[138:139], 0, s[44:45]
	v_readfirstlane_b32 s66, v169
	global_load_lds_dwordx4 v[170:171], off
	v_lshl_add_u64 v[170:171], v[248:249], 0, s[24:25]
	s_mov_b32 m0, s66
	s_nop 0
	global_load_lds_dwordx4 v[170:171], off
	s_waitcnt vmcnt(6)
	s_barrier
	v_mfma_f32_16x16x32_bf16 v[28:31], v[218:221], v[186:189], v[28:31]
	v_mfma_f32_16x16x32_bf16 v[24:27], v[226:229], v[186:189], v[24:27]
	v_mfma_f32_16x16x32_bf16 v[20:23], v[218:221], v[194:197], v[20:23]
	v_mfma_f32_16x16x32_bf16 v[16:19], v[226:229], v[194:197], v[16:19]
	v_mfma_f32_16x16x32_bf16 v[12:15], v[218:221], v[202:205], v[12:15]
	v_mfma_f32_16x16x32_bf16 v[8:11], v[226:229], v[202:205], v[8:11]
	v_mfma_f32_16x16x32_bf16 v[4:7], v[218:221], v[210:213], v[4:7]
	v_mfma_f32_16x16x32_bf16 v[0:3], v[226:229], v[210:213], v[0:3]
	v_mfma_f32_16x16x32_bf16 v[28:31], v[222:225], v[190:193], v[28:31]
	v_mfma_f32_16x16x32_bf16 v[24:27], v[230:233], v[190:193], v[24:27]
	v_mfma_f32_16x16x32_bf16 v[20:23], v[222:225], v[198:201], v[20:23]
	v_mfma_f32_16x16x32_bf16 v[16:19], v[230:233], v[198:201], v[16:19]
	v_mfma_f32_16x16x32_bf16 v[12:15], v[222:225], v[206:209], v[12:15]
	v_mfma_f32_16x16x32_bf16 v[8:11], v[230:233], v[206:209], v[8:11]
	v_mfma_f32_16x16x32_bf16 v[4:7], v[222:225], v[214:217], v[4:7]
	v_mfma_f32_16x16x32_bf16 v[0:3], v[230:233], v[214:217], v[0:3]
	s_barrier
	ds_read_b128 v[174:177], v159
	ds_read_b128 v[178:181], v159 offset:1024
	ds_read_b128 v[182:185], v159 offset:2048
	ds_read_b128 v[186:189], v159 offset:3072
	v_add_u32_e32 v170, 0x4000, v147
	v_add_u32_e32 v171, 0x6000, v147
	v_readfirstlane_b32 s66, v170
	v_lshl_add_u64 v[222:223], v[238:239], 0, s[26:27]
	s_mov_b32 m0, s66
	v_readfirstlane_b32 s66, v171
	ds_read_b128 v[190:193], v155 offset:32768
	ds_read_b128 v[194:197], v155 offset:33792
	ds_read_b128 v[198:201], v154 offset:32768
	ds_read_b128 v[202:205], v154 offset:33792
	ds_read_b128 v[206:209], v153 offset:32768
	ds_read_b128 v[210:213], v153 offset:33792
	ds_read_b128 v[214:217], v152 offset:32768
	ds_read_b128 v[218:221], v152 offset:33792
	global_load_lds_dwordx4 v[222:223], off
	v_lshl_add_u64 v[222:223], v[240:241], 0, s[26:27]
	s_mov_b32 m0, s66
	s_nop 0
	global_load_lds_dwordx4 v[222:223], off
	s_waitcnt lgkmcnt(8)
	s_barrier
	s_waitcnt lgkmcnt(0)
	s_waitcnt lgkmcnt(0)
	v_mfma_f32_16x16x32_bf16 v[124:127], v[174:177], v[190:193], v[124:127]
	v_mfma_f32_16x16x32_bf16 v[120:123], v[182:185], v[190:193], v[120:123]
	v_mfma_f32_16x16x32_bf16 v[116:119], v[174:177], v[198:201], v[116:119]
	v_mfma_f32_16x16x32_bf16 v[112:115], v[182:185], v[198:201], v[112:115]
	v_mfma_f32_16x16x32_bf16 v[108:111], v[174:177], v[206:209], v[108:111]
	v_mfma_f32_16x16x32_bf16 v[104:107], v[182:185], v[206:209], v[104:107]
	v_mfma_f32_16x16x32_bf16 v[100:103], v[174:177], v[214:217], v[100:103]
	v_mfma_f32_16x16x32_bf16 v[96:99], v[182:185], v[214:217], v[96:99]
	v_mfma_f32_16x16x32_bf16 v[124:127], v[178:181], v[194:197], v[124:127]
	v_mfma_f32_16x16x32_bf16 v[120:123], v[186:189], v[194:197], v[120:123]
	v_mfma_f32_16x16x32_bf16 v[116:119], v[178:181], v[202:205], v[116:119]
	v_mfma_f32_16x16x32_bf16 v[112:115], v[186:189], v[202:205], v[112:115]
	v_mfma_f32_16x16x32_bf16 v[108:111], v[178:181], v[210:213], v[108:111]
	v_mfma_f32_16x16x32_bf16 v[104:107], v[186:189], v[210:213], v[104:107]
	v_mfma_f32_16x16x32_bf16 v[100:103], v[178:181], v[218:221], v[100:103]
	v_mfma_f32_16x16x32_bf16 v[96:99], v[186:189], v[218:221], v[96:99]
	s_barrier
	v_readfirstlane_b32 s66, v158
	v_lshl_add_u64 v[242:243], v[242:243], 0, s[36:37]
	s_mov_b32 m0, s66
	ds_read_b128 v[222:225], v157
	ds_read_b128 v[226:229], v157 offset:1024
	ds_read_b128 v[230:233], v157 offset:2048
	ds_read_b128 v[234:237], v157 offset:3072
	global_load_lds_dwordx4 v[242:243], off
	v_lshl_add_u64 v[242:243], v[244:245], 0, s[36:37]
	v_add_u32_e32 v244, 0x2000, v158
	s_nop 0
	v_readfirstlane_b32 s66, v244
	s_mov_b32 m0, s66
	s_nop 0
	global_load_lds_dwordx4 v[242:243], off
	s_barrier
	s_waitcnt lgkmcnt(0)
	s_waitcnt lgkmcnt(0)
	v_mfma_f32_16x16x32_bf16 v[92:95], v[222:225], v[190:193], v[92:95]
	v_mfma_f32_16x16x32_bf16 v[88:91], v[230:233], v[190:193], v[88:91]
	v_mfma_f32_16x16x32_bf16 v[84:87], v[222:225], v[198:201], v[84:87]
	v_mfma_f32_16x16x32_bf16 v[80:83], v[230:233], v[198:201], v[80:83]
	v_mfma_f32_16x16x32_bf16 v[76:79], v[222:225], v[206:209], v[76:79]
	v_mfma_f32_16x16x32_bf16 v[72:75], v[230:233], v[206:209], v[72:75]
	v_mfma_f32_16x16x32_bf16 v[68:71], v[222:225], v[214:217], v[68:71]
	v_mfma_f32_16x16x32_bf16 v[64:67], v[230:233], v[214:217], v[64:67]
	v_mfma_f32_16x16x32_bf16 v[92:95], v[226:229], v[194:197], v[92:95]
	v_mfma_f32_16x16x32_bf16 v[88:91], v[234:237], v[194:197], v[88:91]
	v_mfma_f32_16x16x32_bf16 v[84:87], v[226:229], v[202:205], v[84:87]
	v_mfma_f32_16x16x32_bf16 v[80:83], v[234:237], v[202:205], v[80:83]
	v_mfma_f32_16x16x32_bf16 v[76:79], v[226:229], v[210:213], v[76:79]
	v_mfma_f32_16x16x32_bf16 v[72:75], v[234:237], v[210:213], v[72:75]
	v_mfma_f32_16x16x32_bf16 v[68:71], v[226:229], v[218:221], v[68:71]
	v_mfma_f32_16x16x32_bf16 v[64:67], v[234:237], v[218:221], v[64:67]
	v_readfirstlane_b32 s66, v160
	v_lshl_add_u64 v[238:239], v[238:239], 0, s[38:39]
	s_mov_b32 m0, s66
	v_readfirstlane_b32 s66, v161
	s_barrier
; #define STAGE(P, BASE, LD, br, kt) do { const char* _g = (const char*)((BASE) + (size_t)(br) * (LD) + (size_t)(kt) * 64); \
;     for (int _i = 0; _i < 2; ++_i) { int _b = tidx * 16 + _i * 8192; int _r, _c; stage_rc(_b, _r, _c); \
;       __builtin_amdgcn_global_load_lds((const unsigned*)(_g + (unsigned)((_r * (LD) + _c) * 2)), (unsigned*)((char*)(P) + _b), 16, 0, 0); } } while (0)
; #define LDA(dst, b, h) for (int m = 0; m < 4; ++m) for (int k = 0; k < 2; ++k) \
;     dst[m][k] = *reinterpret_cast<const bf16x8*>((char*)SA(b, h) + lds_byte(wr * 64 + m * 16 + fr, k * 32 + fq * 8))
; #define LDB(dst, b, h) for (int n = 0; n < 2; ++n) for (int k = 0; k < 2; ++k) \
;     dst[n][k] = *reinterpret_cast<const bf16x8*>((char*)SB(b, h) + lds_byte(wc * 32 + n * 16 + fr, k * 32 + fq * 8))
; #define MMA(ai, bj, At_, Bt_) do { __builtin_amdgcn_s_setprio(1); \
;     for (int k = 0; k < 2; ++k) for (int m = 0; m < 4; ++m) for (int n = 0; n < 2; ++n) \
;       acc[ai][bj][m][n] = __builtin_amdgcn_mfma_f32_16x16x32_bf16(At_[m][k], Bt_[n][k], acc[ai][bj][m][n], 0, 0, 0); \
;     __builtin_amdgcn_s_setprio(0); } while (0)
; #define WAIT_V(n) asm volatile("s_waitcnt vmcnt(" #n ")" ::: "memory")
; #define WAIT_L(n) asm volatile("s_waitcnt lgkmcnt(" #n ")" ::: "memory")
; #define BAR __builtin_amdgcn_s_barrier()
; #define SCHED __builtin_amdgcn_sched_barrier(0)
; template <int EPI, int lda, int ldb, int N, int K>
; __device__ __forceinline__ void gemm_phase(const u16* __restrict__ A, const u16* __restrict__ Bt, const GemmEpi ep, int wv) {
;     ...
;       LDA(At, 1, 1); STAGE(SA(1, 0), Ab, lda, brow, t + 3);
;       BAR; WAIT_L(0); MMA(1, 0, At, B0); BAR; SCHED;
;       STAGE(SB(1, 1), Bt, ldb, bcol + HALF, t + 3);
;       WAIT_V(6); BAR; MMA(1, 1, At, B1); BAR;
;     }
;     { LDB(B0, 0, 0); LDA(At, 0, 0); STAGE(SA(1, 1), Ab, lda, brow + HALF, nt - 1);
;       BAR; WAIT_L(0); MMA(0, 0, At, B0); BAR;
;       LDB(B1, 0, 1); BAR; WAIT_L(0); MMA(0, 1, At, B1); BAR;
	ds_read_b128 v[190:193], v155 offset:49152
	ds_read_b128 v[194:197], v155 offset:50176
	ds_read_b128 v[198:201], v154 offset:49152
	ds_read_b128 v[202:205], v154 offset:50176
	ds_read_b128 v[206:209], v153 offset:49152
	ds_read_b128 v[210:213], v153 offset:50176
	ds_read_b128 v[214:217], v152 offset:49152
	ds_read_b128 v[218:221], v152 offset:50176
	global_load_lds_dwordx4 v[238:239], off
	v_lshl_add_u64 v[238:239], v[240:241], 0, s[38:39]
	s_mov_b32 m0, s66
	s_nop 0
	global_load_lds_dwordx4 v[238:239], off
	s_barrier
	s_waitcnt lgkmcnt(0)
	s_waitcnt lgkmcnt(0)
	v_mfma_f32_16x16x32_bf16 v[60:63], v[174:177], v[190:193], v[60:63]
	v_mfma_f32_16x16x32_bf16 v[56:59], v[182:185], v[190:193], v[56:59]
	v_mfma_f32_16x16x32_bf16 v[52:55], v[174:177], v[198:201], v[52:55]
	v_mfma_f32_16x16x32_bf16 v[48:51], v[182:185], v[198:201], v[48:51]
	v_mfma_f32_16x16x32_bf16 v[44:47], v[174:177], v[206:209], v[44:47]
	v_mfma_f32_16x16x32_bf16 v[40:43], v[182:185], v[206:209], v[40:43]
	v_mfma_f32_16x16x32_bf16 v[36:39], v[174:177], v[214:217], v[36:39]
	v_mfma_f32_16x16x32_bf16 v[32:35], v[182:185], v[214:217], v[32:35]
	v_mfma_f32_16x16x32_bf16 v[60:63], v[178:181], v[194:197], v[60:63]
	v_mfma_f32_16x16x32_bf16 v[56:59], v[186:189], v[194:197], v[56:59]
	v_mfma_f32_16x16x32_bf16 v[52:55], v[178:181], v[202:205], v[52:55]
	v_mfma_f32_16x16x32_bf16 v[48:51], v[186:189], v[202:205], v[48:51]
	v_mfma_f32_16x16x32_bf16 v[44:47], v[178:181], v[210:213], v[44:47]
	v_mfma_f32_16x16x32_bf16 v[40:43], v[186:189], v[210:213], v[40:43]
	v_mfma_f32_16x16x32_bf16 v[36:39], v[178:181], v[218:221], v[36:39]
	v_mfma_f32_16x16x32_bf16 v[32:35], v[186:189], v[218:221], v[32:35]
	s_barrier
	v_readfirstlane_b32 s66, v162
	v_add_u32_e32 v176, 0x2000, v162
	v_lshl_add_u64 v[174:175], v[246:247], 0, s[42:43]
	s_mov_b32 m0, s66
	v_readfirstlane_b32 s66, v176
	global_load_lds_dwordx4 v[174:175], off
	v_lshl_add_u64 v[174:175], v[248:249], 0, s[42:43]
	s_mov_b32 m0, s66
	s_nop 0
	global_load_lds_dwordx4 v[174:175], off
	s_waitcnt vmcnt(6)
	s_barrier
	v_mfma_f32_16x16x32_bf16 v[28:31], v[222:225], v[190:193], v[28:31]
	v_mfma_f32_16x16x32_bf16 v[24:27], v[230:233], v[190:193], v[24:27]
	v_mfma_f32_16x16x32_bf16 v[20:23], v[222:225], v[198:201], v[20:23]
	v_mfma_f32_16x16x32_bf16 v[16:19], v[230:233], v[198:201], v[16:19]
	v_mfma_f32_16x16x32_bf16 v[12:15], v[222:225], v[206:209], v[12:15]
	v_mfma_f32_16x16x32_bf16 v[8:11], v[230:233], v[206:209], v[8:11]
	v_mfma_f32_16x16x32_bf16 v[4:7], v[222:225], v[214:217], v[4:7]
	v_mfma_f32_16x16x32_bf16 v[0:3], v[230:233], v[214:217], v[0:3]
	v_mfma_f32_16x16x32_bf16 v[28:31], v[226:229], v[194:197], v[28:31]
	v_mfma_f32_16x16x32_bf16 v[24:27], v[234:237], v[194:197], v[24:27]
	v_mfma_f32_16x16x32_bf16 v[20:23], v[226:229], v[202:205], v[20:23]
	v_mfma_f32_16x16x32_bf16 v[16:19], v[234:237], v[202:205], v[16:19]
	v_mfma_f32_16x16x32_bf16 v[12:15], v[226:229], v[210:213], v[12:15]
	v_mfma_f32_16x16x32_bf16 v[8:11], v[234:237], v[210:213], v[8:11]
	v_mfma_f32_16x16x32_bf16 v[4:7], v[226:229], v[218:221], v[4:7]
	v_mfma_f32_16x16x32_bf16 v[0:3], v[234:237], v[218:221], v[0:3]
	s_add_i32 s65, s65, 2
	s_add_u32 s44, s44, 0x100
	s_addc_u32 s45, s45, 0
	s_cmpk_gt_u32 s65, 0x51
	s_barrier
	s_cbranch_scc0 .LBB0_224
	s_add_i32 s44, s14, 0x80
	s_mul_hi_i32 s45, s44, 0x2b00
	s_mulk_i32 s44, 0x2b00
	s_add_u32 s44, s48, s44
	s_addc_u32 s45, s49, s45
	s_add_u32 s44, s44, 0x2a80
	s_addc_u32 s45, s45, 0
	v_readfirstlane_b32 s65, v172
	v_lshl_add_u64 v[160:161], s[44:45], 0, v[128:129]
	s_mov_b32 m0, s65
	ds_read_b128 v[134:137], v164
	ds_read_b128 v[138:141], v164 offset:1024
	ds_read_b128 v[142:145], v164 offset:2048
	ds_read_b128 v[174:177], v164 offset:3072
	ds_read_b128 v[178:181], v155
	ds_read_b128 v[182:185], v155 offset:1024
	ds_read_b128 v[186:189], v154
	ds_read_b128 v[190:193], v154 offset:1024
	ds_read_b128 v[194:197], v153
	ds_read_b128 v[198:201], v153 offset:1024
	ds_read_b128 v[202:205], v152
	ds_read_b128 v[206:209], v152 offset:1024
	global_load_lds_dwordx4 v[160:161], off
	v_lshl_add_u64 v[160:161], s[44:45], 0, v[132:133]
	v_readfirstlane_b32 s44, v173
	s_mov_b32 m0, s44
	s_nop 0
	global_load_lds_dwordx4 v[160:161], off
	s_barrier
	s_waitcnt lgkmcnt(0)
	s_waitcnt lgkmcnt(0)
	v_mfma_f32_16x16x32_bf16 v[124:127], v[134:137], v[178:181], v[124:127]
	v_mfma_f32_16x16x32_bf16 v[120:123], v[142:145], v[178:181], v[120:123]
	v_mfma_f32_16x16x32_bf16 v[116:119], v[134:137], v[186:189], v[116:119]
	v_mfma_f32_16x16x32_bf16 v[112:115], v[142:145], v[186:189], v[112:115]
	v_mfma_f32_16x16x32_bf16 v[108:111], v[134:137], v[194:197], v[108:111]
	v_mfma_f32_16x16x32_bf16 v[104:107], v[142:145], v[194:197], v[104:107]
	v_mfma_f32_16x16x32_bf16 v[100:103], v[134:137], v[202:205], v[100:103]
	v_mfma_f32_16x16x32_bf16 v[96:99], v[142:145], v[202:205], v[96:99]
	v_mfma_f32_16x16x32_bf16 v[124:127], v[138:141], v[182:185], v[124:127]
	v_mfma_f32_16x16x32_bf16 v[120:123], v[174:177], v[182:185], v[120:123]
	v_mfma_f32_16x16x32_bf16 v[116:119], v[138:141], v[190:193], v[116:119]
	v_mfma_f32_16x16x32_bf16 v[112:115], v[174:177], v[190:193], v[112:115]
	v_mfma_f32_16x16x32_bf16 v[108:111], v[138:141], v[198:201], v[108:111]
	v_mfma_f32_16x16x32_bf16 v[104:107], v[174:177], v[198:201], v[104:107]
	v_mfma_f32_16x16x32_bf16 v[100:103], v[138:141], v[206:209], v[100:103]
	v_mfma_f32_16x16x32_bf16 v[96:99], v[174:177], v[206:209], v[96:99]
	s_barrier
	ds_read_b128 v[210:213], v163
	ds_read_b128 v[214:217], v163 offset:1024
	ds_read_b128 v[218:221], v163 offset:2048
	ds_read_b128 v[160:163], v163 offset:3072
	s_barrier
; #define LDA(dst, b, h) for (int m = 0; m < 4; ++m) for (int k = 0; k < 2; ++k) \
;     dst[m][k] = *reinterpret_cast<const bf16x8*>((char*)SA(b, h) + lds_byte(wr * 64 + m * 16 + fr, k * 32 + fq * 8))
; #define LDB(dst, b, h) for (int n = 0; n < 2; ++n) for (int k = 0; k < 2; ++k) \
;     dst[n][k] = *reinterpret_cast<const bf16x8*>((char*)SB(b, h) + lds_byte(wc * 32 + n * 16 + fr, k * 32 + fq * 8))
; #define MMA(ai, bj, At_, Bt_) do { __builtin_amdgcn_s_setprio(1); \
;     for (int k = 0; k < 2; ++k) for (int m = 0; m < 4; ++m) for (int n = 0; n < 2; ++n) \
;       acc[ai][bj][m][n] = __builtin_amdgcn_mfma_f32_16x16x32_bf16(At_[m][k], Bt_[n][k], acc[ai][bj][m][n], 0, 0, 0); \
;     __builtin_amdgcn_s_setprio(0); } while (0)
; #define WAIT_V(n) asm volatile("s_waitcnt vmcnt(" #n ")" ::: "memory")
; #define WAIT_L(n) asm volatile("s_waitcnt lgkmcnt(" #n ")" ::: "memory")
; #define BAR __builtin_amdgcn_s_barrier()
; template <int EPI, int lda, int ldb, int N, int K>
; __device__ __forceinline__ void gemm_phase(const u16* __restrict__ A, const u16* __restrict__ Bt, const GemmEpi ep, int wv) {
;     ...
;       LDB(B1, 0, 1); BAR; WAIT_L(0); MMA(0, 1, At, B1); BAR;
;       LDA(At, 0, 1); WAIT_V(4); BAR; WAIT_L(0); MMA(1, 0, At, B0); MMA(1, 1, At, B1); BAR; }
;     { LDB(B0, 1, 0); LDA(At, 1, 0); WAIT_V(2); BAR; WAIT_L(0); MMA(0, 0, At, B0); BAR;
	s_waitcnt lgkmcnt(0)
	s_waitcnt lgkmcnt(0)
	v_mfma_f32_16x16x32_bf16 v[92:95], v[210:213], v[178:181], v[92:95]
	v_mfma_f32_16x16x32_bf16 v[88:91], v[218:221], v[178:181], v[88:91]
	v_mfma_f32_16x16x32_bf16 v[76:79], v[210:213], v[194:197], v[76:79]
	v_mfma_f32_16x16x32_bf16 v[72:75], v[218:221], v[194:197], v[72:75]
	v_mfma_f32_16x16x32_bf16 v[84:87], v[210:213], v[186:189], v[84:87]
	v_mfma_f32_16x16x32_bf16 v[80:83], v[218:221], v[186:189], v[80:83]
	v_mfma_f32_16x16x32_bf16 v[68:71], v[210:213], v[202:205], v[68:71]
	v_mfma_f32_16x16x32_bf16 v[64:67], v[218:221], v[202:205], v[64:67]
	v_mfma_f32_16x16x32_bf16 v[92:95], v[214:217], v[182:185], v[92:95]
	v_mfma_f32_16x16x32_bf16 v[88:91], v[160:163], v[182:185], v[88:91]
	v_mfma_f32_16x16x32_bf16 v[76:79], v[214:217], v[198:201], v[76:79]
	v_mfma_f32_16x16x32_bf16 v[72:75], v[160:163], v[198:201], v[72:75]
	v_mfma_f32_16x16x32_bf16 v[178:181], v[214:217], v[190:193], v[84:87]
	v_mfma_f32_16x16x32_bf16 v[182:185], v[160:163], v[190:193], v[80:83]
	v_mfma_f32_16x16x32_bf16 v[186:189], v[214:217], v[206:209], v[68:71]
	v_mfma_f32_16x16x32_bf16 v[190:193], v[160:163], v[206:209], v[64:67]
	s_barrier
	s_nop 0
	ds_read_b128 v[64:67], v155 offset:16384
	ds_read_b128 v[68:71], v155 offset:17408
	ds_read_b128 v[80:83], v154 offset:16384
	ds_read_b128 v[84:87], v154 offset:17408
	ds_read_b128 v[194:197], v153 offset:16384
	ds_read_b128 v[198:201], v153 offset:17408
	ds_read_b128 v[202:205], v152 offset:16384
	ds_read_b128 v[206:209], v152 offset:17408
	s_waitcnt vmcnt(4)
	s_barrier
	s_waitcnt lgkmcnt(0)
	s_waitcnt lgkmcnt(0)
	v_mfma_f32_16x16x32_bf16 v[60:63], v[134:137], v[64:67], v[60:63]
	v_mfma_f32_16x16x32_bf16 v[56:59], v[142:145], v[64:67], v[56:59]
	v_mfma_f32_16x16x32_bf16 v[52:55], v[134:137], v[80:83], v[52:55]
	v_mfma_f32_16x16x32_bf16 v[48:51], v[142:145], v[80:83], v[48:51]
	v_mfma_f32_16x16x32_bf16 v[44:47], v[134:137], v[194:197], v[44:47]
	v_mfma_f32_16x16x32_bf16 v[40:43], v[142:145], v[194:197], v[40:43]
	v_mfma_f32_16x16x32_bf16 v[36:39], v[134:137], v[202:205], v[36:39]
	v_mfma_f32_16x16x32_bf16 v[32:35], v[142:145], v[202:205], v[32:35]
	v_mfma_f32_16x16x32_bf16 v[60:63], v[138:141], v[68:71], v[60:63]
	v_mfma_f32_16x16x32_bf16 v[56:59], v[174:177], v[68:71], v[56:59]
	v_mfma_f32_16x16x32_bf16 v[52:55], v[138:141], v[84:87], v[52:55]
	v_mfma_f32_16x16x32_bf16 v[48:51], v[174:177], v[84:87], v[48:51]
	v_mfma_f32_16x16x32_bf16 v[44:47], v[138:141], v[198:201], v[44:47]
	v_mfma_f32_16x16x32_bf16 v[40:43], v[174:177], v[198:201], v[40:43]
	v_mfma_f32_16x16x32_bf16 v[36:39], v[138:141], v[206:209], v[36:39]
	v_mfma_f32_16x16x32_bf16 v[32:35], v[174:177], v[206:209], v[32:35]
	v_mfma_f32_16x16x32_bf16 v[28:31], v[210:213], v[64:67], v[28:31]
	v_mfma_f32_16x16x32_bf16 v[16:19], v[218:221], v[80:83], v[16:19]
	v_mfma_f32_16x16x32_bf16 v[12:15], v[210:213], v[194:197], v[12:15]
	v_mfma_f32_16x16x32_bf16 v[0:3], v[218:221], v[202:205], v[0:3]
	v_mfma_f32_16x16x32_bf16 v[24:27], v[218:221], v[64:67], v[24:27]
	v_mfma_f32_16x16x32_bf16 v[20:23], v[210:213], v[80:83], v[20:23]
	v_mfma_f32_16x16x32_bf16 v[8:11], v[218:221], v[194:197], v[8:11]
	v_mfma_f32_16x16x32_bf16 v[4:7], v[210:213], v[202:205], v[4:7]
	v_mfma_f32_16x16x32_bf16 v[28:31], v[214:217], v[68:71], v[28:31]
	v_mfma_f32_16x16x32_bf16 v[16:19], v[160:163], v[84:87], v[16:19]
	v_mfma_f32_16x16x32_bf16 v[12:15], v[214:217], v[198:201], v[12:15]
	v_mfma_f32_16x16x32_bf16 v[0:3], v[160:163], v[206:209], v[0:3]
	v_mfma_f32_16x16x32_bf16 v[134:137], v[160:163], v[68:71], v[24:27]
	v_mfma_f32_16x16x32_bf16 v[138:141], v[214:217], v[84:87], v[20:23]
	v_mfma_f32_16x16x32_bf16 v[142:145], v[160:163], v[198:201], v[8:11]
	v_mfma_f32_16x16x32_bf16 v[172:175], v[214:217], v[206:209], v[4:7]
	s_barrier
	s_nop 0
	ds_read_b128 v[4:7], v159
	ds_read_b128 v[8:11], v159 offset:1024
	ds_read_b128 v[20:23], v159 offset:2048
	ds_read_b128 v[158:161], v159 offset:3072
	ds_read_b128 v[24:27], v155 offset:32768
	ds_read_b128 v[194:197], v155 offset:33792
	ds_read_b128 v[198:201], v154 offset:32768
	ds_read_b128 v[202:205], v154 offset:33792
	ds_read_b128 v[206:209], v153 offset:32768
	ds_read_b128 v[210:213], v153 offset:33792
	ds_read_b128 v[214:217], v152 offset:32768
	ds_read_b128 v[218:221], v152 offset:33792
	s_waitcnt vmcnt(2)
	s_barrier
; #define LDA(dst, b, h) for (int m = 0; m < 4; ++m) for (int k = 0; k < 2; ++k) \
;     dst[m][k] = *reinterpret_cast<const bf16x8*>((char*)SA(b, h) + lds_byte(wr * 64 + m * 16 + fr, k * 32 + fq * 8))
; #define LDB(dst, b, h) for (int n = 0; n < 2; ++n) for (int k = 0; k < 2; ++k) \
;     dst[n][k] = *reinterpret_cast<const bf16x8*>((char*)SB(b, h) + lds_byte(wc * 32 + n * 16 + fr, k * 32 + fq * 8))
; #define MMA(ai, bj, At_, Bt_) do { __builtin_amdgcn_s_setprio(1); \
;     for (int k = 0; k < 2; ++k) for (int m = 0; m < 4; ++m) for (int n = 0; n < 2; ++n) \
;       acc[ai][bj][m][n] = __builtin_amdgcn_mfma_f32_16x16x32_bf16(At_[m][k], Bt_[n][k], acc[ai][bj][m][n], 0, 0, 0); \
;     __builtin_amdgcn_s_setprio(0); } while (0)
; #define WAIT_V(n) asm volatile("s_waitcnt vmcnt(" #n ")" ::: "memory")
; #define WAIT_L(n) asm volatile("s_waitcnt lgkmcnt(" #n ")" ::: "memory")
; #define BAR __builtin_amdgcn_s_barrier()
; #define STAGE4(BROW, BCOL, PN) do { const u16* Ab_ = A + (EPI == EPI_RG ? ((PN) >> 1) * 256 : 0); \
;     STAGE(SB(0, 0), Bt, ldb, (BCOL), 0); STAGE(SA(0, 0), Ab_, lda, (BROW), 0); \
;     STAGE(SB(0, 1), Bt, ldb, (BCOL) + HALF, 0); STAGE(SA(0, 1), Ab_, lda, (BROW) + HALF, 0); } while (0)
; template <int EPI, int lda, int ldb, int N, int K>
; __device__ __forceinline__ void gemm_phase(const u16* __restrict__ A, const u16* __restrict__ Bt, const GemmEpi ep, int wv) {
;     ...
;     { LDB(B0, 1, 0); LDA(At, 1, 0); WAIT_V(2); BAR; WAIT_L(0); MMA(0, 0, At, B0); BAR;
;       LDB(B1, 1, 1); WAIT_V(0); BAR; WAIT_L(0); MMA(0, 1, At, B1); BAR;
;       LDA(At, 1, 1); BAR; WAIT_L(0); MMA(1, 0, At, B0); MMA(1, 1, At, B1); BAR; }
;     if (wr == 0) BAR;
;     int ntile = 0, nbrow = 0, nbcol = 0, npn = 0; bool more = false;
;     if constexpr (PF) { ntile = tile + gridDim.x; more = ntile < nwg; if (more) { TILE_COORDS(ntile, nbrow, nbcol, npn); STAGE4(nbrow, nbcol, npn); } }
	s_waitcnt lgkmcnt(0)
	s_waitcnt lgkmcnt(0)
	v_mfma_f32_16x16x32_bf16 v[64:67], v[4:7], v[24:27], v[124:127]
	v_mfma_f32_16x16x32_bf16 v[68:71], v[20:23], v[24:27], v[120:123]
	v_mfma_f32_16x16x32_bf16 v[80:83], v[4:7], v[198:201], v[116:119]
	v_mfma_f32_16x16x32_bf16 v[84:87], v[20:23], v[198:201], v[112:115]
	v_mfma_f32_16x16x32_bf16 v[108:111], v[4:7], v[206:209], v[108:111]
	v_mfma_f32_16x16x32_bf16 v[104:107], v[20:23], v[206:209], v[104:107]
	v_mfma_f32_16x16x32_bf16 v[120:123], v[4:7], v[214:217], v[100:103]
	v_mfma_f32_16x16x32_bf16 v[124:127], v[20:23], v[214:217], v[96:99]
	v_mfma_f32_16x16x32_bf16 v[116:119], v[8:11], v[194:197], v[64:67]
	v_mfma_f32_16x16x32_bf16 v[112:115], v[158:161], v[194:197], v[68:71]
	v_mfma_f32_16x16x32_bf16 v[100:103], v[8:11], v[202:205], v[80:83]
	v_mfma_f32_16x16x32_bf16 v[96:99], v[158:161], v[202:205], v[84:87]
	v_mfma_f32_16x16x32_bf16 v[84:87], v[8:11], v[210:213], v[108:111]
	v_mfma_f32_16x16x32_bf16 v[80:83], v[158:161], v[210:213], v[104:107]
	v_mfma_f32_16x16x32_bf16 v[68:71], v[8:11], v[218:221], v[120:123]
	v_mfma_f32_16x16x32_bf16 v[64:67], v[158:161], v[218:221], v[124:127]
	s_barrier
	ds_read_b128 v[222:225], v157
	ds_read_b128 v[226:229], v157 offset:1024
	ds_read_b128 v[230:233], v157 offset:2048
	ds_read_b128 v[234:237], v157 offset:3072
	s_waitcnt vmcnt(0)
	s_barrier
	s_waitcnt lgkmcnt(0)
	s_waitcnt lgkmcnt(0)
	v_mfma_f32_16x16x32_bf16 v[92:95], v[222:225], v[24:27], v[92:95]
	v_mfma_f32_16x16x32_bf16 v[24:27], v[230:233], v[24:27], v[88:91]
	v_mfma_f32_16x16x32_bf16 v[88:91], v[222:225], v[198:201], v[178:181]
	v_mfma_f32_16x16x32_bf16 v[104:107], v[230:233], v[198:201], v[182:185]
	v_mfma_f32_16x16x32_bf16 v[76:79], v[222:225], v[206:209], v[76:79]
	v_mfma_f32_16x16x32_bf16 v[72:75], v[230:233], v[206:209], v[72:75]
	v_mfma_f32_16x16x32_bf16 v[176:179], v[222:225], v[214:217], v[186:189]
	v_mfma_f32_16x16x32_bf16 v[180:183], v[230:233], v[214:217], v[190:193]
	v_mfma_f32_16x16x32_bf16 v[124:127], v[226:229], v[194:197], v[92:95]
	v_mfma_f32_16x16x32_bf16 v[120:123], v[234:237], v[194:197], v[24:27]
	v_mfma_f32_16x16x32_bf16 v[108:111], v[226:229], v[202:205], v[88:91]
	v_mfma_f32_16x16x32_bf16 v[104:107], v[234:237], v[202:205], v[104:107]
	v_mfma_f32_16x16x32_bf16 v[92:95], v[226:229], v[210:213], v[76:79]
	v_mfma_f32_16x16x32_bf16 v[88:91], v[234:237], v[210:213], v[72:75]
	v_mfma_f32_16x16x32_bf16 v[76:79], v[226:229], v[218:221], v[176:179]
	v_mfma_f32_16x16x32_bf16 v[72:75], v[234:237], v[218:221], v[180:183]
	s_barrier
	ds_read_b128 v[176:179], v155 offset:49152
	ds_read_b128 v[180:183], v155 offset:50176
	ds_read_b128 v[184:187], v154 offset:49152
	ds_read_b128 v[154:157], v154 offset:50176
	ds_read_b128 v[188:191], v153 offset:49152
	ds_read_b128 v[192:195], v153 offset:50176
	ds_read_b128 v[196:199], v152 offset:49152
	ds_read_b128 v[200:203], v152 offset:50176
	s_barrier
	s_waitcnt lgkmcnt(0)
	s_waitcnt lgkmcnt(0)
	v_mfma_f32_16x16x32_bf16 v[24:27], v[4:7], v[176:179], v[60:63]
	v_mfma_f32_16x16x32_bf16 v[60:63], v[20:23], v[176:179], v[56:59]
	v_mfma_f32_16x16x32_bf16 v[204:207], v[4:7], v[184:187], v[52:55]
	v_mfma_f32_16x16x32_bf16 v[48:51], v[20:23], v[184:187], v[48:51]
	v_mfma_f32_16x16x32_bf16 v[44:47], v[4:7], v[188:191], v[44:47]
	v_mfma_f32_16x16x32_bf16 v[208:211], v[20:23], v[188:191], v[40:43]
	v_mfma_f32_16x16x32_bf16 v[4:7], v[4:7], v[196:199], v[36:39]
	v_mfma_f32_16x16x32_bf16 v[32:35], v[20:23], v[196:199], v[32:35]
	v_mfma_f32_16x16x32_bf16 v[56:59], v[8:11], v[180:183], v[24:27]
	v_mfma_f32_16x16x32_bf16 v[52:55], v[158:161], v[180:183], v[60:63]
	v_mfma_f32_16x16x32_bf16 v[40:43], v[8:11], v[154:157], v[204:207]
	v_mfma_f32_16x16x32_bf16 v[36:39], v[158:161], v[154:157], v[48:51]
	v_mfma_f32_16x16x32_bf16 v[24:27], v[8:11], v[192:195], v[44:47]
	v_mfma_f32_16x16x32_bf16 v[20:23], v[158:161], v[192:195], v[208:211]
	v_mfma_f32_16x16x32_bf16 v[8:11], v[8:11], v[200:203], v[4:7]
	v_mfma_f32_16x16x32_bf16 v[4:7], v[158:161], v[200:203], v[32:35]
	v_mfma_f32_16x16x32_bf16 v[28:31], v[222:225], v[176:179], v[28:31]
	v_mfma_f32_16x16x32_bf16 v[32:35], v[230:233], v[176:179], v[134:137]
	v_mfma_f32_16x16x32_bf16 v[44:47], v[222:225], v[184:187], v[138:141]
	v_mfma_f32_16x16x32_bf16 v[16:19], v[230:233], v[184:187], v[16:19]
	v_mfma_f32_16x16x32_bf16 v[12:15], v[222:225], v[188:191], v[12:15]
	v_mfma_f32_16x16x32_bf16 v[134:137], v[230:233], v[188:191], v[142:145]
	v_mfma_f32_16x16x32_bf16 v[138:141], v[222:225], v[196:199], v[172:175]
	v_mfma_f32_16x16x32_bf16 v[0:3], v[230:233], v[196:199], v[0:3]
	v_mfma_f32_16x16x32_bf16 v[60:63], v[226:229], v[180:183], v[28:31]
	v_mfma_f32_16x16x32_bf16 v[48:51], v[234:237], v[180:183], v[32:35]
	v_mfma_f32_16x16x32_bf16 v[44:47], v[226:229], v[154:157], v[44:47]
	v_mfma_f32_16x16x32_bf16 v[32:35], v[234:237], v[154:157], v[16:19]
	v_mfma_f32_16x16x32_bf16 v[28:31], v[226:229], v[192:195], v[12:15]
	v_mfma_f32_16x16x32_bf16 v[16:19], v[234:237], v[192:195], v[134:137]
	v_mfma_f32_16x16x32_bf16 v[12:15], v[226:229], v[200:203], v[138:141]
	v_mfma_f32_16x16x32_bf16 v[0:3], v[234:237], v[200:203], v[0:3]
	v_cmp_gt_u32_e32 vcc, s62, v130
	s_barrier
	s_and_saveexec_b64 s[44:45], vcc
	s_cbranch_execz .LBB0_227
	s_barrier

; #define STAGE(P, BASE, LD, br, kt) do { const char* _g = (const char*)((BASE) + (size_t)(br) * (LD) + (size_t)(kt) * 64); \
;     for (int _i = 0; _i < 2; ++_i) { int _b = tidx * 16 + _i * 8192; int _r, _c; stage_rc(_b, _r, _c); \
;       __builtin_amdgcn_global_load_lds((const unsigned*)(_g + (unsigned)((_r * (LD) + _c) * 2)), (unsigned*)((char*)(P) + _b), 16, 0, 0); } } while (0)
; #define LDA(dst, b, h) for (int m = 0; m < 4; ++m) for (int k = 0; k < 2; ++k) \
;     dst[m][k] = *reinterpret_cast<const bf16x8*>((char*)SA(b, h) + lds_byte(wr * 64 + m * 16 + fr, k * 32 + fq * 8))
; #define LDB(dst, b, h) for (int n = 0; n < 2; ++n) for (int k = 0; k < 2; ++k) \
;     dst[n][k] = *reinterpret_cast<const bf16x8*>((char*)SB(b, h) + lds_byte(wc * 32 + n * 16 + fr, k * 32 + fq * 8))
; #define MMA(ai, bj, At_, Bt_) do { __builtin_amdgcn_s_setprio(1); \
;     for (int k = 0; k < 2; ++k) for (int m = 0; m < 4; ++m) for (int n = 0; n < 2; ++n) \
;       acc[ai][bj][m][n] = __builtin_amdgcn_mfma_f32_16x16x32_bf16(At_[m][k], Bt_[n][k], acc[ai][bj][m][n], 0, 0, 0); \
;     __builtin_amdgcn_s_setprio(0); } while (0)
; #define WAIT_L(n) asm volatile("s_waitcnt lgkmcnt(" #n ")" ::: "memory")
; #define BAR __builtin_amdgcn_s_barrier()
; #define SCHED __builtin_amdgcn_sched_barrier(0)
; template <int EPI, int lda, int ldb, int N, int K>
; __device__ __forceinline__ void gemm_phase(const u16* __restrict__ A, const u16* __restrict__ Bt, const GemmEpi ep, int wv) {
;     ...
;     for (int t = 0; t < nt - 2; t += 2) {
;       LDB(B0, 0, 0); SCHED; LDA(At, 0, 0); STAGE(SA(1, 1), Ab, lda, brow + HALF, t + 1);
;       WAIT_L(8); BAR; WAIT_L(0); MMA(0, 0, At, B0); BAR; SCHED;
;       LDB(B1, 0, 1); STAGE(SB(0, 0), Bt, ldb, bcol, t + 2);
;       BAR; WAIT_L(0); MMA(0, 1, At, B1); BAR;
;       LDA(At, 0, 1); STAGE(SA(0, 0), Ab, lda, brow, t + 2);
;       BAR; WAIT_L(0); MMA(1, 0, At, B0); BAR; SCHED;
.LBB0_340:
	ds_read_b128 v[166:169], v162
	ds_read_b128 v[172:175], v162 offset:1024
	ds_read_b128 v[176:179], v162 offset:2048
	ds_read_b128 v[180:183], v162 offset:3072
	v_add_u32_e32 v170, 0xc000, v149
	v_lshl_add_u64 v[236:237], v[138:139], 0, s[48:49]
	v_readfirstlane_b32 s51, v170
	v_add_u32_e32 v171, 0xe000, v149
	v_lshl_add_u64 v[164:165], v[236:237], 0, s[18:19]
	s_mov_b32 m0, s51
	v_lshl_add_u64 v[238:239], v[140:141], 0, s[48:49]
	v_readfirstlane_b32 s51, v171
	ds_read_b128 v[184:187], v153
	ds_read_b128 v[188:191], v153 offset:1024
	ds_read_b128 v[192:195], v152
	ds_read_b128 v[196:199], v152 offset:1024
	ds_read_b128 v[200:203], v151
	ds_read_b128 v[204:207], v151 offset:1024
	ds_read_b128 v[208:211], v150
	ds_read_b128 v[212:215], v150 offset:1024
	global_load_lds_dwordx4 v[164:165], off
	v_lshl_add_u64 v[164:165], v[238:239], 0, s[18:19]
	s_mov_b32 m0, s51
	s_nop 0
	global_load_lds_dwordx4 v[164:165], off
	s_waitcnt lgkmcnt(8)
	s_barrier
	s_waitcnt lgkmcnt(0)
	s_waitcnt lgkmcnt(0)
	v_mfma_f32_16x16x32_bf16 v[124:127], v[184:187], v[166:169], v[124:127]
	v_mfma_f32_16x16x32_bf16 v[120:123], v[184:187], v[176:179], v[120:123]
	v_mfma_f32_16x16x32_bf16 v[116:119], v[192:195], v[166:169], v[116:119]
	v_mfma_f32_16x16x32_bf16 v[112:115], v[192:195], v[176:179], v[112:115]
	v_mfma_f32_16x16x32_bf16 v[108:111], v[200:203], v[166:169], v[108:111]
	v_mfma_f32_16x16x32_bf16 v[104:107], v[200:203], v[176:179], v[104:107]
	v_mfma_f32_16x16x32_bf16 v[100:103], v[208:211], v[166:169], v[100:103]
	v_mfma_f32_16x16x32_bf16 v[96:99], v[208:211], v[176:179], v[96:99]
	v_mfma_f32_16x16x32_bf16 v[124:127], v[188:191], v[172:175], v[124:127]
	v_mfma_f32_16x16x32_bf16 v[120:123], v[188:191], v[180:183], v[120:123]
	v_mfma_f32_16x16x32_bf16 v[116:119], v[196:199], v[172:175], v[116:119]
	v_mfma_f32_16x16x32_bf16 v[112:115], v[196:199], v[180:183], v[112:115]
	v_mfma_f32_16x16x32_bf16 v[108:111], v[204:207], v[172:175], v[108:111]
	v_mfma_f32_16x16x32_bf16 v[104:107], v[204:207], v[180:183], v[104:107]
	v_mfma_f32_16x16x32_bf16 v[100:103], v[212:215], v[172:175], v[100:103]
	v_mfma_f32_16x16x32_bf16 v[96:99], v[212:215], v[180:183], v[96:99]
	s_barrier
	v_add_u32_e32 v163, s62, v155
	v_lshl_add_u64 v[240:241], v[134:135], 0, s[48:49]
	v_readfirstlane_b32 s51, v163
	v_lshl_add_u64 v[164:165], v[240:241], 0, s[20:21]
	s_mov_b32 m0, s51
	ds_read_b128 v[216:219], v161
	ds_read_b128 v[220:223], v161 offset:1024
	ds_read_b128 v[224:227], v161 offset:2048
	ds_read_b128 v[228:231], v161 offset:3072
	global_load_lds_dwordx4 v[164:165], off
	v_add_u32_e32 v164, 0x2000, v163
	v_lshl_add_u64 v[242:243], v[136:137], 0, s[48:49]
	v_readfirstlane_b32 s51, v164
	v_lshl_add_u64 v[232:233], v[242:243], 0, s[20:21]
	s_mov_b32 m0, s51
	s_nop 0
	global_load_lds_dwordx4 v[232:233], off
	s_barrier
	s_waitcnt lgkmcnt(0)
	s_waitcnt lgkmcnt(0)
	v_mfma_f32_16x16x32_bf16 v[92:95], v[184:187], v[216:219], v[92:95]
	v_mfma_f32_16x16x32_bf16 v[88:91], v[184:187], v[224:227], v[88:91]
	v_mfma_f32_16x16x32_bf16 v[84:87], v[192:195], v[216:219], v[84:87]
	v_mfma_f32_16x16x32_bf16 v[80:83], v[192:195], v[224:227], v[80:83]
	v_mfma_f32_16x16x32_bf16 v[76:79], v[200:203], v[216:219], v[76:79]
	v_mfma_f32_16x16x32_bf16 v[72:75], v[200:203], v[224:227], v[72:75]
	v_mfma_f32_16x16x32_bf16 v[68:71], v[208:211], v[216:219], v[68:71]
	v_mfma_f32_16x16x32_bf16 v[64:67], v[208:211], v[224:227], v[64:67]
	v_mfma_f32_16x16x32_bf16 v[92:95], v[188:191], v[220:223], v[92:95]
	v_mfma_f32_16x16x32_bf16 v[88:91], v[188:191], v[228:231], v[88:91]
	v_mfma_f32_16x16x32_bf16 v[84:87], v[196:199], v[220:223], v[84:87]
	v_mfma_f32_16x16x32_bf16 v[80:83], v[196:199], v[228:231], v[80:83]
	v_mfma_f32_16x16x32_bf16 v[76:79], v[204:207], v[220:223], v[76:79]
	v_mfma_f32_16x16x32_bf16 v[72:75], v[204:207], v[228:231], v[72:75]
	v_mfma_f32_16x16x32_bf16 v[68:71], v[212:215], v[220:223], v[68:71]
	v_mfma_f32_16x16x32_bf16 v[64:67], v[212:215], v[228:231], v[64:67]
	v_readfirstlane_b32 s51, v149
	v_add_u32_e32 v165, 0x2000, v149
	v_lshl_add_u64 v[232:233], v[236:237], 0, s[22:23]
	s_mov_b32 m0, s51
	v_readfirstlane_b32 s51, v165
	s_barrier
	ds_read_b128 v[184:187], v153 offset:16384
	ds_read_b128 v[188:191], v153 offset:17408
	ds_read_b128 v[192:195], v152 offset:16384
	ds_read_b128 v[196:199], v152 offset:17408
	ds_read_b128 v[200:203], v151 offset:16384
	ds_read_b128 v[204:207], v151 offset:17408
	ds_read_b128 v[208:211], v150 offset:16384
	ds_read_b128 v[212:215], v150 offset:17408
	global_load_lds_dwordx4 v[232:233], off
	v_lshl_add_u64 v[232:233], v[238:239], 0, s[22:23]
	s_mov_b32 m0, s51
	s_nop 0
	global_load_lds_dwordx4 v[232:233], off
	s_barrier
	s_waitcnt lgkmcnt(0)
	s_waitcnt lgkmcnt(0)
	v_mfma_f32_16x16x32_bf16 v[60:63], v[184:187], v[166:169], v[60:63]
	v_mfma_f32_16x16x32_bf16 v[56:59], v[184:187], v[176:179], v[56:59]
	v_mfma_f32_16x16x32_bf16 v[52:55], v[192:195], v[166:169], v[52:55]
	v_mfma_f32_16x16x32_bf16 v[48:51], v[192:195], v[176:179], v[48:51]
	v_mfma_f32_16x16x32_bf16 v[44:47], v[200:203], v[166:169], v[44:47]
	v_mfma_f32_16x16x32_bf16 v[40:43], v[200:203], v[176:179], v[40:43]
	v_mfma_f32_16x16x32_bf16 v[36:39], v[208:211], v[166:169], v[36:39]
	v_mfma_f32_16x16x32_bf16 v[32:35], v[208:211], v[176:179], v[32:35]
	v_mfma_f32_16x16x32_bf16 v[60:63], v[188:191], v[172:175], v[60:63]
	v_mfma_f32_16x16x32_bf16 v[56:59], v[188:191], v[180:183], v[56:59]
	v_mfma_f32_16x16x32_bf16 v[52:55], v[196:199], v[172:175], v[52:55]
	v_mfma_f32_16x16x32_bf16 v[48:51], v[196:199], v[180:183], v[48:51]
	v_mfma_f32_16x16x32_bf16 v[44:47], v[204:207], v[172:175], v[44:47]
	v_mfma_f32_16x16x32_bf16 v[40:43], v[204:207], v[180:183], v[40:43]
	v_mfma_f32_16x16x32_bf16 v[36:39], v[212:215], v[172:175], v[36:39]
	v_mfma_f32_16x16x32_bf16 v[32:35], v[212:215], v[180:183], v[32:35]
	s_barrier
; #define STAGE(P, BASE, LD, br, kt) do { const char* _g = (const char*)((BASE) + (size_t)(br) * (LD) + (size_t)(kt) * 64); \
;     for (int _i = 0; _i < 2; ++_i) { int _b = tidx * 16 + _i * 8192; int _r, _c; stage_rc(_b, _r, _c); \
;       __builtin_amdgcn_global_load_lds((const unsigned*)(_g + (unsigned)((_r * (LD) + _c) * 2)), (unsigned*)((char*)(P) + _b), 16, 0, 0); } } while (0)
; #define LDA(dst, b, h) for (int m = 0; m < 4; ++m) for (int k = 0; k < 2; ++k) \
;     dst[m][k] = *reinterpret_cast<const bf16x8*>((char*)SA(b, h) + lds_byte(wr * 64 + m * 16 + fr, k * 32 + fq * 8))
; #define LDB(dst, b, h) for (int n = 0; n < 2; ++n) for (int k = 0; k < 2; ++k) \
;     dst[n][k] = *reinterpret_cast<const bf16x8*>((char*)SB(b, h) + lds_byte(wc * 32 + n * 16 + fr, k * 32 + fq * 8))
; #define MMA(ai, bj, At_, Bt_) do { __builtin_amdgcn_s_setprio(1); \
;     for (int k = 0; k < 2; ++k) for (int m = 0; m < 4; ++m) for (int n = 0; n < 2; ++n) \
;       acc[ai][bj][m][n] = __builtin_amdgcn_mfma_f32_16x16x32_bf16(At_[m][k], Bt_[n][k], acc[ai][bj][m][n], 0, 0, 0); \
;     __builtin_amdgcn_s_setprio(0); } while (0)
; #define WAIT_V(n) asm volatile("s_waitcnt vmcnt(" #n ")" ::: "memory")
; #define WAIT_L(n) asm volatile("s_waitcnt lgkmcnt(" #n ")" ::: "memory")
; #define BAR __builtin_amdgcn_s_barrier()
; #define SCHED __builtin_amdgcn_sched_barrier(0)
; template <int EPI, int lda, int ldb, int N, int K>
; __device__ __forceinline__ void gemm_phase(const u16* __restrict__ A, const u16* __restrict__ Bt, const GemmEpi ep, int wv) {
;     ...
;       STAGE(SB(0, 1), Bt, ldb, bcol + HALF, t + 2);
;       WAIT_V(6); BAR; MMA(1, 1, At, B1); BAR;
;       LDB(B0, 1, 0); SCHED; LDA(At, 1, 0); STAGE(SA(0, 1), Ab, lda, brow + HALF, t + 2);
;       WAIT_L(8); BAR; WAIT_L(0); MMA(0, 0, At, B0); BAR; SCHED;
;       LDB(B1, 1, 1); STAGE(SB(1, 0), Bt, ldb, bcol, t + 3);
;       BAR; WAIT_L(0); MMA(0, 1, At, B1); BAR;
	v_add_u32_e32 v166, s63, v155
	v_add_u32_e32 v167, 0x2000, v166
	v_readfirstlane_b32 s51, v166
	v_lshl_add_u64 v[168:169], v[240:241], 0, s[24:25]
	s_mov_b32 m0, s51
	v_readfirstlane_b32 s51, v167
	global_load_lds_dwordx4 v[168:169], off
	v_lshl_add_u64 v[168:169], v[242:243], 0, s[24:25]
	s_mov_b32 m0, s51
	s_nop 0
	global_load_lds_dwordx4 v[168:169], off
	s_waitcnt vmcnt(6)
	s_barrier
	v_mfma_f32_16x16x32_bf16 v[28:31], v[184:187], v[216:219], v[28:31]
	v_mfma_f32_16x16x32_bf16 v[24:27], v[184:187], v[224:227], v[24:27]
	v_mfma_f32_16x16x32_bf16 v[20:23], v[192:195], v[216:219], v[20:23]
	v_mfma_f32_16x16x32_bf16 v[16:19], v[192:195], v[224:227], v[16:19]
	v_mfma_f32_16x16x32_bf16 v[12:15], v[200:203], v[216:219], v[12:15]
	v_mfma_f32_16x16x32_bf16 v[8:11], v[200:203], v[224:227], v[8:11]
	v_mfma_f32_16x16x32_bf16 v[4:7], v[208:211], v[216:219], v[4:7]
	v_mfma_f32_16x16x32_bf16 v[0:3], v[208:211], v[224:227], v[0:3]
	v_mfma_f32_16x16x32_bf16 v[28:31], v[188:191], v[220:223], v[28:31]
	v_mfma_f32_16x16x32_bf16 v[24:27], v[188:191], v[228:231], v[24:27]
	v_mfma_f32_16x16x32_bf16 v[20:23], v[196:199], v[220:223], v[20:23]
	v_mfma_f32_16x16x32_bf16 v[16:19], v[196:199], v[228:231], v[16:19]
	v_mfma_f32_16x16x32_bf16 v[12:15], v[204:207], v[220:223], v[12:15]
	v_mfma_f32_16x16x32_bf16 v[8:11], v[204:207], v[228:231], v[8:11]
	v_mfma_f32_16x16x32_bf16 v[4:7], v[212:215], v[220:223], v[4:7]
	v_mfma_f32_16x16x32_bf16 v[0:3], v[212:215], v[228:231], v[0:3]
	s_barrier
	ds_read_b128 v[172:175], v156
	ds_read_b128 v[176:179], v156 offset:1024
	ds_read_b128 v[180:183], v156 offset:2048
	ds_read_b128 v[184:187], v156 offset:3072
	v_add_u32_e32 v168, 0x4000, v149
	v_add_u32_e32 v169, 0x6000, v149
	v_readfirstlane_b32 s51, v168
	v_lshl_add_u64 v[220:221], v[236:237], 0, s[26:27]
	s_mov_b32 m0, s51
	v_readfirstlane_b32 s51, v169
	ds_read_b128 v[188:191], v153 offset:32768
	ds_read_b128 v[192:195], v153 offset:33792
	ds_read_b128 v[196:199], v152 offset:32768
	ds_read_b128 v[200:203], v152 offset:33792
	ds_read_b128 v[204:207], v151 offset:32768
	ds_read_b128 v[208:211], v151 offset:33792
	ds_read_b128 v[212:215], v150 offset:32768
	ds_read_b128 v[216:219], v150 offset:33792
	global_load_lds_dwordx4 v[220:221], off
	v_lshl_add_u64 v[220:221], v[238:239], 0, s[26:27]
	s_mov_b32 m0, s51
	s_nop 0
	global_load_lds_dwordx4 v[220:221], off
	s_waitcnt lgkmcnt(8)
	s_barrier
	s_waitcnt lgkmcnt(0)
	s_waitcnt lgkmcnt(0)
	v_mfma_f32_16x16x32_bf16 v[124:127], v[188:191], v[172:175], v[124:127]
	v_mfma_f32_16x16x32_bf16 v[120:123], v[188:191], v[180:183], v[120:123]
	v_mfma_f32_16x16x32_bf16 v[116:119], v[196:199], v[172:175], v[116:119]
	v_mfma_f32_16x16x32_bf16 v[112:115], v[196:199], v[180:183], v[112:115]
	v_mfma_f32_16x16x32_bf16 v[108:111], v[204:207], v[172:175], v[108:111]
	v_mfma_f32_16x16x32_bf16 v[104:107], v[204:207], v[180:183], v[104:107]
	v_mfma_f32_16x16x32_bf16 v[100:103], v[212:215], v[172:175], v[100:103]
	v_mfma_f32_16x16x32_bf16 v[96:99], v[212:215], v[180:183], v[96:99]
	v_mfma_f32_16x16x32_bf16 v[124:127], v[192:195], v[176:179], v[124:127]
	v_mfma_f32_16x16x32_bf16 v[120:123], v[192:195], v[184:187], v[120:123]
	v_mfma_f32_16x16x32_bf16 v[116:119], v[200:203], v[176:179], v[116:119]
	v_mfma_f32_16x16x32_bf16 v[112:115], v[200:203], v[184:187], v[112:115]
	v_mfma_f32_16x16x32_bf16 v[108:111], v[208:211], v[176:179], v[108:111]
	v_mfma_f32_16x16x32_bf16 v[104:107], v[208:211], v[184:187], v[104:107]
	v_mfma_f32_16x16x32_bf16 v[100:103], v[216:219], v[176:179], v[100:103]
	v_mfma_f32_16x16x32_bf16 v[96:99], v[216:219], v[184:187], v[96:99]
	s_barrier
	v_readfirstlane_b32 s51, v157
	v_add_u32_e32 v246, 0x2000, v157
	v_lshl_add_u64 v[244:245], v[240:241], 0, s[36:37]
	s_mov_b32 m0, s51
	v_readfirstlane_b32 s51, v246
	ds_read_b128 v[220:223], v154
	ds_read_b128 v[224:227], v154 offset:1024
	ds_read_b128 v[228:231], v154 offset:2048
	ds_read_b128 v[232:235], v154 offset:3072
	global_load_lds_dwordx4 v[244:245], off
	v_lshl_add_u64 v[244:245], v[242:243], 0, s[36:37]
	s_mov_b32 m0, s51
	s_nop 0
	global_load_lds_dwordx4 v[244:245], off
	s_barrier
	s_waitcnt lgkmcnt(0)
	s_waitcnt lgkmcnt(0)
	v_mfma_f32_16x16x32_bf16 v[92:95], v[188:191], v[220:223], v[92:95]
	v_mfma_f32_16x16x32_bf16 v[88:91], v[188:191], v[228:231], v[88:91]
	v_mfma_f32_16x16x32_bf16 v[84:87], v[196:199], v[220:223], v[84:87]
	v_mfma_f32_16x16x32_bf16 v[80:83], v[196:199], v[228:231], v[80:83]
	v_mfma_f32_16x16x32_bf16 v[76:79], v[204:207], v[220:223], v[76:79]
	v_mfma_f32_16x16x32_bf16 v[72:75], v[204:207], v[228:231], v[72:75]
	v_mfma_f32_16x16x32_bf16 v[68:71], v[212:215], v[220:223], v[68:71]
	v_mfma_f32_16x16x32_bf16 v[64:67], v[212:215], v[228:231], v[64:67]
	v_mfma_f32_16x16x32_bf16 v[92:95], v[192:195], v[224:227], v[92:95]
	v_mfma_f32_16x16x32_bf16 v[88:91], v[192:195], v[232:235], v[88:91]
	v_mfma_f32_16x16x32_bf16 v[84:87], v[200:203], v[224:227], v[84:87]
	v_mfma_f32_16x16x32_bf16 v[80:83], v[200:203], v[232:235], v[80:83]
	v_mfma_f32_16x16x32_bf16 v[76:79], v[208:211], v[224:227], v[76:79]
	v_mfma_f32_16x16x32_bf16 v[72:75], v[208:211], v[232:235], v[72:75]
	v_mfma_f32_16x16x32_bf16 v[68:71], v[216:219], v[224:227], v[68:71]
	v_mfma_f32_16x16x32_bf16 v[64:67], v[216:219], v[232:235], v[64:67]
	v_readfirstlane_b32 s51, v158
	v_lshl_add_u64 v[236:237], v[236:237], 0, s[38:39]
	s_mov_b32 m0, s51
	v_readfirstlane_b32 s51, v159
	s_barrier
; #define STAGE(P, BASE, LD, br, kt) do { const char* _g = (const char*)((BASE) + (size_t)(br) * (LD) + (size_t)(kt) * 64); \
;     for (int _i = 0; _i < 2; ++_i) { int _b = tidx * 16 + _i * 8192; int _r, _c; stage_rc(_b, _r, _c); \
;       __builtin_amdgcn_global_load_lds((const unsigned*)(_g + (unsigned)((_r * (LD) + _c) * 2)), (unsigned*)((char*)(P) + _b), 16, 0, 0); } } while (0)
; #define LDA(dst, b, h) for (int m = 0; m < 4; ++m) for (int k = 0; k < 2; ++k) \
;     dst[m][k] = *reinterpret_cast<const bf16x8*>((char*)SA(b, h) + lds_byte(wr * 64 + m * 16 + fr, k * 32 + fq * 8))
; #define LDB(dst, b, h) for (int n = 0; n < 2; ++n) for (int k = 0; k < 2; ++k) \
;     dst[n][k] = *reinterpret_cast<const bf16x8*>((char*)SB(b, h) + lds_byte(wc * 32 + n * 16 + fr, k * 32 + fq * 8))
; #define MMA(ai, bj, At_, Bt_) do { __builtin_amdgcn_s_setprio(1); \
;     for (int k = 0; k < 2; ++k) for (int m = 0; m < 4; ++m) for (int n = 0; n < 2; ++n) \
;       acc[ai][bj][m][n] = __builtin_amdgcn_mfma_f32_16x16x32_bf16(At_[m][k], Bt_[n][k], acc[ai][bj][m][n], 0, 0, 0); \
;     __builtin_amdgcn_s_setprio(0); } while (0)
; #define WAIT_V(n) asm volatile("s_waitcnt vmcnt(" #n ")" ::: "memory")
; #define WAIT_L(n) asm volatile("s_waitcnt lgkmcnt(" #n ")" ::: "memory")
; #define BAR __builtin_amdgcn_s_barrier()
; #define SCHED __builtin_amdgcn_sched_barrier(0)
; template <int EPI, int lda, int ldb, int N, int K>
; __device__ __forceinline__ void gemm_phase(const u16* __restrict__ A, const u16* __restrict__ Bt, const GemmEpi ep, int wv) {
;     ...
;       LDA(At, 1, 1); STAGE(SA(1, 0), Ab, lda, brow, t + 3);
;       BAR; WAIT_L(0); MMA(1, 0, At, B0); BAR; SCHED;
;       STAGE(SB(1, 1), Bt, ldb, bcol + HALF, t + 3);
;       WAIT_V(6); BAR; MMA(1, 1, At, B1); BAR;
;     }
;     { LDB(B0, 0, 0); LDA(At, 0, 0); STAGE(SA(1, 1), Ab, lda, brow + HALF, nt - 1);
;       BAR; WAIT_L(0); MMA(0, 0, At, B0); BAR;
;       LDB(B1, 0, 1); BAR; WAIT_L(0); MMA(0, 1, At, B1); BAR;
	ds_read_b128 v[188:191], v153 offset:49152
	ds_read_b128 v[192:195], v153 offset:50176
	ds_read_b128 v[196:199], v152 offset:49152
	ds_read_b128 v[200:203], v152 offset:50176
	ds_read_b128 v[204:207], v151 offset:49152
	ds_read_b128 v[208:211], v151 offset:50176
	ds_read_b128 v[212:215], v150 offset:49152
	ds_read_b128 v[216:219], v150 offset:50176
	global_load_lds_dwordx4 v[236:237], off
	v_lshl_add_u64 v[236:237], v[238:239], 0, s[38:39]
	s_mov_b32 m0, s51
	s_nop 0
	global_load_lds_dwordx4 v[236:237], off
	s_barrier
	s_waitcnt lgkmcnt(0)
	s_waitcnt lgkmcnt(0)
	v_mfma_f32_16x16x32_bf16 v[60:63], v[188:191], v[172:175], v[60:63]
	v_mfma_f32_16x16x32_bf16 v[56:59], v[188:191], v[180:183], v[56:59]
	v_mfma_f32_16x16x32_bf16 v[52:55], v[196:199], v[172:175], v[52:55]
	v_mfma_f32_16x16x32_bf16 v[48:51], v[196:199], v[180:183], v[48:51]
	v_mfma_f32_16x16x32_bf16 v[44:47], v[204:207], v[172:175], v[44:47]
	v_mfma_f32_16x16x32_bf16 v[40:43], v[204:207], v[180:183], v[40:43]
	v_mfma_f32_16x16x32_bf16 v[36:39], v[212:215], v[172:175], v[36:39]
	v_mfma_f32_16x16x32_bf16 v[32:35], v[212:215], v[180:183], v[32:35]
	v_mfma_f32_16x16x32_bf16 v[60:63], v[192:195], v[176:179], v[60:63]
	v_mfma_f32_16x16x32_bf16 v[56:59], v[192:195], v[184:187], v[56:59]
	v_mfma_f32_16x16x32_bf16 v[52:55], v[200:203], v[176:179], v[52:55]
	v_mfma_f32_16x16x32_bf16 v[48:51], v[200:203], v[184:187], v[48:51]
	v_mfma_f32_16x16x32_bf16 v[44:47], v[208:211], v[176:179], v[44:47]
	v_mfma_f32_16x16x32_bf16 v[40:43], v[208:211], v[184:187], v[40:43]
	v_mfma_f32_16x16x32_bf16 v[36:39], v[216:219], v[176:179], v[36:39]
	v_mfma_f32_16x16x32_bf16 v[32:35], v[216:219], v[184:187], v[32:35]
	s_barrier
	v_readfirstlane_b32 s51, v160
	v_add_u32_e32 v174, 0x2000, v160
	v_lshl_add_u64 v[172:173], v[240:241], 0, s[42:43]
	s_mov_b32 m0, s51
	v_readfirstlane_b32 s51, v174
	global_load_lds_dwordx4 v[172:173], off
	v_lshl_add_u64 v[172:173], v[242:243], 0, s[42:43]
	s_mov_b32 m0, s51
	s_nop 0
	global_load_lds_dwordx4 v[172:173], off
	s_waitcnt vmcnt(6)
	s_barrier
	v_mfma_f32_16x16x32_bf16 v[28:31], v[188:191], v[220:223], v[28:31]
	v_mfma_f32_16x16x32_bf16 v[24:27], v[188:191], v[228:231], v[24:27]
	v_mfma_f32_16x16x32_bf16 v[20:23], v[196:199], v[220:223], v[20:23]
	v_mfma_f32_16x16x32_bf16 v[16:19], v[196:199], v[228:231], v[16:19]
	v_mfma_f32_16x16x32_bf16 v[12:15], v[204:207], v[220:223], v[12:15]
	v_mfma_f32_16x16x32_bf16 v[8:11], v[204:207], v[228:231], v[8:11]
	v_mfma_f32_16x16x32_bf16 v[4:7], v[212:215], v[220:223], v[4:7]
	v_mfma_f32_16x16x32_bf16 v[0:3], v[212:215], v[228:231], v[0:3]
	v_mfma_f32_16x16x32_bf16 v[28:31], v[192:195], v[224:227], v[28:31]
	v_mfma_f32_16x16x32_bf16 v[24:27], v[192:195], v[232:235], v[24:27]
	v_mfma_f32_16x16x32_bf16 v[20:23], v[200:203], v[224:227], v[20:23]
	v_mfma_f32_16x16x32_bf16 v[16:19], v[200:203], v[232:235], v[16:19]
	v_mfma_f32_16x16x32_bf16 v[12:15], v[208:211], v[224:227], v[12:15]
	v_mfma_f32_16x16x32_bf16 v[8:11], v[208:211], v[232:235], v[8:11]
	v_mfma_f32_16x16x32_bf16 v[4:7], v[216:219], v[224:227], v[4:7]
	v_mfma_f32_16x16x32_bf16 v[0:3], v[216:219], v[232:235], v[0:3]
	s_add_i32 s50, s50, 2
	s_add_u32 s48, s48, 0x100
	s_addc_u32 s49, s49, 0
	s_cmp_gt_u32 s50, 27
	s_barrier
	s_cbranch_scc0 .LBB0_340
	s_add_i32 s48, s46, 0x80
	s_mul_hi_i32 s49, s48, 0x1080
	s_mulk_i32 s48, 0x1080
	s_add_u32 s48, s31, s48
	s_addc_u32 s49, s56, s49
	v_lshl_add_u64 v[158:159], s[48:49], 0, v[128:129]
	v_readfirstlane_b32 s50, v170
	v_lshl_add_u64 v[158:159], v[158:159], 0, s[44:45]
	s_mov_b32 m0, s50
	ds_read_b128 v[134:137], v162
	ds_read_b128 v[138:141], v162 offset:1024
	ds_read_b128 v[172:175], v162 offset:2048
	ds_read_b128 v[176:179], v162 offset:3072
	ds_read_b128 v[180:183], v153
	ds_read_b128 v[184:187], v153 offset:1024
	ds_read_b128 v[188:191], v152
	ds_read_b128 v[192:195], v152 offset:1024
	ds_read_b128 v[196:199], v151
	ds_read_b128 v[200:203], v151 offset:1024
	ds_read_b128 v[204:207], v150
	ds_read_b128 v[208:211], v150 offset:1024
	global_load_lds_dwordx4 v[158:159], off
	v_lshl_add_u64 v[158:159], s[48:49], 0, v[132:133]
	v_readfirstlane_b32 s48, v171
	v_lshl_add_u64 v[158:159], v[158:159], 0, s[44:45]
	s_mov_b32 m0, s48
	s_nop 0
	global_load_lds_dwordx4 v[158:159], off
	s_barrier
	s_waitcnt lgkmcnt(0)
	s_waitcnt lgkmcnt(0)
	v_mfma_f32_16x16x32_bf16 v[124:127], v[180:183], v[134:137], v[124:127]
	v_mfma_f32_16x16x32_bf16 v[120:123], v[180:183], v[172:175], v[120:123]
	v_mfma_f32_16x16x32_bf16 v[116:119], v[188:191], v[134:137], v[116:119]
	v_mfma_f32_16x16x32_bf16 v[112:115], v[188:191], v[172:175], v[112:115]
	v_mfma_f32_16x16x32_bf16 v[108:111], v[196:199], v[134:137], v[108:111]
	v_mfma_f32_16x16x32_bf16 v[104:107], v[196:199], v[172:175], v[104:107]
	v_mfma_f32_16x16x32_bf16 v[100:103], v[204:207], v[134:137], v[100:103]
	v_mfma_f32_16x16x32_bf16 v[96:99], v[204:207], v[172:175], v[96:99]
	v_mfma_f32_16x16x32_bf16 v[124:127], v[184:187], v[138:141], v[124:127]
	v_mfma_f32_16x16x32_bf16 v[120:123], v[184:187], v[176:179], v[120:123]
	v_mfma_f32_16x16x32_bf16 v[116:119], v[192:195], v[138:141], v[116:119]
	v_mfma_f32_16x16x32_bf16 v[112:115], v[192:195], v[176:179], v[112:115]
	v_mfma_f32_16x16x32_bf16 v[108:111], v[200:203], v[138:141], v[108:111]
	v_mfma_f32_16x16x32_bf16 v[104:107], v[200:203], v[176:179], v[104:107]
	v_mfma_f32_16x16x32_bf16 v[100:103], v[208:211], v[138:141], v[100:103]
	v_mfma_f32_16x16x32_bf16 v[96:99], v[208:211], v[176:179], v[96:99]
	s_barrier
	ds_read_b128 v[212:215], v161
	ds_read_b128 v[216:219], v161 offset:1024
	ds_read_b128 v[220:223], v161 offset:2048
	ds_read_b128 v[158:161], v161 offset:3072
	s_barrier
; #define LDA(dst, b, h) for (int m = 0; m < 4; ++m) for (int k = 0; k < 2; ++k) \
;     dst[m][k] = *reinterpret_cast<const bf16x8*>((char*)SA(b, h) + lds_byte(wr * 64 + m * 16 + fr, k * 32 + fq * 8))
; #define LDB(dst, b, h) for (int n = 0; n < 2; ++n) for (int k = 0; k < 2; ++k) \
;     dst[n][k] = *reinterpret_cast<const bf16x8*>((char*)SB(b, h) + lds_byte(wc * 32 + n * 16 + fr, k * 32 + fq * 8))
; #define MMA(ai, bj, At_, Bt_) do { __builtin_amdgcn_s_setprio(1); \
;     for (int k = 0; k < 2; ++k) for (int m = 0; m < 4; ++m) for (int n = 0; n < 2; ++n) \
;       acc[ai][bj][m][n] = __builtin_amdgcn_mfma_f32_16x16x32_bf16(At_[m][k], Bt_[n][k], acc[ai][bj][m][n], 0, 0, 0); \
;     __builtin_amdgcn_s_setprio(0); } while (0)
; #define WAIT_V(n) asm volatile("s_waitcnt vmcnt(" #n ")" ::: "memory")
; #define WAIT_L(n) asm volatile("s_waitcnt lgkmcnt(" #n ")" ::: "memory")
; #define BAR __builtin_amdgcn_s_barrier()
; template <int EPI, int lda, int ldb, int N, int K>
; __device__ __forceinline__ void gemm_phase(const u16* __restrict__ A, const u16* __restrict__ Bt, const GemmEpi ep, int wv) {
;     ...
;       LDB(B1, 0, 1); BAR; WAIT_L(0); MMA(0, 1, At, B1); BAR;
;       LDA(At, 0, 1); WAIT_V(4); BAR; WAIT_L(0); MMA(1, 0, At, B0); MMA(1, 1, At, B1); BAR; }
;     { LDB(B0, 1, 0); LDA(At, 1, 0); WAIT_V(2); BAR; WAIT_L(0); MMA(0, 0, At, B0); BAR;
	s_waitcnt lgkmcnt(0)
	s_waitcnt lgkmcnt(0)
	v_mfma_f32_16x16x32_bf16 v[92:95], v[180:183], v[212:215], v[92:95]
	v_mfma_f32_16x16x32_bf16 v[88:91], v[180:183], v[220:223], v[88:91]
	v_mfma_f32_16x16x32_bf16 v[76:79], v[196:199], v[212:215], v[76:79]
	v_mfma_f32_16x16x32_bf16 v[72:75], v[196:199], v[220:223], v[72:75]
	v_mfma_f32_16x16x32_bf16 v[68:71], v[204:207], v[212:215], v[68:71]
	v_mfma_f32_16x16x32_bf16 v[64:67], v[204:207], v[220:223], v[64:67]
	v_mfma_f32_16x16x32_bf16 v[84:87], v[188:191], v[212:215], v[84:87]
	v_mfma_f32_16x16x32_bf16 v[80:83], v[188:191], v[220:223], v[80:83]
	v_mfma_f32_16x16x32_bf16 v[92:95], v[184:187], v[216:219], v[92:95]
	v_mfma_f32_16x16x32_bf16 v[88:91], v[184:187], v[158:161], v[88:91]
	v_mfma_f32_16x16x32_bf16 v[76:79], v[200:203], v[216:219], v[76:79]
	v_mfma_f32_16x16x32_bf16 v[72:75], v[200:203], v[158:161], v[72:75]
	v_mfma_f32_16x16x32_bf16 v[68:71], v[208:211], v[216:219], v[68:71]
	v_mfma_f32_16x16x32_bf16 v[64:67], v[208:211], v[158:161], v[64:67]
	v_mfma_f32_16x16x32_bf16 v[180:183], v[192:195], v[216:219], v[84:87]
	v_mfma_f32_16x16x32_bf16 v[184:187], v[192:195], v[158:161], v[80:83]
	s_barrier
	s_nop 0
	ds_read_b128 v[80:83], v153 offset:16384
	ds_read_b128 v[84:87], v153 offset:17408
	ds_read_b128 v[188:191], v152 offset:16384
	ds_read_b128 v[192:195], v152 offset:17408
	ds_read_b128 v[196:199], v151 offset:16384
	ds_read_b128 v[200:203], v151 offset:17408
	ds_read_b128 v[204:207], v150 offset:16384
	ds_read_b128 v[208:211], v150 offset:17408
	s_waitcnt vmcnt(4)
	s_barrier
	s_waitcnt lgkmcnt(0)
	s_waitcnt lgkmcnt(0)
	v_mfma_f32_16x16x32_bf16 v[60:63], v[80:83], v[134:137], v[60:63]
	v_mfma_f32_16x16x32_bf16 v[44:47], v[196:199], v[134:137], v[44:47]
	v_mfma_f32_16x16x32_bf16 v[40:43], v[196:199], v[172:175], v[40:43]
	v_mfma_f32_16x16x32_bf16 v[36:39], v[204:207], v[134:137], v[36:39]
	v_mfma_f32_16x16x32_bf16 v[32:35], v[204:207], v[172:175], v[32:35]
	v_mfma_f32_16x16x32_bf16 v[56:59], v[80:83], v[172:175], v[56:59]
	v_mfma_f32_16x16x32_bf16 v[52:55], v[188:191], v[134:137], v[52:55]
	v_mfma_f32_16x16x32_bf16 v[48:51], v[188:191], v[172:175], v[48:51]
	v_mfma_f32_16x16x32_bf16 v[60:63], v[84:87], v[138:141], v[60:63]
	v_mfma_f32_16x16x32_bf16 v[44:47], v[200:203], v[138:141], v[44:47]
	v_mfma_f32_16x16x32_bf16 v[40:43], v[200:203], v[176:179], v[40:43]
	v_mfma_f32_16x16x32_bf16 v[36:39], v[208:211], v[138:141], v[36:39]
	v_mfma_f32_16x16x32_bf16 v[32:35], v[208:211], v[176:179], v[32:35]
	v_mfma_f32_16x16x32_bf16 v[134:137], v[84:87], v[176:179], v[56:59]
	v_mfma_f32_16x16x32_bf16 v[170:173], v[192:195], v[138:141], v[52:55]
	v_mfma_f32_16x16x32_bf16 v[224:227], v[192:195], v[176:179], v[48:51]
	v_mfma_f32_16x16x32_bf16 v[28:31], v[80:83], v[212:215], v[28:31]
	v_mfma_f32_16x16x32_bf16 v[20:23], v[188:191], v[212:215], v[20:23]
	v_mfma_f32_16x16x32_bf16 v[12:15], v[196:199], v[212:215], v[12:15]
	v_mfma_f32_16x16x32_bf16 v[4:7], v[204:207], v[212:215], v[4:7]
	v_mfma_f32_16x16x32_bf16 v[24:27], v[80:83], v[220:223], v[24:27]
	v_mfma_f32_16x16x32_bf16 v[16:19], v[188:191], v[220:223], v[16:19]
	v_mfma_f32_16x16x32_bf16 v[8:11], v[196:199], v[220:223], v[8:11]
	v_mfma_f32_16x16x32_bf16 v[0:3], v[204:207], v[220:223], v[0:3]
	v_mfma_f32_16x16x32_bf16 v[28:31], v[84:87], v[216:219], v[28:31]
	v_mfma_f32_16x16x32_bf16 v[20:23], v[192:195], v[216:219], v[20:23]
	v_mfma_f32_16x16x32_bf16 v[12:15], v[200:203], v[216:219], v[12:15]
	v_mfma_f32_16x16x32_bf16 v[4:7], v[208:211], v[216:219], v[4:7]
	v_mfma_f32_16x16x32_bf16 v[138:141], v[84:87], v[158:161], v[24:27]
	v_mfma_f32_16x16x32_bf16 v[174:177], v[192:195], v[158:161], v[16:19]
	v_mfma_f32_16x16x32_bf16 v[188:191], v[200:203], v[158:161], v[8:11]
	v_mfma_f32_16x16x32_bf16 v[158:161], v[208:211], v[158:161], v[0:3]
	s_barrier
	s_nop 0
	ds_read_b128 v[0:3], v156
	ds_read_b128 v[8:11], v156 offset:1024
	ds_read_b128 v[16:19], v156 offset:2048
	ds_read_b128 v[192:195], v156 offset:3072
	ds_read_b128 v[24:27], v153 offset:32768
	ds_read_b128 v[56:59], v153 offset:33792
	ds_read_b128 v[196:199], v152 offset:32768
	ds_read_b128 v[200:203], v152 offset:33792
	ds_read_b128 v[204:207], v151 offset:32768
	ds_read_b128 v[208:211], v151 offset:33792
	ds_read_b128 v[212:215], v150 offset:32768
	ds_read_b128 v[216:219], v150 offset:33792
	s_waitcnt vmcnt(2)
	s_barrier
; #define LDA(dst, b, h) for (int m = 0; m < 4; ++m) for (int k = 0; k < 2; ++k) \
;     dst[m][k] = *reinterpret_cast<const bf16x8*>((char*)SA(b, h) + lds_byte(wr * 64 + m * 16 + fr, k * 32 + fq * 8))
; #define LDB(dst, b, h) for (int n = 0; n < 2; ++n) for (int k = 0; k < 2; ++k) \
;     dst[n][k] = *reinterpret_cast<const bf16x8*>((char*)SB(b, h) + lds_byte(wc * 32 + n * 16 + fr, k * 32 + fq * 8))
; #define MMA(ai, bj, At_, Bt_) do { __builtin_amdgcn_s_setprio(1); \
;     for (int k = 0; k < 2; ++k) for (int m = 0; m < 4; ++m) for (int n = 0; n < 2; ++n) \
;       acc[ai][bj][m][n] = __builtin_amdgcn_mfma_f32_16x16x32_bf16(At_[m][k], Bt_[n][k], acc[ai][bj][m][n], 0, 0, 0); \
;     __builtin_amdgcn_s_setprio(0); } while (0)
; #define WAIT_V(n) asm volatile("s_waitcnt vmcnt(" #n ")" ::: "memory")
; #define WAIT_L(n) asm volatile("s_waitcnt lgkmcnt(" #n ")" ::: "memory")
; #define BAR __builtin_amdgcn_s_barrier()
; #define STAGE4(BROW, BCOL, PN) do { const u16* Ab_ = A + (EPI == EPI_RG ? ((PN) >> 1) * 256 : 0); \
;     STAGE(SB(0, 0), Bt, ldb, (BCOL), 0); STAGE(SA(0, 0), Ab_, lda, (BROW), 0); \
;     STAGE(SB(0, 1), Bt, ldb, (BCOL) + HALF, 0); STAGE(SA(0, 1), Ab_, lda, (BROW) + HALF, 0); } while (0)
; template <int EPI, int lda, int ldb, int N, int K>
; __device__ __forceinline__ void gemm_phase(const u16* __restrict__ A, const u16* __restrict__ Bt, const GemmEpi ep, int wv) {
;     ...
;     { LDB(B0, 1, 0); LDA(At, 1, 0); WAIT_V(2); BAR; WAIT_L(0); MMA(0, 0, At, B0); BAR;
;       LDB(B1, 1, 1); WAIT_V(0); BAR; WAIT_L(0); MMA(0, 1, At, B1); BAR;
;       LDA(At, 1, 1); BAR; WAIT_L(0); MMA(1, 0, At, B0); MMA(1, 1, At, B1); BAR; }
;     if (wr == 0) BAR;
;     int ntile = 0, nbrow = 0, nbcol = 0, npn = 0; bool more = false;
;     if constexpr (PF) { ntile = tile + gridDim.x; more = ntile < nwg; if (more) { TILE_COORDS(ntile, nbrow, nbcol, npn); STAGE4(nbrow, nbcol, npn); } }
	s_waitcnt lgkmcnt(0)
	s_waitcnt lgkmcnt(0)
	v_mfma_f32_16x16x32_bf16 v[48:51], v[24:27], v[0:3], v[124:127]
	v_mfma_f32_16x16x32_bf16 v[52:55], v[24:27], v[16:19], v[120:123]
	v_mfma_f32_16x16x32_bf16 v[80:83], v[196:199], v[0:3], v[116:119]
	v_mfma_f32_16x16x32_bf16 v[84:87], v[196:199], v[16:19], v[112:115]
	v_mfma_f32_16x16x32_bf16 v[108:111], v[204:207], v[0:3], v[108:111]
	v_mfma_f32_16x16x32_bf16 v[104:107], v[204:207], v[16:19], v[104:107]
	v_mfma_f32_16x16x32_bf16 v[112:115], v[212:215], v[0:3], v[100:103]
	v_mfma_f32_16x16x32_bf16 v[120:123], v[212:215], v[16:19], v[96:99]
	v_mfma_f32_16x16x32_bf16 v[124:127], v[56:59], v[8:11], v[48:51]
	v_mfma_f32_16x16x32_bf16 v[116:119], v[56:59], v[192:195], v[52:55]
	v_mfma_f32_16x16x32_bf16 v[100:103], v[200:203], v[8:11], v[80:83]
	v_mfma_f32_16x16x32_bf16 v[96:99], v[200:203], v[192:195], v[84:87]
	v_mfma_f32_16x16x32_bf16 v[84:87], v[208:211], v[8:11], v[108:111]
	v_mfma_f32_16x16x32_bf16 v[80:83], v[208:211], v[192:195], v[104:107]
	v_mfma_f32_16x16x32_bf16 v[52:55], v[216:219], v[8:11], v[112:115]
	v_mfma_f32_16x16x32_bf16 v[48:51], v[216:219], v[192:195], v[120:123]
	s_barrier
	ds_read_b128 v[220:223], v154
	ds_read_b128 v[228:231], v154 offset:1024
	ds_read_b128 v[232:235], v154 offset:2048
	ds_read_b128 v[154:157], v154 offset:3072
	s_waitcnt vmcnt(0)
	s_barrier
	s_waitcnt lgkmcnt(0)
	s_waitcnt lgkmcnt(0)
	v_mfma_f32_16x16x32_bf16 v[92:95], v[24:27], v[220:223], v[92:95]
	v_mfma_f32_16x16x32_bf16 v[24:27], v[24:27], v[232:235], v[88:91]
	v_mfma_f32_16x16x32_bf16 v[88:91], v[196:199], v[220:223], v[180:183]
	v_mfma_f32_16x16x32_bf16 v[104:107], v[196:199], v[232:235], v[184:187]
	v_mfma_f32_16x16x32_bf16 v[76:79], v[204:207], v[220:223], v[76:79]
	v_mfma_f32_16x16x32_bf16 v[72:75], v[204:207], v[232:235], v[72:75]
	v_mfma_f32_16x16x32_bf16 v[68:71], v[212:215], v[220:223], v[68:71]
	v_mfma_f32_16x16x32_bf16 v[64:67], v[212:215], v[232:235], v[64:67]
	v_mfma_f32_16x16x32_bf16 v[120:123], v[56:59], v[228:231], v[92:95]
	v_mfma_f32_16x16x32_bf16 v[112:115], v[56:59], v[154:157], v[24:27]
	v_mfma_f32_16x16x32_bf16 v[108:111], v[200:203], v[228:231], v[88:91]
	v_mfma_f32_16x16x32_bf16 v[104:107], v[200:203], v[154:157], v[104:107]
	v_mfma_f32_16x16x32_bf16 v[92:95], v[208:211], v[228:231], v[76:79]
	v_mfma_f32_16x16x32_bf16 v[88:91], v[208:211], v[154:157], v[72:75]
	v_mfma_f32_16x16x32_bf16 v[68:71], v[216:219], v[228:231], v[68:71]
	v_mfma_f32_16x16x32_bf16 v[56:59], v[216:219], v[154:157], v[64:67]
	s_barrier
	s_nop 0
	ds_read_b128 v[64:67], v153 offset:49152
	ds_read_b128 v[178:181], v153 offset:50176
	ds_read_b128 v[76:79], v152 offset:49152
	ds_read_b128 v[182:185], v152 offset:50176
	ds_read_b128 v[196:199], v151 offset:49152
	ds_read_b128 v[200:203], v151 offset:50176
	ds_read_b128 v[204:207], v150 offset:49152
	ds_read_b128 v[150:153], v150 offset:50176
	s_barrier
	s_waitcnt lgkmcnt(0)
	s_waitcnt lgkmcnt(0)
	v_mfma_f32_16x16x32_bf16 v[24:27], v[64:67], v[0:3], v[60:63]
	v_mfma_f32_16x16x32_bf16 v[60:63], v[64:67], v[16:19], v[134:137]
	v_mfma_f32_16x16x32_bf16 v[134:137], v[76:79], v[0:3], v[170:173]
	v_mfma_f32_16x16x32_bf16 v[170:173], v[76:79], v[16:19], v[224:227]
	v_mfma_f32_16x16x32_bf16 v[44:47], v[196:199], v[0:3], v[44:47]
	v_mfma_f32_16x16x32_bf16 v[208:211], v[196:199], v[16:19], v[40:43]
	v_mfma_f32_16x16x32_bf16 v[0:3], v[204:207], v[0:3], v[36:39]
	v_mfma_f32_16x16x32_bf16 v[36:39], v[204:207], v[16:19], v[32:35]
	v_mfma_f32_16x16x32_bf16 v[72:75], v[178:181], v[8:11], v[24:27]
	v_mfma_f32_16x16x32_bf16 v[60:63], v[178:181], v[192:195], v[60:63]
	v_mfma_f32_16x16x32_bf16 v[40:43], v[182:185], v[8:11], v[134:137]
	v_mfma_f32_16x16x32_bf16 v[32:35], v[182:185], v[192:195], v[170:173]
	v_mfma_f32_16x16x32_bf16 v[24:27], v[200:203], v[8:11], v[44:47]
	v_mfma_f32_16x16x32_bf16 v[16:19], v[200:203], v[192:195], v[208:211]
	v_mfma_f32_16x16x32_bf16 v[8:11], v[150:153], v[8:11], v[0:3]
	v_mfma_f32_16x16x32_bf16 v[0:3], v[150:153], v[192:195], v[36:39]
	v_mfma_f32_16x16x32_bf16 v[28:31], v[64:67], v[220:223], v[28:31]
	v_mfma_f32_16x16x32_bf16 v[36:39], v[64:67], v[232:235], v[138:141]
	v_mfma_f32_16x16x32_bf16 v[20:23], v[76:79], v[220:223], v[20:23]
	v_mfma_f32_16x16x32_bf16 v[134:137], v[76:79], v[232:235], v[174:177]
	v_mfma_f32_16x16x32_bf16 v[12:15], v[196:199], v[220:223], v[12:15]
	v_mfma_f32_16x16x32_bf16 v[138:141], v[196:199], v[232:235], v[188:191]
	v_mfma_f32_16x16x32_bf16 v[4:7], v[204:207], v[220:223], v[4:7]
	v_mfma_f32_16x16x32_bf16 v[158:161], v[204:207], v[232:235], v[158:161]
	v_mfma_f32_16x16x32_bf16 v[76:79], v[178:181], v[228:231], v[28:31]
	v_mfma_f32_16x16x32_bf16 v[64:67], v[178:181], v[154:157], v[36:39]
	v_mfma_f32_16x16x32_bf16 v[44:47], v[182:185], v[228:231], v[20:23]
	v_mfma_f32_16x16x32_bf16 v[36:39], v[182:185], v[154:157], v[134:137]
	v_mfma_f32_16x16x32_bf16 v[28:31], v[200:203], v[228:231], v[12:15]
	v_mfma_f32_16x16x32_bf16 v[20:23], v[200:203], v[154:157], v[138:141]
	v_mfma_f32_16x16x32_bf16 v[12:15], v[150:153], v[228:231], v[4:7]
	v_mfma_f32_16x16x32_bf16 v[4:7], v[150:153], v[154:157], v[158:161]
	v_cmp_gt_u32_e32 vcc, s64, v130
	s_barrier
	s_and_saveexec_b64 s[48:49], vcc
	s_cbranch_execz .LBB0_343
	s_barrier

; #define STAGE(P, BASE, LD, br, kt) do { const char* _g = (const char*)((BASE) + (size_t)(br) * (LD) + (size_t)(kt) * 64); \
;     for (int _i = 0; _i < 2; ++_i) { int _b = tidx * 16 + _i * 8192; int _r, _c; stage_rc(_b, _r, _c); \
;       __builtin_amdgcn_global_load_lds((const unsigned*)(_g + (unsigned)((_r * (LD) + _c) * 2)), (unsigned*)((char*)(P) + _b), 16, 0, 0); } } while (0)
; #define LDA(dst, b, h) for (int m = 0; m < 4; ++m) for (int k = 0; k < 2; ++k) \
;     dst[m][k] = *reinterpret_cast<const bf16x8*>((char*)SA(b, h) + lds_byte(wr * 64 + m * 16 + fr, k * 32 + fq * 8))
; #define LDB(dst, b, h) for (int n = 0; n < 2; ++n) for (int k = 0; k < 2; ++k) \
;     dst[n][k] = *reinterpret_cast<const bf16x8*>((char*)SB(b, h) + lds_byte(wc * 32 + n * 16 + fr, k * 32 + fq * 8))
; #define MMA(ai, bj, At_, Bt_) do { __builtin_amdgcn_s_setprio(1); \
;     for (int k = 0; k < 2; ++k) for (int m = 0; m < 4; ++m) for (int n = 0; n < 2; ++n) \
;       acc[ai][bj][m][n] = __builtin_amdgcn_mfma_f32_16x16x32_bf16(At_[m][k], Bt_[n][k], acc[ai][bj][m][n], 0, 0, 0); \
;     __builtin_amdgcn_s_setprio(0); } while (0)
; #define WAIT_L(n) asm volatile("s_waitcnt lgkmcnt(" #n ")" ::: "memory")
; #define BAR __builtin_amdgcn_s_barrier()
; #define SCHED __builtin_amdgcn_sched_barrier(0)
; template <int EPI, int lda, int ldb, int N, int K>
; __device__ __forceinline__ void gemm_phase(const u16* __restrict__ A, const u16* __restrict__ Bt, const GemmEpi ep, int wv) {
;     ...
;     for (int t = 0; t < nt - 2; t += 2) {
;       LDB(B0, 0, 0); SCHED; LDA(At, 0, 0); STAGE(SA(1, 1), Ab, lda, brow + HALF, t + 1);
;       WAIT_L(8); BAR; WAIT_L(0); MMA(0, 0, At, B0); BAR; SCHED;
;       LDB(B1, 0, 1); STAGE(SB(0, 0), Bt, ldb, bcol, t + 2);
;       BAR; WAIT_L(0); MMA(0, 1, At, B1); BAR;
;       LDA(At, 0, 1); STAGE(SA(0, 0), Ab, lda, brow, t + 2);
;       BAR; WAIT_L(0); MMA(1, 0, At, B0); BAR; SCHED;
.LBB0_654:
	ds_read_b128 v[164:167], v160
	ds_read_b128 v[170:173], v160 offset:1024
	ds_read_b128 v[174:177], v160 offset:2048
	ds_read_b128 v[178:181], v160 offset:3072
	v_add_u32_e32 v168, 0xc000, v143
	v_lshl_add_u64 v[234:235], v[138:139], 0, s[52:53]
	v_readfirstlane_b32 s55, v168
	v_add_u32_e32 v169, 0xe000, v143
	v_lshl_add_u64 v[162:163], v[234:235], 0, s[20:21]
	s_mov_b32 m0, s55
	v_lshl_add_u64 v[236:237], v[140:141], 0, s[52:53]
	v_readfirstlane_b32 s55, v169
	ds_read_b128 v[182:185], v151
	ds_read_b128 v[186:189], v151 offset:1024
	ds_read_b128 v[190:193], v150
	ds_read_b128 v[194:197], v150 offset:1024
	ds_read_b128 v[198:201], v149
	ds_read_b128 v[202:205], v149 offset:1024
	ds_read_b128 v[206:209], v148
	ds_read_b128 v[210:213], v148 offset:1024
	global_load_lds_dwordx4 v[162:163], off
	v_lshl_add_u64 v[162:163], v[236:237], 0, s[20:21]
	s_mov_b32 m0, s55
	s_nop 0
	global_load_lds_dwordx4 v[162:163], off
	s_waitcnt lgkmcnt(8)
	s_barrier
	s_waitcnt lgkmcnt(0)
	s_waitcnt lgkmcnt(0)
	v_mfma_f32_16x16x32_bf16 v[124:127], v[164:167], v[182:185], v[124:127]
	v_mfma_f32_16x16x32_bf16 v[120:123], v[174:177], v[182:185], v[120:123]
	v_mfma_f32_16x16x32_bf16 v[116:119], v[164:167], v[190:193], v[116:119]
	v_mfma_f32_16x16x32_bf16 v[112:115], v[174:177], v[190:193], v[112:115]
	v_mfma_f32_16x16x32_bf16 v[108:111], v[164:167], v[198:201], v[108:111]
	v_mfma_f32_16x16x32_bf16 v[104:107], v[174:177], v[198:201], v[104:107]
	v_mfma_f32_16x16x32_bf16 v[100:103], v[164:167], v[206:209], v[100:103]
	v_mfma_f32_16x16x32_bf16 v[96:99], v[174:177], v[206:209], v[96:99]
	v_mfma_f32_16x16x32_bf16 v[124:127], v[170:173], v[186:189], v[124:127]
	v_mfma_f32_16x16x32_bf16 v[120:123], v[178:181], v[186:189], v[120:123]
	v_mfma_f32_16x16x32_bf16 v[116:119], v[170:173], v[194:197], v[116:119]
	v_mfma_f32_16x16x32_bf16 v[112:115], v[178:181], v[194:197], v[112:115]
	v_mfma_f32_16x16x32_bf16 v[108:111], v[170:173], v[202:205], v[108:111]
	v_mfma_f32_16x16x32_bf16 v[104:107], v[178:181], v[202:205], v[104:107]
	v_mfma_f32_16x16x32_bf16 v[100:103], v[170:173], v[210:213], v[100:103]
	v_mfma_f32_16x16x32_bf16 v[96:99], v[178:181], v[210:213], v[96:99]
	s_barrier
	v_add_u32_e32 v161, s65, v153
	v_lshl_add_u64 v[238:239], v[134:135], 0, s[52:53]
	v_readfirstlane_b32 s55, v161
	v_lshl_add_u64 v[162:163], v[238:239], 0, s[22:23]
	s_mov_b32 m0, s55
	ds_read_b128 v[214:217], v159
	ds_read_b128 v[218:221], v159 offset:1024
	ds_read_b128 v[222:225], v159 offset:2048
	ds_read_b128 v[226:229], v159 offset:3072
	global_load_lds_dwordx4 v[162:163], off
	v_add_u32_e32 v162, 0x2000, v161
	v_lshl_add_u64 v[240:241], v[136:137], 0, s[52:53]
	v_readfirstlane_b32 s55, v162
	v_lshl_add_u64 v[230:231], v[240:241], 0, s[22:23]
	s_mov_b32 m0, s55
	s_nop 0
	global_load_lds_dwordx4 v[230:231], off
	s_barrier
	s_waitcnt lgkmcnt(0)
	s_waitcnt lgkmcnt(0)
	v_mfma_f32_16x16x32_bf16 v[92:95], v[214:217], v[182:185], v[92:95]
	v_mfma_f32_16x16x32_bf16 v[88:91], v[222:225], v[182:185], v[88:91]
	v_mfma_f32_16x16x32_bf16 v[84:87], v[214:217], v[190:193], v[84:87]
	v_mfma_f32_16x16x32_bf16 v[80:83], v[222:225], v[190:193], v[80:83]
	v_mfma_f32_16x16x32_bf16 v[76:79], v[214:217], v[198:201], v[76:79]
	v_mfma_f32_16x16x32_bf16 v[72:75], v[222:225], v[198:201], v[72:75]
	v_mfma_f32_16x16x32_bf16 v[68:71], v[214:217], v[206:209], v[68:71]
	v_mfma_f32_16x16x32_bf16 v[64:67], v[222:225], v[206:209], v[64:67]
	v_mfma_f32_16x16x32_bf16 v[92:95], v[218:221], v[186:189], v[92:95]
	v_mfma_f32_16x16x32_bf16 v[88:91], v[226:229], v[186:189], v[88:91]
	v_mfma_f32_16x16x32_bf16 v[84:87], v[218:221], v[194:197], v[84:87]
	v_mfma_f32_16x16x32_bf16 v[80:83], v[226:229], v[194:197], v[80:83]
	v_mfma_f32_16x16x32_bf16 v[76:79], v[218:221], v[202:205], v[76:79]
	v_mfma_f32_16x16x32_bf16 v[72:75], v[226:229], v[202:205], v[72:75]
	v_mfma_f32_16x16x32_bf16 v[68:71], v[218:221], v[210:213], v[68:71]
	v_mfma_f32_16x16x32_bf16 v[64:67], v[226:229], v[210:213], v[64:67]
	v_readfirstlane_b32 s55, v143
	v_add_u32_e32 v163, 0x2000, v143
	v_lshl_add_u64 v[230:231], v[234:235], 0, s[24:25]
	s_mov_b32 m0, s55
	v_readfirstlane_b32 s55, v163
	s_barrier
	ds_read_b128 v[182:185], v151 offset:16384
	ds_read_b128 v[186:189], v151 offset:17408
	ds_read_b128 v[190:193], v150 offset:16384
	ds_read_b128 v[194:197], v150 offset:17408
	ds_read_b128 v[198:201], v149 offset:16384
	ds_read_b128 v[202:205], v149 offset:17408
	ds_read_b128 v[206:209], v148 offset:16384
	ds_read_b128 v[210:213], v148 offset:17408
	global_load_lds_dwordx4 v[230:231], off
	v_lshl_add_u64 v[230:231], v[236:237], 0, s[24:25]
	s_mov_b32 m0, s55
	s_nop 0
	global_load_lds_dwordx4 v[230:231], off
	s_barrier
	s_waitcnt lgkmcnt(0)
	s_waitcnt lgkmcnt(0)
	v_mfma_f32_16x16x32_bf16 v[60:63], v[164:167], v[182:185], v[60:63]
	v_mfma_f32_16x16x32_bf16 v[56:59], v[174:177], v[182:185], v[56:59]
	v_mfma_f32_16x16x32_bf16 v[52:55], v[164:167], v[190:193], v[52:55]
	v_mfma_f32_16x16x32_bf16 v[48:51], v[174:177], v[190:193], v[48:51]
	v_mfma_f32_16x16x32_bf16 v[44:47], v[164:167], v[198:201], v[44:47]
	v_mfma_f32_16x16x32_bf16 v[40:43], v[174:177], v[198:201], v[40:43]
	v_mfma_f32_16x16x32_bf16 v[36:39], v[164:167], v[206:209], v[36:39]
	v_mfma_f32_16x16x32_bf16 v[32:35], v[174:177], v[206:209], v[32:35]
	v_mfma_f32_16x16x32_bf16 v[60:63], v[170:173], v[186:189], v[60:63]
	v_mfma_f32_16x16x32_bf16 v[56:59], v[178:181], v[186:189], v[56:59]
	v_mfma_f32_16x16x32_bf16 v[52:55], v[170:173], v[194:197], v[52:55]
	v_mfma_f32_16x16x32_bf16 v[48:51], v[178:181], v[194:197], v[48:51]
	v_mfma_f32_16x16x32_bf16 v[44:47], v[170:173], v[202:205], v[44:47]
	v_mfma_f32_16x16x32_bf16 v[40:43], v[178:181], v[202:205], v[40:43]
	v_mfma_f32_16x16x32_bf16 v[36:39], v[170:173], v[210:213], v[36:39]
	v_mfma_f32_16x16x32_bf16 v[32:35], v[178:181], v[210:213], v[32:35]
	s_barrier
; #define STAGE(P, BASE, LD, br, kt) do { const char* _g = (const char*)((BASE) + (size_t)(br) * (LD) + (size_t)(kt) * 64); \
;     for (int _i = 0; _i < 2; ++_i) { int _b = tidx * 16 + _i * 8192; int _r, _c; stage_rc(_b, _r, _c); \
;       __builtin_amdgcn_global_load_lds((const unsigned*)(_g + (unsigned)((_r * (LD) + _c) * 2)), (unsigned*)((char*)(P) + _b), 16, 0, 0); } } while (0)
; #define LDA(dst, b, h) for (int m = 0; m < 4; ++m) for (int k = 0; k < 2; ++k) \
;     dst[m][k] = *reinterpret_cast<const bf16x8*>((char*)SA(b, h) + lds_byte(wr * 64 + m * 16 + fr, k * 32 + fq * 8))
; #define LDB(dst, b, h) for (int n = 0; n < 2; ++n) for (int k = 0; k < 2; ++k) \
;     dst[n][k] = *reinterpret_cast<const bf16x8*>((char*)SB(b, h) + lds_byte(wc * 32 + n * 16 + fr, k * 32 + fq * 8))
; #define MMA(ai, bj, At_, Bt_) do { __builtin_amdgcn_s_setprio(1); \
;     for (int k = 0; k < 2; ++k) for (int m = 0; m < 4; ++m) for (int n = 0; n < 2; ++n) \
;       acc[ai][bj][m][n] = __builtin_amdgcn_mfma_f32_16x16x32_bf16(At_[m][k], Bt_[n][k], acc[ai][bj][m][n], 0, 0, 0); \
;     __builtin_amdgcn_s_setprio(0); } while (0)
; #define WAIT_V(n) asm volatile("s_waitcnt vmcnt(" #n ")" ::: "memory")
; #define WAIT_L(n) asm volatile("s_waitcnt lgkmcnt(" #n ")" ::: "memory")
; #define BAR __builtin_amdgcn_s_barrier()
; #define SCHED __builtin_amdgcn_sched_barrier(0)
; template <int EPI, int lda, int ldb, int N, int K>
; __device__ __forceinline__ void gemm_phase(const u16* __restrict__ A, const u16* __restrict__ Bt, const GemmEpi ep, int wv) {
;     ...
;       STAGE(SB(0, 1), Bt, ldb, bcol + HALF, t + 2);
;       WAIT_V(6); BAR; MMA(1, 1, At, B1); BAR;
;       LDB(B0, 1, 0); SCHED; LDA(At, 1, 0); STAGE(SA(0, 1), Ab, lda, brow + HALF, t + 2);
;       WAIT_L(8); BAR; WAIT_L(0); MMA(0, 0, At, B0); BAR; SCHED;
;       LDB(B1, 1, 1); STAGE(SB(1, 0), Bt, ldb, bcol, t + 3);
;       BAR; WAIT_L(0); MMA(0, 1, At, B1); BAR;
	v_add_u32_e32 v164, s66, v153
	v_add_u32_e32 v165, 0x2000, v164
	v_readfirstlane_b32 s55, v164
	v_lshl_add_u64 v[166:167], v[238:239], 0, s[26:27]
	s_mov_b32 m0, s55
	v_readfirstlane_b32 s55, v165
	global_load_lds_dwordx4 v[166:167], off
	v_lshl_add_u64 v[166:167], v[240:241], 0, s[26:27]
	s_mov_b32 m0, s55
	s_nop 0
	global_load_lds_dwordx4 v[166:167], off
	s_waitcnt vmcnt(6)
	s_barrier
	v_mfma_f32_16x16x32_bf16 v[28:31], v[214:217], v[182:185], v[28:31]
	v_mfma_f32_16x16x32_bf16 v[24:27], v[222:225], v[182:185], v[24:27]
	v_mfma_f32_16x16x32_bf16 v[20:23], v[214:217], v[190:193], v[20:23]
	v_mfma_f32_16x16x32_bf16 v[16:19], v[222:225], v[190:193], v[16:19]
	v_mfma_f32_16x16x32_bf16 v[12:15], v[214:217], v[198:201], v[12:15]
	v_mfma_f32_16x16x32_bf16 v[8:11], v[222:225], v[198:201], v[8:11]
	v_mfma_f32_16x16x32_bf16 v[4:7], v[214:217], v[206:209], v[4:7]
	v_mfma_f32_16x16x32_bf16 v[0:3], v[222:225], v[206:209], v[0:3]
	v_mfma_f32_16x16x32_bf16 v[28:31], v[218:221], v[186:189], v[28:31]
	v_mfma_f32_16x16x32_bf16 v[24:27], v[226:229], v[186:189], v[24:27]
	v_mfma_f32_16x16x32_bf16 v[20:23], v[218:221], v[194:197], v[20:23]
	v_mfma_f32_16x16x32_bf16 v[16:19], v[226:229], v[194:197], v[16:19]
	v_mfma_f32_16x16x32_bf16 v[12:15], v[218:221], v[202:205], v[12:15]
	v_mfma_f32_16x16x32_bf16 v[8:11], v[226:229], v[202:205], v[8:11]
	v_mfma_f32_16x16x32_bf16 v[4:7], v[218:221], v[210:213], v[4:7]
	v_mfma_f32_16x16x32_bf16 v[0:3], v[226:229], v[210:213], v[0:3]
	s_barrier
	ds_read_b128 v[170:173], v154
	ds_read_b128 v[174:177], v154 offset:1024
	ds_read_b128 v[178:181], v154 offset:2048
	ds_read_b128 v[182:185], v154 offset:3072
	v_add_u32_e32 v166, 0x4000, v143
	v_add_u32_e32 v167, 0x6000, v143
	v_readfirstlane_b32 s55, v166
	v_lshl_add_u64 v[218:219], v[234:235], 0, s[42:43]
	s_mov_b32 m0, s55
	v_readfirstlane_b32 s55, v167
	ds_read_b128 v[186:189], v151 offset:32768
	ds_read_b128 v[190:193], v151 offset:33792
	ds_read_b128 v[194:197], v150 offset:32768
	ds_read_b128 v[198:201], v150 offset:33792
	ds_read_b128 v[202:205], v149 offset:32768
	ds_read_b128 v[206:209], v149 offset:33792
	ds_read_b128 v[210:213], v148 offset:32768
	ds_read_b128 v[214:217], v148 offset:33792
	global_load_lds_dwordx4 v[218:219], off
	v_lshl_add_u64 v[218:219], v[236:237], 0, s[42:43]
	s_mov_b32 m0, s55
	s_nop 0
	global_load_lds_dwordx4 v[218:219], off
	s_waitcnt lgkmcnt(8)
	s_barrier
	s_waitcnt lgkmcnt(0)
	s_waitcnt lgkmcnt(0)
	v_mfma_f32_16x16x32_bf16 v[124:127], v[170:173], v[186:189], v[124:127]
	v_mfma_f32_16x16x32_bf16 v[120:123], v[178:181], v[186:189], v[120:123]
	v_mfma_f32_16x16x32_bf16 v[116:119], v[170:173], v[194:197], v[116:119]
	v_mfma_f32_16x16x32_bf16 v[112:115], v[178:181], v[194:197], v[112:115]
	v_mfma_f32_16x16x32_bf16 v[108:111], v[170:173], v[202:205], v[108:111]
	v_mfma_f32_16x16x32_bf16 v[104:107], v[178:181], v[202:205], v[104:107]
	v_mfma_f32_16x16x32_bf16 v[100:103], v[170:173], v[210:213], v[100:103]
	v_mfma_f32_16x16x32_bf16 v[96:99], v[178:181], v[210:213], v[96:99]
	v_mfma_f32_16x16x32_bf16 v[124:127], v[174:177], v[190:193], v[124:127]
	v_mfma_f32_16x16x32_bf16 v[120:123], v[182:185], v[190:193], v[120:123]
	v_mfma_f32_16x16x32_bf16 v[116:119], v[174:177], v[198:201], v[116:119]
	v_mfma_f32_16x16x32_bf16 v[112:115], v[182:185], v[198:201], v[112:115]
	v_mfma_f32_16x16x32_bf16 v[108:111], v[174:177], v[206:209], v[108:111]
	v_mfma_f32_16x16x32_bf16 v[104:107], v[182:185], v[206:209], v[104:107]
	v_mfma_f32_16x16x32_bf16 v[100:103], v[174:177], v[214:217], v[100:103]
	v_mfma_f32_16x16x32_bf16 v[96:99], v[182:185], v[214:217], v[96:99]
	s_barrier
	v_readfirstlane_b32 s55, v155
	v_add_u32_e32 v244, 0x2000, v155
	v_lshl_add_u64 v[242:243], v[238:239], 0, s[44:45]
	s_mov_b32 m0, s55
	v_readfirstlane_b32 s55, v244
	ds_read_b128 v[218:221], v152
	ds_read_b128 v[222:225], v152 offset:1024
	ds_read_b128 v[226:229], v152 offset:2048
	ds_read_b128 v[230:233], v152 offset:3072
	global_load_lds_dwordx4 v[242:243], off
	v_lshl_add_u64 v[242:243], v[240:241], 0, s[44:45]
	s_mov_b32 m0, s55
	s_nop 0
	global_load_lds_dwordx4 v[242:243], off
	s_barrier
	s_waitcnt lgkmcnt(0)
	s_waitcnt lgkmcnt(0)
	v_mfma_f32_16x16x32_bf16 v[92:95], v[218:221], v[186:189], v[92:95]
	v_mfma_f32_16x16x32_bf16 v[88:91], v[226:229], v[186:189], v[88:91]
	v_mfma_f32_16x16x32_bf16 v[84:87], v[218:221], v[194:197], v[84:87]
	v_mfma_f32_16x16x32_bf16 v[80:83], v[226:229], v[194:197], v[80:83]
	v_mfma_f32_16x16x32_bf16 v[76:79], v[218:221], v[202:205], v[76:79]
	v_mfma_f32_16x16x32_bf16 v[72:75], v[226:229], v[202:205], v[72:75]
	v_mfma_f32_16x16x32_bf16 v[68:71], v[218:221], v[210:213], v[68:71]
	v_mfma_f32_16x16x32_bf16 v[64:67], v[226:229], v[210:213], v[64:67]
	v_mfma_f32_16x16x32_bf16 v[92:95], v[222:225], v[190:193], v[92:95]
	v_mfma_f32_16x16x32_bf16 v[88:91], v[230:233], v[190:193], v[88:91]
	v_mfma_f32_16x16x32_bf16 v[84:87], v[222:225], v[198:201], v[84:87]
	v_mfma_f32_16x16x32_bf16 v[80:83], v[230:233], v[198:201], v[80:83]
	v_mfma_f32_16x16x32_bf16 v[76:79], v[222:225], v[206:209], v[76:79]
	v_mfma_f32_16x16x32_bf16 v[72:75], v[230:233], v[206:209], v[72:75]
	v_mfma_f32_16x16x32_bf16 v[68:71], v[222:225], v[214:217], v[68:71]
	v_mfma_f32_16x16x32_bf16 v[64:67], v[230:233], v[214:217], v[64:67]
	v_readfirstlane_b32 s55, v156
	v_lshl_add_u64 v[234:235], v[234:235], 0, s[46:47]
	s_mov_b32 m0, s55
	v_readfirstlane_b32 s55, v157
	s_barrier
; #define STAGE(P, BASE, LD, br, kt) do { const char* _g = (const char*)((BASE) + (size_t)(br) * (LD) + (size_t)(kt) * 64); \
;     for (int _i = 0; _i < 2; ++_i) { int _b = tidx * 16 + _i * 8192; int _r, _c; stage_rc(_b, _r, _c); \
;       __builtin_amdgcn_global_load_lds((const unsigned*)(_g + (unsigned)((_r * (LD) + _c) * 2)), (unsigned*)((char*)(P) + _b), 16, 0, 0); } } while (0)
; #define LDA(dst, b, h) for (int m = 0; m < 4; ++m) for (int k = 0; k < 2; ++k) \
;     dst[m][k] = *reinterpret_cast<const bf16x8*>((char*)SA(b, h) + lds_byte(wr * 64 + m * 16 + fr, k * 32 + fq * 8))
; #define LDB(dst, b, h) for (int n = 0; n < 2; ++n) for (int k = 0; k < 2; ++k) \
;     dst[n][k] = *reinterpret_cast<const bf16x8*>((char*)SB(b, h) + lds_byte(wc * 32 + n * 16 + fr, k * 32 + fq * 8))
; #define MMA(ai, bj, At_, Bt_) do { __builtin_amdgcn_s_setprio(1); \
;     for (int k = 0; k < 2; ++k) for (int m = 0; m < 4; ++m) for (int n = 0; n < 2; ++n) \
;       acc[ai][bj][m][n] = __builtin_amdgcn_mfma_f32_16x16x32_bf16(At_[m][k], Bt_[n][k], acc[ai][bj][m][n], 0, 0, 0); \
;     __builtin_amdgcn_s_setprio(0); } while (0)
; #define WAIT_V(n) asm volatile("s_waitcnt vmcnt(" #n ")" ::: "memory")
; #define WAIT_L(n) asm volatile("s_waitcnt lgkmcnt(" #n ")" ::: "memory")
; #define BAR __builtin_amdgcn_s_barrier()
; #define SCHED __builtin_amdgcn_sched_barrier(0)
; template <int EPI, int lda, int ldb, int N, int K>
; __device__ __forceinline__ void gemm_phase(const u16* __restrict__ A, const u16* __restrict__ Bt, const GemmEpi ep, int wv) {
;     ...
;       LDA(At, 1, 1); STAGE(SA(1, 0), Ab, lda, brow, t + 3);
;       BAR; WAIT_L(0); MMA(1, 0, At, B0); BAR; SCHED;
;       STAGE(SB(1, 1), Bt, ldb, bcol + HALF, t + 3);
;       WAIT_V(6); BAR; MMA(1, 1, At, B1); BAR;
;     }
;     { LDB(B0, 0, 0); LDA(At, 0, 0); STAGE(SA(1, 1), Ab, lda, brow + HALF, nt - 1);
;       BAR; WAIT_L(0); MMA(0, 0, At, B0); BAR;
;       LDB(B1, 0, 1); BAR; WAIT_L(0); MMA(0, 1, At, B1); BAR;
	ds_read_b128 v[186:189], v151 offset:49152
	ds_read_b128 v[190:193], v151 offset:50176
	ds_read_b128 v[194:197], v150 offset:49152
	ds_read_b128 v[198:201], v150 offset:50176
	ds_read_b128 v[202:205], v149 offset:49152
	ds_read_b128 v[206:209], v149 offset:50176
	ds_read_b128 v[210:213], v148 offset:49152
	ds_read_b128 v[214:217], v148 offset:50176
	global_load_lds_dwordx4 v[234:235], off
	v_lshl_add_u64 v[234:235], v[236:237], 0, s[46:47]
	s_mov_b32 m0, s55
	s_nop 0
	global_load_lds_dwordx4 v[234:235], off
	s_barrier
	s_waitcnt lgkmcnt(0)
	s_waitcnt lgkmcnt(0)
	v_mfma_f32_16x16x32_bf16 v[60:63], v[170:173], v[186:189], v[60:63]
	v_mfma_f32_16x16x32_bf16 v[56:59], v[178:181], v[186:189], v[56:59]
	v_mfma_f32_16x16x32_bf16 v[52:55], v[170:173], v[194:197], v[52:55]
	v_mfma_f32_16x16x32_bf16 v[48:51], v[178:181], v[194:197], v[48:51]
	v_mfma_f32_16x16x32_bf16 v[44:47], v[170:173], v[202:205], v[44:47]
	v_mfma_f32_16x16x32_bf16 v[40:43], v[178:181], v[202:205], v[40:43]
	v_mfma_f32_16x16x32_bf16 v[36:39], v[170:173], v[210:213], v[36:39]
	v_mfma_f32_16x16x32_bf16 v[32:35], v[178:181], v[210:213], v[32:35]
	v_mfma_f32_16x16x32_bf16 v[60:63], v[174:177], v[190:193], v[60:63]
	v_mfma_f32_16x16x32_bf16 v[56:59], v[182:185], v[190:193], v[56:59]
	v_mfma_f32_16x16x32_bf16 v[52:55], v[174:177], v[198:201], v[52:55]
	v_mfma_f32_16x16x32_bf16 v[48:51], v[182:185], v[198:201], v[48:51]
	v_mfma_f32_16x16x32_bf16 v[44:47], v[174:177], v[206:209], v[44:47]
	v_mfma_f32_16x16x32_bf16 v[40:43], v[182:185], v[206:209], v[40:43]
	v_mfma_f32_16x16x32_bf16 v[36:39], v[174:177], v[214:217], v[36:39]
	v_mfma_f32_16x16x32_bf16 v[32:35], v[182:185], v[214:217], v[32:35]
	s_barrier
	v_readfirstlane_b32 s55, v158
	v_add_u32_e32 v172, 0x2000, v158
	v_lshl_add_u64 v[170:171], v[238:239], 0, s[48:49]
	s_mov_b32 m0, s55
	v_readfirstlane_b32 s55, v172
	global_load_lds_dwordx4 v[170:171], off
	v_lshl_add_u64 v[170:171], v[240:241], 0, s[48:49]
	s_mov_b32 m0, s55
	s_nop 0
	global_load_lds_dwordx4 v[170:171], off
	s_waitcnt vmcnt(6)
	s_barrier
	v_mfma_f32_16x16x32_bf16 v[28:31], v[218:221], v[186:189], v[28:31]
	v_mfma_f32_16x16x32_bf16 v[24:27], v[226:229], v[186:189], v[24:27]
	v_mfma_f32_16x16x32_bf16 v[20:23], v[218:221], v[194:197], v[20:23]
	v_mfma_f32_16x16x32_bf16 v[16:19], v[226:229], v[194:197], v[16:19]
	v_mfma_f32_16x16x32_bf16 v[12:15], v[218:221], v[202:205], v[12:15]
	v_mfma_f32_16x16x32_bf16 v[8:11], v[226:229], v[202:205], v[8:11]
	v_mfma_f32_16x16x32_bf16 v[4:7], v[218:221], v[210:213], v[4:7]
	v_mfma_f32_16x16x32_bf16 v[0:3], v[226:229], v[210:213], v[0:3]
	v_mfma_f32_16x16x32_bf16 v[28:31], v[222:225], v[190:193], v[28:31]
	v_mfma_f32_16x16x32_bf16 v[24:27], v[230:233], v[190:193], v[24:27]
	v_mfma_f32_16x16x32_bf16 v[20:23], v[222:225], v[198:201], v[20:23]
	v_mfma_f32_16x16x32_bf16 v[16:19], v[230:233], v[198:201], v[16:19]
	v_mfma_f32_16x16x32_bf16 v[12:15], v[222:225], v[206:209], v[12:15]
	v_mfma_f32_16x16x32_bf16 v[8:11], v[230:233], v[206:209], v[8:11]
	v_mfma_f32_16x16x32_bf16 v[4:7], v[222:225], v[214:217], v[4:7]
	v_mfma_f32_16x16x32_bf16 v[0:3], v[230:233], v[214:217], v[0:3]
	s_add_i32 s54, s54, 2
	s_add_u32 s52, s52, 0x100
	s_addc_u32 s53, s53, 0
	s_cmp_gt_u32 s54, 27
	s_barrier
	s_cbranch_scc0 .LBB0_654
	s_lshl_b64 s[52:53], s[16:17], 12
	s_add_u32 s52, s14, s52
	s_addc_u32 s53, s15, s53
	s_add_u32 s52, s52, 0x80000
	s_addc_u32 s53, s53, 0
	v_lshl_add_u64 v[156:157], s[52:53], 0, v[128:129]
	v_readfirstlane_b32 s54, v168
	v_lshl_add_u64 v[156:157], v[156:157], 0, s[50:51]
	s_mov_b32 m0, s54
	ds_read_b128 v[134:137], v160
	ds_read_b128 v[138:141], v160 offset:1024
	ds_read_b128 v[170:173], v160 offset:2048
	ds_read_b128 v[174:177], v160 offset:3072
	ds_read_b128 v[178:181], v151
	ds_read_b128 v[182:185], v151 offset:1024
	ds_read_b128 v[186:189], v150
	ds_read_b128 v[190:193], v150 offset:1024
	ds_read_b128 v[194:197], v149
	ds_read_b128 v[198:201], v149 offset:1024
	ds_read_b128 v[202:205], v148
	ds_read_b128 v[206:209], v148 offset:1024
	global_load_lds_dwordx4 v[156:157], off
	v_lshl_add_u64 v[156:157], s[52:53], 0, v[132:133]
	v_readfirstlane_b32 s52, v169
	v_lshl_add_u64 v[156:157], v[156:157], 0, s[50:51]
	s_mov_b32 m0, s52
	s_nop 0
	global_load_lds_dwordx4 v[156:157], off
	s_barrier
	s_waitcnt lgkmcnt(0)
	s_waitcnt lgkmcnt(0)
	v_mfma_f32_16x16x32_bf16 v[124:127], v[134:137], v[178:181], v[124:127]
	v_mfma_f32_16x16x32_bf16 v[120:123], v[170:173], v[178:181], v[120:123]
	v_mfma_f32_16x16x32_bf16 v[116:119], v[134:137], v[186:189], v[116:119]
	v_mfma_f32_16x16x32_bf16 v[112:115], v[170:173], v[186:189], v[112:115]
	v_mfma_f32_16x16x32_bf16 v[108:111], v[134:137], v[194:197], v[108:111]
	v_mfma_f32_16x16x32_bf16 v[104:107], v[170:173], v[194:197], v[104:107]
	v_mfma_f32_16x16x32_bf16 v[100:103], v[134:137], v[202:205], v[100:103]
	v_mfma_f32_16x16x32_bf16 v[96:99], v[170:173], v[202:205], v[96:99]
	v_mfma_f32_16x16x32_bf16 v[124:127], v[138:141], v[182:185], v[124:127]
	v_mfma_f32_16x16x32_bf16 v[120:123], v[174:177], v[182:185], v[120:123]
	v_mfma_f32_16x16x32_bf16 v[116:119], v[138:141], v[190:193], v[116:119]
	v_mfma_f32_16x16x32_bf16 v[112:115], v[174:177], v[190:193], v[112:115]
	v_mfma_f32_16x16x32_bf16 v[108:111], v[138:141], v[198:201], v[108:111]
	v_mfma_f32_16x16x32_bf16 v[104:107], v[174:177], v[198:201], v[104:107]
	v_mfma_f32_16x16x32_bf16 v[100:103], v[138:141], v[206:209], v[100:103]
	v_mfma_f32_16x16x32_bf16 v[96:99], v[174:177], v[206:209], v[96:99]
	s_barrier
	ds_read_b128 v[210:213], v159
	ds_read_b128 v[214:217], v159 offset:1024
	ds_read_b128 v[218:221], v159 offset:2048
	ds_read_b128 v[156:159], v159 offset:3072
	s_barrier
; #define LDA(dst, b, h) for (int m = 0; m < 4; ++m) for (int k = 0; k < 2; ++k) \
;     dst[m][k] = *reinterpret_cast<const bf16x8*>((char*)SA(b, h) + lds_byte(wr * 64 + m * 16 + fr, k * 32 + fq * 8))
; #define LDB(dst, b, h) for (int n = 0; n < 2; ++n) for (int k = 0; k < 2; ++k) \
;     dst[n][k] = *reinterpret_cast<const bf16x8*>((char*)SB(b, h) + lds_byte(wc * 32 + n * 16 + fr, k * 32 + fq * 8))
; #define MMA(ai, bj, At_, Bt_) do { __builtin_amdgcn_s_setprio(1); \
;     for (int k = 0; k < 2; ++k) for (int m = 0; m < 4; ++m) for (int n = 0; n < 2; ++n) \
;       acc[ai][bj][m][n] = __builtin_amdgcn_mfma_f32_16x16x32_bf16(At_[m][k], Bt_[n][k], acc[ai][bj][m][n], 0, 0, 0); \
;     __builtin_amdgcn_s_setprio(0); } while (0)
; #define WAIT_V(n) asm volatile("s_waitcnt vmcnt(" #n ")" ::: "memory")
; #define WAIT_L(n) asm volatile("s_waitcnt lgkmcnt(" #n ")" ::: "memory")
; #define BAR __builtin_amdgcn_s_barrier()
; template <int EPI, int lda, int ldb, int N, int K>
; __device__ __forceinline__ void gemm_phase(const u16* __restrict__ A, const u16* __restrict__ Bt, const GemmEpi ep, int wv) {
;     ...
;       LDB(B1, 0, 1); BAR; WAIT_L(0); MMA(0, 1, At, B1); BAR;
;       LDA(At, 0, 1); WAIT_V(4); BAR; WAIT_L(0); MMA(1, 0, At, B0); MMA(1, 1, At, B1); BAR; }
;     { LDB(B0, 1, 0); LDA(At, 1, 0); WAIT_V(2); BAR; WAIT_L(0); MMA(0, 0, At, B0); BAR;
	s_waitcnt lgkmcnt(0)
	s_waitcnt lgkmcnt(0)
	v_mfma_f32_16x16x32_bf16 v[92:95], v[210:213], v[178:181], v[92:95]
	v_mfma_f32_16x16x32_bf16 v[88:91], v[218:221], v[178:181], v[88:91]
	v_mfma_f32_16x16x32_bf16 v[76:79], v[210:213], v[194:197], v[76:79]
	v_mfma_f32_16x16x32_bf16 v[72:75], v[218:221], v[194:197], v[72:75]
	v_mfma_f32_16x16x32_bf16 v[84:87], v[210:213], v[186:189], v[84:87]
	v_mfma_f32_16x16x32_bf16 v[80:83], v[218:221], v[186:189], v[80:83]
	v_mfma_f32_16x16x32_bf16 v[68:71], v[210:213], v[202:205], v[68:71]
	v_mfma_f32_16x16x32_bf16 v[64:67], v[218:221], v[202:205], v[64:67]
	v_mfma_f32_16x16x32_bf16 v[92:95], v[214:217], v[182:185], v[92:95]
	v_mfma_f32_16x16x32_bf16 v[88:91], v[156:159], v[182:185], v[88:91]
	v_mfma_f32_16x16x32_bf16 v[76:79], v[214:217], v[198:201], v[76:79]
	v_mfma_f32_16x16x32_bf16 v[72:75], v[156:159], v[198:201], v[72:75]
	v_mfma_f32_16x16x32_bf16 v[178:181], v[214:217], v[190:193], v[84:87]
	v_mfma_f32_16x16x32_bf16 v[182:185], v[156:159], v[190:193], v[80:83]
	v_mfma_f32_16x16x32_bf16 v[186:189], v[214:217], v[206:209], v[68:71]
	v_mfma_f32_16x16x32_bf16 v[190:193], v[156:159], v[206:209], v[64:67]
	s_barrier
	s_nop 0
	ds_read_b128 v[64:67], v151 offset:16384
	ds_read_b128 v[68:71], v151 offset:17408
	ds_read_b128 v[80:83], v150 offset:16384
	ds_read_b128 v[84:87], v150 offset:17408
	ds_read_b128 v[194:197], v149 offset:16384
	ds_read_b128 v[198:201], v149 offset:17408
	ds_read_b128 v[202:205], v148 offset:16384
	ds_read_b128 v[206:209], v148 offset:17408
	s_waitcnt vmcnt(4)
	s_barrier
	s_waitcnt lgkmcnt(0)
	s_waitcnt lgkmcnt(0)
	v_mfma_f32_16x16x32_bf16 v[60:63], v[134:137], v[64:67], v[60:63]
	v_mfma_f32_16x16x32_bf16 v[56:59], v[170:173], v[64:67], v[56:59]
	v_mfma_f32_16x16x32_bf16 v[52:55], v[134:137], v[80:83], v[52:55]
	v_mfma_f32_16x16x32_bf16 v[48:51], v[170:173], v[80:83], v[48:51]
	v_mfma_f32_16x16x32_bf16 v[44:47], v[134:137], v[194:197], v[44:47]
	v_mfma_f32_16x16x32_bf16 v[40:43], v[170:173], v[194:197], v[40:43]
	v_mfma_f32_16x16x32_bf16 v[36:39], v[134:137], v[202:205], v[36:39]
	v_mfma_f32_16x16x32_bf16 v[32:35], v[170:173], v[202:205], v[32:35]
	v_mfma_f32_16x16x32_bf16 v[60:63], v[138:141], v[68:71], v[60:63]
	v_mfma_f32_16x16x32_bf16 v[56:59], v[174:177], v[68:71], v[56:59]
	v_mfma_f32_16x16x32_bf16 v[52:55], v[138:141], v[84:87], v[52:55]
	v_mfma_f32_16x16x32_bf16 v[48:51], v[174:177], v[84:87], v[48:51]
	v_mfma_f32_16x16x32_bf16 v[44:47], v[138:141], v[198:201], v[44:47]
	v_mfma_f32_16x16x32_bf16 v[40:43], v[174:177], v[198:201], v[40:43]
	v_mfma_f32_16x16x32_bf16 v[36:39], v[138:141], v[206:209], v[36:39]
	v_mfma_f32_16x16x32_bf16 v[32:35], v[174:177], v[206:209], v[32:35]
	v_mfma_f32_16x16x32_bf16 v[28:31], v[210:213], v[64:67], v[28:31]
	v_mfma_f32_16x16x32_bf16 v[20:23], v[210:213], v[80:83], v[20:23]
	v_mfma_f32_16x16x32_bf16 v[12:15], v[210:213], v[194:197], v[12:15]
	v_mfma_f32_16x16x32_bf16 v[4:7], v[210:213], v[202:205], v[4:7]
	v_mfma_f32_16x16x32_bf16 v[24:27], v[218:221], v[64:67], v[24:27]
	v_mfma_f32_16x16x32_bf16 v[16:19], v[218:221], v[80:83], v[16:19]
	v_mfma_f32_16x16x32_bf16 v[8:11], v[218:221], v[194:197], v[8:11]
	v_mfma_f32_16x16x32_bf16 v[0:3], v[218:221], v[202:205], v[0:3]
	v_mfma_f32_16x16x32_bf16 v[28:31], v[214:217], v[68:71], v[28:31]
	v_mfma_f32_16x16x32_bf16 v[20:23], v[214:217], v[84:87], v[20:23]
	v_mfma_f32_16x16x32_bf16 v[12:15], v[214:217], v[198:201], v[12:15]
	v_mfma_f32_16x16x32_bf16 v[4:7], v[214:217], v[206:209], v[4:7]
	v_mfma_f32_16x16x32_bf16 v[134:137], v[156:159], v[68:71], v[24:27]
	v_mfma_f32_16x16x32_bf16 v[138:141], v[156:159], v[84:87], v[16:19]
	v_mfma_f32_16x16x32_bf16 v[168:171], v[156:159], v[198:201], v[8:11]
	v_mfma_f32_16x16x32_bf16 v[156:159], v[156:159], v[206:209], v[0:3]
	s_barrier
	s_nop 0
	ds_read_b128 v[0:3], v154
	ds_read_b128 v[8:11], v154 offset:1024
	ds_read_b128 v[16:19], v154 offset:2048
	ds_read_b128 v[172:175], v154 offset:3072
	ds_read_b128 v[24:27], v151 offset:32768
	ds_read_b128 v[194:197], v151 offset:33792
	ds_read_b128 v[198:201], v150 offset:32768
	ds_read_b128 v[202:205], v150 offset:33792
	ds_read_b128 v[206:209], v149 offset:32768
	ds_read_b128 v[210:213], v149 offset:33792
	ds_read_b128 v[214:217], v148 offset:32768
	ds_read_b128 v[218:221], v148 offset:33792
	s_waitcnt vmcnt(2)
	s_barrier
; #define LDA(dst, b, h) for (int m = 0; m < 4; ++m) for (int k = 0; k < 2; ++k) \
;     dst[m][k] = *reinterpret_cast<const bf16x8*>((char*)SA(b, h) + lds_byte(wr * 64 + m * 16 + fr, k * 32 + fq * 8))
; #define LDB(dst, b, h) for (int n = 0; n < 2; ++n) for (int k = 0; k < 2; ++k) \
;     dst[n][k] = *reinterpret_cast<const bf16x8*>((char*)SB(b, h) + lds_byte(wc * 32 + n * 16 + fr, k * 32 + fq * 8))
; #define MMA(ai, bj, At_, Bt_) do { __builtin_amdgcn_s_setprio(1); \
;     for (int k = 0; k < 2; ++k) for (int m = 0; m < 4; ++m) for (int n = 0; n < 2; ++n) \
;       acc[ai][bj][m][n] = __builtin_amdgcn_mfma_f32_16x16x32_bf16(At_[m][k], Bt_[n][k], acc[ai][bj][m][n], 0, 0, 0); \
;     __builtin_amdgcn_s_setprio(0); } while (0)
; #define WAIT_V(n) asm volatile("s_waitcnt vmcnt(" #n ")" ::: "memory")
; #define WAIT_L(n) asm volatile("s_waitcnt lgkmcnt(" #n ")" ::: "memory")
; #define BAR __builtin_amdgcn_s_barrier()
; #define STAGE4(BROW, BCOL, PN) do { const u16* Ab_ = A + (EPI == EPI_RG ? ((PN) >> 1) * 256 : 0); \
;     STAGE(SB(0, 0), Bt, ldb, (BCOL), 0); STAGE(SA(0, 0), Ab_, lda, (BROW), 0); \
;     STAGE(SB(0, 1), Bt, ldb, (BCOL) + HALF, 0); STAGE(SA(0, 1), Ab_, lda, (BROW) + HALF, 0); } while (0)
; template <int EPI, int lda, int ldb, int N, int K>
; __device__ __forceinline__ void gemm_phase(const u16* __restrict__ A, const u16* __restrict__ Bt, const GemmEpi ep, int wv) {
;     ...
;     { LDB(B0, 1, 0); LDA(At, 1, 0); WAIT_V(2); BAR; WAIT_L(0); MMA(0, 0, At, B0); BAR;
;       LDB(B1, 1, 1); WAIT_V(0); BAR; WAIT_L(0); MMA(0, 1, At, B1); BAR;
;       LDA(At, 1, 1); BAR; WAIT_L(0); MMA(1, 0, At, B0); MMA(1, 1, At, B1); BAR; }
;     if (wr == 0) BAR;
;     int ntile = 0, nbrow = 0, nbcol = 0, npn = 0; bool more = false;
;     if constexpr (PF) { ntile = tile + gridDim.x; more = ntile < nwg; if (more) { TILE_COORDS(ntile, nbrow, nbcol, npn); STAGE4(nbrow, nbcol, npn); } }
	s_waitcnt lgkmcnt(0)
	s_waitcnt lgkmcnt(0)
	v_mfma_f32_16x16x32_bf16 v[64:67], v[0:3], v[24:27], v[124:127]
	v_mfma_f32_16x16x32_bf16 v[68:71], v[16:19], v[24:27], v[120:123]
	v_mfma_f32_16x16x32_bf16 v[80:83], v[0:3], v[198:201], v[116:119]
	v_mfma_f32_16x16x32_bf16 v[84:87], v[16:19], v[198:201], v[112:115]
	v_mfma_f32_16x16x32_bf16 v[108:111], v[0:3], v[206:209], v[108:111]
	v_mfma_f32_16x16x32_bf16 v[104:107], v[16:19], v[206:209], v[104:107]
	v_mfma_f32_16x16x32_bf16 v[120:123], v[0:3], v[214:217], v[100:103]
	v_mfma_f32_16x16x32_bf16 v[124:127], v[16:19], v[214:217], v[96:99]
	v_mfma_f32_16x16x32_bf16 v[116:119], v[8:11], v[194:197], v[64:67]
	v_mfma_f32_16x16x32_bf16 v[112:115], v[172:175], v[194:197], v[68:71]
	v_mfma_f32_16x16x32_bf16 v[100:103], v[8:11], v[202:205], v[80:83]
	v_mfma_f32_16x16x32_bf16 v[96:99], v[172:175], v[202:205], v[84:87]
	v_mfma_f32_16x16x32_bf16 v[84:87], v[8:11], v[210:213], v[108:111]
	v_mfma_f32_16x16x32_bf16 v[80:83], v[172:175], v[210:213], v[104:107]
	v_mfma_f32_16x16x32_bf16 v[68:71], v[8:11], v[218:221], v[120:123]
	v_mfma_f32_16x16x32_bf16 v[64:67], v[172:175], v[218:221], v[124:127]
	s_barrier
	ds_read_b128 v[222:225], v152
	ds_read_b128 v[226:229], v152 offset:1024
	ds_read_b128 v[230:233], v152 offset:2048
	ds_read_b128 v[152:155], v152 offset:3072
	s_waitcnt vmcnt(0)
	s_barrier
	s_waitcnt lgkmcnt(0)
	s_waitcnt lgkmcnt(0)
	v_mfma_f32_16x16x32_bf16 v[92:95], v[222:225], v[24:27], v[92:95]
	v_mfma_f32_16x16x32_bf16 v[24:27], v[230:233], v[24:27], v[88:91]
	v_mfma_f32_16x16x32_bf16 v[88:91], v[222:225], v[198:201], v[178:181]
	v_mfma_f32_16x16x32_bf16 v[104:107], v[230:233], v[198:201], v[182:185]
	v_mfma_f32_16x16x32_bf16 v[76:79], v[222:225], v[206:209], v[76:79]
	v_mfma_f32_16x16x32_bf16 v[72:75], v[230:233], v[206:209], v[72:75]
	v_mfma_f32_16x16x32_bf16 v[176:179], v[222:225], v[214:217], v[186:189]
	v_mfma_f32_16x16x32_bf16 v[180:183], v[230:233], v[214:217], v[190:193]
	v_mfma_f32_16x16x32_bf16 v[124:127], v[226:229], v[194:197], v[92:95]
	v_mfma_f32_16x16x32_bf16 v[120:123], v[152:155], v[194:197], v[24:27]
	v_mfma_f32_16x16x32_bf16 v[108:111], v[226:229], v[202:205], v[88:91]
	v_mfma_f32_16x16x32_bf16 v[104:107], v[152:155], v[202:205], v[104:107]
	v_mfma_f32_16x16x32_bf16 v[92:95], v[226:229], v[210:213], v[76:79]
	v_mfma_f32_16x16x32_bf16 v[88:91], v[152:155], v[210:213], v[72:75]
	v_mfma_f32_16x16x32_bf16 v[76:79], v[226:229], v[218:221], v[176:179]
	v_mfma_f32_16x16x32_bf16 v[72:75], v[152:155], v[218:221], v[180:183]
	s_barrier
	ds_read_b128 v[176:179], v151 offset:49152
	ds_read_b128 v[180:183], v151 offset:50176
	ds_read_b128 v[184:187], v150 offset:49152
	ds_read_b128 v[188:191], v150 offset:50176
	ds_read_b128 v[192:195], v149 offset:49152
	ds_read_b128 v[196:199], v149 offset:50176
	ds_read_b128 v[200:203], v148 offset:49152
	ds_read_b128 v[148:151], v148 offset:50176
	s_barrier
	s_waitcnt lgkmcnt(0)
	s_waitcnt lgkmcnt(0)
	v_mfma_f32_16x16x32_bf16 v[24:27], v[0:3], v[176:179], v[60:63]
	v_mfma_f32_16x16x32_bf16 v[60:63], v[16:19], v[176:179], v[56:59]
	v_mfma_f32_16x16x32_bf16 v[52:55], v[0:3], v[184:187], v[52:55]
	v_mfma_f32_16x16x32_bf16 v[204:207], v[16:19], v[184:187], v[48:51]
	v_mfma_f32_16x16x32_bf16 v[44:47], v[0:3], v[192:195], v[44:47]
	v_mfma_f32_16x16x32_bf16 v[208:211], v[16:19], v[192:195], v[40:43]
	v_mfma_f32_16x16x32_bf16 v[0:3], v[0:3], v[200:203], v[36:39]
	v_mfma_f32_16x16x32_bf16 v[36:39], v[16:19], v[200:203], v[32:35]
	v_mfma_f32_16x16x32_bf16 v[56:59], v[8:11], v[180:183], v[24:27]
	v_mfma_f32_16x16x32_bf16 v[48:51], v[172:175], v[180:183], v[60:63]
	v_mfma_f32_16x16x32_bf16 v[40:43], v[8:11], v[188:191], v[52:55]
	v_mfma_f32_16x16x32_bf16 v[32:35], v[172:175], v[188:191], v[204:207]
	v_mfma_f32_16x16x32_bf16 v[24:27], v[8:11], v[196:199], v[44:47]
	v_mfma_f32_16x16x32_bf16 v[16:19], v[172:175], v[196:199], v[208:211]
	v_mfma_f32_16x16x32_bf16 v[8:11], v[8:11], v[148:151], v[0:3]
	v_mfma_f32_16x16x32_bf16 v[0:3], v[172:175], v[148:151], v[36:39]
	v_mfma_f32_16x16x32_bf16 v[28:31], v[222:225], v[176:179], v[28:31]
	v_mfma_f32_16x16x32_bf16 v[36:39], v[230:233], v[176:179], v[134:137]
	v_mfma_f32_16x16x32_bf16 v[20:23], v[222:225], v[184:187], v[20:23]
	v_mfma_f32_16x16x32_bf16 v[134:137], v[230:233], v[184:187], v[138:141]
	v_mfma_f32_16x16x32_bf16 v[12:15], v[222:225], v[192:195], v[12:15]
	v_mfma_f32_16x16x32_bf16 v[138:141], v[230:233], v[192:195], v[168:171]
	v_mfma_f32_16x16x32_bf16 v[4:7], v[222:225], v[200:203], v[4:7]
	v_mfma_f32_16x16x32_bf16 v[156:159], v[230:233], v[200:203], v[156:159]
	v_mfma_f32_16x16x32_bf16 v[60:63], v[226:229], v[180:183], v[28:31]
	v_mfma_f32_16x16x32_bf16 v[52:55], v[152:155], v[180:183], v[36:39]
	v_mfma_f32_16x16x32_bf16 v[44:47], v[226:229], v[188:191], v[20:23]
	v_mfma_f32_16x16x32_bf16 v[36:39], v[152:155], v[188:191], v[134:137]
	v_mfma_f32_16x16x32_bf16 v[28:31], v[226:229], v[196:199], v[12:15]
	v_mfma_f32_16x16x32_bf16 v[20:23], v[152:155], v[196:199], v[138:141]
	v_mfma_f32_16x16x32_bf16 v[12:15], v[226:229], v[148:151], v[4:7]
	v_mfma_f32_16x16x32_bf16 v[4:7], v[152:155], v[148:151], v[156:159]
	v_cmp_gt_u32_e32 vcc, s70, v130
	s_barrier
	s_and_saveexec_b64 s[52:53], vcc
	s_cbranch_execz .LBB0_657
	s_barrier

; #define STAGE(P, BASE, LD, br, kt) do { const char* _g = (const char*)((BASE) + (size_t)(br) * (LD) + (size_t)(kt) * 64); \
;     for (int _i = 0; _i < 2; ++_i) { int _b = tidx * 16 + _i * 8192; int _r, _c; stage_rc(_b, _r, _c); \
;       __builtin_amdgcn_global_load_lds((const unsigned*)(_g + (unsigned)((_r * (LD) + _c) * 2)), (unsigned*)((char*)(P) + _b), 16, 0, 0); } } while (0)
; #define LDA(dst, b, h) for (int m = 0; m < 4; ++m) for (int k = 0; k < 2; ++k) \
;     dst[m][k] = *reinterpret_cast<const bf16x8*>((char*)SA(b, h) + lds_byte(wr * 64 + m * 16 + fr, k * 32 + fq * 8))
; #define LDB(dst, b, h) for (int n = 0; n < 2; ++n) for (int k = 0; k < 2; ++k) \
;     dst[n][k] = *reinterpret_cast<const bf16x8*>((char*)SB(b, h) + lds_byte(wc * 32 + n * 16 + fr, k * 32 + fq * 8))
; #define MMA(ai, bj, At_, Bt_) do { __builtin_amdgcn_s_setprio(1); \
;     for (int k = 0; k < 2; ++k) for (int m = 0; m < 4; ++m) for (int n = 0; n < 2; ++n) \
;       acc[ai][bj][m][n] = __builtin_amdgcn_mfma_f32_16x16x32_bf16(At_[m][k], Bt_[n][k], acc[ai][bj][m][n], 0, 0, 0); \
;     __builtin_amdgcn_s_setprio(0); } while (0)
; #define WAIT_L(n) asm volatile("s_waitcnt lgkmcnt(" #n ")" ::: "memory")
; #define BAR __builtin_amdgcn_s_barrier()
; #define SCHED __builtin_amdgcn_sched_barrier(0)
; template <int EPI, int lda, int ldb, int N, int K>
; __device__ __forceinline__ void gemm_phase(const u16* __restrict__ A, const u16* __restrict__ Bt, const GemmEpi ep, int wv) {
;     ...
;     for (int t = 0; t < nt - 2; t += 2) {
;       LDB(B0, 0, 0); SCHED; LDA(At, 0, 0); STAGE(SA(1, 1), Ab, lda, brow + HALF, t + 1);
;       WAIT_L(8); BAR; WAIT_L(0); MMA(0, 0, At, B0); BAR; SCHED;
;       LDB(B1, 0, 1); STAGE(SB(0, 0), Bt, ldb, bcol, t + 2);
;       BAR; WAIT_L(0); MMA(0, 1, At, B1); BAR;
;       LDA(At, 0, 1); STAGE(SA(0, 0), Ab, lda, brow, t + 2);
;       BAR; WAIT_L(0); MMA(1, 0, At, B0); BAR; SCHED;
.LBB0_770:
	ds_read_b128 v[172:175], v161
	ds_read_b128 v[176:179], v161 offset:1024
	ds_read_b128 v[180:183], v161 offset:2048
	ds_read_b128 v[184:187], v161 offset:3072
	v_add_u32_e32 v169, 0xc000, v148
	v_lshl_add_u64 v[236:237], v[136:137], 0, s[50:51]
	v_readfirstlane_b32 s53, v169
	v_add_u32_e32 v170, 0xe000, v148
	v_lshl_add_u64 v[162:163], v[236:237], 0, s[18:19]
	s_mov_b32 m0, s53
	v_lshl_add_u64 v[238:239], v[134:135], 0, s[50:51]
	v_readfirstlane_b32 s53, v170
	ds_read_b128 v[164:167], v152
	ds_read_b128 v[188:191], v152 offset:1024
	ds_read_b128 v[192:195], v151
	ds_read_b128 v[196:199], v151 offset:1024
	ds_read_b128 v[200:203], v150
	ds_read_b128 v[204:207], v150 offset:1024
	ds_read_b128 v[208:211], v149
	ds_read_b128 v[212:215], v149 offset:1024
	global_load_lds_dwordx4 v[162:163], off
	v_lshl_add_u64 v[162:163], v[238:239], 0, s[18:19]
	s_mov_b32 m0, s53
	s_nop 0
	global_load_lds_dwordx4 v[162:163], off
	s_waitcnt lgkmcnt(8)
	s_barrier
	s_waitcnt lgkmcnt(0)
	s_waitcnt lgkmcnt(0)
	v_mfma_f32_16x16x32_bf16 v[124:127], v[172:175], v[164:167], v[124:127]
	v_mfma_f32_16x16x32_bf16 v[120:123], v[180:183], v[164:167], v[120:123]
	v_mfma_f32_16x16x32_bf16 v[116:119], v[172:175], v[192:195], v[116:119]
	v_mfma_f32_16x16x32_bf16 v[112:115], v[180:183], v[192:195], v[112:115]
	v_mfma_f32_16x16x32_bf16 v[108:111], v[172:175], v[200:203], v[108:111]
	v_mfma_f32_16x16x32_bf16 v[104:107], v[180:183], v[200:203], v[104:107]
	v_mfma_f32_16x16x32_bf16 v[100:103], v[172:175], v[208:211], v[100:103]
	v_mfma_f32_16x16x32_bf16 v[96:99], v[180:183], v[208:211], v[96:99]
	v_mfma_f32_16x16x32_bf16 v[124:127], v[176:179], v[188:191], v[124:127]
	v_mfma_f32_16x16x32_bf16 v[120:123], v[184:187], v[188:191], v[120:123]
	v_mfma_f32_16x16x32_bf16 v[116:119], v[176:179], v[196:199], v[116:119]
	v_mfma_f32_16x16x32_bf16 v[112:115], v[184:187], v[196:199], v[112:115]
	v_mfma_f32_16x16x32_bf16 v[108:111], v[176:179], v[204:207], v[108:111]
	v_mfma_f32_16x16x32_bf16 v[104:107], v[184:187], v[204:207], v[104:107]
	v_mfma_f32_16x16x32_bf16 v[100:103], v[176:179], v[212:215], v[100:103]
	v_mfma_f32_16x16x32_bf16 v[96:99], v[184:187], v[212:215], v[96:99]
	s_barrier
	v_add_u32_e32 v162, s64, v153
	v_lshl_add_u64 v[240:241], v[140:141], 0, s[50:51]
	v_readfirstlane_b32 s53, v162
	v_add_u32_e32 v163, 0x2000, v162
	v_lshl_add_u64 v[232:233], v[240:241], 0, s[20:21]
	s_mov_b32 m0, s53
	v_lshl_add_u64 v[242:243], v[138:139], 0, s[50:51]
	v_readfirstlane_b32 s53, v163
	ds_read_b128 v[216:219], v160
	ds_read_b128 v[220:223], v160 offset:1024
	ds_read_b128 v[224:227], v160 offset:2048
	ds_read_b128 v[228:231], v160 offset:3072
	global_load_lds_dwordx4 v[232:233], off
	v_lshl_add_u64 v[232:233], v[242:243], 0, s[20:21]
	s_mov_b32 m0, s53
	s_nop 0
	global_load_lds_dwordx4 v[232:233], off
	s_barrier
	s_waitcnt lgkmcnt(0)
	s_waitcnt lgkmcnt(0)
	v_mfma_f32_16x16x32_bf16 v[92:95], v[216:219], v[164:167], v[92:95]
	v_mfma_f32_16x16x32_bf16 v[88:91], v[224:227], v[164:167], v[88:91]
	v_mfma_f32_16x16x32_bf16 v[84:87], v[216:219], v[192:195], v[84:87]
	v_mfma_f32_16x16x32_bf16 v[80:83], v[224:227], v[192:195], v[80:83]
	v_mfma_f32_16x16x32_bf16 v[76:79], v[216:219], v[200:203], v[76:79]
	v_mfma_f32_16x16x32_bf16 v[72:75], v[224:227], v[200:203], v[72:75]
	v_mfma_f32_16x16x32_bf16 v[68:71], v[216:219], v[208:211], v[68:71]
	v_mfma_f32_16x16x32_bf16 v[64:67], v[224:227], v[208:211], v[64:67]
	v_mfma_f32_16x16x32_bf16 v[92:95], v[220:223], v[188:191], v[92:95]
	v_mfma_f32_16x16x32_bf16 v[88:91], v[228:231], v[188:191], v[88:91]
	v_mfma_f32_16x16x32_bf16 v[84:87], v[220:223], v[196:199], v[84:87]
	v_mfma_f32_16x16x32_bf16 v[80:83], v[228:231], v[196:199], v[80:83]
	v_mfma_f32_16x16x32_bf16 v[76:79], v[220:223], v[204:207], v[76:79]
	v_mfma_f32_16x16x32_bf16 v[72:75], v[228:231], v[204:207], v[72:75]
	v_mfma_f32_16x16x32_bf16 v[68:71], v[220:223], v[212:215], v[68:71]
	v_mfma_f32_16x16x32_bf16 v[64:67], v[228:231], v[212:215], v[64:67]
	v_readfirstlane_b32 s53, v148
	v_lshl_add_u64 v[164:165], v[236:237], 0, s[22:23]
	s_mov_b32 m0, s53
	s_barrier
	ds_read_b128 v[188:191], v152 offset:16384
	ds_read_b128 v[192:195], v152 offset:17408
	ds_read_b128 v[196:199], v151 offset:16384
	ds_read_b128 v[200:203], v151 offset:17408
	ds_read_b128 v[204:207], v150 offset:16384
	ds_read_b128 v[208:211], v150 offset:17408
	ds_read_b128 v[212:215], v149 offset:16384
	ds_read_b128 v[232:235], v149 offset:17408
	global_load_lds_dwordx4 v[164:165], off
	v_add_u32_e32 v164, 0x2000, v148
	v_lshl_add_u64 v[166:167], v[238:239], 0, s[22:23]
	v_readfirstlane_b32 s53, v164
	s_mov_b32 m0, s53
	s_nop 0
	global_load_lds_dwordx4 v[166:167], off
	s_barrier
	s_waitcnt lgkmcnt(0)
	s_waitcnt lgkmcnt(0)
	v_mfma_f32_16x16x32_bf16 v[60:63], v[172:175], v[188:191], v[60:63]
	v_mfma_f32_16x16x32_bf16 v[56:59], v[180:183], v[188:191], v[56:59]
	v_mfma_f32_16x16x32_bf16 v[52:55], v[172:175], v[196:199], v[52:55]
	v_mfma_f32_16x16x32_bf16 v[48:51], v[180:183], v[196:199], v[48:51]
	v_mfma_f32_16x16x32_bf16 v[44:47], v[172:175], v[204:207], v[44:47]
	v_mfma_f32_16x16x32_bf16 v[40:43], v[180:183], v[204:207], v[40:43]
	v_mfma_f32_16x16x32_bf16 v[36:39], v[172:175], v[212:215], v[36:39]
	v_mfma_f32_16x16x32_bf16 v[32:35], v[180:183], v[212:215], v[32:35]
	v_mfma_f32_16x16x32_bf16 v[60:63], v[176:179], v[192:195], v[60:63]
	v_mfma_f32_16x16x32_bf16 v[56:59], v[184:187], v[192:195], v[56:59]
	v_mfma_f32_16x16x32_bf16 v[52:55], v[176:179], v[200:203], v[52:55]
	v_mfma_f32_16x16x32_bf16 v[48:51], v[184:187], v[200:203], v[48:51]
	v_mfma_f32_16x16x32_bf16 v[44:47], v[176:179], v[208:211], v[44:47]
	v_mfma_f32_16x16x32_bf16 v[40:43], v[184:187], v[208:211], v[40:43]
	v_mfma_f32_16x16x32_bf16 v[36:39], v[176:179], v[232:235], v[36:39]
	v_mfma_f32_16x16x32_bf16 v[32:35], v[184:187], v[232:235], v[32:35]
	s_barrier
; #define STAGE(P, BASE, LD, br, kt) do { const char* _g = (const char*)((BASE) + (size_t)(br) * (LD) + (size_t)(kt) * 64); \
;     for (int _i = 0; _i < 2; ++_i) { int _b = tidx * 16 + _i * 8192; int _r, _c; stage_rc(_b, _r, _c); \
;       __builtin_amdgcn_global_load_lds((const unsigned*)(_g + (unsigned)((_r * (LD) + _c) * 2)), (unsigned*)((char*)(P) + _b), 16, 0, 0); } } while (0)
; #define LDA(dst, b, h) for (int m = 0; m < 4; ++m) for (int k = 0; k < 2; ++k) \
;     dst[m][k] = *reinterpret_cast<const bf16x8*>((char*)SA(b, h) + lds_byte(wr * 64 + m * 16 + fr, k * 32 + fq * 8))
; #define LDB(dst, b, h) for (int n = 0; n < 2; ++n) for (int k = 0; k < 2; ++k) \
;     dst[n][k] = *reinterpret_cast<const bf16x8*>((char*)SB(b, h) + lds_byte(wc * 32 + n * 16 + fr, k * 32 + fq * 8))
; #define MMA(ai, bj, At_, Bt_) do { __builtin_amdgcn_s_setprio(1); \
;     for (int k = 0; k < 2; ++k) for (int m = 0; m < 4; ++m) for (int n = 0; n < 2; ++n) \
;       acc[ai][bj][m][n] = __builtin_amdgcn_mfma_f32_16x16x32_bf16(At_[m][k], Bt_[n][k], acc[ai][bj][m][n], 0, 0, 0); \
;     __builtin_amdgcn_s_setprio(0); } while (0)
; #define WAIT_V(n) asm volatile("s_waitcnt vmcnt(" #n ")" ::: "memory")
; #define WAIT_L(n) asm volatile("s_waitcnt lgkmcnt(" #n ")" ::: "memory")
; #define BAR __builtin_amdgcn_s_barrier()
; #define SCHED __builtin_amdgcn_sched_barrier(0)
; template <int EPI, int lda, int ldb, int N, int K>
; __device__ __forceinline__ void gemm_phase(const u16* __restrict__ A, const u16* __restrict__ Bt, const GemmEpi ep, int wv) {
;     ...
;       STAGE(SB(0, 1), Bt, ldb, bcol + HALF, t + 2);
;       WAIT_V(6); BAR; MMA(1, 1, At, B1); BAR;
;       LDB(B0, 1, 0); SCHED; LDA(At, 1, 0); STAGE(SA(0, 1), Ab, lda, brow + HALF, t + 2);
;       WAIT_L(8); BAR; WAIT_L(0); MMA(0, 0, At, B0); BAR; SCHED;
;       LDB(B1, 1, 1); STAGE(SB(1, 0), Bt, ldb, bcol, t + 3);
;       BAR; WAIT_L(0); MMA(0, 1, At, B1); BAR;
	v_add_u32_e32 v165, s65, v153
	v_lshl_add_u64 v[166:167], v[240:241], 0, s[24:25]
	v_readfirstlane_b32 s53, v165
	s_mov_b32 m0, s53
	v_lshl_add_u64 v[172:173], v[242:243], 0, s[24:25]
	global_load_lds_dwordx4 v[166:167], off
	v_add_u32_e32 v166, 0x2000, v165
	s_nop 0
	v_readfirstlane_b32 s53, v166
	s_mov_b32 m0, s53
	s_nop 0
	global_load_lds_dwordx4 v[172:173], off
	s_waitcnt vmcnt(6)
	s_barrier
	v_mfma_f32_16x16x32_bf16 v[28:31], v[216:219], v[188:191], v[28:31]
	v_mfma_f32_16x16x32_bf16 v[24:27], v[224:227], v[188:191], v[24:27]
	v_mfma_f32_16x16x32_bf16 v[20:23], v[216:219], v[196:199], v[20:23]
	v_mfma_f32_16x16x32_bf16 v[16:19], v[224:227], v[196:199], v[16:19]
	v_mfma_f32_16x16x32_bf16 v[12:15], v[216:219], v[204:207], v[12:15]
	v_mfma_f32_16x16x32_bf16 v[8:11], v[224:227], v[204:207], v[8:11]
	v_mfma_f32_16x16x32_bf16 v[4:7], v[216:219], v[212:215], v[4:7]
	v_mfma_f32_16x16x32_bf16 v[0:3], v[224:227], v[212:215], v[0:3]
	v_mfma_f32_16x16x32_bf16 v[28:31], v[220:223], v[192:195], v[28:31]
	v_mfma_f32_16x16x32_bf16 v[24:27], v[228:231], v[192:195], v[24:27]
	v_mfma_f32_16x16x32_bf16 v[20:23], v[220:223], v[200:203], v[20:23]
	v_mfma_f32_16x16x32_bf16 v[16:19], v[228:231], v[200:203], v[16:19]
	v_mfma_f32_16x16x32_bf16 v[12:15], v[220:223], v[208:211], v[12:15]
	v_mfma_f32_16x16x32_bf16 v[8:11], v[228:231], v[208:211], v[8:11]
	v_mfma_f32_16x16x32_bf16 v[4:7], v[220:223], v[232:235], v[4:7]
	v_mfma_f32_16x16x32_bf16 v[0:3], v[228:231], v[232:235], v[0:3]
	s_barrier
	ds_read_b128 v[172:175], v156
	ds_read_b128 v[176:179], v156 offset:1024
	ds_read_b128 v[180:183], v156 offset:2048
	ds_read_b128 v[184:187], v156 offset:3072
	v_add_u32_e32 v167, 0x4000, v148
	v_add_u32_e32 v168, 0x6000, v148
	v_readfirstlane_b32 s53, v167
	v_lshl_add_u64 v[220:221], v[236:237], 0, s[26:27]
	s_mov_b32 m0, s53
	v_readfirstlane_b32 s53, v168
	ds_read_b128 v[188:191], v152 offset:32768
	ds_read_b128 v[192:195], v152 offset:33792
	ds_read_b128 v[196:199], v151 offset:32768
	ds_read_b128 v[200:203], v151 offset:33792
	ds_read_b128 v[204:207], v150 offset:32768
	ds_read_b128 v[208:211], v150 offset:33792
	ds_read_b128 v[212:215], v149 offset:32768
	ds_read_b128 v[216:219], v149 offset:33792
	global_load_lds_dwordx4 v[220:221], off
	v_lshl_add_u64 v[220:221], v[238:239], 0, s[26:27]
	s_mov_b32 m0, s53
	s_nop 0
	global_load_lds_dwordx4 v[220:221], off
	s_waitcnt lgkmcnt(8)
	s_barrier
	s_waitcnt lgkmcnt(0)
	s_waitcnt lgkmcnt(0)
	v_mfma_f32_16x16x32_bf16 v[124:127], v[172:175], v[188:191], v[124:127]
	v_mfma_f32_16x16x32_bf16 v[120:123], v[180:183], v[188:191], v[120:123]
	v_mfma_f32_16x16x32_bf16 v[116:119], v[172:175], v[196:199], v[116:119]
	v_mfma_f32_16x16x32_bf16 v[112:115], v[180:183], v[196:199], v[112:115]
	v_mfma_f32_16x16x32_bf16 v[108:111], v[172:175], v[204:207], v[108:111]
	v_mfma_f32_16x16x32_bf16 v[104:107], v[180:183], v[204:207], v[104:107]
	v_mfma_f32_16x16x32_bf16 v[100:103], v[172:175], v[212:215], v[100:103]
	v_mfma_f32_16x16x32_bf16 v[96:99], v[180:183], v[212:215], v[96:99]
	v_mfma_f32_16x16x32_bf16 v[124:127], v[176:179], v[192:195], v[124:127]
	v_mfma_f32_16x16x32_bf16 v[120:123], v[184:187], v[192:195], v[120:123]
	v_mfma_f32_16x16x32_bf16 v[116:119], v[176:179], v[200:203], v[116:119]
	v_mfma_f32_16x16x32_bf16 v[112:115], v[184:187], v[200:203], v[112:115]
	v_mfma_f32_16x16x32_bf16 v[108:111], v[176:179], v[208:211], v[108:111]
	v_mfma_f32_16x16x32_bf16 v[104:107], v[184:187], v[208:211], v[104:107]
	v_mfma_f32_16x16x32_bf16 v[100:103], v[176:179], v[216:219], v[100:103]
	v_mfma_f32_16x16x32_bf16 v[96:99], v[184:187], v[216:219], v[96:99]
	s_barrier
	v_readfirstlane_b32 s53, v155
	v_add_u32_e32 v171, 0x2000, v155
	v_lshl_add_u64 v[244:245], v[240:241], 0, s[40:41]
	s_mov_b32 m0, s53
	v_readfirstlane_b32 s53, v171
	ds_read_b128 v[220:223], v154
	ds_read_b128 v[224:227], v154 offset:1024
	ds_read_b128 v[228:231], v154 offset:2048
	ds_read_b128 v[232:235], v154 offset:3072
	global_load_lds_dwordx4 v[244:245], off
	v_lshl_add_u64 v[244:245], v[242:243], 0, s[40:41]
	s_mov_b32 m0, s53
	s_nop 0
	global_load_lds_dwordx4 v[244:245], off
	s_barrier
	s_waitcnt lgkmcnt(0)
	s_waitcnt lgkmcnt(0)
	v_mfma_f32_16x16x32_bf16 v[92:95], v[220:223], v[188:191], v[92:95]
	v_mfma_f32_16x16x32_bf16 v[88:91], v[228:231], v[188:191], v[88:91]
	v_mfma_f32_16x16x32_bf16 v[84:87], v[220:223], v[196:199], v[84:87]
	v_mfma_f32_16x16x32_bf16 v[80:83], v[228:231], v[196:199], v[80:83]
	v_mfma_f32_16x16x32_bf16 v[76:79], v[220:223], v[204:207], v[76:79]
	v_mfma_f32_16x16x32_bf16 v[72:75], v[228:231], v[204:207], v[72:75]
	v_mfma_f32_16x16x32_bf16 v[68:71], v[220:223], v[212:215], v[68:71]
	v_mfma_f32_16x16x32_bf16 v[64:67], v[228:231], v[212:215], v[64:67]
	v_mfma_f32_16x16x32_bf16 v[92:95], v[224:227], v[192:195], v[92:95]
	v_mfma_f32_16x16x32_bf16 v[88:91], v[232:235], v[192:195], v[88:91]
	v_mfma_f32_16x16x32_bf16 v[84:87], v[224:227], v[200:203], v[84:87]
	v_mfma_f32_16x16x32_bf16 v[80:83], v[232:235], v[200:203], v[80:83]
	v_mfma_f32_16x16x32_bf16 v[76:79], v[224:227], v[208:211], v[76:79]
	v_mfma_f32_16x16x32_bf16 v[72:75], v[232:235], v[208:211], v[72:75]
	v_mfma_f32_16x16x32_bf16 v[68:71], v[224:227], v[216:219], v[68:71]
	v_mfma_f32_16x16x32_bf16 v[64:67], v[232:235], v[216:219], v[64:67]
	v_readfirstlane_b32 s53, v157
	v_lshl_add_u64 v[236:237], v[236:237], 0, s[42:43]
	s_mov_b32 m0, s53
	v_readfirstlane_b32 s53, v158
	s_barrier
; #define STAGE(P, BASE, LD, br, kt) do { const char* _g = (const char*)((BASE) + (size_t)(br) * (LD) + (size_t)(kt) * 64); \
;     for (int _i = 0; _i < 2; ++_i) { int _b = tidx * 16 + _i * 8192; int _r, _c; stage_rc(_b, _r, _c); \
;       __builtin_amdgcn_global_load_lds((const unsigned*)(_g + (unsigned)((_r * (LD) + _c) * 2)), (unsigned*)((char*)(P) + _b), 16, 0, 0); } } while (0)
; #define LDA(dst, b, h) for (int m = 0; m < 4; ++m) for (int k = 0; k < 2; ++k) \
;     dst[m][k] = *reinterpret_cast<const bf16x8*>((char*)SA(b, h) + lds_byte(wr * 64 + m * 16 + fr, k * 32 + fq * 8))
; #define LDB(dst, b, h) for (int n = 0; n < 2; ++n) for (int k = 0; k < 2; ++k) \
;     dst[n][k] = *reinterpret_cast<const bf16x8*>((char*)SB(b, h) + lds_byte(wc * 32 + n * 16 + fr, k * 32 + fq * 8))
; #define MMA(ai, bj, At_, Bt_) do { __builtin_amdgcn_s_setprio(1); \
;     for (int k = 0; k < 2; ++k) for (int m = 0; m < 4; ++m) for (int n = 0; n < 2; ++n) \
;       acc[ai][bj][m][n] = __builtin_amdgcn_mfma_f32_16x16x32_bf16(At_[m][k], Bt_[n][k], acc[ai][bj][m][n], 0, 0, 0); \
;     __builtin_amdgcn_s_setprio(0); } while (0)
; #define WAIT_V(n) asm volatile("s_waitcnt vmcnt(" #n ")" ::: "memory")
; #define WAIT_L(n) asm volatile("s_waitcnt lgkmcnt(" #n ")" ::: "memory")
; #define BAR __builtin_amdgcn_s_barrier()
; #define SCHED __builtin_amdgcn_sched_barrier(0)
; template <int EPI, int lda, int ldb, int N, int K>
; __device__ __forceinline__ void gemm_phase(const u16* __restrict__ A, const u16* __restrict__ Bt, const GemmEpi ep, int wv) {
;     ...
;       LDA(At, 1, 1); STAGE(SA(1, 0), Ab, lda, brow, t + 3);
;       BAR; WAIT_L(0); MMA(1, 0, At, B0); BAR; SCHED;
;       STAGE(SB(1, 1), Bt, ldb, bcol + HALF, t + 3);
;       WAIT_V(6); BAR; MMA(1, 1, At, B1); BAR;
;     }
;     { LDB(B0, 0, 0); LDA(At, 0, 0); STAGE(SA(1, 1), Ab, lda, brow + HALF, nt - 1);
;       BAR; WAIT_L(0); MMA(0, 0, At, B0); BAR;
;       LDB(B1, 0, 1); BAR; WAIT_L(0); MMA(0, 1, At, B1); BAR;
	ds_read_b128 v[188:191], v152 offset:49152
	ds_read_b128 v[192:195], v152 offset:50176
	ds_read_b128 v[196:199], v151 offset:49152
	ds_read_b128 v[200:203], v151 offset:50176
	ds_read_b128 v[204:207], v150 offset:49152
	ds_read_b128 v[208:211], v150 offset:50176
	ds_read_b128 v[212:215], v149 offset:49152
	ds_read_b128 v[216:219], v149 offset:50176
	global_load_lds_dwordx4 v[236:237], off
	v_lshl_add_u64 v[236:237], v[238:239], 0, s[42:43]
	s_mov_b32 m0, s53
	s_nop 0
	global_load_lds_dwordx4 v[236:237], off
	s_barrier
	s_waitcnt lgkmcnt(0)
	s_waitcnt lgkmcnt(0)
	v_mfma_f32_16x16x32_bf16 v[60:63], v[172:175], v[188:191], v[60:63]
	v_mfma_f32_16x16x32_bf16 v[56:59], v[180:183], v[188:191], v[56:59]
	v_mfma_f32_16x16x32_bf16 v[52:55], v[172:175], v[196:199], v[52:55]
	v_mfma_f32_16x16x32_bf16 v[48:51], v[180:183], v[196:199], v[48:51]
	v_mfma_f32_16x16x32_bf16 v[44:47], v[172:175], v[204:207], v[44:47]
	v_mfma_f32_16x16x32_bf16 v[40:43], v[180:183], v[204:207], v[40:43]
	v_mfma_f32_16x16x32_bf16 v[36:39], v[172:175], v[212:215], v[36:39]
	v_mfma_f32_16x16x32_bf16 v[32:35], v[180:183], v[212:215], v[32:35]
	v_mfma_f32_16x16x32_bf16 v[60:63], v[176:179], v[192:195], v[60:63]
	v_mfma_f32_16x16x32_bf16 v[56:59], v[184:187], v[192:195], v[56:59]
	v_mfma_f32_16x16x32_bf16 v[52:55], v[176:179], v[200:203], v[52:55]
	v_mfma_f32_16x16x32_bf16 v[48:51], v[184:187], v[200:203], v[48:51]
	v_mfma_f32_16x16x32_bf16 v[44:47], v[176:179], v[208:211], v[44:47]
	v_mfma_f32_16x16x32_bf16 v[40:43], v[184:187], v[208:211], v[40:43]
	v_mfma_f32_16x16x32_bf16 v[36:39], v[176:179], v[216:219], v[36:39]
	v_mfma_f32_16x16x32_bf16 v[32:35], v[184:187], v[216:219], v[32:35]
	s_barrier
	v_readfirstlane_b32 s53, v159
	v_add_u32_e32 v171, 0x2000, v159
	v_lshl_add_u64 v[172:173], v[240:241], 0, s[44:45]
	s_mov_b32 m0, s53
	v_readfirstlane_b32 s53, v171
	global_load_lds_dwordx4 v[172:173], off
	v_lshl_add_u64 v[172:173], v[242:243], 0, s[44:45]
	s_mov_b32 m0, s53
	s_nop 0
	global_load_lds_dwordx4 v[172:173], off
	s_waitcnt vmcnt(6)
	s_barrier
	v_mfma_f32_16x16x32_bf16 v[28:31], v[220:223], v[188:191], v[28:31]
	v_mfma_f32_16x16x32_bf16 v[24:27], v[228:231], v[188:191], v[24:27]
	v_mfma_f32_16x16x32_bf16 v[20:23], v[220:223], v[196:199], v[20:23]
	v_mfma_f32_16x16x32_bf16 v[16:19], v[228:231], v[196:199], v[16:19]
	v_mfma_f32_16x16x32_bf16 v[12:15], v[220:223], v[204:207], v[12:15]
	v_mfma_f32_16x16x32_bf16 v[8:11], v[228:231], v[204:207], v[8:11]
	v_mfma_f32_16x16x32_bf16 v[4:7], v[220:223], v[212:215], v[4:7]
	v_mfma_f32_16x16x32_bf16 v[0:3], v[228:231], v[212:215], v[0:3]
	v_mfma_f32_16x16x32_bf16 v[28:31], v[224:227], v[192:195], v[28:31]
	v_mfma_f32_16x16x32_bf16 v[24:27], v[232:235], v[192:195], v[24:27]
	v_mfma_f32_16x16x32_bf16 v[20:23], v[224:227], v[200:203], v[20:23]
	v_mfma_f32_16x16x32_bf16 v[16:19], v[232:235], v[200:203], v[16:19]
	v_mfma_f32_16x16x32_bf16 v[12:15], v[224:227], v[208:211], v[12:15]
	v_mfma_f32_16x16x32_bf16 v[8:11], v[232:235], v[208:211], v[8:11]
	v_mfma_f32_16x16x32_bf16 v[4:7], v[224:227], v[216:219], v[4:7]
	v_mfma_f32_16x16x32_bf16 v[0:3], v[232:235], v[216:219], v[0:3]
	s_add_i32 s52, s52, 2
	s_add_u32 s50, s50, 0x100
	s_addc_u32 s51, s51, 0
	s_cmp_gt_u32 s52, 27
	s_barrier
	s_cbranch_scc0 .LBB0_770
	s_add_i32 s50, s48, 0x80
	s_mul_hi_i32 s51, s50, 0x1080
	s_mulk_i32 s50, 0x1080
	s_add_u32 s50, s61, s50
	s_addc_u32 s51, s62, s51
	v_lshl_add_u64 v[158:159], s[50:51], 0, v[128:129]
	v_readfirstlane_b32 s52, v169
	v_lshl_add_u64 v[158:159], v[158:159], 0, s[46:47]
	s_mov_b32 m0, s52
	ds_read_b128 v[134:137], v161
	ds_read_b128 v[138:141], v161 offset:1024
	ds_read_b128 v[172:175], v161 offset:2048
	ds_read_b128 v[176:179], v161 offset:3072
	ds_read_b128 v[180:183], v152
	ds_read_b128 v[184:187], v152 offset:1024
	ds_read_b128 v[188:191], v151
	ds_read_b128 v[192:195], v151 offset:1024
	ds_read_b128 v[196:199], v150
	ds_read_b128 v[200:203], v150 offset:1024
	ds_read_b128 v[204:207], v149
	ds_read_b128 v[208:211], v149 offset:1024
	global_load_lds_dwordx4 v[158:159], off
	v_lshl_add_u64 v[158:159], s[50:51], 0, v[132:133]
	v_readfirstlane_b32 s50, v170
	v_lshl_add_u64 v[158:159], v[158:159], 0, s[46:47]
	s_mov_b32 m0, s50
	s_nop 0
	global_load_lds_dwordx4 v[158:159], off
	s_barrier
	s_waitcnt lgkmcnt(0)
	s_waitcnt lgkmcnt(0)
	v_mfma_f32_16x16x32_bf16 v[124:127], v[134:137], v[180:183], v[124:127]
	v_mfma_f32_16x16x32_bf16 v[120:123], v[172:175], v[180:183], v[120:123]
	v_mfma_f32_16x16x32_bf16 v[116:119], v[134:137], v[188:191], v[116:119]
	v_mfma_f32_16x16x32_bf16 v[112:115], v[172:175], v[188:191], v[112:115]
	v_mfma_f32_16x16x32_bf16 v[108:111], v[134:137], v[196:199], v[108:111]
	v_mfma_f32_16x16x32_bf16 v[104:107], v[172:175], v[196:199], v[104:107]
	v_mfma_f32_16x16x32_bf16 v[100:103], v[134:137], v[204:207], v[100:103]
	v_mfma_f32_16x16x32_bf16 v[96:99], v[172:175], v[204:207], v[96:99]
	v_mfma_f32_16x16x32_bf16 v[124:127], v[138:141], v[184:187], v[124:127]
	v_mfma_f32_16x16x32_bf16 v[120:123], v[176:179], v[184:187], v[120:123]
	v_mfma_f32_16x16x32_bf16 v[116:119], v[138:141], v[192:195], v[116:119]
	v_mfma_f32_16x16x32_bf16 v[112:115], v[176:179], v[192:195], v[112:115]
	v_mfma_f32_16x16x32_bf16 v[108:111], v[138:141], v[200:203], v[108:111]
	v_mfma_f32_16x16x32_bf16 v[104:107], v[176:179], v[200:203], v[104:107]
	v_mfma_f32_16x16x32_bf16 v[100:103], v[138:141], v[208:211], v[100:103]
	v_mfma_f32_16x16x32_bf16 v[96:99], v[176:179], v[208:211], v[96:99]
	s_barrier
	ds_read_b128 v[212:215], v160
	ds_read_b128 v[216:219], v160 offset:1024
	ds_read_b128 v[220:223], v160 offset:2048
	ds_read_b128 v[158:161], v160 offset:3072
	s_barrier
; #define LDA(dst, b, h) for (int m = 0; m < 4; ++m) for (int k = 0; k < 2; ++k) \
;     dst[m][k] = *reinterpret_cast<const bf16x8*>((char*)SA(b, h) + lds_byte(wr * 64 + m * 16 + fr, k * 32 + fq * 8))
; #define LDB(dst, b, h) for (int n = 0; n < 2; ++n) for (int k = 0; k < 2; ++k) \
;     dst[n][k] = *reinterpret_cast<const bf16x8*>((char*)SB(b, h) + lds_byte(wc * 32 + n * 16 + fr, k * 32 + fq * 8))
; #define MMA(ai, bj, At_, Bt_) do { __builtin_amdgcn_s_setprio(1); \
;     for (int k = 0; k < 2; ++k) for (int m = 0; m < 4; ++m) for (int n = 0; n < 2; ++n) \
;       acc[ai][bj][m][n] = __builtin_amdgcn_mfma_f32_16x16x32_bf16(At_[m][k], Bt_[n][k], acc[ai][bj][m][n], 0, 0, 0); \
;     __builtin_amdgcn_s_setprio(0); } while (0)
; #define WAIT_V(n) asm volatile("s_waitcnt vmcnt(" #n ")" ::: "memory")
; #define WAIT_L(n) asm volatile("s_waitcnt lgkmcnt(" #n ")" ::: "memory")
; #define BAR __builtin_amdgcn_s_barrier()
; template <int EPI, int lda, int ldb, int N, int K>
; __device__ __forceinline__ void gemm_phase(const u16* __restrict__ A, const u16* __restrict__ Bt, const GemmEpi ep, int wv) {
;     ...
;       LDB(B1, 0, 1); BAR; WAIT_L(0); MMA(0, 1, At, B1); BAR;
;       LDA(At, 0, 1); WAIT_V(4); BAR; WAIT_L(0); MMA(1, 0, At, B0); MMA(1, 1, At, B1); BAR; }
;     { LDB(B0, 1, 0); LDA(At, 1, 0); WAIT_V(2); BAR; WAIT_L(0); MMA(0, 0, At, B0); BAR;
	s_waitcnt lgkmcnt(0)
	s_waitcnt lgkmcnt(0)
	v_mfma_f32_16x16x32_bf16 v[92:95], v[212:215], v[180:183], v[92:95]
	v_mfma_f32_16x16x32_bf16 v[88:91], v[220:223], v[180:183], v[88:91]
	v_mfma_f32_16x16x32_bf16 v[76:79], v[212:215], v[196:199], v[76:79]
	v_mfma_f32_16x16x32_bf16 v[72:75], v[220:223], v[196:199], v[72:75]
	v_mfma_f32_16x16x32_bf16 v[84:87], v[212:215], v[188:191], v[84:87]
	v_mfma_f32_16x16x32_bf16 v[80:83], v[220:223], v[188:191], v[80:83]
	v_mfma_f32_16x16x32_bf16 v[68:71], v[212:215], v[204:207], v[68:71]
	v_mfma_f32_16x16x32_bf16 v[64:67], v[220:223], v[204:207], v[64:67]
	v_mfma_f32_16x16x32_bf16 v[92:95], v[216:219], v[184:187], v[92:95]
	v_mfma_f32_16x16x32_bf16 v[88:91], v[158:161], v[184:187], v[88:91]
	v_mfma_f32_16x16x32_bf16 v[76:79], v[216:219], v[200:203], v[76:79]
	v_mfma_f32_16x16x32_bf16 v[72:75], v[158:161], v[200:203], v[72:75]
	v_mfma_f32_16x16x32_bf16 v[180:183], v[216:219], v[192:195], v[84:87]
	v_mfma_f32_16x16x32_bf16 v[184:187], v[158:161], v[192:195], v[80:83]
	v_mfma_f32_16x16x32_bf16 v[188:191], v[216:219], v[208:211], v[68:71]
	v_mfma_f32_16x16x32_bf16 v[192:195], v[158:161], v[208:211], v[64:67]
	s_barrier
	s_nop 0
	ds_read_b128 v[64:67], v152 offset:16384
	ds_read_b128 v[68:71], v152 offset:17408
	ds_read_b128 v[80:83], v151 offset:16384
	ds_read_b128 v[84:87], v151 offset:17408
	ds_read_b128 v[196:199], v150 offset:16384
	ds_read_b128 v[200:203], v150 offset:17408
	ds_read_b128 v[204:207], v149 offset:16384
	ds_read_b128 v[208:211], v149 offset:17408
	s_waitcnt vmcnt(4)
	s_barrier
	s_waitcnt lgkmcnt(0)
	s_waitcnt lgkmcnt(0)
	v_mfma_f32_16x16x32_bf16 v[60:63], v[134:137], v[64:67], v[60:63]
	v_mfma_f32_16x16x32_bf16 v[56:59], v[172:175], v[64:67], v[56:59]
	v_mfma_f32_16x16x32_bf16 v[52:55], v[134:137], v[80:83], v[52:55]
	v_mfma_f32_16x16x32_bf16 v[48:51], v[172:175], v[80:83], v[48:51]
	v_mfma_f32_16x16x32_bf16 v[44:47], v[134:137], v[196:199], v[44:47]
	v_mfma_f32_16x16x32_bf16 v[40:43], v[172:175], v[196:199], v[40:43]
	v_mfma_f32_16x16x32_bf16 v[36:39], v[134:137], v[204:207], v[36:39]
	v_mfma_f32_16x16x32_bf16 v[32:35], v[172:175], v[204:207], v[32:35]
	v_mfma_f32_16x16x32_bf16 v[60:63], v[138:141], v[68:71], v[60:63]
	v_mfma_f32_16x16x32_bf16 v[56:59], v[176:179], v[68:71], v[56:59]
	v_mfma_f32_16x16x32_bf16 v[52:55], v[138:141], v[84:87], v[52:55]
	v_mfma_f32_16x16x32_bf16 v[48:51], v[176:179], v[84:87], v[48:51]
	v_mfma_f32_16x16x32_bf16 v[44:47], v[138:141], v[200:203], v[44:47]
	v_mfma_f32_16x16x32_bf16 v[40:43], v[176:179], v[200:203], v[40:43]
	v_mfma_f32_16x16x32_bf16 v[36:39], v[138:141], v[208:211], v[36:39]
	v_mfma_f32_16x16x32_bf16 v[32:35], v[176:179], v[208:211], v[32:35]
	v_mfma_f32_16x16x32_bf16 v[28:31], v[212:215], v[64:67], v[28:31]
	v_mfma_f32_16x16x32_bf16 v[24:27], v[220:223], v[64:67], v[24:27]
	v_mfma_f32_16x16x32_bf16 v[12:15], v[212:215], v[196:199], v[12:15]
	v_mfma_f32_16x16x32_bf16 v[8:11], v[220:223], v[196:199], v[8:11]
	v_mfma_f32_16x16x32_bf16 v[20:23], v[212:215], v[80:83], v[20:23]
	v_mfma_f32_16x16x32_bf16 v[16:19], v[220:223], v[80:83], v[16:19]
	v_mfma_f32_16x16x32_bf16 v[4:7], v[212:215], v[204:207], v[4:7]
	v_mfma_f32_16x16x32_bf16 v[0:3], v[220:223], v[204:207], v[0:3]
	v_mfma_f32_16x16x32_bf16 v[28:31], v[216:219], v[68:71], v[28:31]
	v_mfma_f32_16x16x32_bf16 v[24:27], v[158:161], v[68:71], v[24:27]
	v_mfma_f32_16x16x32_bf16 v[12:15], v[216:219], v[200:203], v[12:15]
	v_mfma_f32_16x16x32_bf16 v[8:11], v[158:161], v[200:203], v[8:11]
	v_mfma_f32_16x16x32_bf16 v[134:137], v[216:219], v[84:87], v[20:23]
	v_mfma_f32_16x16x32_bf16 v[138:141], v[158:161], v[84:87], v[16:19]
	v_mfma_f32_16x16x32_bf16 v[170:173], v[216:219], v[208:211], v[4:7]
	v_mfma_f32_16x16x32_bf16 v[158:161], v[158:161], v[208:211], v[0:3]
	s_barrier
	s_nop 0
	ds_read_b128 v[0:3], v156
	ds_read_b128 v[4:7], v156 offset:1024
	ds_read_b128 v[16:19], v156 offset:2048
	ds_read_b128 v[174:177], v156 offset:3072
	ds_read_b128 v[20:23], v152 offset:32768
	ds_read_b128 v[196:199], v152 offset:33792
	ds_read_b128 v[200:203], v151 offset:32768
	ds_read_b128 v[204:207], v151 offset:33792
	ds_read_b128 v[208:211], v150 offset:32768
	ds_read_b128 v[212:215], v150 offset:33792
	ds_read_b128 v[216:219], v149 offset:32768
	ds_read_b128 v[220:223], v149 offset:33792
	s_waitcnt vmcnt(2)
	s_barrier
; #define LDA(dst, b, h) for (int m = 0; m < 4; ++m) for (int k = 0; k < 2; ++k) \
;     dst[m][k] = *reinterpret_cast<const bf16x8*>((char*)SA(b, h) + lds_byte(wr * 64 + m * 16 + fr, k * 32 + fq * 8))
; #define LDB(dst, b, h) for (int n = 0; n < 2; ++n) for (int k = 0; k < 2; ++k) \
;     dst[n][k] = *reinterpret_cast<const bf16x8*>((char*)SB(b, h) + lds_byte(wc * 32 + n * 16 + fr, k * 32 + fq * 8))
; #define MMA(ai, bj, At_, Bt_) do { __builtin_amdgcn_s_setprio(1); \
;     for (int k = 0; k < 2; ++k) for (int m = 0; m < 4; ++m) for (int n = 0; n < 2; ++n) \
;       acc[ai][bj][m][n] = __builtin_amdgcn_mfma_f32_16x16x32_bf16(At_[m][k], Bt_[n][k], acc[ai][bj][m][n], 0, 0, 0); \
;     __builtin_amdgcn_s_setprio(0); } while (0)
; #define WAIT_V(n) asm volatile("s_waitcnt vmcnt(" #n ")" ::: "memory")
; #define WAIT_L(n) asm volatile("s_waitcnt lgkmcnt(" #n ")" ::: "memory")
; #define BAR __builtin_amdgcn_s_barrier()
; #define STAGE4(BROW, BCOL, PN) do { const u16* Ab_ = A + (EPI == EPI_RG ? ((PN) >> 1) * 256 : 0); \
;     STAGE(SB(0, 0), Bt, ldb, (BCOL), 0); STAGE(SA(0, 0), Ab_, lda, (BROW), 0); \
;     STAGE(SB(0, 1), Bt, ldb, (BCOL) + HALF, 0); STAGE(SA(0, 1), Ab_, lda, (BROW) + HALF, 0); } while (0)
; template <int EPI, int lda, int ldb, int N, int K>
; __device__ __forceinline__ void gemm_phase(const u16* __restrict__ A, const u16* __restrict__ Bt, const GemmEpi ep, int wv) {
;     ...
;     { LDB(B0, 1, 0); LDA(At, 1, 0); WAIT_V(2); BAR; WAIT_L(0); MMA(0, 0, At, B0); BAR;
;       LDB(B1, 1, 1); WAIT_V(0); BAR; WAIT_L(0); MMA(0, 1, At, B1); BAR;
;       LDA(At, 1, 1); BAR; WAIT_L(0); MMA(1, 0, At, B0); MMA(1, 1, At, B1); BAR; }
;     if (wr == 0) BAR;
;     int ntile = 0, nbrow = 0, nbcol = 0, npn = 0; bool more = false;
;     if constexpr (PF) { ntile = tile + gridDim.x; more = ntile < nwg; if (more) { TILE_COORDS(ntile, nbrow, nbcol, npn); STAGE4(nbrow, nbcol, npn); } }
	s_waitcnt lgkmcnt(0)
	s_waitcnt lgkmcnt(0)
	v_mfma_f32_16x16x32_bf16 v[64:67], v[0:3], v[20:23], v[124:127]
	v_mfma_f32_16x16x32_bf16 v[68:71], v[16:19], v[20:23], v[120:123]
	v_mfma_f32_16x16x32_bf16 v[80:83], v[0:3], v[200:203], v[116:119]
	v_mfma_f32_16x16x32_bf16 v[84:87], v[16:19], v[200:203], v[112:115]
	v_mfma_f32_16x16x32_bf16 v[108:111], v[0:3], v[208:211], v[108:111]
	v_mfma_f32_16x16x32_bf16 v[104:107], v[16:19], v[208:211], v[104:107]
	v_mfma_f32_16x16x32_bf16 v[120:123], v[0:3], v[216:219], v[100:103]
	v_mfma_f32_16x16x32_bf16 v[124:127], v[16:19], v[216:219], v[96:99]
	v_mfma_f32_16x16x32_bf16 v[116:119], v[4:7], v[196:199], v[64:67]
	v_mfma_f32_16x16x32_bf16 v[112:115], v[174:177], v[196:199], v[68:71]
	v_mfma_f32_16x16x32_bf16 v[100:103], v[4:7], v[204:207], v[80:83]
	v_mfma_f32_16x16x32_bf16 v[96:99], v[174:177], v[204:207], v[84:87]
	v_mfma_f32_16x16x32_bf16 v[84:87], v[4:7], v[212:215], v[108:111]
	v_mfma_f32_16x16x32_bf16 v[80:83], v[174:177], v[212:215], v[104:107]
	v_mfma_f32_16x16x32_bf16 v[68:71], v[4:7], v[220:223], v[120:123]
	v_mfma_f32_16x16x32_bf16 v[64:67], v[174:177], v[220:223], v[124:127]
	s_barrier
	ds_read_b128 v[224:227], v154
	ds_read_b128 v[228:231], v154 offset:1024
	ds_read_b128 v[232:235], v154 offset:2048
	ds_read_b128 v[154:157], v154 offset:3072
	s_waitcnt vmcnt(0)
	s_barrier
	s_waitcnt lgkmcnt(0)
	s_waitcnt lgkmcnt(0)
	v_mfma_f32_16x16x32_bf16 v[92:95], v[224:227], v[20:23], v[92:95]
	v_mfma_f32_16x16x32_bf16 v[20:23], v[232:235], v[20:23], v[88:91]
	v_mfma_f32_16x16x32_bf16 v[88:91], v[224:227], v[200:203], v[180:183]
	v_mfma_f32_16x16x32_bf16 v[104:107], v[232:235], v[200:203], v[184:187]
	v_mfma_f32_16x16x32_bf16 v[76:79], v[224:227], v[208:211], v[76:79]
	v_mfma_f32_16x16x32_bf16 v[72:75], v[232:235], v[208:211], v[72:75]
	v_mfma_f32_16x16x32_bf16 v[178:181], v[224:227], v[216:219], v[188:191]
	v_mfma_f32_16x16x32_bf16 v[182:185], v[232:235], v[216:219], v[192:195]
	v_mfma_f32_16x16x32_bf16 v[124:127], v[228:231], v[196:199], v[92:95]
	v_mfma_f32_16x16x32_bf16 v[120:123], v[154:157], v[196:199], v[20:23]
	v_mfma_f32_16x16x32_bf16 v[108:111], v[228:231], v[204:207], v[88:91]
	v_mfma_f32_16x16x32_bf16 v[104:107], v[154:157], v[204:207], v[104:107]
	v_mfma_f32_16x16x32_bf16 v[92:95], v[228:231], v[212:215], v[76:79]
	v_mfma_f32_16x16x32_bf16 v[88:91], v[154:157], v[212:215], v[72:75]
	v_mfma_f32_16x16x32_bf16 v[76:79], v[228:231], v[220:223], v[178:181]
	v_mfma_f32_16x16x32_bf16 v[72:75], v[154:157], v[220:223], v[182:185]
	s_barrier
	ds_read_b128 v[178:181], v152 offset:49152
	ds_read_b128 v[182:185], v152 offset:50176
	ds_read_b128 v[186:189], v151 offset:49152
	ds_read_b128 v[190:193], v151 offset:50176
	ds_read_b128 v[194:197], v150 offset:49152
	ds_read_b128 v[150:153], v150 offset:50176
	ds_read_b128 v[198:201], v149 offset:49152
	ds_read_b128 v[202:205], v149 offset:50176
	s_barrier
	s_waitcnt lgkmcnt(0)
	s_waitcnt lgkmcnt(0)
	v_mfma_f32_16x16x32_bf16 v[20:23], v[0:3], v[178:181], v[60:63]
	v_mfma_f32_16x16x32_bf16 v[56:59], v[16:19], v[178:181], v[56:59]
	v_mfma_f32_16x16x32_bf16 v[60:63], v[0:3], v[186:189], v[52:55]
	v_mfma_f32_16x16x32_bf16 v[206:209], v[16:19], v[186:189], v[48:51]
	v_mfma_f32_16x16x32_bf16 v[44:47], v[0:3], v[194:197], v[44:47]
	v_mfma_f32_16x16x32_bf16 v[40:43], v[16:19], v[194:197], v[40:43]
	v_mfma_f32_16x16x32_bf16 v[0:3], v[0:3], v[198:201], v[36:39]
	v_mfma_f32_16x16x32_bf16 v[210:213], v[16:19], v[198:201], v[32:35]
	v_mfma_f32_16x16x32_bf16 v[52:55], v[4:7], v[182:185], v[20:23]
	v_mfma_f32_16x16x32_bf16 v[48:51], v[174:177], v[182:185], v[56:59]
	v_mfma_f32_16x16x32_bf16 v[36:39], v[4:7], v[190:193], v[60:63]
	v_mfma_f32_16x16x32_bf16 v[32:35], v[174:177], v[190:193], v[206:209]
	v_mfma_f32_16x16x32_bf16 v[20:23], v[4:7], v[150:153], v[44:47]
	v_mfma_f32_16x16x32_bf16 v[16:19], v[174:177], v[150:153], v[40:43]
	v_mfma_f32_16x16x32_bf16 v[4:7], v[4:7], v[202:205], v[0:3]
	v_mfma_f32_16x16x32_bf16 v[0:3], v[174:177], v[202:205], v[210:213]
	v_mfma_f32_16x16x32_bf16 v[28:31], v[224:227], v[178:181], v[28:31]
	v_mfma_f32_16x16x32_bf16 v[24:27], v[232:235], v[178:181], v[24:27]
	v_mfma_f32_16x16x32_bf16 v[40:43], v[224:227], v[186:189], v[134:137]
	v_mfma_f32_16x16x32_bf16 v[134:137], v[232:235], v[186:189], v[138:141]
	v_mfma_f32_16x16x32_bf16 v[12:15], v[224:227], v[194:197], v[12:15]
	v_mfma_f32_16x16x32_bf16 v[8:11], v[232:235], v[194:197], v[8:11]
	v_mfma_f32_16x16x32_bf16 v[138:141], v[224:227], v[198:201], v[170:173]
	v_mfma_f32_16x16x32_bf16 v[158:161], v[232:235], v[198:201], v[158:161]
	v_mfma_f32_16x16x32_bf16 v[60:63], v[228:231], v[182:185], v[28:31]
	v_mfma_f32_16x16x32_bf16 v[56:59], v[154:157], v[182:185], v[24:27]
	v_mfma_f32_16x16x32_bf16 v[44:47], v[228:231], v[190:193], v[40:43]
	v_mfma_f32_16x16x32_bf16 v[40:43], v[154:157], v[190:193], v[134:137]
	v_mfma_f32_16x16x32_bf16 v[28:31], v[228:231], v[150:153], v[12:15]
	v_mfma_f32_16x16x32_bf16 v[24:27], v[154:157], v[150:153], v[8:11]
	v_mfma_f32_16x16x32_bf16 v[12:15], v[228:231], v[202:205], v[138:141]
	v_mfma_f32_16x16x32_bf16 v[8:11], v[154:157], v[202:205], v[158:161]
	v_cmp_gt_u32_e32 vcc, s66, v130
	s_barrier
	s_and_saveexec_b64 s[50:51], vcc
	s_cbranch_execz .LBB0_773
	s_barrier

; #define STAGE(P, BASE, LD, br, kt) do { const char* _g = (const char*)((BASE) + (size_t)(br) * (LD) + (size_t)(kt) * 64); \
;     for (int _i = 0; _i < 2; ++_i) { int _b = tidx * 16 + _i * 8192; int _r, _c; stage_rc(_b, _r, _c); \
;       __builtin_amdgcn_global_load_lds((const unsigned*)(_g + (unsigned)((_r * (LD) + _c) * 2)), (unsigned*)((char*)(P) + _b), 16, 0, 0); } } while (0)
; #define LDA(dst, b, h) for (int m = 0; m < 4; ++m) for (int k = 0; k < 2; ++k) \
;     dst[m][k] = *reinterpret_cast<const bf16x8*>((char*)SA(b, h) + lds_byte(wr * 64 + m * 16 + fr, k * 32 + fq * 8))
; #define LDB(dst, b, h) for (int n = 0; n < 2; ++n) for (int k = 0; k < 2; ++k) \
;     dst[n][k] = *reinterpret_cast<const bf16x8*>((char*)SB(b, h) + lds_byte(wc * 32 + n * 16 + fr, k * 32 + fq * 8))
; #define MMA(ai, bj, At_, Bt_) do { __builtin_amdgcn_s_setprio(1); \
;     for (int k = 0; k < 2; ++k) for (int m = 0; m < 4; ++m) for (int n = 0; n < 2; ++n) \
;       acc[ai][bj][m][n] = __builtin_amdgcn_mfma_f32_16x16x32_bf16(At_[m][k], Bt_[n][k], acc[ai][bj][m][n], 0, 0, 0); \
;     __builtin_amdgcn_s_setprio(0); } while (0)
; #define WAIT_L(n) asm volatile("s_waitcnt lgkmcnt(" #n ")" ::: "memory")
; #define BAR __builtin_amdgcn_s_barrier()
; #define SCHED __builtin_amdgcn_sched_barrier(0)
; template <int EPI, int lda, int ldb, int N, int K>
; __device__ __forceinline__ void gemm_phase(const u16* __restrict__ A, const u16* __restrict__ Bt, const GemmEpi ep, int wv) {
;     ...
;       LDB(B0, 0, 0); SCHED; LDA(At, 0, 0); STAGE(SA(1, 1), Ab, lda, brow + HALF, t + 1);
;       WAIT_L(8); BAR; WAIT_L(0); MMA(0, 0, At, B0); BAR; SCHED;
;       LDB(B1, 0, 1); STAGE(SB(0, 0), Bt, ldb, bcol, t + 2);
;       BAR; WAIT_L(0); MMA(0, 1, At, B1); BAR;
;       LDA(At, 0, 1); STAGE(SA(0, 0), Ab, lda, brow, t + 2);
;       BAR; WAIT_L(0); MMA(1, 0, At, B0); BAR; SCHED;
.LBB0_838:
	ds_read_b128 v[168:171], v164
	ds_read_b128 v[174:177], v164 offset:1024
	ds_read_b128 v[178:181], v164 offset:2048
	ds_read_b128 v[182:185], v164 offset:3072
	v_add_u32_e32 v172, 0xc000, v147
	v_lshl_add_u64 v[238:239], v[136:137], 0, s[50:51]
	v_readfirstlane_b32 s73, v172
	v_add_u32_e32 v173, 0xe000, v147
	v_lshl_add_u64 v[166:167], v[238:239], 0, s[22:23]
	s_mov_b32 m0, s73
	v_lshl_add_u64 v[240:241], v[134:135], 0, s[50:51]
	v_readfirstlane_b32 s73, v173
	ds_read_b128 v[186:189], v155
	ds_read_b128 v[190:193], v155 offset:1024
	ds_read_b128 v[194:197], v154
	ds_read_b128 v[198:201], v154 offset:1024
	ds_read_b128 v[202:205], v153
	ds_read_b128 v[206:209], v153 offset:1024
	ds_read_b128 v[210:213], v152
	ds_read_b128 v[214:217], v152 offset:1024
	global_load_lds_dwordx4 v[166:167], off
	v_lshl_add_u64 v[166:167], v[240:241], 0, s[22:23]
	s_mov_b32 m0, s73
	s_nop 0
	global_load_lds_dwordx4 v[166:167], off
	s_waitcnt lgkmcnt(8)
	s_barrier
	s_waitcnt lgkmcnt(0)
	s_waitcnt lgkmcnt(0)
	v_mfma_f32_16x16x32_bf16 v[124:127], v[168:171], v[186:189], v[124:127]
	v_mfma_f32_16x16x32_bf16 v[120:123], v[178:181], v[186:189], v[120:123]
	v_mfma_f32_16x16x32_bf16 v[116:119], v[168:171], v[194:197], v[116:119]
	v_mfma_f32_16x16x32_bf16 v[112:115], v[178:181], v[194:197], v[112:115]
	v_mfma_f32_16x16x32_bf16 v[108:111], v[168:171], v[202:205], v[108:111]
	v_mfma_f32_16x16x32_bf16 v[104:107], v[178:181], v[202:205], v[104:107]
	v_mfma_f32_16x16x32_bf16 v[100:103], v[168:171], v[210:213], v[100:103]
	v_mfma_f32_16x16x32_bf16 v[96:99], v[178:181], v[210:213], v[96:99]
	v_mfma_f32_16x16x32_bf16 v[124:127], v[174:177], v[190:193], v[124:127]
	v_mfma_f32_16x16x32_bf16 v[120:123], v[182:185], v[190:193], v[120:123]
	v_mfma_f32_16x16x32_bf16 v[116:119], v[174:177], v[198:201], v[116:119]
	v_mfma_f32_16x16x32_bf16 v[112:115], v[182:185], v[198:201], v[112:115]
	v_mfma_f32_16x16x32_bf16 v[108:111], v[174:177], v[206:209], v[108:111]
	v_mfma_f32_16x16x32_bf16 v[104:107], v[182:185], v[206:209], v[104:107]
	v_mfma_f32_16x16x32_bf16 v[100:103], v[174:177], v[214:217], v[100:103]
	v_mfma_f32_16x16x32_bf16 v[96:99], v[182:185], v[214:217], v[96:99]
	s_barrier
	v_add_u32_e32 v165, s63, v156
	v_lshl_add_u64 v[242:243], v[144:145], 0, s[50:51]
	v_readfirstlane_b32 s73, v165
	v_lshl_add_u64 v[166:167], v[242:243], 0, s[24:25]
	s_mov_b32 m0, s73
	ds_read_b128 v[218:221], v163
	ds_read_b128 v[222:225], v163 offset:1024
	ds_read_b128 v[226:229], v163 offset:2048
	ds_read_b128 v[230:233], v163 offset:3072
	global_load_lds_dwordx4 v[166:167], off
	v_add_u32_e32 v166, 0x2000, v165
	v_lshl_add_u64 v[244:245], v[142:143], 0, s[50:51]
	v_readfirstlane_b32 s73, v166
	v_lshl_add_u64 v[234:235], v[244:245], 0, s[24:25]
	s_mov_b32 m0, s73
	s_nop 0
	global_load_lds_dwordx4 v[234:235], off
	s_barrier
	s_waitcnt lgkmcnt(0)
	s_waitcnt lgkmcnt(0)
	v_mfma_f32_16x16x32_bf16 v[92:95], v[218:221], v[186:189], v[92:95]
	v_mfma_f32_16x16x32_bf16 v[88:91], v[226:229], v[186:189], v[88:91]
	v_mfma_f32_16x16x32_bf16 v[84:87], v[218:221], v[194:197], v[84:87]
	v_mfma_f32_16x16x32_bf16 v[80:83], v[226:229], v[194:197], v[80:83]
	v_mfma_f32_16x16x32_bf16 v[76:79], v[218:221], v[202:205], v[76:79]
	v_mfma_f32_16x16x32_bf16 v[72:75], v[226:229], v[202:205], v[72:75]
	v_mfma_f32_16x16x32_bf16 v[68:71], v[218:221], v[210:213], v[68:71]
	v_mfma_f32_16x16x32_bf16 v[64:67], v[226:229], v[210:213], v[64:67]
	v_mfma_f32_16x16x32_bf16 v[92:95], v[222:225], v[190:193], v[92:95]
	v_mfma_f32_16x16x32_bf16 v[88:91], v[230:233], v[190:193], v[88:91]
	v_mfma_f32_16x16x32_bf16 v[84:87], v[222:225], v[198:201], v[84:87]
	v_mfma_f32_16x16x32_bf16 v[80:83], v[230:233], v[198:201], v[80:83]
	v_mfma_f32_16x16x32_bf16 v[76:79], v[222:225], v[206:209], v[76:79]
	v_mfma_f32_16x16x32_bf16 v[72:75], v[230:233], v[206:209], v[72:75]
	v_mfma_f32_16x16x32_bf16 v[68:71], v[222:225], v[214:217], v[68:71]
	v_mfma_f32_16x16x32_bf16 v[64:67], v[230:233], v[214:217], v[64:67]
	v_readfirstlane_b32 s73, v147
	v_add_u32_e32 v167, 0x2000, v147
	v_lshl_add_u64 v[234:235], v[238:239], 0, s[26:27]
	s_mov_b32 m0, s73
	v_readfirstlane_b32 s73, v167
	s_barrier
	ds_read_b128 v[186:189], v155 offset:16384
	ds_read_b128 v[190:193], v155 offset:17408
	ds_read_b128 v[194:197], v154 offset:16384
	ds_read_b128 v[198:201], v154 offset:17408
	ds_read_b128 v[202:205], v153 offset:16384
	ds_read_b128 v[206:209], v153 offset:17408
	ds_read_b128 v[210:213], v152 offset:16384
	ds_read_b128 v[214:217], v152 offset:17408
	global_load_lds_dwordx4 v[234:235], off
	v_lshl_add_u64 v[234:235], v[240:241], 0, s[26:27]
	s_mov_b32 m0, s73
	s_nop 0
	global_load_lds_dwordx4 v[234:235], off
	s_barrier
	s_waitcnt lgkmcnt(0)
	s_waitcnt lgkmcnt(0)
	v_mfma_f32_16x16x32_bf16 v[60:63], v[168:171], v[186:189], v[60:63]
	v_mfma_f32_16x16x32_bf16 v[56:59], v[178:181], v[186:189], v[56:59]
	v_mfma_f32_16x16x32_bf16 v[52:55], v[168:171], v[194:197], v[52:55]
	v_mfma_f32_16x16x32_bf16 v[48:51], v[178:181], v[194:197], v[48:51]
	v_mfma_f32_16x16x32_bf16 v[44:47], v[168:171], v[202:205], v[44:47]
	v_mfma_f32_16x16x32_bf16 v[40:43], v[178:181], v[202:205], v[40:43]
	v_mfma_f32_16x16x32_bf16 v[36:39], v[168:171], v[210:213], v[36:39]
	v_mfma_f32_16x16x32_bf16 v[32:35], v[178:181], v[210:213], v[32:35]
	v_mfma_f32_16x16x32_bf16 v[60:63], v[174:177], v[190:193], v[60:63]
	v_mfma_f32_16x16x32_bf16 v[56:59], v[182:185], v[190:193], v[56:59]
	v_mfma_f32_16x16x32_bf16 v[52:55], v[174:177], v[198:201], v[52:55]
	v_mfma_f32_16x16x32_bf16 v[48:51], v[182:185], v[198:201], v[48:51]
	v_mfma_f32_16x16x32_bf16 v[44:47], v[174:177], v[206:209], v[44:47]
	v_mfma_f32_16x16x32_bf16 v[40:43], v[182:185], v[206:209], v[40:43]
	v_mfma_f32_16x16x32_bf16 v[36:39], v[174:177], v[214:217], v[36:39]
	v_mfma_f32_16x16x32_bf16 v[32:35], v[182:185], v[214:217], v[32:35]
	s_barrier
; #define STAGE(P, BASE, LD, br, kt) do { const char* _g = (const char*)((BASE) + (size_t)(br) * (LD) + (size_t)(kt) * 64); \
;     for (int _i = 0; _i < 2; ++_i) { int _b = tidx * 16 + _i * 8192; int _r, _c; stage_rc(_b, _r, _c); \
;       __builtin_amdgcn_global_load_lds((const unsigned*)(_g + (unsigned)((_r * (LD) + _c) * 2)), (unsigned*)((char*)(P) + _b), 16, 0, 0); } } while (0)
; #define LDA(dst, b, h) for (int m = 0; m < 4; ++m) for (int k = 0; k < 2; ++k) \
;     dst[m][k] = *reinterpret_cast<const bf16x8*>((char*)SA(b, h) + lds_byte(wr * 64 + m * 16 + fr, k * 32 + fq * 8))
; #define LDB(dst, b, h) for (int n = 0; n < 2; ++n) for (int k = 0; k < 2; ++k) \
;     dst[n][k] = *reinterpret_cast<const bf16x8*>((char*)SB(b, h) + lds_byte(wc * 32 + n * 16 + fr, k * 32 + fq * 8))
; #define MMA(ai, bj, At_, Bt_) do { __builtin_amdgcn_s_setprio(1); \
;     for (int k = 0; k < 2; ++k) for (int m = 0; m < 4; ++m) for (int n = 0; n < 2; ++n) \
;       acc[ai][bj][m][n] = __builtin_amdgcn_mfma_f32_16x16x32_bf16(At_[m][k], Bt_[n][k], acc[ai][bj][m][n], 0, 0, 0); \
;     __builtin_amdgcn_s_setprio(0); } while (0)
; #define WAIT_V(n) asm volatile("s_waitcnt vmcnt(" #n ")" ::: "memory")
; #define WAIT_L(n) asm volatile("s_waitcnt lgkmcnt(" #n ")" ::: "memory")
; #define BAR __builtin_amdgcn_s_barrier()
; #define SCHED __builtin_amdgcn_sched_barrier(0)
; template <int EPI, int lda, int ldb, int N, int K>
; __device__ __forceinline__ void gemm_phase(const u16* __restrict__ A, const u16* __restrict__ Bt, const GemmEpi ep, int wv) {
;     ...
;       STAGE(SB(0, 1), Bt, ldb, bcol + HALF, t + 2);
;       WAIT_V(6); BAR; MMA(1, 1, At, B1); BAR;
;       LDB(B0, 1, 0); SCHED; LDA(At, 1, 0); STAGE(SA(0, 1), Ab, lda, brow + HALF, t + 2);
;       WAIT_L(8); BAR; WAIT_L(0); MMA(0, 0, At, B0); BAR; SCHED;
;       LDB(B1, 1, 1); STAGE(SB(1, 0), Bt, ldb, bcol, t + 3);
;       BAR; WAIT_L(0); MMA(0, 1, At, B1); BAR;
;       LDA(At, 1, 1); STAGE(SA(1, 0), Ab, lda, brow, t + 3);
	v_add_u32_e32 v168, s64, v156
	v_lshl_add_u64 v[246:247], v[140:141], 0, s[50:51]
	v_readfirstlane_b32 s73, v168
	v_add_u32_e32 v169, 0x2000, v168
	v_lshl_add_u64 v[170:171], v[246:247], 0, s[40:41]
	s_mov_b32 m0, s73
	v_lshl_add_u64 v[248:249], v[138:139], 0, s[50:51]
	v_readfirstlane_b32 s73, v169
	global_load_lds_dwordx4 v[170:171], off
	v_lshl_add_u64 v[170:171], v[248:249], 0, s[40:41]
	s_mov_b32 m0, s73
	s_nop 0
	global_load_lds_dwordx4 v[170:171], off
	s_waitcnt vmcnt(6)
	s_barrier
	v_mfma_f32_16x16x32_bf16 v[28:31], v[218:221], v[186:189], v[28:31]
	v_mfma_f32_16x16x32_bf16 v[24:27], v[226:229], v[186:189], v[24:27]
	v_mfma_f32_16x16x32_bf16 v[20:23], v[218:221], v[194:197], v[20:23]
	v_mfma_f32_16x16x32_bf16 v[16:19], v[226:229], v[194:197], v[16:19]
	v_mfma_f32_16x16x32_bf16 v[12:15], v[218:221], v[202:205], v[12:15]
	v_mfma_f32_16x16x32_bf16 v[8:11], v[226:229], v[202:205], v[8:11]
	v_mfma_f32_16x16x32_bf16 v[4:7], v[218:221], v[210:213], v[4:7]
	v_mfma_f32_16x16x32_bf16 v[0:3], v[226:229], v[210:213], v[0:3]
	v_mfma_f32_16x16x32_bf16 v[28:31], v[222:225], v[190:193], v[28:31]
	v_mfma_f32_16x16x32_bf16 v[24:27], v[230:233], v[190:193], v[24:27]
	v_mfma_f32_16x16x32_bf16 v[20:23], v[222:225], v[198:201], v[20:23]
	v_mfma_f32_16x16x32_bf16 v[16:19], v[230:233], v[198:201], v[16:19]
	v_mfma_f32_16x16x32_bf16 v[12:15], v[222:225], v[206:209], v[12:15]
	v_mfma_f32_16x16x32_bf16 v[8:11], v[230:233], v[206:209], v[8:11]
	v_mfma_f32_16x16x32_bf16 v[4:7], v[222:225], v[214:217], v[4:7]
	v_mfma_f32_16x16x32_bf16 v[0:3], v[230:233], v[214:217], v[0:3]
	s_barrier
	ds_read_b128 v[174:177], v159
	ds_read_b128 v[178:181], v159 offset:1024
	ds_read_b128 v[182:185], v159 offset:2048
	ds_read_b128 v[186:189], v159 offset:3072
	v_add_u32_e32 v170, 0x4000, v147
	v_add_u32_e32 v171, 0x6000, v147
	v_readfirstlane_b32 s73, v170
	v_lshl_add_u64 v[222:223], v[238:239], 0, s[42:43]
	s_mov_b32 m0, s73
	v_readfirstlane_b32 s73, v171
	ds_read_b128 v[190:193], v155 offset:32768
	ds_read_b128 v[194:197], v155 offset:33792
	ds_read_b128 v[198:201], v154 offset:32768
	ds_read_b128 v[202:205], v154 offset:33792
	ds_read_b128 v[206:209], v153 offset:32768
	ds_read_b128 v[210:213], v153 offset:33792
	ds_read_b128 v[214:217], v152 offset:32768
	ds_read_b128 v[218:221], v152 offset:33792
	global_load_lds_dwordx4 v[222:223], off
	v_lshl_add_u64 v[222:223], v[240:241], 0, s[42:43]
	s_mov_b32 m0, s73
	s_nop 0
	global_load_lds_dwordx4 v[222:223], off
	s_waitcnt lgkmcnt(8)
	s_barrier
	s_waitcnt lgkmcnt(0)
	s_waitcnt lgkmcnt(0)
	v_mfma_f32_16x16x32_bf16 v[124:127], v[174:177], v[190:193], v[124:127]
	v_mfma_f32_16x16x32_bf16 v[120:123], v[182:185], v[190:193], v[120:123]
	v_mfma_f32_16x16x32_bf16 v[116:119], v[174:177], v[198:201], v[116:119]
	v_mfma_f32_16x16x32_bf16 v[112:115], v[182:185], v[198:201], v[112:115]
	v_mfma_f32_16x16x32_bf16 v[108:111], v[174:177], v[206:209], v[108:111]
	v_mfma_f32_16x16x32_bf16 v[104:107], v[182:185], v[206:209], v[104:107]
	v_mfma_f32_16x16x32_bf16 v[100:103], v[174:177], v[214:217], v[100:103]
	v_mfma_f32_16x16x32_bf16 v[96:99], v[182:185], v[214:217], v[96:99]
	v_mfma_f32_16x16x32_bf16 v[124:127], v[178:181], v[194:197], v[124:127]
	v_mfma_f32_16x16x32_bf16 v[120:123], v[186:189], v[194:197], v[120:123]
	v_mfma_f32_16x16x32_bf16 v[116:119], v[178:181], v[202:205], v[116:119]
	v_mfma_f32_16x16x32_bf16 v[112:115], v[186:189], v[202:205], v[112:115]
	v_mfma_f32_16x16x32_bf16 v[108:111], v[178:181], v[210:213], v[108:111]
	v_mfma_f32_16x16x32_bf16 v[104:107], v[186:189], v[210:213], v[104:107]
	v_mfma_f32_16x16x32_bf16 v[100:103], v[178:181], v[218:221], v[100:103]
	v_mfma_f32_16x16x32_bf16 v[96:99], v[186:189], v[218:221], v[96:99]
	s_barrier
	v_readfirstlane_b32 s73, v158
	v_lshl_add_u64 v[242:243], v[242:243], 0, s[44:45]
	s_mov_b32 m0, s73
	ds_read_b128 v[222:225], v157
	ds_read_b128 v[226:229], v157 offset:1024
	ds_read_b128 v[230:233], v157 offset:2048
	ds_read_b128 v[234:237], v157 offset:3072
	global_load_lds_dwordx4 v[242:243], off
	v_lshl_add_u64 v[242:243], v[244:245], 0, s[44:45]
	v_add_u32_e32 v244, 0x2000, v158
	s_nop 0
	v_readfirstlane_b32 s73, v244
	s_mov_b32 m0, s73
	s_nop 0
	global_load_lds_dwordx4 v[242:243], off
	s_barrier
	s_waitcnt lgkmcnt(0)
	s_waitcnt lgkmcnt(0)
	v_mfma_f32_16x16x32_bf16 v[92:95], v[222:225], v[190:193], v[92:95]
	v_mfma_f32_16x16x32_bf16 v[88:91], v[230:233], v[190:193], v[88:91]
	v_mfma_f32_16x16x32_bf16 v[84:87], v[222:225], v[198:201], v[84:87]
	v_mfma_f32_16x16x32_bf16 v[80:83], v[230:233], v[198:201], v[80:83]
	v_mfma_f32_16x16x32_bf16 v[76:79], v[222:225], v[206:209], v[76:79]
	v_mfma_f32_16x16x32_bf16 v[72:75], v[230:233], v[206:209], v[72:75]
	v_mfma_f32_16x16x32_bf16 v[68:71], v[222:225], v[214:217], v[68:71]
	v_mfma_f32_16x16x32_bf16 v[64:67], v[230:233], v[214:217], v[64:67]
	v_mfma_f32_16x16x32_bf16 v[92:95], v[226:229], v[194:197], v[92:95]
	v_mfma_f32_16x16x32_bf16 v[88:91], v[234:237], v[194:197], v[88:91]
	v_mfma_f32_16x16x32_bf16 v[84:87], v[226:229], v[202:205], v[84:87]
	v_mfma_f32_16x16x32_bf16 v[80:83], v[234:237], v[202:205], v[80:83]
	v_mfma_f32_16x16x32_bf16 v[76:79], v[226:229], v[210:213], v[76:79]
	v_mfma_f32_16x16x32_bf16 v[72:75], v[234:237], v[210:213], v[72:75]
	v_mfma_f32_16x16x32_bf16 v[68:71], v[226:229], v[218:221], v[68:71]
	v_mfma_f32_16x16x32_bf16 v[64:67], v[234:237], v[218:221], v[64:67]
	v_readfirstlane_b32 s73, v160
	v_lshl_add_u64 v[238:239], v[238:239], 0, s[46:47]
	s_mov_b32 m0, s73
	v_readfirstlane_b32 s73, v161
	s_barrier
; #define STAGE(P, BASE, LD, br, kt) do { const char* _g = (const char*)((BASE) + (size_t)(br) * (LD) + (size_t)(kt) * 64); \
;     for (int _i = 0; _i < 2; ++_i) { int _b = tidx * 16 + _i * 8192; int _r, _c; stage_rc(_b, _r, _c); \
;       __builtin_amdgcn_global_load_lds((const unsigned*)(_g + (unsigned)((_r * (LD) + _c) * 2)), (unsigned*)((char*)(P) + _b), 16, 0, 0); } } while (0)
; #define LDA(dst, b, h) for (int m = 0; m < 4; ++m) for (int k = 0; k < 2; ++k) \
;     dst[m][k] = *reinterpret_cast<const bf16x8*>((char*)SA(b, h) + lds_byte(wr * 64 + m * 16 + fr, k * 32 + fq * 8))
; #define LDB(dst, b, h) for (int n = 0; n < 2; ++n) for (int k = 0; k < 2; ++k) \
;     dst[n][k] = *reinterpret_cast<const bf16x8*>((char*)SB(b, h) + lds_byte(wc * 32 + n * 16 + fr, k * 32 + fq * 8))
; #define MMA(ai, bj, At_, Bt_) do { __builtin_amdgcn_s_setprio(1); \
;     for (int k = 0; k < 2; ++k) for (int m = 0; m < 4; ++m) for (int n = 0; n < 2; ++n) \
;       acc[ai][bj][m][n] = __builtin_amdgcn_mfma_f32_16x16x32_bf16(At_[m][k], Bt_[n][k], acc[ai][bj][m][n], 0, 0, 0); \
;     __builtin_amdgcn_s_setprio(0); } while (0)
; #define WAIT_V(n) asm volatile("s_waitcnt vmcnt(" #n ")" ::: "memory")
; #define WAIT_L(n) asm volatile("s_waitcnt lgkmcnt(" #n ")" ::: "memory")
; #define BAR __builtin_amdgcn_s_barrier()
; #define SCHED __builtin_amdgcn_sched_barrier(0)
; template <int EPI, int lda, int ldb, int N, int K>
; __device__ __forceinline__ void gemm_phase(const u16* __restrict__ A, const u16* __restrict__ Bt, const GemmEpi ep, int wv) {
;     ...
;       LDA(At, 1, 1); STAGE(SA(1, 0), Ab, lda, brow, t + 3);
;       BAR; WAIT_L(0); MMA(1, 0, At, B0); BAR; SCHED;
;       STAGE(SB(1, 1), Bt, ldb, bcol + HALF, t + 3);
;       WAIT_V(6); BAR; MMA(1, 1, At, B1); BAR;
;     }
;     { LDB(B0, 0, 0); LDA(At, 0, 0); STAGE(SA(1, 1), Ab, lda, brow + HALF, nt - 1);
;       BAR; WAIT_L(0); MMA(0, 0, At, B0); BAR;
;       LDB(B1, 0, 1); BAR; WAIT_L(0); MMA(0, 1, At, B1); BAR;
	ds_read_b128 v[190:193], v155 offset:49152
	ds_read_b128 v[194:197], v155 offset:50176
	ds_read_b128 v[198:201], v154 offset:49152
	ds_read_b128 v[202:205], v154 offset:50176
	ds_read_b128 v[206:209], v153 offset:49152
	ds_read_b128 v[210:213], v153 offset:50176
	ds_read_b128 v[214:217], v152 offset:49152
	ds_read_b128 v[218:221], v152 offset:50176
	global_load_lds_dwordx4 v[238:239], off
	v_lshl_add_u64 v[238:239], v[240:241], 0, s[46:47]
	s_mov_b32 m0, s73
	s_nop 0
	global_load_lds_dwordx4 v[238:239], off
	s_barrier
	s_waitcnt lgkmcnt(0)
	s_waitcnt lgkmcnt(0)
	v_mfma_f32_16x16x32_bf16 v[60:63], v[174:177], v[190:193], v[60:63]
	v_mfma_f32_16x16x32_bf16 v[56:59], v[182:185], v[190:193], v[56:59]
	v_mfma_f32_16x16x32_bf16 v[52:55], v[174:177], v[198:201], v[52:55]
	v_mfma_f32_16x16x32_bf16 v[48:51], v[182:185], v[198:201], v[48:51]
	v_mfma_f32_16x16x32_bf16 v[44:47], v[174:177], v[206:209], v[44:47]
	v_mfma_f32_16x16x32_bf16 v[40:43], v[182:185], v[206:209], v[40:43]
	v_mfma_f32_16x16x32_bf16 v[36:39], v[174:177], v[214:217], v[36:39]
	v_mfma_f32_16x16x32_bf16 v[32:35], v[182:185], v[214:217], v[32:35]
	v_mfma_f32_16x16x32_bf16 v[60:63], v[178:181], v[194:197], v[60:63]
	v_mfma_f32_16x16x32_bf16 v[56:59], v[186:189], v[194:197], v[56:59]
	v_mfma_f32_16x16x32_bf16 v[52:55], v[178:181], v[202:205], v[52:55]
	v_mfma_f32_16x16x32_bf16 v[48:51], v[186:189], v[202:205], v[48:51]
	v_mfma_f32_16x16x32_bf16 v[44:47], v[178:181], v[210:213], v[44:47]
	v_mfma_f32_16x16x32_bf16 v[40:43], v[186:189], v[210:213], v[40:43]
	v_mfma_f32_16x16x32_bf16 v[36:39], v[178:181], v[218:221], v[36:39]
	v_mfma_f32_16x16x32_bf16 v[32:35], v[186:189], v[218:221], v[32:35]
	s_barrier
	v_readfirstlane_b32 s73, v162
	v_add_u32_e32 v176, 0x2000, v162
	v_lshl_add_u64 v[174:175], v[246:247], 0, s[48:49]
	s_mov_b32 m0, s73
	v_readfirstlane_b32 s73, v176
	global_load_lds_dwordx4 v[174:175], off
	v_lshl_add_u64 v[174:175], v[248:249], 0, s[48:49]
	s_mov_b32 m0, s73
	s_nop 0
	global_load_lds_dwordx4 v[174:175], off
	s_waitcnt vmcnt(6)
	s_barrier
	v_mfma_f32_16x16x32_bf16 v[28:31], v[222:225], v[190:193], v[28:31]
	v_mfma_f32_16x16x32_bf16 v[24:27], v[230:233], v[190:193], v[24:27]
	v_mfma_f32_16x16x32_bf16 v[20:23], v[222:225], v[198:201], v[20:23]
	v_mfma_f32_16x16x32_bf16 v[16:19], v[230:233], v[198:201], v[16:19]
	v_mfma_f32_16x16x32_bf16 v[12:15], v[222:225], v[206:209], v[12:15]
	v_mfma_f32_16x16x32_bf16 v[8:11], v[230:233], v[206:209], v[8:11]
	v_mfma_f32_16x16x32_bf16 v[4:7], v[222:225], v[214:217], v[4:7]
	v_mfma_f32_16x16x32_bf16 v[0:3], v[230:233], v[214:217], v[0:3]
	v_mfma_f32_16x16x32_bf16 v[28:31], v[226:229], v[194:197], v[28:31]
	v_mfma_f32_16x16x32_bf16 v[24:27], v[234:237], v[194:197], v[24:27]
	v_mfma_f32_16x16x32_bf16 v[20:23], v[226:229], v[202:205], v[20:23]
	v_mfma_f32_16x16x32_bf16 v[16:19], v[234:237], v[202:205], v[16:19]
	v_mfma_f32_16x16x32_bf16 v[12:15], v[226:229], v[210:213], v[12:15]
	v_mfma_f32_16x16x32_bf16 v[8:11], v[234:237], v[210:213], v[8:11]
	v_mfma_f32_16x16x32_bf16 v[4:7], v[226:229], v[218:221], v[4:7]
	v_mfma_f32_16x16x32_bf16 v[0:3], v[234:237], v[218:221], v[0:3]
	s_add_i32 s72, s72, 2
	s_add_u32 s50, s50, 0x100
	s_addc_u32 s51, s51, 0
	s_cmpk_gt_u32 s72, 0x51
	s_barrier
	s_cbranch_scc0 .LBB0_838
	s_add_i32 s50, s18, 0x80
	s_mul_hi_i32 s51, s50, 0x2b00
	s_mulk_i32 s50, 0x2b00
	s_add_u32 s50, s56, s50
	s_addc_u32 s51, s57, s51
	s_add_u32 s50, s50, 0x2a80
	s_addc_u32 s51, s51, 0
	v_readfirstlane_b32 s72, v172
	v_lshl_add_u64 v[160:161], s[50:51], 0, v[128:129]
	s_mov_b32 m0, s72
	ds_read_b128 v[134:137], v164
	ds_read_b128 v[138:141], v164 offset:1024
	ds_read_b128 v[142:145], v164 offset:2048
	ds_read_b128 v[174:177], v164 offset:3072
	ds_read_b128 v[178:181], v155
	ds_read_b128 v[182:185], v155 offset:1024
	ds_read_b128 v[186:189], v154
	ds_read_b128 v[190:193], v154 offset:1024
	ds_read_b128 v[194:197], v153
	ds_read_b128 v[198:201], v153 offset:1024
	ds_read_b128 v[202:205], v152
	ds_read_b128 v[206:209], v152 offset:1024
	global_load_lds_dwordx4 v[160:161], off
	v_lshl_add_u64 v[160:161], s[50:51], 0, v[132:133]
	v_readfirstlane_b32 s50, v173
	s_mov_b32 m0, s50
	s_nop 0
	global_load_lds_dwordx4 v[160:161], off
	s_barrier
	s_waitcnt lgkmcnt(0)
	s_waitcnt lgkmcnt(0)
	v_mfma_f32_16x16x32_bf16 v[124:127], v[134:137], v[178:181], v[124:127]
	v_mfma_f32_16x16x32_bf16 v[120:123], v[142:145], v[178:181], v[120:123]
	v_mfma_f32_16x16x32_bf16 v[116:119], v[134:137], v[186:189], v[116:119]
	v_mfma_f32_16x16x32_bf16 v[112:115], v[142:145], v[186:189], v[112:115]
	v_mfma_f32_16x16x32_bf16 v[108:111], v[134:137], v[194:197], v[108:111]
	v_mfma_f32_16x16x32_bf16 v[104:107], v[142:145], v[194:197], v[104:107]
	v_mfma_f32_16x16x32_bf16 v[100:103], v[134:137], v[202:205], v[100:103]
	v_mfma_f32_16x16x32_bf16 v[96:99], v[142:145], v[202:205], v[96:99]
	v_mfma_f32_16x16x32_bf16 v[124:127], v[138:141], v[182:185], v[124:127]
	v_mfma_f32_16x16x32_bf16 v[120:123], v[174:177], v[182:185], v[120:123]
	v_mfma_f32_16x16x32_bf16 v[116:119], v[138:141], v[190:193], v[116:119]
	v_mfma_f32_16x16x32_bf16 v[112:115], v[174:177], v[190:193], v[112:115]
	v_mfma_f32_16x16x32_bf16 v[108:111], v[138:141], v[198:201], v[108:111]
	v_mfma_f32_16x16x32_bf16 v[104:107], v[174:177], v[198:201], v[104:107]
	v_mfma_f32_16x16x32_bf16 v[100:103], v[138:141], v[206:209], v[100:103]
	v_mfma_f32_16x16x32_bf16 v[96:99], v[174:177], v[206:209], v[96:99]
	s_barrier
	ds_read_b128 v[210:213], v163
	ds_read_b128 v[214:217], v163 offset:1024
	ds_read_b128 v[218:221], v163 offset:2048
	ds_read_b128 v[160:163], v163 offset:3072
	s_barrier
; #define LDA(dst, b, h) for (int m = 0; m < 4; ++m) for (int k = 0; k < 2; ++k) \
;     dst[m][k] = *reinterpret_cast<const bf16x8*>((char*)SA(b, h) + lds_byte(wr * 64 + m * 16 + fr, k * 32 + fq * 8))
; #define LDB(dst, b, h) for (int n = 0; n < 2; ++n) for (int k = 0; k < 2; ++k) \
;     dst[n][k] = *reinterpret_cast<const bf16x8*>((char*)SB(b, h) + lds_byte(wc * 32 + n * 16 + fr, k * 32 + fq * 8))
; #define MMA(ai, bj, At_, Bt_) do { __builtin_amdgcn_s_setprio(1); \
;     for (int k = 0; k < 2; ++k) for (int m = 0; m < 4; ++m) for (int n = 0; n < 2; ++n) \
;       acc[ai][bj][m][n] = __builtin_amdgcn_mfma_f32_16x16x32_bf16(At_[m][k], Bt_[n][k], acc[ai][bj][m][n], 0, 0, 0); \
;     __builtin_amdgcn_s_setprio(0); } while (0)
; #define WAIT_V(n) asm volatile("s_waitcnt vmcnt(" #n ")" ::: "memory")
; #define WAIT_L(n) asm volatile("s_waitcnt lgkmcnt(" #n ")" ::: "memory")
; #define BAR __builtin_amdgcn_s_barrier()
; template <int EPI, int lda, int ldb, int N, int K>
; __device__ __forceinline__ void gemm_phase(const u16* __restrict__ A, const u16* __restrict__ Bt, const GemmEpi ep, int wv) {
;     ...
;       LDB(B1, 0, 1); BAR; WAIT_L(0); MMA(0, 1, At, B1); BAR;
;       LDA(At, 0, 1); WAIT_V(4); BAR; WAIT_L(0); MMA(1, 0, At, B0); MMA(1, 1, At, B1); BAR; }
;     { LDB(B0, 1, 0); LDA(At, 1, 0); WAIT_V(2); BAR; WAIT_L(0); MMA(0, 0, At, B0); BAR;
	s_waitcnt lgkmcnt(0)
	s_waitcnt lgkmcnt(0)
	v_mfma_f32_16x16x32_bf16 v[92:95], v[210:213], v[178:181], v[92:95]
	v_mfma_f32_16x16x32_bf16 v[88:91], v[218:221], v[178:181], v[88:91]
	v_mfma_f32_16x16x32_bf16 v[76:79], v[210:213], v[194:197], v[76:79]
	v_mfma_f32_16x16x32_bf16 v[72:75], v[218:221], v[194:197], v[72:75]
	v_mfma_f32_16x16x32_bf16 v[84:87], v[210:213], v[186:189], v[84:87]
	v_mfma_f32_16x16x32_bf16 v[80:83], v[218:221], v[186:189], v[80:83]
	v_mfma_f32_16x16x32_bf16 v[68:71], v[210:213], v[202:205], v[68:71]
	v_mfma_f32_16x16x32_bf16 v[64:67], v[218:221], v[202:205], v[64:67]
	v_mfma_f32_16x16x32_bf16 v[92:95], v[214:217], v[182:185], v[92:95]
	v_mfma_f32_16x16x32_bf16 v[88:91], v[160:163], v[182:185], v[88:91]
	v_mfma_f32_16x16x32_bf16 v[76:79], v[214:217], v[198:201], v[76:79]
	v_mfma_f32_16x16x32_bf16 v[72:75], v[160:163], v[198:201], v[72:75]
	v_mfma_f32_16x16x32_bf16 v[178:181], v[214:217], v[190:193], v[84:87]
	v_mfma_f32_16x16x32_bf16 v[182:185], v[160:163], v[190:193], v[80:83]
	v_mfma_f32_16x16x32_bf16 v[186:189], v[214:217], v[206:209], v[68:71]
	v_mfma_f32_16x16x32_bf16 v[190:193], v[160:163], v[206:209], v[64:67]
	s_barrier
	s_nop 0
	ds_read_b128 v[64:67], v155 offset:16384
	ds_read_b128 v[68:71], v155 offset:17408
	ds_read_b128 v[80:83], v154 offset:16384
	ds_read_b128 v[84:87], v154 offset:17408
	ds_read_b128 v[194:197], v153 offset:16384
	ds_read_b128 v[198:201], v153 offset:17408
	ds_read_b128 v[202:205], v152 offset:16384
	ds_read_b128 v[206:209], v152 offset:17408
	s_waitcnt vmcnt(4)
	s_barrier
	s_waitcnt lgkmcnt(0)
	s_waitcnt lgkmcnt(0)
	v_mfma_f32_16x16x32_bf16 v[60:63], v[134:137], v[64:67], v[60:63]
	v_mfma_f32_16x16x32_bf16 v[56:59], v[142:145], v[64:67], v[56:59]
	v_mfma_f32_16x16x32_bf16 v[52:55], v[134:137], v[80:83], v[52:55]
	v_mfma_f32_16x16x32_bf16 v[48:51], v[142:145], v[80:83], v[48:51]
	v_mfma_f32_16x16x32_bf16 v[44:47], v[134:137], v[194:197], v[44:47]
	v_mfma_f32_16x16x32_bf16 v[40:43], v[142:145], v[194:197], v[40:43]
	v_mfma_f32_16x16x32_bf16 v[36:39], v[134:137], v[202:205], v[36:39]
	v_mfma_f32_16x16x32_bf16 v[32:35], v[142:145], v[202:205], v[32:35]
	v_mfma_f32_16x16x32_bf16 v[60:63], v[138:141], v[68:71], v[60:63]
	v_mfma_f32_16x16x32_bf16 v[56:59], v[174:177], v[68:71], v[56:59]
	v_mfma_f32_16x16x32_bf16 v[52:55], v[138:141], v[84:87], v[52:55]
	v_mfma_f32_16x16x32_bf16 v[48:51], v[174:177], v[84:87], v[48:51]
	v_mfma_f32_16x16x32_bf16 v[44:47], v[138:141], v[198:201], v[44:47]
	v_mfma_f32_16x16x32_bf16 v[40:43], v[174:177], v[198:201], v[40:43]
	v_mfma_f32_16x16x32_bf16 v[36:39], v[138:141], v[206:209], v[36:39]
	v_mfma_f32_16x16x32_bf16 v[32:35], v[174:177], v[206:209], v[32:35]
	v_mfma_f32_16x16x32_bf16 v[28:31], v[210:213], v[64:67], v[28:31]
	v_mfma_f32_16x16x32_bf16 v[16:19], v[218:221], v[80:83], v[16:19]
	v_mfma_f32_16x16x32_bf16 v[12:15], v[210:213], v[194:197], v[12:15]
	v_mfma_f32_16x16x32_bf16 v[0:3], v[218:221], v[202:205], v[0:3]
	v_mfma_f32_16x16x32_bf16 v[24:27], v[218:221], v[64:67], v[24:27]
	v_mfma_f32_16x16x32_bf16 v[20:23], v[210:213], v[80:83], v[20:23]
	v_mfma_f32_16x16x32_bf16 v[8:11], v[218:221], v[194:197], v[8:11]
	v_mfma_f32_16x16x32_bf16 v[4:7], v[210:213], v[202:205], v[4:7]
	v_mfma_f32_16x16x32_bf16 v[28:31], v[214:217], v[68:71], v[28:31]
	v_mfma_f32_16x16x32_bf16 v[16:19], v[160:163], v[84:87], v[16:19]
	v_mfma_f32_16x16x32_bf16 v[12:15], v[214:217], v[198:201], v[12:15]
	v_mfma_f32_16x16x32_bf16 v[0:3], v[160:163], v[206:209], v[0:3]
	v_mfma_f32_16x16x32_bf16 v[134:137], v[160:163], v[68:71], v[24:27]
	v_mfma_f32_16x16x32_bf16 v[138:141], v[214:217], v[84:87], v[20:23]
	v_mfma_f32_16x16x32_bf16 v[142:145], v[160:163], v[198:201], v[8:11]
	v_mfma_f32_16x16x32_bf16 v[172:175], v[214:217], v[206:209], v[4:7]
	s_barrier
	s_nop 0
	ds_read_b128 v[4:7], v159
	ds_read_b128 v[8:11], v159 offset:1024
	ds_read_b128 v[20:23], v159 offset:2048
	ds_read_b128 v[158:161], v159 offset:3072
	ds_read_b128 v[24:27], v155 offset:32768
	ds_read_b128 v[194:197], v155 offset:33792
	ds_read_b128 v[198:201], v154 offset:32768
	ds_read_b128 v[202:205], v154 offset:33792
	ds_read_b128 v[206:209], v153 offset:32768
	ds_read_b128 v[210:213], v153 offset:33792
	ds_read_b128 v[214:217], v152 offset:32768
	ds_read_b128 v[218:221], v152 offset:33792
	s_waitcnt vmcnt(2)
	s_barrier
; #define LDA(dst, b, h) for (int m = 0; m < 4; ++m) for (int k = 0; k < 2; ++k) \
;     dst[m][k] = *reinterpret_cast<const bf16x8*>((char*)SA(b, h) + lds_byte(wr * 64 + m * 16 + fr, k * 32 + fq * 8))
; #define LDB(dst, b, h) for (int n = 0; n < 2; ++n) for (int k = 0; k < 2; ++k) \
;     dst[n][k] = *reinterpret_cast<const bf16x8*>((char*)SB(b, h) + lds_byte(wc * 32 + n * 16 + fr, k * 32 + fq * 8))
; #define MMA(ai, bj, At_, Bt_) do { __builtin_amdgcn_s_setprio(1); \
;     for (int k = 0; k < 2; ++k) for (int m = 0; m < 4; ++m) for (int n = 0; n < 2; ++n) \
;       acc[ai][bj][m][n] = __builtin_amdgcn_mfma_f32_16x16x32_bf16(At_[m][k], Bt_[n][k], acc[ai][bj][m][n], 0, 0, 0); \
;     __builtin_amdgcn_s_setprio(0); } while (0)
; #define WAIT_V(n) asm volatile("s_waitcnt vmcnt(" #n ")" ::: "memory")
; #define WAIT_L(n) asm volatile("s_waitcnt lgkmcnt(" #n ")" ::: "memory")
; #define BAR __builtin_amdgcn_s_barrier()
; #define STAGE4(BROW, BCOL, PN) do { const u16* Ab_ = A + (EPI == EPI_RG ? ((PN) >> 1) * 256 : 0); \
;     STAGE(SB(0, 0), Bt, ldb, (BCOL), 0); STAGE(SA(0, 0), Ab_, lda, (BROW), 0); \
;     STAGE(SB(0, 1), Bt, ldb, (BCOL) + HALF, 0); STAGE(SA(0, 1), Ab_, lda, (BROW) + HALF, 0); } while (0)
; template <int EPI, int lda, int ldb, int N, int K>
; __device__ __forceinline__ void gemm_phase(const u16* __restrict__ A, const u16* __restrict__ Bt, const GemmEpi ep, int wv) {
;     ...
;     { LDB(B0, 1, 0); LDA(At, 1, 0); WAIT_V(2); BAR; WAIT_L(0); MMA(0, 0, At, B0); BAR;
;       LDB(B1, 1, 1); WAIT_V(0); BAR; WAIT_L(0); MMA(0, 1, At, B1); BAR;
;       LDA(At, 1, 1); BAR; WAIT_L(0); MMA(1, 0, At, B0); MMA(1, 1, At, B1); BAR; }
;     if (wr == 0) BAR;
;     int ntile = 0, nbrow = 0, nbcol = 0, npn = 0; bool more = false;
;     if constexpr (PF) { ntile = tile + gridDim.x; more = ntile < nwg; if (more) { TILE_COORDS(ntile, nbrow, nbcol, npn); STAGE4(nbrow, nbcol, npn); } }
	s_waitcnt lgkmcnt(0)
	s_waitcnt lgkmcnt(0)
	v_mfma_f32_16x16x32_bf16 v[64:67], v[4:7], v[24:27], v[124:127]
	v_mfma_f32_16x16x32_bf16 v[68:71], v[20:23], v[24:27], v[120:123]
	v_mfma_f32_16x16x32_bf16 v[80:83], v[4:7], v[198:201], v[116:119]
	v_mfma_f32_16x16x32_bf16 v[84:87], v[20:23], v[198:201], v[112:115]
	v_mfma_f32_16x16x32_bf16 v[108:111], v[4:7], v[206:209], v[108:111]
	v_mfma_f32_16x16x32_bf16 v[104:107], v[20:23], v[206:209], v[104:107]
	v_mfma_f32_16x16x32_bf16 v[120:123], v[4:7], v[214:217], v[100:103]
	v_mfma_f32_16x16x32_bf16 v[124:127], v[20:23], v[214:217], v[96:99]
	v_mfma_f32_16x16x32_bf16 v[116:119], v[8:11], v[194:197], v[64:67]
	v_mfma_f32_16x16x32_bf16 v[112:115], v[158:161], v[194:197], v[68:71]
	v_mfma_f32_16x16x32_bf16 v[100:103], v[8:11], v[202:205], v[80:83]
	v_mfma_f32_16x16x32_bf16 v[96:99], v[158:161], v[202:205], v[84:87]
	v_mfma_f32_16x16x32_bf16 v[84:87], v[8:11], v[210:213], v[108:111]
	v_mfma_f32_16x16x32_bf16 v[80:83], v[158:161], v[210:213], v[104:107]
	v_mfma_f32_16x16x32_bf16 v[68:71], v[8:11], v[218:221], v[120:123]
	v_mfma_f32_16x16x32_bf16 v[64:67], v[158:161], v[218:221], v[124:127]
	s_barrier
	ds_read_b128 v[222:225], v157
	ds_read_b128 v[226:229], v157 offset:1024
	ds_read_b128 v[230:233], v157 offset:2048
	ds_read_b128 v[234:237], v157 offset:3072
	s_waitcnt vmcnt(0)
	s_barrier
	s_waitcnt lgkmcnt(0)
	s_waitcnt lgkmcnt(0)
	v_mfma_f32_16x16x32_bf16 v[92:95], v[222:225], v[24:27], v[92:95]
	v_mfma_f32_16x16x32_bf16 v[24:27], v[230:233], v[24:27], v[88:91]
	v_mfma_f32_16x16x32_bf16 v[88:91], v[222:225], v[198:201], v[178:181]
	v_mfma_f32_16x16x32_bf16 v[104:107], v[230:233], v[198:201], v[182:185]
	v_mfma_f32_16x16x32_bf16 v[76:79], v[222:225], v[206:209], v[76:79]
	v_mfma_f32_16x16x32_bf16 v[72:75], v[230:233], v[206:209], v[72:75]
	v_mfma_f32_16x16x32_bf16 v[176:179], v[222:225], v[214:217], v[186:189]
	v_mfma_f32_16x16x32_bf16 v[180:183], v[230:233], v[214:217], v[190:193]
	v_mfma_f32_16x16x32_bf16 v[124:127], v[226:229], v[194:197], v[92:95]
	v_mfma_f32_16x16x32_bf16 v[120:123], v[234:237], v[194:197], v[24:27]
	v_mfma_f32_16x16x32_bf16 v[108:111], v[226:229], v[202:205], v[88:91]
	v_mfma_f32_16x16x32_bf16 v[104:107], v[234:237], v[202:205], v[104:107]
	v_mfma_f32_16x16x32_bf16 v[92:95], v[226:229], v[210:213], v[76:79]
	v_mfma_f32_16x16x32_bf16 v[88:91], v[234:237], v[210:213], v[72:75]
	v_mfma_f32_16x16x32_bf16 v[76:79], v[226:229], v[218:221], v[176:179]
	v_mfma_f32_16x16x32_bf16 v[72:75], v[234:237], v[218:221], v[180:183]
	s_barrier
	ds_read_b128 v[176:179], v155 offset:49152
	ds_read_b128 v[180:183], v155 offset:50176
	ds_read_b128 v[184:187], v154 offset:49152
	ds_read_b128 v[154:157], v154 offset:50176
	ds_read_b128 v[188:191], v153 offset:49152
	ds_read_b128 v[192:195], v153 offset:50176
	ds_read_b128 v[196:199], v152 offset:49152
	ds_read_b128 v[200:203], v152 offset:50176
	s_barrier
	s_waitcnt lgkmcnt(0)
	s_waitcnt lgkmcnt(0)
	v_mfma_f32_16x16x32_bf16 v[24:27], v[4:7], v[176:179], v[60:63]
	v_mfma_f32_16x16x32_bf16 v[60:63], v[20:23], v[176:179], v[56:59]
	v_mfma_f32_16x16x32_bf16 v[204:207], v[4:7], v[184:187], v[52:55]
	v_mfma_f32_16x16x32_bf16 v[48:51], v[20:23], v[184:187], v[48:51]
	v_mfma_f32_16x16x32_bf16 v[44:47], v[4:7], v[188:191], v[44:47]
	v_mfma_f32_16x16x32_bf16 v[208:211], v[20:23], v[188:191], v[40:43]
	v_mfma_f32_16x16x32_bf16 v[4:7], v[4:7], v[196:199], v[36:39]
	v_mfma_f32_16x16x32_bf16 v[32:35], v[20:23], v[196:199], v[32:35]
	v_mfma_f32_16x16x32_bf16 v[56:59], v[8:11], v[180:183], v[24:27]
	v_mfma_f32_16x16x32_bf16 v[52:55], v[158:161], v[180:183], v[60:63]
	v_mfma_f32_16x16x32_bf16 v[40:43], v[8:11], v[154:157], v[204:207]
	v_mfma_f32_16x16x32_bf16 v[36:39], v[158:161], v[154:157], v[48:51]
	v_mfma_f32_16x16x32_bf16 v[24:27], v[8:11], v[192:195], v[44:47]
	v_mfma_f32_16x16x32_bf16 v[20:23], v[158:161], v[192:195], v[208:211]
	v_mfma_f32_16x16x32_bf16 v[8:11], v[8:11], v[200:203], v[4:7]
	v_mfma_f32_16x16x32_bf16 v[4:7], v[158:161], v[200:203], v[32:35]
	v_mfma_f32_16x16x32_bf16 v[28:31], v[222:225], v[176:179], v[28:31]
	v_mfma_f32_16x16x32_bf16 v[32:35], v[230:233], v[176:179], v[134:137]
	v_mfma_f32_16x16x32_bf16 v[44:47], v[222:225], v[184:187], v[138:141]
	v_mfma_f32_16x16x32_bf16 v[16:19], v[230:233], v[184:187], v[16:19]
	v_mfma_f32_16x16x32_bf16 v[12:15], v[222:225], v[188:191], v[12:15]
	v_mfma_f32_16x16x32_bf16 v[134:137], v[230:233], v[188:191], v[142:145]
	v_mfma_f32_16x16x32_bf16 v[138:141], v[222:225], v[196:199], v[172:175]
	v_mfma_f32_16x16x32_bf16 v[0:3], v[230:233], v[196:199], v[0:3]
	v_mfma_f32_16x16x32_bf16 v[60:63], v[226:229], v[180:183], v[28:31]
	v_mfma_f32_16x16x32_bf16 v[48:51], v[234:237], v[180:183], v[32:35]
	v_mfma_f32_16x16x32_bf16 v[44:47], v[226:229], v[154:157], v[44:47]
	v_mfma_f32_16x16x32_bf16 v[32:35], v[234:237], v[154:157], v[16:19]
	v_mfma_f32_16x16x32_bf16 v[28:31], v[226:229], v[192:195], v[12:15]
	v_mfma_f32_16x16x32_bf16 v[16:19], v[234:237], v[192:195], v[134:137]
	v_mfma_f32_16x16x32_bf16 v[12:15], v[226:229], v[200:203], v[138:141]
	v_mfma_f32_16x16x32_bf16 v[0:3], v[234:237], v[200:203], v[0:3]
	v_cmp_gt_u32_e32 vcc, s69, v130
	s_barrier
	s_and_saveexec_b64 s[50:51], vcc
	s_cbranch_execz .LBB0_841
	s_barrier

; #define STAGE(P, BASE, LD, br, kt) do { const char* _g = (const char*)((BASE) + (size_t)(br) * (LD) + (size_t)(kt) * 64); \
;     for (int _i = 0; _i < 2; ++_i) { int _b = tidx * 16 + _i * 8192; int _r, _c; stage_rc(_b, _r, _c); \
;       __builtin_amdgcn_global_load_lds((const unsigned*)(_g + (unsigned)((_r * (LD) + _c) * 2)), (unsigned*)((char*)(P) + _b), 16, 0, 0); } } while (0)
; #define LDA(dst, b, h) for (int m = 0; m < 4; ++m) for (int k = 0; k < 2; ++k) \
;     dst[m][k] = *reinterpret_cast<const bf16x8*>((char*)SA(b, h) + lds_byte(wr * 64 + m * 16 + fr, k * 32 + fq * 8))
; #define LDB(dst, b, h) for (int n = 0; n < 2; ++n) for (int k = 0; k < 2; ++k) \
;     dst[n][k] = *reinterpret_cast<const bf16x8*>((char*)SB(b, h) + lds_byte(wc * 32 + n * 16 + fr, k * 32 + fq * 8))
; #define MMA(ai, bj, At_, Bt_) do { __builtin_amdgcn_s_setprio(1); \
;     for (int k = 0; k < 2; ++k) for (int m = 0; m < 4; ++m) for (int n = 0; n < 2; ++n) \
;       acc[ai][bj][m][n] = __builtin_amdgcn_mfma_f32_16x16x32_bf16(At_[m][k], Bt_[n][k], acc[ai][bj][m][n], 0, 0, 0); \
;     __builtin_amdgcn_s_setprio(0); } while (0)
; #define WAIT_L(n) asm volatile("s_waitcnt lgkmcnt(" #n ")" ::: "memory")
; #define BAR __builtin_amdgcn_s_barrier()
; #define SCHED __builtin_amdgcn_sched_barrier(0)
; template <int EPI, int lda, int ldb, int N, int K>
; __device__ __forceinline__ void gemm_phase(const u16* __restrict__ A, const u16* __restrict__ Bt, const GemmEpi ep, int wv) {
;     ...
;       LDB(B0, 0, 0); SCHED; LDA(At, 0, 0); STAGE(SA(1, 1), Ab, lda, brow + HALF, t + 1);
;       WAIT_L(8); BAR; WAIT_L(0); MMA(0, 0, At, B0); BAR; SCHED;
;       LDB(B1, 0, 1); STAGE(SB(0, 0), Bt, ldb, bcol, t + 2);
;       BAR; WAIT_L(0); MMA(0, 1, At, B1); BAR;
;       LDA(At, 0, 1); STAGE(SA(0, 0), Ab, lda, brow, t + 2);
;       BAR; WAIT_L(0); MMA(1, 0, At, B0); BAR; SCHED;
.LBB0_1147:
	ds_read_b128 v[172:175], v161
	ds_read_b128 v[176:179], v161 offset:1024
	ds_read_b128 v[180:183], v161 offset:2048
	ds_read_b128 v[184:187], v161 offset:3072
	v_add_u32_e32 v169, 0xc000, v148
	v_lshl_add_u64 v[236:237], v[138:139], 0, s[60:61]
	v_readfirstlane_b32 s63, v169
	v_add_u32_e32 v170, 0xe000, v148
	v_lshl_add_u64 v[162:163], v[236:237], 0, s[22:23]
	s_mov_b32 m0, s63
	v_lshl_add_u64 v[238:239], v[140:141], 0, s[60:61]
	v_readfirstlane_b32 s63, v170
	ds_read_b128 v[164:167], v152
	ds_read_b128 v[188:191], v152 offset:1024
	ds_read_b128 v[192:195], v151
	ds_read_b128 v[196:199], v151 offset:1024
	ds_read_b128 v[200:203], v150
	ds_read_b128 v[204:207], v150 offset:1024
	ds_read_b128 v[208:211], v149
	ds_read_b128 v[212:215], v149 offset:1024
	global_load_lds_dwordx4 v[162:163], off
	v_lshl_add_u64 v[162:163], v[238:239], 0, s[22:23]
	s_mov_b32 m0, s63
	s_nop 0
	global_load_lds_dwordx4 v[162:163], off
	s_waitcnt lgkmcnt(8)
	s_barrier
	s_waitcnt lgkmcnt(0)
	s_waitcnt lgkmcnt(0)
	v_mfma_f32_16x16x32_bf16 v[124:127], v[164:167], v[172:175], v[124:127]
	v_mfma_f32_16x16x32_bf16 v[120:123], v[164:167], v[180:183], v[120:123]
	v_mfma_f32_16x16x32_bf16 v[116:119], v[192:195], v[172:175], v[116:119]
	v_mfma_f32_16x16x32_bf16 v[112:115], v[192:195], v[180:183], v[112:115]
	v_mfma_f32_16x16x32_bf16 v[108:111], v[200:203], v[172:175], v[108:111]
	v_mfma_f32_16x16x32_bf16 v[104:107], v[200:203], v[180:183], v[104:107]
	v_mfma_f32_16x16x32_bf16 v[100:103], v[208:211], v[172:175], v[100:103]
	v_mfma_f32_16x16x32_bf16 v[96:99], v[208:211], v[180:183], v[96:99]
	v_mfma_f32_16x16x32_bf16 v[124:127], v[188:191], v[176:179], v[124:127]
	v_mfma_f32_16x16x32_bf16 v[120:123], v[188:191], v[184:187], v[120:123]
	v_mfma_f32_16x16x32_bf16 v[116:119], v[196:199], v[176:179], v[116:119]
	v_mfma_f32_16x16x32_bf16 v[112:115], v[196:199], v[184:187], v[112:115]
	v_mfma_f32_16x16x32_bf16 v[108:111], v[204:207], v[176:179], v[108:111]
	v_mfma_f32_16x16x32_bf16 v[104:107], v[204:207], v[184:187], v[104:107]
	v_mfma_f32_16x16x32_bf16 v[100:103], v[212:215], v[176:179], v[100:103]
	v_mfma_f32_16x16x32_bf16 v[96:99], v[212:215], v[184:187], v[96:99]
	s_barrier
	v_add_u32_e32 v162, s75, v154
	v_lshl_add_u64 v[240:241], v[134:135], 0, s[60:61]
	v_readfirstlane_b32 s63, v162
	v_add_u32_e32 v163, 0x2000, v162
	v_lshl_add_u64 v[232:233], v[240:241], 0, s[24:25]
	s_mov_b32 m0, s63
	v_lshl_add_u64 v[242:243], v[136:137], 0, s[60:61]
	v_readfirstlane_b32 s63, v163
	ds_read_b128 v[216:219], v160
	ds_read_b128 v[220:223], v160 offset:1024
	ds_read_b128 v[224:227], v160 offset:2048
	ds_read_b128 v[228:231], v160 offset:3072
	global_load_lds_dwordx4 v[232:233], off
	v_lshl_add_u64 v[232:233], v[242:243], 0, s[24:25]
	s_mov_b32 m0, s63
	s_nop 0
	global_load_lds_dwordx4 v[232:233], off
	s_barrier
	s_waitcnt lgkmcnt(0)
	s_waitcnt lgkmcnt(0)
	v_mfma_f32_16x16x32_bf16 v[92:95], v[164:167], v[216:219], v[92:95]
	v_mfma_f32_16x16x32_bf16 v[88:91], v[164:167], v[224:227], v[88:91]
	v_mfma_f32_16x16x32_bf16 v[84:87], v[192:195], v[216:219], v[84:87]
	v_mfma_f32_16x16x32_bf16 v[80:83], v[192:195], v[224:227], v[80:83]
	v_mfma_f32_16x16x32_bf16 v[76:79], v[200:203], v[216:219], v[76:79]
	v_mfma_f32_16x16x32_bf16 v[72:75], v[200:203], v[224:227], v[72:75]
	v_mfma_f32_16x16x32_bf16 v[68:71], v[208:211], v[216:219], v[68:71]
	v_mfma_f32_16x16x32_bf16 v[64:67], v[208:211], v[224:227], v[64:67]
	v_mfma_f32_16x16x32_bf16 v[92:95], v[188:191], v[220:223], v[92:95]
	v_mfma_f32_16x16x32_bf16 v[88:91], v[188:191], v[228:231], v[88:91]
	v_mfma_f32_16x16x32_bf16 v[84:87], v[196:199], v[220:223], v[84:87]
	v_mfma_f32_16x16x32_bf16 v[80:83], v[196:199], v[228:231], v[80:83]
	v_mfma_f32_16x16x32_bf16 v[76:79], v[204:207], v[220:223], v[76:79]
	v_mfma_f32_16x16x32_bf16 v[72:75], v[204:207], v[228:231], v[72:75]
	v_mfma_f32_16x16x32_bf16 v[68:71], v[212:215], v[220:223], v[68:71]
	v_mfma_f32_16x16x32_bf16 v[64:67], v[212:215], v[228:231], v[64:67]
	v_readfirstlane_b32 s63, v148
	v_lshl_add_u64 v[164:165], v[236:237], 0, s[26:27]
	s_mov_b32 m0, s63
	s_barrier
	ds_read_b128 v[188:191], v152 offset:16384
	ds_read_b128 v[192:195], v152 offset:17408
	ds_read_b128 v[196:199], v151 offset:16384
	ds_read_b128 v[200:203], v151 offset:17408
	ds_read_b128 v[204:207], v150 offset:16384
	ds_read_b128 v[208:211], v150 offset:17408
	ds_read_b128 v[212:215], v149 offset:16384
	ds_read_b128 v[232:235], v149 offset:17408
	global_load_lds_dwordx4 v[164:165], off
	v_add_u32_e32 v164, 0x2000, v148
	v_lshl_add_u64 v[166:167], v[238:239], 0, s[26:27]
	v_readfirstlane_b32 s63, v164
	s_mov_b32 m0, s63
	s_nop 0
	global_load_lds_dwordx4 v[166:167], off
	s_barrier
	s_waitcnt lgkmcnt(0)
	s_waitcnt lgkmcnt(0)
	v_mfma_f32_16x16x32_bf16 v[60:63], v[188:191], v[172:175], v[60:63]
	v_mfma_f32_16x16x32_bf16 v[56:59], v[188:191], v[180:183], v[56:59]
	v_mfma_f32_16x16x32_bf16 v[52:55], v[196:199], v[172:175], v[52:55]
	v_mfma_f32_16x16x32_bf16 v[48:51], v[196:199], v[180:183], v[48:51]
	v_mfma_f32_16x16x32_bf16 v[44:47], v[204:207], v[172:175], v[44:47]
	v_mfma_f32_16x16x32_bf16 v[40:43], v[204:207], v[180:183], v[40:43]
	v_mfma_f32_16x16x32_bf16 v[36:39], v[212:215], v[172:175], v[36:39]
	v_mfma_f32_16x16x32_bf16 v[32:35], v[212:215], v[180:183], v[32:35]
	v_mfma_f32_16x16x32_bf16 v[60:63], v[192:195], v[176:179], v[60:63]
	v_mfma_f32_16x16x32_bf16 v[56:59], v[192:195], v[184:187], v[56:59]
	v_mfma_f32_16x16x32_bf16 v[52:55], v[200:203], v[176:179], v[52:55]
	v_mfma_f32_16x16x32_bf16 v[48:51], v[200:203], v[184:187], v[48:51]
	v_mfma_f32_16x16x32_bf16 v[44:47], v[208:211], v[176:179], v[44:47]
	v_mfma_f32_16x16x32_bf16 v[40:43], v[208:211], v[184:187], v[40:43]
	v_mfma_f32_16x16x32_bf16 v[36:39], v[232:235], v[176:179], v[36:39]
	v_mfma_f32_16x16x32_bf16 v[32:35], v[232:235], v[184:187], v[32:35]
	s_barrier
; #define STAGE(P, BASE, LD, br, kt) do { const char* _g = (const char*)((BASE) + (size_t)(br) * (LD) + (size_t)(kt) * 64); \
;     for (int _i = 0; _i < 2; ++_i) { int _b = tidx * 16 + _i * 8192; int _r, _c; stage_rc(_b, _r, _c); \
;       __builtin_amdgcn_global_load_lds((const unsigned*)(_g + (unsigned)((_r * (LD) + _c) * 2)), (unsigned*)((char*)(P) + _b), 16, 0, 0); } } while (0)
; #define LDA(dst, b, h) for (int m = 0; m < 4; ++m) for (int k = 0; k < 2; ++k) \
;     dst[m][k] = *reinterpret_cast<const bf16x8*>((char*)SA(b, h) + lds_byte(wr * 64 + m * 16 + fr, k * 32 + fq * 8))
; #define LDB(dst, b, h) for (int n = 0; n < 2; ++n) for (int k = 0; k < 2; ++k) \
;     dst[n][k] = *reinterpret_cast<const bf16x8*>((char*)SB(b, h) + lds_byte(wc * 32 + n * 16 + fr, k * 32 + fq * 8))
; #define MMA(ai, bj, At_, Bt_) do { __builtin_amdgcn_s_setprio(1); \
;     for (int k = 0; k < 2; ++k) for (int m = 0; m < 4; ++m) for (int n = 0; n < 2; ++n) \
;       acc[ai][bj][m][n] = __builtin_amdgcn_mfma_f32_16x16x32_bf16(At_[m][k], Bt_[n][k], acc[ai][bj][m][n], 0, 0, 0); \
;     __builtin_amdgcn_s_setprio(0); } while (0)
; #define WAIT_V(n) asm volatile("s_waitcnt vmcnt(" #n ")" ::: "memory")
; #define WAIT_L(n) asm volatile("s_waitcnt lgkmcnt(" #n ")" ::: "memory")
; #define BAR __builtin_amdgcn_s_barrier()
; #define SCHED __builtin_amdgcn_sched_barrier(0)
; template <int EPI, int lda, int ldb, int N, int K>
; __device__ __forceinline__ void gemm_phase(const u16* __restrict__ A, const u16* __restrict__ Bt, const GemmEpi ep, int wv) {
;     ...
;       STAGE(SB(0, 1), Bt, ldb, bcol + HALF, t + 2);
;       WAIT_V(6); BAR; MMA(1, 1, At, B1); BAR;
;       LDB(B0, 1, 0); SCHED; LDA(At, 1, 0); STAGE(SA(0, 1), Ab, lda, brow + HALF, t + 2);
;       WAIT_L(8); BAR; WAIT_L(0); MMA(0, 0, At, B0); BAR; SCHED;
;       LDB(B1, 1, 1); STAGE(SB(1, 0), Bt, ldb, bcol, t + 3);
;       BAR; WAIT_L(0); MMA(0, 1, At, B1); BAR;
;       LDA(At, 1, 1); STAGE(SA(1, 0), Ab, lda, brow, t + 3);
	v_add_u32_e32 v165, s76, v154
	v_lshl_add_u64 v[166:167], v[240:241], 0, s[40:41]
	v_readfirstlane_b32 s63, v165
	s_mov_b32 m0, s63
	v_lshl_add_u64 v[172:173], v[242:243], 0, s[40:41]
	global_load_lds_dwordx4 v[166:167], off
	v_add_u32_e32 v166, 0x2000, v165
	s_nop 0
	v_readfirstlane_b32 s63, v166
	s_mov_b32 m0, s63
	s_nop 0
	global_load_lds_dwordx4 v[172:173], off
	s_waitcnt vmcnt(6)
	s_barrier
	v_mfma_f32_16x16x32_bf16 v[28:31], v[188:191], v[216:219], v[28:31]
	v_mfma_f32_16x16x32_bf16 v[24:27], v[188:191], v[224:227], v[24:27]
	v_mfma_f32_16x16x32_bf16 v[20:23], v[196:199], v[216:219], v[20:23]
	v_mfma_f32_16x16x32_bf16 v[16:19], v[196:199], v[224:227], v[16:19]
	v_mfma_f32_16x16x32_bf16 v[12:15], v[204:207], v[216:219], v[12:15]
	v_mfma_f32_16x16x32_bf16 v[8:11], v[204:207], v[224:227], v[8:11]
	v_mfma_f32_16x16x32_bf16 v[4:7], v[212:215], v[216:219], v[4:7]
	v_mfma_f32_16x16x32_bf16 v[0:3], v[212:215], v[224:227], v[0:3]
	v_mfma_f32_16x16x32_bf16 v[28:31], v[192:195], v[220:223], v[28:31]
	v_mfma_f32_16x16x32_bf16 v[24:27], v[192:195], v[228:231], v[24:27]
	v_mfma_f32_16x16x32_bf16 v[20:23], v[200:203], v[220:223], v[20:23]
	v_mfma_f32_16x16x32_bf16 v[16:19], v[200:203], v[228:231], v[16:19]
	v_mfma_f32_16x16x32_bf16 v[12:15], v[208:211], v[220:223], v[12:15]
	v_mfma_f32_16x16x32_bf16 v[8:11], v[208:211], v[228:231], v[8:11]
	v_mfma_f32_16x16x32_bf16 v[4:7], v[232:235], v[220:223], v[4:7]
	v_mfma_f32_16x16x32_bf16 v[0:3], v[232:235], v[228:231], v[0:3]
	s_barrier
	ds_read_b128 v[172:175], v155
	ds_read_b128 v[176:179], v155 offset:1024
	ds_read_b128 v[180:183], v155 offset:2048
	ds_read_b128 v[184:187], v155 offset:3072
	v_add_u32_e32 v167, 0x4000, v148
	v_add_u32_e32 v168, 0x6000, v148
	v_readfirstlane_b32 s63, v167
	v_lshl_add_u64 v[220:221], v[236:237], 0, s[42:43]
	s_mov_b32 m0, s63
	v_readfirstlane_b32 s63, v168
	ds_read_b128 v[188:191], v152 offset:32768
	ds_read_b128 v[192:195], v152 offset:33792
	ds_read_b128 v[196:199], v151 offset:32768
	ds_read_b128 v[200:203], v151 offset:33792
	ds_read_b128 v[204:207], v150 offset:32768
	ds_read_b128 v[208:211], v150 offset:33792
	ds_read_b128 v[212:215], v149 offset:32768
	ds_read_b128 v[216:219], v149 offset:33792
	global_load_lds_dwordx4 v[220:221], off
	v_lshl_add_u64 v[220:221], v[238:239], 0, s[42:43]
	s_mov_b32 m0, s63
	s_nop 0
	global_load_lds_dwordx4 v[220:221], off
	s_waitcnt lgkmcnt(8)
	s_barrier
	s_waitcnt lgkmcnt(0)
	s_waitcnt lgkmcnt(0)
	v_mfma_f32_16x16x32_bf16 v[124:127], v[188:191], v[172:175], v[124:127]
	v_mfma_f32_16x16x32_bf16 v[120:123], v[188:191], v[180:183], v[120:123]
	v_mfma_f32_16x16x32_bf16 v[116:119], v[196:199], v[172:175], v[116:119]
	v_mfma_f32_16x16x32_bf16 v[112:115], v[196:199], v[180:183], v[112:115]
	v_mfma_f32_16x16x32_bf16 v[108:111], v[204:207], v[172:175], v[108:111]
	v_mfma_f32_16x16x32_bf16 v[104:107], v[204:207], v[180:183], v[104:107]
	v_mfma_f32_16x16x32_bf16 v[100:103], v[212:215], v[172:175], v[100:103]
	v_mfma_f32_16x16x32_bf16 v[96:99], v[212:215], v[180:183], v[96:99]
	v_mfma_f32_16x16x32_bf16 v[124:127], v[192:195], v[176:179], v[124:127]
	v_mfma_f32_16x16x32_bf16 v[120:123], v[192:195], v[184:187], v[120:123]
	v_mfma_f32_16x16x32_bf16 v[116:119], v[200:203], v[176:179], v[116:119]
	v_mfma_f32_16x16x32_bf16 v[112:115], v[200:203], v[184:187], v[112:115]
	v_mfma_f32_16x16x32_bf16 v[108:111], v[208:211], v[176:179], v[108:111]
	v_mfma_f32_16x16x32_bf16 v[104:107], v[208:211], v[184:187], v[104:107]
	v_mfma_f32_16x16x32_bf16 v[100:103], v[216:219], v[176:179], v[100:103]
	v_mfma_f32_16x16x32_bf16 v[96:99], v[216:219], v[184:187], v[96:99]
	s_barrier
	v_readfirstlane_b32 s63, v156
	v_add_u32_e32 v171, 0x2000, v156
	v_lshl_add_u64 v[244:245], v[240:241], 0, s[44:45]
	s_mov_b32 m0, s63
	v_readfirstlane_b32 s63, v171
	ds_read_b128 v[220:223], v153
	ds_read_b128 v[224:227], v153 offset:1024
	ds_read_b128 v[228:231], v153 offset:2048
	ds_read_b128 v[232:235], v153 offset:3072
	global_load_lds_dwordx4 v[244:245], off
	v_lshl_add_u64 v[244:245], v[242:243], 0, s[44:45]
	s_mov_b32 m0, s63
	s_nop 0
	global_load_lds_dwordx4 v[244:245], off
	s_barrier
	s_waitcnt lgkmcnt(0)
	s_waitcnt lgkmcnt(0)
	v_mfma_f32_16x16x32_bf16 v[92:95], v[188:191], v[220:223], v[92:95]
	v_mfma_f32_16x16x32_bf16 v[88:91], v[188:191], v[228:231], v[88:91]
	v_mfma_f32_16x16x32_bf16 v[84:87], v[196:199], v[220:223], v[84:87]
	v_mfma_f32_16x16x32_bf16 v[80:83], v[196:199], v[228:231], v[80:83]
	v_mfma_f32_16x16x32_bf16 v[76:79], v[204:207], v[220:223], v[76:79]
	v_mfma_f32_16x16x32_bf16 v[72:75], v[204:207], v[228:231], v[72:75]
	v_mfma_f32_16x16x32_bf16 v[68:71], v[212:215], v[220:223], v[68:71]
	v_mfma_f32_16x16x32_bf16 v[64:67], v[212:215], v[228:231], v[64:67]
	v_mfma_f32_16x16x32_bf16 v[92:95], v[192:195], v[224:227], v[92:95]
	v_mfma_f32_16x16x32_bf16 v[88:91], v[192:195], v[232:235], v[88:91]
	v_mfma_f32_16x16x32_bf16 v[84:87], v[200:203], v[224:227], v[84:87]
	v_mfma_f32_16x16x32_bf16 v[80:83], v[200:203], v[232:235], v[80:83]
	v_mfma_f32_16x16x32_bf16 v[76:79], v[208:211], v[224:227], v[76:79]
	v_mfma_f32_16x16x32_bf16 v[72:75], v[208:211], v[232:235], v[72:75]
	v_mfma_f32_16x16x32_bf16 v[68:71], v[216:219], v[224:227], v[68:71]
	v_mfma_f32_16x16x32_bf16 v[64:67], v[216:219], v[232:235], v[64:67]
	v_readfirstlane_b32 s63, v157
	v_lshl_add_u64 v[236:237], v[236:237], 0, s[46:47]
	s_mov_b32 m0, s63
	v_readfirstlane_b32 s63, v158
	s_barrier
; #define STAGE(P, BASE, LD, br, kt) do { const char* _g = (const char*)((BASE) + (size_t)(br) * (LD) + (size_t)(kt) * 64); \
;     for (int _i = 0; _i < 2; ++_i) { int _b = tidx * 16 + _i * 8192; int _r, _c; stage_rc(_b, _r, _c); \
;       __builtin_amdgcn_global_load_lds((const unsigned*)(_g + (unsigned)((_r * (LD) + _c) * 2)), (unsigned*)((char*)(P) + _b), 16, 0, 0); } } while (0)
; #define LDA(dst, b, h) for (int m = 0; m < 4; ++m) for (int k = 0; k < 2; ++k) \
;     dst[m][k] = *reinterpret_cast<const bf16x8*>((char*)SA(b, h) + lds_byte(wr * 64 + m * 16 + fr, k * 32 + fq * 8))
; #define LDB(dst, b, h) for (int n = 0; n < 2; ++n) for (int k = 0; k < 2; ++k) \
;     dst[n][k] = *reinterpret_cast<const bf16x8*>((char*)SB(b, h) + lds_byte(wc * 32 + n * 16 + fr, k * 32 + fq * 8))
; #define MMA(ai, bj, At_, Bt_) do { __builtin_amdgcn_s_setprio(1); \
;     for (int k = 0; k < 2; ++k) for (int m = 0; m < 4; ++m) for (int n = 0; n < 2; ++n) \
;       acc[ai][bj][m][n] = __builtin_amdgcn_mfma_f32_16x16x32_bf16(At_[m][k], Bt_[n][k], acc[ai][bj][m][n], 0, 0, 0); \
;     __builtin_amdgcn_s_setprio(0); } while (0)
; #define WAIT_V(n) asm volatile("s_waitcnt vmcnt(" #n ")" ::: "memory")
; #define WAIT_L(n) asm volatile("s_waitcnt lgkmcnt(" #n ")" ::: "memory")
; #define BAR __builtin_amdgcn_s_barrier()
; #define SCHED __builtin_amdgcn_sched_barrier(0)
; template <int EPI, int lda, int ldb, int N, int K>
; __device__ __forceinline__ void gemm_phase(const u16* __restrict__ A, const u16* __restrict__ Bt, const GemmEpi ep, int wv) {
;     ...
;       LDA(At, 1, 1); STAGE(SA(1, 0), Ab, lda, brow, t + 3);
;       BAR; WAIT_L(0); MMA(1, 0, At, B0); BAR; SCHED;
;       STAGE(SB(1, 1), Bt, ldb, bcol + HALF, t + 3);
;       WAIT_V(6); BAR; MMA(1, 1, At, B1); BAR;
;     }
;     { LDB(B0, 0, 0); LDA(At, 0, 0); STAGE(SA(1, 1), Ab, lda, brow + HALF, nt - 1);
;       BAR; WAIT_L(0); MMA(0, 0, At, B0); BAR;
;       LDB(B1, 0, 1); BAR; WAIT_L(0); MMA(0, 1, At, B1); BAR;
	ds_read_b128 v[188:191], v152 offset:49152
	ds_read_b128 v[192:195], v152 offset:50176
	ds_read_b128 v[196:199], v151 offset:49152
	ds_read_b128 v[200:203], v151 offset:50176
	ds_read_b128 v[204:207], v150 offset:49152
	ds_read_b128 v[208:211], v150 offset:50176
	ds_read_b128 v[212:215], v149 offset:49152
	ds_read_b128 v[216:219], v149 offset:50176
	global_load_lds_dwordx4 v[236:237], off
	v_lshl_add_u64 v[236:237], v[238:239], 0, s[46:47]
	s_mov_b32 m0, s63
	s_nop 0
	global_load_lds_dwordx4 v[236:237], off
	s_barrier
	s_waitcnt lgkmcnt(0)
	s_waitcnt lgkmcnt(0)
	v_mfma_f32_16x16x32_bf16 v[60:63], v[188:191], v[172:175], v[60:63]
	v_mfma_f32_16x16x32_bf16 v[56:59], v[188:191], v[180:183], v[56:59]
	v_mfma_f32_16x16x32_bf16 v[52:55], v[196:199], v[172:175], v[52:55]
	v_mfma_f32_16x16x32_bf16 v[48:51], v[196:199], v[180:183], v[48:51]
	v_mfma_f32_16x16x32_bf16 v[44:47], v[204:207], v[172:175], v[44:47]
	v_mfma_f32_16x16x32_bf16 v[40:43], v[204:207], v[180:183], v[40:43]
	v_mfma_f32_16x16x32_bf16 v[36:39], v[212:215], v[172:175], v[36:39]
	v_mfma_f32_16x16x32_bf16 v[32:35], v[212:215], v[180:183], v[32:35]
	v_mfma_f32_16x16x32_bf16 v[60:63], v[192:195], v[176:179], v[60:63]
	v_mfma_f32_16x16x32_bf16 v[56:59], v[192:195], v[184:187], v[56:59]
	v_mfma_f32_16x16x32_bf16 v[52:55], v[200:203], v[176:179], v[52:55]
	v_mfma_f32_16x16x32_bf16 v[48:51], v[200:203], v[184:187], v[48:51]
	v_mfma_f32_16x16x32_bf16 v[44:47], v[208:211], v[176:179], v[44:47]
	v_mfma_f32_16x16x32_bf16 v[40:43], v[208:211], v[184:187], v[40:43]
	v_mfma_f32_16x16x32_bf16 v[36:39], v[216:219], v[176:179], v[36:39]
	v_mfma_f32_16x16x32_bf16 v[32:35], v[216:219], v[184:187], v[32:35]
	s_barrier
	v_readfirstlane_b32 s63, v159
	v_add_u32_e32 v171, 0x2000, v159
	v_lshl_add_u64 v[172:173], v[240:241], 0, s[48:49]
	s_mov_b32 m0, s63
	v_readfirstlane_b32 s63, v171
	global_load_lds_dwordx4 v[172:173], off
	v_lshl_add_u64 v[172:173], v[242:243], 0, s[48:49]
	s_mov_b32 m0, s63
	s_nop 0
	global_load_lds_dwordx4 v[172:173], off
	s_waitcnt vmcnt(6)
	s_barrier
	v_mfma_f32_16x16x32_bf16 v[28:31], v[188:191], v[220:223], v[28:31]
	v_mfma_f32_16x16x32_bf16 v[24:27], v[188:191], v[228:231], v[24:27]
	v_mfma_f32_16x16x32_bf16 v[20:23], v[196:199], v[220:223], v[20:23]
	v_mfma_f32_16x16x32_bf16 v[16:19], v[196:199], v[228:231], v[16:19]
	v_mfma_f32_16x16x32_bf16 v[12:15], v[204:207], v[220:223], v[12:15]
	v_mfma_f32_16x16x32_bf16 v[8:11], v[204:207], v[228:231], v[8:11]
	v_mfma_f32_16x16x32_bf16 v[4:7], v[212:215], v[220:223], v[4:7]
	v_mfma_f32_16x16x32_bf16 v[0:3], v[212:215], v[228:231], v[0:3]
	v_mfma_f32_16x16x32_bf16 v[28:31], v[192:195], v[224:227], v[28:31]
	v_mfma_f32_16x16x32_bf16 v[24:27], v[192:195], v[232:235], v[24:27]
	v_mfma_f32_16x16x32_bf16 v[20:23], v[200:203], v[224:227], v[20:23]
	v_mfma_f32_16x16x32_bf16 v[16:19], v[200:203], v[232:235], v[16:19]
	v_mfma_f32_16x16x32_bf16 v[12:15], v[208:211], v[224:227], v[12:15]
	v_mfma_f32_16x16x32_bf16 v[8:11], v[208:211], v[232:235], v[8:11]
	v_mfma_f32_16x16x32_bf16 v[4:7], v[216:219], v[224:227], v[4:7]
	v_mfma_f32_16x16x32_bf16 v[0:3], v[216:219], v[232:235], v[0:3]
	s_add_i32 s62, s62, 2
	s_add_u32 s60, s60, 0x100
	s_addc_u32 s61, s61, 0
	s_cmp_gt_u32 s62, 27
	s_barrier
	s_cbranch_scc0 .LBB0_1147
	s_add_i32 s60, s58, 0x80
	s_mul_hi_i32 s61, s60, 0x1080
	s_mulk_i32 s60, 0x1080
	s_add_u32 s60, s69, s60
	s_addc_u32 s61, s70, s61
	v_lshl_add_u64 v[208:209], s[60:61], 0, v[128:129]
	v_readfirstlane_b32 s62, v169
	v_lshl_add_u64 v[208:209], v[208:209], 0, s[50:51]
	s_mov_b32 m0, s62
	ds_read_b128 v[134:137], v161
	ds_read_b128 v[138:141], v161 offset:1024
	ds_read_b128 v[156:159], v161 offset:2048
	ds_read_b128 v[172:175], v161 offset:3072
	ds_read_b128 v[176:179], v152
	ds_read_b128 v[180:183], v152 offset:1024
	ds_read_b128 v[184:187], v151
	ds_read_b128 v[188:191], v151 offset:1024
	ds_read_b128 v[192:195], v150
	ds_read_b128 v[196:199], v150 offset:1024
	ds_read_b128 v[200:203], v149
	ds_read_b128 v[204:207], v149 offset:1024
	global_load_lds_dwordx4 v[208:209], off
	v_lshl_add_u64 v[208:209], s[60:61], 0, v[132:133]
	v_readfirstlane_b32 s60, v170
	v_lshl_add_u64 v[208:209], v[208:209], 0, s[50:51]
	s_mov_b32 m0, s60
	s_nop 0
	global_load_lds_dwordx4 v[208:209], off
	s_barrier
	s_waitcnt lgkmcnt(0)
	s_waitcnt lgkmcnt(0)
	v_mfma_f32_16x16x32_bf16 v[124:127], v[176:179], v[134:137], v[124:127]
	v_mfma_f32_16x16x32_bf16 v[120:123], v[176:179], v[156:159], v[120:123]
	v_mfma_f32_16x16x32_bf16 v[116:119], v[184:187], v[134:137], v[116:119]
	v_mfma_f32_16x16x32_bf16 v[112:115], v[184:187], v[156:159], v[112:115]
	v_mfma_f32_16x16x32_bf16 v[108:111], v[192:195], v[134:137], v[108:111]
	v_mfma_f32_16x16x32_bf16 v[104:107], v[192:195], v[156:159], v[104:107]
	v_mfma_f32_16x16x32_bf16 v[100:103], v[200:203], v[134:137], v[100:103]
	v_mfma_f32_16x16x32_bf16 v[96:99], v[200:203], v[156:159], v[96:99]
	v_mfma_f32_16x16x32_bf16 v[124:127], v[180:183], v[138:141], v[124:127]
	v_mfma_f32_16x16x32_bf16 v[120:123], v[180:183], v[172:175], v[120:123]
	v_mfma_f32_16x16x32_bf16 v[116:119], v[188:191], v[138:141], v[116:119]
	v_mfma_f32_16x16x32_bf16 v[112:115], v[188:191], v[172:175], v[112:115]
	v_mfma_f32_16x16x32_bf16 v[108:111], v[196:199], v[138:141], v[108:111]
	v_mfma_f32_16x16x32_bf16 v[104:107], v[196:199], v[172:175], v[104:107]
	v_mfma_f32_16x16x32_bf16 v[100:103], v[204:207], v[138:141], v[100:103]
	v_mfma_f32_16x16x32_bf16 v[96:99], v[204:207], v[172:175], v[96:99]
	s_barrier
	ds_read_b128 v[208:211], v160
	ds_read_b128 v[212:215], v160 offset:1024
	ds_read_b128 v[216:219], v160 offset:2048
	ds_read_b128 v[220:223], v160 offset:3072
	s_barrier
; #define LDA(dst, b, h) for (int m = 0; m < 4; ++m) for (int k = 0; k < 2; ++k) \
;     dst[m][k] = *reinterpret_cast<const bf16x8*>((char*)SA(b, h) + lds_byte(wr * 64 + m * 16 + fr, k * 32 + fq * 8))
; #define LDB(dst, b, h) for (int n = 0; n < 2; ++n) for (int k = 0; k < 2; ++k) \
;     dst[n][k] = *reinterpret_cast<const bf16x8*>((char*)SB(b, h) + lds_byte(wc * 32 + n * 16 + fr, k * 32 + fq * 8))
; #define MMA(ai, bj, At_, Bt_) do { __builtin_amdgcn_s_setprio(1); \
;     for (int k = 0; k < 2; ++k) for (int m = 0; m < 4; ++m) for (int n = 0; n < 2; ++n) \
;       acc[ai][bj][m][n] = __builtin_amdgcn_mfma_f32_16x16x32_bf16(At_[m][k], Bt_[n][k], acc[ai][bj][m][n], 0, 0, 0); \
;     __builtin_amdgcn_s_setprio(0); } while (0)
; #define WAIT_V(n) asm volatile("s_waitcnt vmcnt(" #n ")" ::: "memory")
; #define WAIT_L(n) asm volatile("s_waitcnt lgkmcnt(" #n ")" ::: "memory")
; #define BAR __builtin_amdgcn_s_barrier()
; template <int EPI, int lda, int ldb, int N, int K>
; __device__ __forceinline__ void gemm_phase(const u16* __restrict__ A, const u16* __restrict__ Bt, const GemmEpi ep, int wv) {
;     ...
;       LDB(B1, 0, 1); BAR; WAIT_L(0); MMA(0, 1, At, B1); BAR;
;       LDA(At, 0, 1); WAIT_V(4); BAR; WAIT_L(0); MMA(1, 0, At, B0); MMA(1, 1, At, B1); BAR; }
;     { LDB(B0, 1, 0); LDA(At, 1, 0); WAIT_V(2); BAR; WAIT_L(0); MMA(0, 0, At, B0); BAR;
	s_waitcnt lgkmcnt(0)
	s_waitcnt lgkmcnt(0)
	v_mfma_f32_16x16x32_bf16 v[92:95], v[176:179], v[208:211], v[92:95]
	v_mfma_f32_16x16x32_bf16 v[88:91], v[176:179], v[216:219], v[88:91]
	v_mfma_f32_16x16x32_bf16 v[76:79], v[192:195], v[208:211], v[76:79]
	v_mfma_f32_16x16x32_bf16 v[72:75], v[192:195], v[216:219], v[72:75]
	v_mfma_f32_16x16x32_bf16 v[84:87], v[184:187], v[208:211], v[84:87]
	v_mfma_f32_16x16x32_bf16 v[80:83], v[184:187], v[216:219], v[80:83]
	v_mfma_f32_16x16x32_bf16 v[68:71], v[200:203], v[208:211], v[68:71]
	v_mfma_f32_16x16x32_bf16 v[64:67], v[200:203], v[216:219], v[64:67]
	v_mfma_f32_16x16x32_bf16 v[92:95], v[180:183], v[212:215], v[92:95]
	v_mfma_f32_16x16x32_bf16 v[88:91], v[180:183], v[220:223], v[88:91]
	v_mfma_f32_16x16x32_bf16 v[76:79], v[196:199], v[212:215], v[76:79]
	v_mfma_f32_16x16x32_bf16 v[72:75], v[196:199], v[220:223], v[72:75]
	v_mfma_f32_16x16x32_bf16 v[176:179], v[188:191], v[212:215], v[84:87]
	v_mfma_f32_16x16x32_bf16 v[180:183], v[188:191], v[220:223], v[80:83]
	v_mfma_f32_16x16x32_bf16 v[184:187], v[204:207], v[212:215], v[68:71]
	v_mfma_f32_16x16x32_bf16 v[188:191], v[204:207], v[220:223], v[64:67]
	s_barrier
	s_nop 0
	ds_read_b128 v[64:67], v152 offset:16384
	ds_read_b128 v[68:71], v152 offset:17408
	ds_read_b128 v[80:83], v151 offset:16384
	ds_read_b128 v[84:87], v151 offset:17408
	ds_read_b128 v[192:195], v150 offset:16384
	ds_read_b128 v[196:199], v150 offset:17408
	ds_read_b128 v[200:203], v149 offset:16384
	ds_read_b128 v[204:207], v149 offset:17408
	s_waitcnt vmcnt(4)
	s_barrier
	s_waitcnt lgkmcnt(0)
	s_waitcnt lgkmcnt(0)
	v_mfma_f32_16x16x32_bf16 v[60:63], v[64:67], v[134:137], v[60:63]
	v_mfma_f32_16x16x32_bf16 v[56:59], v[64:67], v[156:159], v[56:59]
	v_mfma_f32_16x16x32_bf16 v[52:55], v[80:83], v[134:137], v[52:55]
	v_mfma_f32_16x16x32_bf16 v[48:51], v[80:83], v[156:159], v[48:51]
	v_mfma_f32_16x16x32_bf16 v[44:47], v[192:195], v[134:137], v[44:47]
	v_mfma_f32_16x16x32_bf16 v[40:43], v[192:195], v[156:159], v[40:43]
	v_mfma_f32_16x16x32_bf16 v[36:39], v[200:203], v[134:137], v[36:39]
	v_mfma_f32_16x16x32_bf16 v[32:35], v[200:203], v[156:159], v[32:35]
	v_mfma_f32_16x16x32_bf16 v[60:63], v[68:71], v[138:141], v[60:63]
	v_mfma_f32_16x16x32_bf16 v[56:59], v[68:71], v[172:175], v[56:59]
	v_mfma_f32_16x16x32_bf16 v[52:55], v[84:87], v[138:141], v[52:55]
	v_mfma_f32_16x16x32_bf16 v[48:51], v[84:87], v[172:175], v[48:51]
	v_mfma_f32_16x16x32_bf16 v[44:47], v[196:199], v[138:141], v[44:47]
	v_mfma_f32_16x16x32_bf16 v[40:43], v[196:199], v[172:175], v[40:43]
	v_mfma_f32_16x16x32_bf16 v[36:39], v[204:207], v[138:141], v[36:39]
	v_mfma_f32_16x16x32_bf16 v[32:35], v[204:207], v[172:175], v[32:35]
	v_mfma_f32_16x16x32_bf16 v[28:31], v[64:67], v[208:211], v[28:31]
	v_mfma_f32_16x16x32_bf16 v[24:27], v[64:67], v[216:219], v[24:27]
	v_mfma_f32_16x16x32_bf16 v[12:15], v[192:195], v[208:211], v[12:15]
	v_mfma_f32_16x16x32_bf16 v[8:11], v[192:195], v[216:219], v[8:11]
	v_mfma_f32_16x16x32_bf16 v[20:23], v[80:83], v[208:211], v[20:23]
	v_mfma_f32_16x16x32_bf16 v[16:19], v[80:83], v[216:219], v[16:19]
	v_mfma_f32_16x16x32_bf16 v[4:7], v[200:203], v[208:211], v[4:7]
	v_mfma_f32_16x16x32_bf16 v[0:3], v[200:203], v[216:219], v[0:3]
	v_mfma_f32_16x16x32_bf16 v[28:31], v[68:71], v[212:215], v[28:31]
	v_mfma_f32_16x16x32_bf16 v[24:27], v[68:71], v[220:223], v[24:27]
	v_mfma_f32_16x16x32_bf16 v[12:15], v[196:199], v[212:215], v[12:15]
	v_mfma_f32_16x16x32_bf16 v[8:11], v[196:199], v[220:223], v[8:11]
	v_mfma_f32_16x16x32_bf16 v[134:137], v[84:87], v[212:215], v[20:23]
	v_mfma_f32_16x16x32_bf16 v[138:141], v[84:87], v[220:223], v[16:19]
	v_mfma_f32_16x16x32_bf16 v[156:159], v[204:207], v[212:215], v[4:7]
	v_mfma_f32_16x16x32_bf16 v[170:173], v[204:207], v[220:223], v[0:3]
	s_barrier
	s_nop 0
	ds_read_b128 v[0:3], v155
	ds_read_b128 v[4:7], v155 offset:1024
	ds_read_b128 v[16:19], v155 offset:2048
	ds_read_b128 v[192:195], v155 offset:3072
	ds_read_b128 v[20:23], v152 offset:32768
	ds_read_b128 v[196:199], v152 offset:33792
	ds_read_b128 v[200:203], v151 offset:32768
	ds_read_b128 v[204:207], v151 offset:33792
	ds_read_b128 v[208:211], v150 offset:32768
	ds_read_b128 v[212:215], v150 offset:33792
	ds_read_b128 v[216:219], v149 offset:32768
	ds_read_b128 v[220:223], v149 offset:33792
	s_waitcnt vmcnt(2)
	s_barrier
; #define LDA(dst, b, h) for (int m = 0; m < 4; ++m) for (int k = 0; k < 2; ++k) \
;     dst[m][k] = *reinterpret_cast<const bf16x8*>((char*)SA(b, h) + lds_byte(wr * 64 + m * 16 + fr, k * 32 + fq * 8))
; #define LDB(dst, b, h) for (int n = 0; n < 2; ++n) for (int k = 0; k < 2; ++k) \
;     dst[n][k] = *reinterpret_cast<const bf16x8*>((char*)SB(b, h) + lds_byte(wc * 32 + n * 16 + fr, k * 32 + fq * 8))
; #define MMA(ai, bj, At_, Bt_) do { __builtin_amdgcn_s_setprio(1); \
;     for (int k = 0; k < 2; ++k) for (int m = 0; m < 4; ++m) for (int n = 0; n < 2; ++n) \
;       acc[ai][bj][m][n] = __builtin_amdgcn_mfma_f32_16x16x32_bf16(At_[m][k], Bt_[n][k], acc[ai][bj][m][n], 0, 0, 0); \
;     __builtin_amdgcn_s_setprio(0); } while (0)
; #define WAIT_V(n) asm volatile("s_waitcnt vmcnt(" #n ")" ::: "memory")
; #define WAIT_L(n) asm volatile("s_waitcnt lgkmcnt(" #n ")" ::: "memory")
; #define BAR __builtin_amdgcn_s_barrier()
; #define STAGE4(BROW, BCOL, PN) do { const u16* Ab_ = A + (EPI == EPI_RG ? ((PN) >> 1) * 256 : 0); \
;     STAGE(SB(0, 0), Bt, ldb, (BCOL), 0); STAGE(SA(0, 0), Ab_, lda, (BROW), 0); \
;     STAGE(SB(0, 1), Bt, ldb, (BCOL) + HALF, 0); STAGE(SA(0, 1), Ab_, lda, (BROW) + HALF, 0); } while (0)
; template <int EPI, int lda, int ldb, int N, int K>
; __device__ __forceinline__ void gemm_phase(const u16* __restrict__ A, const u16* __restrict__ Bt, const GemmEpi ep, int wv) {
;     ...
;     { LDB(B0, 1, 0); LDA(At, 1, 0); WAIT_V(2); BAR; WAIT_L(0); MMA(0, 0, At, B0); BAR;
;       LDB(B1, 1, 1); WAIT_V(0); BAR; WAIT_L(0); MMA(0, 1, At, B1); BAR;
;       LDA(At, 1, 1); BAR; WAIT_L(0); MMA(1, 0, At, B0); MMA(1, 1, At, B1); BAR; }
;     if (wr == 0) BAR;
;     int ntile = 0, nbrow = 0, nbcol = 0, npn = 0; bool more = false;
;     if constexpr (PF) { ntile = tile + gridDim.x; more = ntile < nwg; if (more) { TILE_COORDS(ntile, nbrow, nbcol, npn); STAGE4(nbrow, nbcol, npn); } }
	s_waitcnt lgkmcnt(0)
	s_waitcnt lgkmcnt(0)
	v_mfma_f32_16x16x32_bf16 v[64:67], v[20:23], v[0:3], v[124:127]
	v_mfma_f32_16x16x32_bf16 v[68:71], v[20:23], v[16:19], v[120:123]
	v_mfma_f32_16x16x32_bf16 v[80:83], v[200:203], v[0:3], v[116:119]
	v_mfma_f32_16x16x32_bf16 v[84:87], v[200:203], v[16:19], v[112:115]
	v_mfma_f32_16x16x32_bf16 v[108:111], v[208:211], v[0:3], v[108:111]
	v_mfma_f32_16x16x32_bf16 v[104:107], v[208:211], v[16:19], v[104:107]
	v_mfma_f32_16x16x32_bf16 v[120:123], v[216:219], v[0:3], v[100:103]
	v_mfma_f32_16x16x32_bf16 v[124:127], v[216:219], v[16:19], v[96:99]
	v_mfma_f32_16x16x32_bf16 v[116:119], v[196:199], v[4:7], v[64:67]
	v_mfma_f32_16x16x32_bf16 v[112:115], v[196:199], v[192:195], v[68:71]
	v_mfma_f32_16x16x32_bf16 v[100:103], v[204:207], v[4:7], v[80:83]
	v_mfma_f32_16x16x32_bf16 v[96:99], v[204:207], v[192:195], v[84:87]
	v_mfma_f32_16x16x32_bf16 v[84:87], v[212:215], v[4:7], v[108:111]
	v_mfma_f32_16x16x32_bf16 v[80:83], v[212:215], v[192:195], v[104:107]
	v_mfma_f32_16x16x32_bf16 v[68:71], v[220:223], v[4:7], v[120:123]
	v_mfma_f32_16x16x32_bf16 v[64:67], v[220:223], v[192:195], v[124:127]
	s_barrier
	ds_read_b128 v[224:227], v153
	ds_read_b128 v[228:231], v153 offset:1024
	ds_read_b128 v[232:235], v153 offset:2048
	ds_read_b128 v[236:239], v153 offset:3072
	s_waitcnt vmcnt(0)
	s_barrier
	s_waitcnt lgkmcnt(0)
	s_waitcnt lgkmcnt(0)
	v_mfma_f32_16x16x32_bf16 v[92:95], v[20:23], v[224:227], v[92:95]
	v_mfma_f32_16x16x32_bf16 v[20:23], v[20:23], v[232:235], v[88:91]
	v_mfma_f32_16x16x32_bf16 v[88:91], v[200:203], v[224:227], v[176:179]
	v_mfma_f32_16x16x32_bf16 v[104:107], v[200:203], v[232:235], v[180:183]
	v_mfma_f32_16x16x32_bf16 v[76:79], v[208:211], v[224:227], v[76:79]
	v_mfma_f32_16x16x32_bf16 v[72:75], v[208:211], v[232:235], v[72:75]
	v_mfma_f32_16x16x32_bf16 v[174:177], v[216:219], v[224:227], v[184:187]
	v_mfma_f32_16x16x32_bf16 v[178:181], v[216:219], v[232:235], v[188:191]
	v_mfma_f32_16x16x32_bf16 v[124:127], v[196:199], v[228:231], v[92:95]
	v_mfma_f32_16x16x32_bf16 v[120:123], v[196:199], v[236:239], v[20:23]
	v_mfma_f32_16x16x32_bf16 v[108:111], v[204:207], v[228:231], v[88:91]
	v_mfma_f32_16x16x32_bf16 v[104:107], v[204:207], v[236:239], v[104:107]
	v_mfma_f32_16x16x32_bf16 v[92:95], v[212:215], v[228:231], v[76:79]
	v_mfma_f32_16x16x32_bf16 v[88:91], v[212:215], v[236:239], v[72:75]
	v_mfma_f32_16x16x32_bf16 v[76:79], v[220:223], v[228:231], v[174:177]
	v_mfma_f32_16x16x32_bf16 v[72:75], v[220:223], v[236:239], v[178:181]
	s_barrier
	ds_read_b128 v[174:177], v152 offset:49152
	ds_read_b128 v[152:155], v152 offset:50176
	ds_read_b128 v[178:181], v151 offset:49152
	ds_read_b128 v[182:185], v151 offset:50176
	ds_read_b128 v[186:189], v150 offset:49152
	ds_read_b128 v[196:199], v150 offset:50176
	ds_read_b128 v[200:203], v149 offset:49152
	ds_read_b128 v[204:207], v149 offset:50176
	s_barrier
	s_waitcnt lgkmcnt(0)
	s_waitcnt lgkmcnt(0)
	v_mfma_f32_16x16x32_bf16 v[20:23], v[174:177], v[0:3], v[60:63]
	v_mfma_f32_16x16x32_bf16 v[56:59], v[174:177], v[16:19], v[56:59]
	v_mfma_f32_16x16x32_bf16 v[60:63], v[178:181], v[0:3], v[52:55]
	v_mfma_f32_16x16x32_bf16 v[208:211], v[178:181], v[16:19], v[48:51]
	v_mfma_f32_16x16x32_bf16 v[44:47], v[186:189], v[0:3], v[44:47]
	v_mfma_f32_16x16x32_bf16 v[40:43], v[186:189], v[16:19], v[40:43]
	v_mfma_f32_16x16x32_bf16 v[0:3], v[200:203], v[0:3], v[36:39]
	v_mfma_f32_16x16x32_bf16 v[212:215], v[200:203], v[16:19], v[32:35]
	v_mfma_f32_16x16x32_bf16 v[52:55], v[152:155], v[4:7], v[20:23]
	v_mfma_f32_16x16x32_bf16 v[48:51], v[152:155], v[192:195], v[56:59]
	v_mfma_f32_16x16x32_bf16 v[36:39], v[182:185], v[4:7], v[60:63]
	v_mfma_f32_16x16x32_bf16 v[32:35], v[182:185], v[192:195], v[208:211]
	v_mfma_f32_16x16x32_bf16 v[20:23], v[196:199], v[4:7], v[44:47]
	v_mfma_f32_16x16x32_bf16 v[16:19], v[196:199], v[192:195], v[40:43]
	v_mfma_f32_16x16x32_bf16 v[4:7], v[204:207], v[4:7], v[0:3]
	v_mfma_f32_16x16x32_bf16 v[0:3], v[204:207], v[192:195], v[212:215]
	v_mfma_f32_16x16x32_bf16 v[28:31], v[174:177], v[224:227], v[28:31]
	v_mfma_f32_16x16x32_bf16 v[24:27], v[174:177], v[232:235], v[24:27]
	v_mfma_f32_16x16x32_bf16 v[40:43], v[178:181], v[224:227], v[134:137]
	v_mfma_f32_16x16x32_bf16 v[134:137], v[178:181], v[232:235], v[138:141]
	v_mfma_f32_16x16x32_bf16 v[12:15], v[186:189], v[224:227], v[12:15]
	v_mfma_f32_16x16x32_bf16 v[8:11], v[186:189], v[232:235], v[8:11]
	v_mfma_f32_16x16x32_bf16 v[138:141], v[200:203], v[224:227], v[156:159]
	v_mfma_f32_16x16x32_bf16 v[156:159], v[200:203], v[232:235], v[170:173]
	v_mfma_f32_16x16x32_bf16 v[60:63], v[152:155], v[228:231], v[28:31]
	v_mfma_f32_16x16x32_bf16 v[56:59], v[152:155], v[236:239], v[24:27]
	v_mfma_f32_16x16x32_bf16 v[44:47], v[182:185], v[228:231], v[40:43]
	v_mfma_f32_16x16x32_bf16 v[40:43], v[182:185], v[236:239], v[134:137]
	v_mfma_f32_16x16x32_bf16 v[28:31], v[196:199], v[228:231], v[12:15]
	v_mfma_f32_16x16x32_bf16 v[24:27], v[196:199], v[236:239], v[8:11]
	v_mfma_f32_16x16x32_bf16 v[12:15], v[204:207], v[228:231], v[138:141]
	v_mfma_f32_16x16x32_bf16 v[8:11], v[204:207], v[236:239], v[156:159]
	v_cmp_gt_u32_e32 vcc, s80, v130
	s_barrier
	s_and_saveexec_b64 s[60:61], vcc
	s_cbranch_execz .LBB0_1150
	s_barrier

; #define STAGE(P, BASE, LD, br, kt) do { const char* _g = (const char*)((BASE) + (size_t)(br) * (LD) + (size_t)(kt) * 64); \
;     for (int _i = 0; _i < 2; ++_i) { int _b = tidx * 16 + _i * 8192; int _r, _c; stage_rc(_b, _r, _c); \
;       __builtin_amdgcn_global_load_lds((const unsigned*)(_g + (unsigned)((_r * (LD) + _c) * 2)), (unsigned*)((char*)(P) + _b), 16, 0, 0); } } while (0)
; #define LDA(dst, b, h) for (int m = 0; m < 4; ++m) for (int k = 0; k < 2; ++k) \
;     dst[m][k] = *reinterpret_cast<const bf16x8*>((char*)SA(b, h) + lds_byte(wr * 64 + m * 16 + fr, k * 32 + fq * 8))
; #define LDB(dst, b, h) for (int n = 0; n < 2; ++n) for (int k = 0; k < 2; ++k) \
;     dst[n][k] = *reinterpret_cast<const bf16x8*>((char*)SB(b, h) + lds_byte(wc * 32 + n * 16 + fr, k * 32 + fq * 8))
; #define MMA(ai, bj, At_, Bt_) do { __builtin_amdgcn_s_setprio(1); \
;     for (int k = 0; k < 2; ++k) for (int m = 0; m < 4; ++m) for (int n = 0; n < 2; ++n) \
;       acc[ai][bj][m][n] = __builtin_amdgcn_mfma_f32_16x16x32_bf16(At_[m][k], Bt_[n][k], acc[ai][bj][m][n], 0, 0, 0); \
;     __builtin_amdgcn_s_setprio(0); } while (0)
; #define WAIT_V(n) asm volatile("s_waitcnt vmcnt(" #n ")" ::: "memory")
; #define WAIT_L(n) asm volatile("s_waitcnt lgkmcnt(" #n ")" ::: "memory")
; #define BAR __builtin_amdgcn_s_barrier()
; #define SCHED __builtin_amdgcn_sched_barrier(0)
; template <int EPI, int lda, int ldb, int N, int K>
; __device__ __forceinline__ void gemm_phase(const u16* __restrict__ A, const u16* __restrict__ Bt, const GemmEpi ep, int wv) {
;     ...
;     WAIT_V(4); BAR;
;     STAGE(SB(1, 0), Bt, ldb, bcol, 1); STAGE(SA(1, 0), Ab, lda, brow, 1); STAGE(SB(1, 1), Bt, ldb, bcol + HALF, 1);
;     WAIT_V(6); BAR;
;     for (int t = 0; t < nt - 2; t += 2) {
;       LDB(B0, 0, 0); SCHED; LDA(At, 0, 0); STAGE(SA(1, 1), Ab, lda, brow + HALF, t + 1);
;       WAIT_L(8); BAR; WAIT_L(0); MMA(0, 0, At, B0); BAR; SCHED;
;       LDB(B1, 0, 1); STAGE(SB(0, 0), Bt, ldb, bcol, t + 2);
;       BAR; WAIT_L(0); MMA(0, 1, At, B1); BAR;
.LBB0_1248:
	s_or_b64 exec, exec, s[54:55]
	v_mov_b32_e32 v1, v129
	v_add_u32_e32 v7, s60, v6
	v_lshl_add_u64 v[12:13], s[46:47], 0, v[128:129]
	v_lshl_add_u64 v[14:15], s[46:47], 0, v[0:1]
	v_lshl_add_u64 v[2:3], s[52:53], 0, v[128:129]
	v_lshl_add_u64 v[0:1], s[52:53], 0, v[0:1]
	v_readfirstlane_b32 s53, v7
	v_add_u32_e32 v7, 0x2000, v7
	v_mov_b32_e32 v5, v129
	v_mov_b32_e32 v17, v129
	v_lshl_add_u64 v[26:27], v[12:13], 0, s[40:41]
	s_mov_b32 m0, s53
	v_readfirstlane_b32 s52, v7
	v_add_u32_e32 v7, 0x8000, v23
	v_lshl_add_u64 v[8:9], s[50:51], 0, v[4:5]
	v_lshl_add_u64 v[10:11], s[50:51], 0, v[16:17]
	s_waitcnt vmcnt(4)
	s_barrier
	global_load_lds_dwordx4 v[26:27], off
	v_lshl_add_u64 v[26:27], v[14:15], 0, s[40:41]
	s_mov_b32 m0, s52
	v_readfirstlane_b32 s51, v7
	v_add_u32_e32 v7, 0xa000, v23
	global_load_lds_dwordx4 v[26:27], off
	v_lshl_add_u64 v[26:27], v[8:9], 0, s[40:41]
	s_mov_b32 m0, s51
	v_readfirstlane_b32 s50, v7
	v_add_u32_e32 v25, s61, v6
	global_load_lds_dwordx4 v[26:27], off
	v_lshl_add_u64 v[26:27], v[10:11], 0, s[40:41]
	s_mov_b32 m0, s50
	v_readfirstlane_b32 s13, v25
	v_add_u32_e32 v25, 0x2000, v25
	global_load_lds_dwordx4 v[26:27], off
	v_lshl_add_u64 v[26:27], v[2:3], 0, s[40:41]
	s_mov_b32 m0, s13
	v_readfirstlane_b32 s11, v25
	global_load_lds_dwordx4 v[26:27], off
	v_lshl_add_u64 v[6:7], v[0:1], 0, s[40:41]
	s_mov_b32 m0, s11
	v_and_b32_e32 v132, 15, v20
	global_load_lds_dwordx4 v[6:7], off
	v_bfe_u32 v128, v20, 4, 2
	v_lshlrev_b32_e32 v7, 2, v20
	v_bfe_u32 v131, v130, 6, 2
	v_lshlrev_b32_e32 v25, 4, v128
	v_lshlrev_b32_e32 v6, 6, v132
	v_and_b32_e32 v50, 32, v7
	v_lshlrev_b32_e32 v126, 12, v131
	v_bitop3_b32 v127, v25, v50, v6 bitop3:0x36
	v_add3_u32 v133, s58, v127, v126
	s_waitcnt vmcnt(6)
	s_barrier
	ds_read_b128 v[26:29], v133
	ds_read_b128 v[30:33], v133 offset:1024
	ds_read_b128 v[34:37], v133 offset:2048
	ds_read_b128 v[38:41], v133 offset:3072
	v_lshl_add_u64 v[6:7], s[48:49], 0, v[4:5]
	v_lshl_add_u64 v[4:5], s[48:49], 0, v[16:17]
	v_lshlrev_b32_e32 v17, 6, v20
	v_and_b32_e32 v17, 0x3c0, v17
	v_add_u32_e32 v20, 0xc000, v23
	v_lshlrev_b32_e32 v16, 13, v143
	v_bitop3_b32 v17, v17, v50, v25 bitop3:0x36
	v_readfirstlane_b32 s47, v20
	v_add_u32_e32 v20, 0xe000, v23
	v_add3_u32 v228, 0, v127, v16
	v_add3_u32 v229, 0, v17, v16
	v_lshl_add_u64 v[16:17], v[6:7], 0, s[40:41]
	s_mov_b32 m0, s47
	v_readfirstlane_b32 s46, v20
	ds_read_b128 v[42:45], v228
	ds_read_b128 v[46:49], v228 offset:1024
	ds_read_b128 v[50:53], v229 offset:2048
	ds_read_b128 v[54:57], v229 offset:3072
	ds_read_b128 v[58:61], v229 offset:4096
	ds_read_b128 v[62:65], v229 offset:5120
	ds_read_b128 v[66:69], v229 offset:6144
	ds_read_b128 v[70:73], v229 offset:7168
	global_load_lds_dwordx4 v[16:17], off
	v_lshl_add_u64 v[16:17], v[4:5], 0, s[40:41]
	s_mov_b32 m0, s46
	s_nop 0
	global_load_lds_dwordx4 v[16:17], off
	s_waitcnt lgkmcnt(8)
	s_barrier
	s_waitcnt lgkmcnt(0)
	s_waitcnt lgkmcnt(0)
	v_mfma_f32_16x16x32_bf16 v[74:77], v[42:45], v[26:29], 0
	v_mfma_f32_16x16x32_bf16 v[78:81], v[42:45], v[34:37], 0
	v_mfma_f32_16x16x32_bf16 v[82:85], v[50:53], v[26:29], 0
	v_mfma_f32_16x16x32_bf16 v[86:89], v[50:53], v[34:37], 0
	v_mfma_f32_16x16x32_bf16 v[90:93], v[58:61], v[26:29], 0
	v_mfma_f32_16x16x32_bf16 v[94:97], v[58:61], v[34:37], 0
	v_mfma_f32_16x16x32_bf16 v[98:101], v[66:69], v[26:29], 0
	v_mfma_f32_16x16x32_bf16 v[102:105], v[66:69], v[34:37], 0
	v_mfma_f32_16x16x32_bf16 v[74:77], v[46:49], v[30:33], v[74:77]
	v_mfma_f32_16x16x32_bf16 v[78:81], v[46:49], v[38:41], v[78:81]
	v_mfma_f32_16x16x32_bf16 v[82:85], v[54:57], v[30:33], v[82:85]
	v_mfma_f32_16x16x32_bf16 v[86:89], v[54:57], v[38:41], v[86:89]
	v_mfma_f32_16x16x32_bf16 v[90:93], v[62:65], v[30:33], v[90:93]
	v_mfma_f32_16x16x32_bf16 v[94:97], v[62:65], v[38:41], v[94:97]
	v_mfma_f32_16x16x32_bf16 v[98:101], v[70:73], v[30:33], v[98:101]
	v_mfma_f32_16x16x32_bf16 v[102:105], v[70:73], v[38:41], v[102:105]
	s_barrier
	v_readfirstlane_b32 s48, v21
	v_add_u32_e32 v20, 0x2000, v21
	v_add3_u32 v224, s59, v127, v126
	v_lshl_add_u64 v[16:17], v[12:13], 0, s[42:43]
	s_mov_b32 m0, s48
	v_readfirstlane_b32 s48, v20
	ds_read_b128 v[106:109], v224
	ds_read_b128 v[110:113], v224 offset:1024
	ds_read_b128 v[114:117], v224 offset:2048
	ds_read_b128 v[118:121], v224 offset:3072
	global_load_lds_dwordx4 v[16:17], off
	v_lshl_add_u64 v[16:17], v[14:15], 0, s[42:43]
	s_mov_b32 m0, s48
	s_nop 0
	global_load_lds_dwordx4 v[16:17], off
	s_barrier
	s_waitcnt lgkmcnt(0)
	s_waitcnt lgkmcnt(0)
	v_mfma_f32_16x16x32_bf16 v[122:125], v[42:45], v[106:109], 0
	v_mfma_f32_16x16x32_bf16 v[42:45], v[42:45], v[114:117], 0
	v_mfma_f32_16x16x32_bf16 v[134:137], v[50:53], v[106:109], 0
	v_mfma_f32_16x16x32_bf16 v[50:53], v[50:53], v[114:117], 0
	v_mfma_f32_16x16x32_bf16 v[144:147], v[58:61], v[106:109], 0
	v_mfma_f32_16x16x32_bf16 v[58:61], v[58:61], v[114:117], 0
	v_mfma_f32_16x16x32_bf16 v[148:151], v[66:69], v[106:109], 0
	v_mfma_f32_16x16x32_bf16 v[66:69], v[66:69], v[114:117], 0
	v_mfma_f32_16x16x32_bf16 v[122:125], v[46:49], v[110:113], v[122:125]
	v_mfma_f32_16x16x32_bf16 v[42:45], v[46:49], v[118:121], v[42:45]
	v_mfma_f32_16x16x32_bf16 v[46:49], v[54:57], v[110:113], v[134:137]
	v_mfma_f32_16x16x32_bf16 v[50:53], v[54:57], v[118:121], v[50:53]
	v_mfma_f32_16x16x32_bf16 v[54:57], v[62:65], v[110:113], v[144:147]
	v_mfma_f32_16x16x32_bf16 v[58:61], v[62:65], v[118:121], v[58:61]
	v_mfma_f32_16x16x32_bf16 v[62:65], v[70:73], v[110:113], v[148:151]
	v_mfma_f32_16x16x32_bf16 v[66:69], v[70:73], v[118:121], v[66:69]
	v_readfirstlane_b32 s48, v23
	v_lshl_add_u64 v[16:17], v[8:9], 0, s[42:43]
	s_mov_b32 m0, s48
	v_readfirstlane_b32 s48, v24
	s_barrier
; #define STAGE(P, BASE, LD, br, kt) do { const char* _g = (const char*)((BASE) + (size_t)(br) * (LD) + (size_t)(kt) * 64); \
;     for (int _i = 0; _i < 2; ++_i) { int _b = tidx * 16 + _i * 8192; int _r, _c; stage_rc(_b, _r, _c); \
;       __builtin_amdgcn_global_load_lds((const unsigned*)(_g + (unsigned)((_r * (LD) + _c) * 2)), (unsigned*)((char*)(P) + _b), 16, 0, 0); } } while (0)
; #define LDA(dst, b, h) for (int m = 0; m < 4; ++m) for (int k = 0; k < 2; ++k) \
;     dst[m][k] = *reinterpret_cast<const bf16x8*>((char*)SA(b, h) + lds_byte(wr * 64 + m * 16 + fr, k * 32 + fq * 8))
; #define LDB(dst, b, h) for (int n = 0; n < 2; ++n) for (int k = 0; k < 2; ++k) \
;     dst[n][k] = *reinterpret_cast<const bf16x8*>((char*)SB(b, h) + lds_byte(wc * 32 + n * 16 + fr, k * 32 + fq * 8))
; #define MMA(ai, bj, At_, Bt_) do { __builtin_amdgcn_s_setprio(1); \
;     for (int k = 0; k < 2; ++k) for (int m = 0; m < 4; ++m) for (int n = 0; n < 2; ++n) \
;       acc[ai][bj][m][n] = __builtin_amdgcn_mfma_f32_16x16x32_bf16(At_[m][k], Bt_[n][k], acc[ai][bj][m][n], 0, 0, 0); \
;     __builtin_amdgcn_s_setprio(0); } while (0)
; #define WAIT_V(n) asm volatile("s_waitcnt vmcnt(" #n ")" ::: "memory")
; #define WAIT_L(n) asm volatile("s_waitcnt lgkmcnt(" #n ")" ::: "memory")
; #define BAR __builtin_amdgcn_s_barrier()
; #define SCHED __builtin_amdgcn_sched_barrier(0)
; template <int EPI, int lda, int ldb, int N, int K>
; __device__ __forceinline__ void gemm_phase(const u16* __restrict__ A, const u16* __restrict__ Bt, const GemmEpi ep, int wv) {
;     ...
;       LDA(At, 0, 1); STAGE(SA(0, 0), Ab, lda, brow, t + 2);
;       BAR; WAIT_L(0); MMA(1, 0, At, B0); BAR; SCHED;
;       STAGE(SB(0, 1), Bt, ldb, bcol + HALF, t + 2);
;       WAIT_V(6); BAR; MMA(1, 1, At, B1); BAR;
;       LDB(B0, 1, 0); SCHED; LDA(At, 1, 0); STAGE(SA(0, 1), Ab, lda, brow + HALF, t + 2);
;       WAIT_L(8); BAR; WAIT_L(0); MMA(0, 0, At, B0); BAR; SCHED;
;       LDB(B1, 1, 1); STAGE(SB(1, 0), Bt, ldb, bcol, t + 3);
	ds_read_b128 v[70:73], v228 offset:16384
	ds_read_b128 v[134:137], v228 offset:17408
	ds_read_b128 v[144:147], v229 offset:18432
	ds_read_b128 v[148:151], v229 offset:19456
	ds_read_b128 v[152:155], v229 offset:20480
	ds_read_b128 v[156:159], v229 offset:21504
	ds_read_b128 v[160:163], v229 offset:22528
	ds_read_b128 v[164:167], v229 offset:23552
	global_load_lds_dwordx4 v[16:17], off
	v_lshl_add_u64 v[16:17], v[10:11], 0, s[42:43]
	s_mov_b32 m0, s48
	s_nop 0
	global_load_lds_dwordx4 v[16:17], off
	s_barrier
	s_waitcnt lgkmcnt(0)
	s_waitcnt lgkmcnt(0)
	v_mfma_f32_16x16x32_bf16 v[168:171], v[70:73], v[26:29], 0
	v_mfma_f32_16x16x32_bf16 v[172:175], v[70:73], v[34:37], 0
	v_mfma_f32_16x16x32_bf16 v[176:179], v[144:147], v[26:29], 0
	v_mfma_f32_16x16x32_bf16 v[180:183], v[144:147], v[34:37], 0
	v_mfma_f32_16x16x32_bf16 v[184:187], v[152:155], v[26:29], 0
	v_mfma_f32_16x16x32_bf16 v[188:191], v[152:155], v[34:37], 0
	v_mfma_f32_16x16x32_bf16 v[24:27], v[160:163], v[26:29], 0
	v_mfma_f32_16x16x32_bf16 v[34:37], v[160:163], v[34:37], 0
	v_mfma_f32_16x16x32_bf16 v[168:171], v[134:137], v[30:33], v[168:171]
	v_mfma_f32_16x16x32_bf16 v[176:179], v[148:151], v[30:33], v[176:179]
	v_mfma_f32_16x16x32_bf16 v[184:187], v[156:159], v[30:33], v[184:187]
	v_mfma_f32_16x16x32_bf16 v[24:27], v[164:167], v[30:33], v[24:27]
	v_mfma_f32_16x16x32_bf16 v[28:31], v[164:167], v[38:41], v[34:37]
	v_mfma_f32_16x16x32_bf16 v[172:175], v[134:137], v[38:41], v[172:175]
	v_mfma_f32_16x16x32_bf16 v[180:183], v[148:151], v[38:41], v[180:183]
	v_mfma_f32_16x16x32_bf16 v[188:191], v[156:159], v[38:41], v[188:191]
	s_barrier
	v_readfirstlane_b32 s48, v22
	v_add_u32_e32 v20, 0x2000, v22
	v_lshl_add_u64 v[16:17], v[2:3], 0, s[42:43]
	s_mov_b32 m0, s48
	v_readfirstlane_b32 s48, v20
	global_load_lds_dwordx4 v[16:17], off
	v_lshl_add_u64 v[16:17], v[0:1], 0, s[42:43]
	s_mov_b32 m0, s48
	s_nop 0
	global_load_lds_dwordx4 v[16:17], off
	s_waitcnt vmcnt(6)
	s_barrier
	v_mfma_f32_16x16x32_bf16 v[20:23], v[70:73], v[106:109], 0
	v_mfma_f32_16x16x32_bf16 v[32:35], v[70:73], v[114:117], 0
	v_mfma_f32_16x16x32_bf16 v[36:39], v[144:147], v[106:109], 0
	v_mfma_f32_16x16x32_bf16 v[70:73], v[144:147], v[114:117], 0
	v_mfma_f32_16x16x32_bf16 v[144:147], v[152:155], v[106:109], 0
	v_mfma_f32_16x16x32_bf16 v[152:155], v[152:155], v[114:117], 0
	v_mfma_f32_16x16x32_bf16 v[106:109], v[160:163], v[106:109], 0
	v_mfma_f32_16x16x32_bf16 v[114:117], v[160:163], v[114:117], 0
	v_mfma_f32_16x16x32_bf16 v[20:23], v[134:137], v[110:113], v[20:23]
	v_mfma_f32_16x16x32_bf16 v[32:35], v[134:137], v[118:121], v[32:35]
	v_mfma_f32_16x16x32_bf16 v[36:39], v[148:151], v[110:113], v[36:39]
	v_mfma_f32_16x16x32_bf16 v[70:73], v[148:151], v[118:121], v[70:73]
	v_mfma_f32_16x16x32_bf16 v[134:137], v[156:159], v[110:113], v[144:147]
	v_mfma_f32_16x16x32_bf16 v[106:109], v[164:167], v[110:113], v[106:109]
	v_mfma_f32_16x16x32_bf16 v[110:113], v[164:167], v[118:121], v[114:117]
	v_mfma_f32_16x16x32_bf16 v[144:147], v[156:159], v[118:121], v[152:155]
	v_add3_u32 v225, s60, v127, v126
	s_barrier
	ds_read_b128 v[114:117], v225
	ds_read_b128 v[118:121], v225 offset:1024
	ds_read_b128 v[148:151], v225 offset:2048
	ds_read_b128 v[152:155], v225 offset:3072
	v_readfirstlane_b32 s48, v18
	v_lshl_add_u64 v[16:17], v[6:7], 0, s[42:43]
	s_mov_b32 m0, s48
	v_readfirstlane_b32 s48, v19
	ds_read_b128 v[156:159], v228 offset:32768
	ds_read_b128 v[160:163], v228 offset:33792
	ds_read_b128 v[164:167], v229 offset:34816
	ds_read_b128 v[192:195], v229 offset:35840
	ds_read_b128 v[196:199], v229 offset:36864
	ds_read_b128 v[200:203], v229 offset:37888
	ds_read_b128 v[204:207], v229 offset:38912
	ds_read_b128 v[208:211], v229 offset:39936
	global_load_lds_dwordx4 v[16:17], off
	v_lshl_add_u64 v[16:17], v[4:5], 0, s[42:43]
	s_mov_b32 m0, s48
	s_nop 0
	global_load_lds_dwordx4 v[16:17], off
	s_waitcnt lgkmcnt(8)
	s_barrier
	s_waitcnt lgkmcnt(0)
	s_waitcnt lgkmcnt(0)
	v_mfma_f32_16x16x32_bf16 v[16:19], v[156:159], v[114:117], v[74:77]
	v_mfma_f32_16x16x32_bf16 v[74:77], v[156:159], v[148:151], v[78:81]
	v_mfma_f32_16x16x32_bf16 v[78:81], v[164:167], v[114:117], v[82:85]
	v_mfma_f32_16x16x32_bf16 v[82:85], v[164:167], v[148:151], v[86:89]
	v_mfma_f32_16x16x32_bf16 v[86:89], v[196:199], v[114:117], v[90:93]
	v_mfma_f32_16x16x32_bf16 v[90:93], v[196:199], v[148:151], v[94:97]
	v_mfma_f32_16x16x32_bf16 v[94:97], v[204:207], v[114:117], v[98:101]
	v_mfma_f32_16x16x32_bf16 v[98:101], v[204:207], v[148:151], v[102:105]
	v_mfma_f32_16x16x32_bf16 v[16:19], v[160:163], v[118:121], v[16:19]
	v_mfma_f32_16x16x32_bf16 v[74:77], v[160:163], v[152:155], v[74:77]
	v_mfma_f32_16x16x32_bf16 v[78:81], v[192:195], v[118:121], v[78:81]
	v_mfma_f32_16x16x32_bf16 v[82:85], v[192:195], v[152:155], v[82:85]
	v_mfma_f32_16x16x32_bf16 v[86:89], v[200:203], v[118:121], v[86:89]
	v_mfma_f32_16x16x32_bf16 v[90:93], v[200:203], v[152:155], v[90:93]
	v_mfma_f32_16x16x32_bf16 v[94:97], v[208:211], v[118:121], v[94:97]
	v_mfma_f32_16x16x32_bf16 v[98:101], v[208:211], v[152:155], v[98:101]
	s_barrier
	s_mov_b32 m0, s53
	v_add3_u32 v226, s61, v127, v126
	v_lshl_add_u64 v[12:13], v[12:13], 0, s[44:45]
	ds_read_b128 v[102:105], v226
	ds_read_b128 v[212:215], v226 offset:1024
	ds_read_b128 v[216:219], v226 offset:2048
	ds_read_b128 v[220:223], v226 offset:3072
	global_load_lds_dwordx4 v[12:13], off
	v_lshl_add_u64 v[12:13], v[14:15], 0, s[44:45]
	s_mov_b32 m0, s52
	s_nop 0
	global_load_lds_dwordx4 v[12:13], off
	s_barrier
; #define STAGE(P, BASE, LD, br, kt) do { const char* _g = (const char*)((BASE) + (size_t)(br) * (LD) + (size_t)(kt) * 64); \
;     for (int _i = 0; _i < 2; ++_i) { int _b = tidx * 16 + _i * 8192; int _r, _c; stage_rc(_b, _r, _c); \
;       __builtin_amdgcn_global_load_lds((const unsigned*)(_g + (unsigned)((_r * (LD) + _c) * 2)), (unsigned*)((char*)(P) + _b), 16, 0, 0); } } while (0)
; #define LDA(dst, b, h) for (int m = 0; m < 4; ++m) for (int k = 0; k < 2; ++k) \
;     dst[m][k] = *reinterpret_cast<const bf16x8*>((char*)SA(b, h) + lds_byte(wr * 64 + m * 16 + fr, k * 32 + fq * 8))
; #define LDB(dst, b, h) for (int n = 0; n < 2; ++n) for (int k = 0; k < 2; ++k) \
;     dst[n][k] = *reinterpret_cast<const bf16x8*>((char*)SB(b, h) + lds_byte(wc * 32 + n * 16 + fr, k * 32 + fq * 8))
; #define MMA(ai, bj, At_, Bt_) do { __builtin_amdgcn_s_setprio(1); \
;     for (int k = 0; k < 2; ++k) for (int m = 0; m < 4; ++m) for (int n = 0; n < 2; ++n) \
;       acc[ai][bj][m][n] = __builtin_amdgcn_mfma_f32_16x16x32_bf16(At_[m][k], Bt_[n][k], acc[ai][bj][m][n], 0, 0, 0); \
;     __builtin_amdgcn_s_setprio(0); } while (0)
; #define WAIT_V(n) asm volatile("s_waitcnt vmcnt(" #n ")" ::: "memory")
; #define WAIT_L(n) asm volatile("s_waitcnt lgkmcnt(" #n ")" ::: "memory")
; #define BAR __builtin_amdgcn_s_barrier()
; #define SCHED __builtin_amdgcn_sched_barrier(0)
; template <int EPI, int lda, int ldb, int N, int K>
; __device__ __forceinline__ void gemm_phase(const u16* __restrict__ A, const u16* __restrict__ Bt, const GemmEpi ep, int wv) {
;     ...
;       BAR; WAIT_L(0); MMA(0, 1, At, B1); BAR;
;       LDA(At, 1, 1); STAGE(SA(1, 0), Ab, lda, brow, t + 3);
;       BAR; WAIT_L(0); MMA(1, 0, At, B0); BAR; SCHED;
;       STAGE(SB(1, 1), Bt, ldb, bcol + HALF, t + 3);
;       WAIT_V(6); BAR; MMA(1, 1, At, B1); BAR;
;     }
;     { LDB(B0, 0, 0); LDA(At, 0, 0); STAGE(SA(1, 1), Ab, lda, brow + HALF, nt - 1);
;       BAR; WAIT_L(0); MMA(0, 0, At, B0); BAR;
	s_waitcnt lgkmcnt(0)
	s_waitcnt lgkmcnt(0)
	v_mfma_f32_16x16x32_bf16 v[12:15], v[156:159], v[102:105], v[122:125]
	v_mfma_f32_16x16x32_bf16 v[40:43], v[156:159], v[216:219], v[42:45]
	v_mfma_f32_16x16x32_bf16 v[44:47], v[164:167], v[102:105], v[46:49]
	v_mfma_f32_16x16x32_bf16 v[48:51], v[164:167], v[216:219], v[50:53]
	v_mfma_f32_16x16x32_bf16 v[52:55], v[196:199], v[102:105], v[54:57]
	v_mfma_f32_16x16x32_bf16 v[56:59], v[196:199], v[216:219], v[58:61]
	v_mfma_f32_16x16x32_bf16 v[60:63], v[204:207], v[102:105], v[62:65]
	v_mfma_f32_16x16x32_bf16 v[64:67], v[204:207], v[216:219], v[66:69]
	v_mfma_f32_16x16x32_bf16 v[12:15], v[160:163], v[212:215], v[12:15]
	v_mfma_f32_16x16x32_bf16 v[40:43], v[160:163], v[220:223], v[40:43]
	v_mfma_f32_16x16x32_bf16 v[44:47], v[192:195], v[212:215], v[44:47]
	v_mfma_f32_16x16x32_bf16 v[48:51], v[192:195], v[220:223], v[48:51]
	v_mfma_f32_16x16x32_bf16 v[52:55], v[200:203], v[212:215], v[52:55]
	v_mfma_f32_16x16x32_bf16 v[56:59], v[200:203], v[220:223], v[56:59]
	v_mfma_f32_16x16x32_bf16 v[60:63], v[208:211], v[212:215], v[60:63]
	v_mfma_f32_16x16x32_bf16 v[64:67], v[208:211], v[220:223], v[64:67]
	s_mov_b32 m0, s51
	v_lshl_add_u64 v[8:9], v[8:9], 0, s[44:45]
	s_barrier
	ds_read_b128 v[122:125], v228 offset:49152
	ds_read_b128 v[156:159], v228 offset:50176
	ds_read_b128 v[160:163], v229 offset:51200
	ds_read_b128 v[164:167], v229 offset:52224
	ds_read_b128 v[192:195], v229 offset:53248
	ds_read_b128 v[196:199], v229 offset:54272
	ds_read_b128 v[200:203], v229 offset:55296
	ds_read_b128 v[204:207], v229 offset:56320
	global_load_lds_dwordx4 v[8:9], off
	v_lshl_add_u64 v[8:9], v[10:11], 0, s[44:45]
	s_mov_b32 m0, s50
	s_nop 0
	global_load_lds_dwordx4 v[8:9], off
	s_barrier
	s_waitcnt lgkmcnt(0)
	s_waitcnt lgkmcnt(0)
	v_mfma_f32_16x16x32_bf16 v[8:11], v[122:125], v[114:117], v[168:171]
	v_mfma_f32_16x16x32_bf16 v[168:171], v[122:125], v[148:151], v[172:175]
	v_mfma_f32_16x16x32_bf16 v[24:27], v[200:203], v[114:117], v[24:27]
	v_mfma_f32_16x16x32_bf16 v[28:31], v[200:203], v[148:151], v[28:31]
	v_mfma_f32_16x16x32_bf16 v[172:175], v[160:163], v[114:117], v[176:179]
	v_mfma_f32_16x16x32_bf16 v[176:179], v[160:163], v[148:151], v[180:183]
	v_mfma_f32_16x16x32_bf16 v[180:183], v[192:195], v[114:117], v[184:187]
	v_mfma_f32_16x16x32_bf16 v[184:187], v[192:195], v[148:151], v[188:191]
	v_mfma_f32_16x16x32_bf16 v[8:11], v[156:159], v[118:121], v[8:11]
	v_mfma_f32_16x16x32_bf16 v[114:117], v[156:159], v[152:155], v[168:171]
	v_mfma_f32_16x16x32_bf16 v[24:27], v[204:207], v[118:121], v[24:27]
	v_mfma_f32_16x16x32_bf16 v[28:31], v[204:207], v[152:155], v[28:31]
	v_mfma_f32_16x16x32_bf16 v[148:151], v[164:167], v[118:121], v[172:175]
	v_mfma_f32_16x16x32_bf16 v[168:171], v[164:167], v[152:155], v[176:179]
	v_mfma_f32_16x16x32_bf16 v[172:175], v[196:199], v[118:121], v[180:183]
	v_mfma_f32_16x16x32_bf16 v[176:179], v[196:199], v[152:155], v[184:187]
	s_barrier
	s_mov_b32 m0, s13
	v_lshl_add_u64 v[2:3], v[2:3], 0, s[44:45]
	global_load_lds_dwordx4 v[2:3], off
	v_lshl_add_u64 v[0:1], v[0:1], 0, s[44:45]
	s_mov_b32 m0, s11
	s_nop 0
	global_load_lds_dwordx4 v[0:1], off
	s_waitcnt vmcnt(6)
	s_barrier
	v_mfma_f32_16x16x32_bf16 v[0:3], v[122:125], v[102:105], v[20:23]
	v_mfma_f32_16x16x32_bf16 v[20:23], v[122:125], v[216:219], v[32:35]
	v_mfma_f32_16x16x32_bf16 v[32:35], v[160:163], v[102:105], v[36:39]
	v_mfma_f32_16x16x32_bf16 v[36:39], v[160:163], v[216:219], v[70:73]
	v_mfma_f32_16x16x32_bf16 v[68:71], v[192:195], v[102:105], v[134:137]
	v_mfma_f32_16x16x32_bf16 v[118:121], v[192:195], v[216:219], v[144:147]
	v_mfma_f32_16x16x32_bf16 v[102:105], v[200:203], v[102:105], v[106:109]
	v_mfma_f32_16x16x32_bf16 v[106:109], v[200:203], v[216:219], v[110:113]
	v_mfma_f32_16x16x32_bf16 v[0:3], v[156:159], v[212:215], v[0:3]
	v_mfma_f32_16x16x32_bf16 v[20:23], v[156:159], v[220:223], v[20:23]
	v_mfma_f32_16x16x32_bf16 v[32:35], v[164:167], v[212:215], v[32:35]
	v_mfma_f32_16x16x32_bf16 v[36:39], v[164:167], v[220:223], v[36:39]
	v_mfma_f32_16x16x32_bf16 v[68:71], v[196:199], v[212:215], v[68:71]
	v_mfma_f32_16x16x32_bf16 v[110:113], v[196:199], v[220:223], v[118:121]
	v_mfma_f32_16x16x32_bf16 v[102:105], v[204:207], v[212:215], v[102:105]
	v_mfma_f32_16x16x32_bf16 v[106:109], v[204:207], v[220:223], v[106:109]
	s_mov_b32 m0, s47
	v_lshl_add_u64 v[6:7], v[6:7], 0, s[44:45]
	s_barrier
	ds_read_b128 v[118:121], v133
	ds_read_b128 v[122:125], v133 offset:1024
	ds_read_b128 v[134:137], v133 offset:2048
	ds_read_b128 v[144:147], v133 offset:3072
	ds_read_b128 v[152:155], v228
	ds_read_b128 v[156:159], v228 offset:1024
	ds_read_b128 v[160:163], v229 offset:2048
	ds_read_b128 v[164:167], v229 offset:3072
	ds_read_b128 v[180:183], v229 offset:4096
	ds_read_b128 v[184:187], v229 offset:5120
	ds_read_b128 v[188:191], v229 offset:6144
	ds_read_b128 v[192:195], v229 offset:7168
	global_load_lds_dwordx4 v[6:7], off
	v_lshl_add_u64 v[4:5], v[4:5], 0, s[44:45]
	s_mov_b32 m0, s46
	s_nop 0
	global_load_lds_dwordx4 v[4:5], off
	s_barrier
	s_waitcnt lgkmcnt(0)
	s_waitcnt lgkmcnt(0)
	v_mfma_f32_16x16x32_bf16 v[4:7], v[152:155], v[118:121], v[16:19]
	v_mfma_f32_16x16x32_bf16 v[16:19], v[152:155], v[134:137], v[74:77]
	v_mfma_f32_16x16x32_bf16 v[72:75], v[160:163], v[118:121], v[78:81]
	v_mfma_f32_16x16x32_bf16 v[76:79], v[160:163], v[134:137], v[82:85]
	v_mfma_f32_16x16x32_bf16 v[80:83], v[180:183], v[118:121], v[86:89]
	v_mfma_f32_16x16x32_bf16 v[84:87], v[180:183], v[134:137], v[90:93]
	v_mfma_f32_16x16x32_bf16 v[88:91], v[188:191], v[118:121], v[94:97]
	v_mfma_f32_16x16x32_bf16 v[92:95], v[188:191], v[134:137], v[98:101]
	v_mfma_f32_16x16x32_bf16 v[4:7], v[156:159], v[122:125], v[4:7]
	v_mfma_f32_16x16x32_bf16 v[16:19], v[156:159], v[144:147], v[16:19]
	v_mfma_f32_16x16x32_bf16 v[72:75], v[164:167], v[122:125], v[72:75]
	v_mfma_f32_16x16x32_bf16 v[76:79], v[164:167], v[144:147], v[76:79]
	v_mfma_f32_16x16x32_bf16 v[80:83], v[184:187], v[122:125], v[80:83]
	v_mfma_f32_16x16x32_bf16 v[84:87], v[184:187], v[144:147], v[84:87]
	v_mfma_f32_16x16x32_bf16 v[88:91], v[192:195], v[122:125], v[88:91]
	v_mfma_f32_16x16x32_bf16 v[92:95], v[192:195], v[144:147], v[92:95]
	s_barrier
; #define LDA(dst, b, h) for (int m = 0; m < 4; ++m) for (int k = 0; k < 2; ++k) \
;     dst[m][k] = *reinterpret_cast<const bf16x8*>((char*)SA(b, h) + lds_byte(wr * 64 + m * 16 + fr, k * 32 + fq * 8))
; #define LDB(dst, b, h) for (int n = 0; n < 2; ++n) for (int k = 0; k < 2; ++k) \
;     dst[n][k] = *reinterpret_cast<const bf16x8*>((char*)SB(b, h) + lds_byte(wc * 32 + n * 16 + fr, k * 32 + fq * 8))
; #define MMA(ai, bj, At_, Bt_) do { __builtin_amdgcn_s_setprio(1); \
;     for (int k = 0; k < 2; ++k) for (int m = 0; m < 4; ++m) for (int n = 0; n < 2; ++n) \
;       acc[ai][bj][m][n] = __builtin_amdgcn_mfma_f32_16x16x32_bf16(At_[m][k], Bt_[n][k], acc[ai][bj][m][n], 0, 0, 0); \
;     __builtin_amdgcn_s_setprio(0); } while (0)
; #define WAIT_V(n) asm volatile("s_waitcnt vmcnt(" #n ")" ::: "memory")
; #define WAIT_L(n) asm volatile("s_waitcnt lgkmcnt(" #n ")" ::: "memory")
; #define BAR __builtin_amdgcn_s_barrier()
; template <int EPI, int lda, int ldb, int N, int K>
; __device__ __forceinline__ void gemm_phase(const u16* __restrict__ A, const u16* __restrict__ Bt, const GemmEpi ep, int wv) {
;     ...
;       LDB(B1, 0, 1); BAR; WAIT_L(0); MMA(0, 1, At, B1); BAR;
;       LDA(At, 0, 1); WAIT_V(4); BAR; WAIT_L(0); MMA(1, 0, At, B0); MMA(1, 1, At, B1); BAR; }
;     { LDB(B0, 1, 0); LDA(At, 1, 0); WAIT_V(2); BAR; WAIT_L(0); MMA(0, 0, At, B0); BAR;
	ds_read_b128 v[96:99], v224
	ds_read_b128 v[196:199], v224 offset:1024
	ds_read_b128 v[200:203], v224 offset:2048
	ds_read_b128 v[204:207], v224 offset:3072
	s_barrier
	s_waitcnt lgkmcnt(0)
	s_waitcnt lgkmcnt(0)
	v_mfma_f32_16x16x32_bf16 v[12:15], v[152:155], v[96:99], v[12:15]
	v_mfma_f32_16x16x32_bf16 v[40:43], v[152:155], v[200:203], v[40:43]
	v_mfma_f32_16x16x32_bf16 v[52:55], v[180:183], v[96:99], v[52:55]
	v_mfma_f32_16x16x32_bf16 v[56:59], v[180:183], v[200:203], v[56:59]
	v_mfma_f32_16x16x32_bf16 v[64:67], v[188:191], v[200:203], v[64:67]
	v_mfma_f32_16x16x32_bf16 v[44:47], v[160:163], v[96:99], v[44:47]
	v_mfma_f32_16x16x32_bf16 v[48:51], v[160:163], v[200:203], v[48:51]
	v_mfma_f32_16x16x32_bf16 v[60:63], v[188:191], v[96:99], v[60:63]
	v_mfma_f32_16x16x32_bf16 v[12:15], v[156:159], v[196:199], v[12:15]
	v_mfma_f32_16x16x32_bf16 v[40:43], v[156:159], v[204:207], v[40:43]
	v_mfma_f32_16x16x32_bf16 v[52:55], v[184:187], v[196:199], v[52:55]
	v_mfma_f32_16x16x32_bf16 v[56:59], v[184:187], v[204:207], v[56:59]
	v_mfma_f32_16x16x32_bf16 v[64:67], v[192:195], v[204:207], v[64:67]
	v_mfma_f32_16x16x32_bf16 v[152:155], v[164:167], v[196:199], v[44:47]
	v_mfma_f32_16x16x32_bf16 v[156:159], v[164:167], v[204:207], v[48:51]
	v_mfma_f32_16x16x32_bf16 v[160:163], v[192:195], v[196:199], v[60:63]
	s_barrier
	ds_read_b128 v[44:47], v228 offset:16384
	ds_read_b128 v[48:51], v228 offset:17408
	ds_read_b128 v[60:63], v229 offset:18432
	ds_read_b128 v[164:167], v229 offset:19456
	ds_read_b128 v[180:183], v229 offset:20480
	ds_read_b128 v[184:187], v229 offset:21504
	ds_read_b128 v[188:191], v229 offset:22528
	ds_read_b128 v[192:195], v229 offset:23552
	s_waitcnt vmcnt(4)
	s_barrier
	s_waitcnt lgkmcnt(0)
	s_waitcnt lgkmcnt(0)
	v_mfma_f32_16x16x32_bf16 v[8:11], v[44:47], v[118:121], v[8:11]
	v_mfma_f32_16x16x32_bf16 v[24:27], v[188:191], v[118:121], v[24:27]
	v_mfma_f32_16x16x32_bf16 v[28:31], v[188:191], v[134:137], v[28:31]
	v_mfma_f32_16x16x32_bf16 v[114:117], v[44:47], v[134:137], v[114:117]
	v_mfma_f32_16x16x32_bf16 v[148:151], v[60:63], v[118:121], v[148:151]
	v_mfma_f32_16x16x32_bf16 v[168:171], v[60:63], v[134:137], v[168:171]
	v_mfma_f32_16x16x32_bf16 v[172:175], v[180:183], v[118:121], v[172:175]
	v_mfma_f32_16x16x32_bf16 v[176:179], v[180:183], v[134:137], v[176:179]
	v_mfma_f32_16x16x32_bf16 v[8:11], v[48:51], v[122:125], v[8:11]
	v_mfma_f32_16x16x32_bf16 v[24:27], v[192:195], v[122:125], v[24:27]
	v_mfma_f32_16x16x32_bf16 v[28:31], v[192:195], v[144:147], v[28:31]
	v_mfma_f32_16x16x32_bf16 v[134:137], v[48:51], v[144:147], v[114:117]
	v_mfma_f32_16x16x32_bf16 v[148:151], v[164:167], v[122:125], v[148:151]
	v_mfma_f32_16x16x32_bf16 v[168:171], v[164:167], v[144:147], v[168:171]
	v_mfma_f32_16x16x32_bf16 v[172:175], v[184:187], v[122:125], v[172:175]
	v_mfma_f32_16x16x32_bf16 v[176:179], v[184:187], v[144:147], v[176:179]
	v_mfma_f32_16x16x32_bf16 v[0:3], v[44:47], v[96:99], v[0:3]
	v_mfma_f32_16x16x32_bf16 v[20:23], v[44:47], v[200:203], v[20:23]
	v_mfma_f32_16x16x32_bf16 v[44:47], v[180:183], v[96:99], v[68:71]
	v_mfma_f32_16x16x32_bf16 v[68:71], v[188:191], v[96:99], v[102:105]
	v_mfma_f32_16x16x32_bf16 v[32:35], v[60:63], v[96:99], v[32:35]
	v_mfma_f32_16x16x32_bf16 v[36:39], v[60:63], v[200:203], v[36:39]
	v_mfma_f32_16x16x32_bf16 v[60:63], v[180:183], v[200:203], v[110:113]
	v_mfma_f32_16x16x32_bf16 v[96:99], v[188:191], v[200:203], v[106:109]
	v_mfma_f32_16x16x32_bf16 v[20:23], v[48:51], v[204:207], v[20:23]
	v_mfma_f32_16x16x32_bf16 v[68:71], v[192:195], v[196:199], v[68:71]
	v_mfma_f32_16x16x32_bf16 v[144:147], v[48:51], v[196:199], v[0:3]
	v_mfma_f32_16x16x32_bf16 v[180:183], v[164:167], v[196:199], v[32:35]
	v_mfma_f32_16x16x32_bf16 v[164:167], v[164:167], v[204:207], v[36:39]
	v_mfma_f32_16x16x32_bf16 v[188:191], v[184:187], v[196:199], v[44:47]
	v_mfma_f32_16x16x32_bf16 v[184:187], v[184:187], v[204:207], v[60:63]
	v_mfma_f32_16x16x32_bf16 v[192:195], v[192:195], v[204:207], v[96:99]
	s_barrier
	ds_read_b128 v[0:3], v225
	ds_read_b128 v[196:199], v225 offset:1024
	ds_read_b128 v[200:203], v225 offset:2048
	ds_read_b128 v[204:207], v225 offset:3072
	ds_read_b128 v[36:39], v228 offset:32768
	ds_read_b128 v[100:103], v228 offset:33792
	ds_read_b128 v[108:111], v229 offset:34816
	ds_read_b128 v[208:211], v229 offset:35840
	ds_read_b128 v[116:119], v229 offset:36864
	ds_read_b128 v[212:215], v229 offset:37888
	ds_read_b128 v[124:127], v229 offset:38912
	ds_read_b128 v[216:219], v229 offset:39936
	s_waitcnt vmcnt(2)
	s_barrier
; #define LDA(dst, b, h) for (int m = 0; m < 4; ++m) for (int k = 0; k < 2; ++k) \
;     dst[m][k] = *reinterpret_cast<const bf16x8*>((char*)SA(b, h) + lds_byte(wr * 64 + m * 16 + fr, k * 32 + fq * 8))
; #define LDB(dst, b, h) for (int n = 0; n < 2; ++n) for (int k = 0; k < 2; ++k) \
;     dst[n][k] = *reinterpret_cast<const bf16x8*>((char*)SB(b, h) + lds_byte(wc * 32 + n * 16 + fr, k * 32 + fq * 8))
; #define MMA(ai, bj, At_, Bt_) do { __builtin_amdgcn_s_setprio(1); \
;     for (int k = 0; k < 2; ++k) for (int m = 0; m < 4; ++m) for (int n = 0; n < 2; ++n) \
;       acc[ai][bj][m][n] = __builtin_amdgcn_mfma_f32_16x16x32_bf16(At_[m][k], Bt_[n][k], acc[ai][bj][m][n], 0, 0, 0); \
;     __builtin_amdgcn_s_setprio(0); } while (0)
; #define WAIT_V(n) asm volatile("s_waitcnt vmcnt(" #n ")" ::: "memory")
; #define WAIT_L(n) asm volatile("s_waitcnt lgkmcnt(" #n ")" ::: "memory")
; #define BAR __builtin_amdgcn_s_barrier()
; template <int EPI, int lda, int ldb, int N, int K>
; __device__ __forceinline__ void gemm_phase(const u16* __restrict__ A, const u16* __restrict__ Bt, const GemmEpi ep, int wv) {
;     ...
;     { LDB(B0, 1, 0); LDA(At, 1, 0); WAIT_V(2); BAR; WAIT_L(0); MMA(0, 0, At, B0); BAR;
;       LDB(B1, 1, 1); WAIT_V(0); BAR; WAIT_L(0); MMA(0, 1, At, B1); BAR;
;       LDA(At, 1, 1); BAR; WAIT_L(0); MMA(1, 0, At, B0); MMA(1, 1, At, B1); BAR; }
;     if (wr == 0) BAR;
	s_waitcnt lgkmcnt(0)
	s_waitcnt lgkmcnt(0)
	v_mfma_f32_16x16x32_bf16 v[4:7], v[36:39], v[0:3], v[4:7]
	v_mfma_f32_16x16x32_bf16 v[16:19], v[36:39], v[200:203], v[16:19]
	v_mfma_f32_16x16x32_bf16 v[32:35], v[108:111], v[0:3], v[72:75]
	v_mfma_f32_16x16x32_bf16 v[44:47], v[108:111], v[200:203], v[76:79]
	v_mfma_f32_16x16x32_bf16 v[72:75], v[116:119], v[0:3], v[80:83]
	v_mfma_f32_16x16x32_bf16 v[76:79], v[116:119], v[200:203], v[84:87]
	v_mfma_f32_16x16x32_bf16 v[80:83], v[124:127], v[0:3], v[88:91]
	v_mfma_f32_16x16x32_bf16 v[84:87], v[124:127], v[200:203], v[92:95]
	v_mfma_f32_16x16x32_bf16 v[120:123], v[100:103], v[196:199], v[4:7]
	v_mfma_f32_16x16x32_bf16 v[60:63], v[100:103], v[204:207], v[16:19]
	v_mfma_f32_16x16x32_bf16 v[112:115], v[208:211], v[196:199], v[32:35]
	v_mfma_f32_16x16x32_bf16 v[48:51], v[208:211], v[204:207], v[44:47]
	v_mfma_f32_16x16x32_bf16 v[104:107], v[212:215], v[196:199], v[72:75]
	v_mfma_f32_16x16x32_bf16 v[44:47], v[212:215], v[204:207], v[76:79]
	v_mfma_f32_16x16x32_bf16 v[96:99], v[216:219], v[196:199], v[80:83]
	v_mfma_f32_16x16x32_bf16 v[32:35], v[216:219], v[204:207], v[84:87]
	s_barrier
	ds_read_b128 v[4:7], v226
	ds_read_b128 v[220:223], v226 offset:1024
	ds_read_b128 v[76:79], v226 offset:2048
	ds_read_b128 v[224:227], v226 offset:3072
	s_waitcnt vmcnt(0)
	s_barrier
	s_waitcnt lgkmcnt(0)
	s_waitcnt lgkmcnt(0)
	v_mfma_f32_16x16x32_bf16 v[12:15], v[36:39], v[4:7], v[12:15]
	v_mfma_f32_16x16x32_bf16 v[16:19], v[36:39], v[76:79], v[40:43]
	v_mfma_f32_16x16x32_bf16 v[36:39], v[108:111], v[4:7], v[152:155]
	v_mfma_f32_16x16x32_bf16 v[40:43], v[108:111], v[76:79], v[156:159]
	v_mfma_f32_16x16x32_bf16 v[72:75], v[116:119], v[4:7], v[52:55]
	v_mfma_f32_16x16x32_bf16 v[80:83], v[116:119], v[76:79], v[56:59]
	v_mfma_f32_16x16x32_bf16 v[84:87], v[124:127], v[4:7], v[160:163]
	v_mfma_f32_16x16x32_bf16 v[64:67], v[124:127], v[76:79], v[64:67]
	v_mfma_f32_16x16x32_bf16 v[124:127], v[100:103], v[220:223], v[12:15]
	v_mfma_f32_16x16x32_bf16 v[56:59], v[100:103], v[224:227], v[16:19]
	v_mfma_f32_16x16x32_bf16 v[116:119], v[208:211], v[220:223], v[36:39]
	v_mfma_f32_16x16x32_bf16 v[52:55], v[208:211], v[224:227], v[40:43]
	v_mfma_f32_16x16x32_bf16 v[108:111], v[212:215], v[220:223], v[72:75]
	v_mfma_f32_16x16x32_bf16 v[40:43], v[212:215], v[224:227], v[80:83]
	v_mfma_f32_16x16x32_bf16 v[100:103], v[216:219], v[220:223], v[84:87]
	v_mfma_f32_16x16x32_bf16 v[36:39], v[216:219], v[224:227], v[64:67]
	s_barrier
	ds_read_b128 v[84:87], v228 offset:49152
	ds_read_b128 v[152:155], v228 offset:50176
	ds_read_b128 v[92:95], v229 offset:51200
	ds_read_b128 v[156:159], v229 offset:52224
	ds_read_b128 v[160:163], v229 offset:53248
	ds_read_b128 v[208:211], v229 offset:54272
	ds_read_b128 v[212:215], v229 offset:55296
	ds_read_b128 v[216:219], v229 offset:56320
	s_barrier
	s_waitcnt lgkmcnt(0)
	s_waitcnt lgkmcnt(0)
	v_mfma_f32_16x16x32_bf16 v[8:11], v[84:87], v[0:3], v[8:11]
	v_mfma_f32_16x16x32_bf16 v[12:15], v[84:87], v[200:203], v[134:137]
	v_mfma_f32_16x16x32_bf16 v[16:19], v[92:95], v[0:3], v[148:151]
	v_mfma_f32_16x16x32_bf16 v[64:67], v[92:95], v[200:203], v[168:171]
	v_mfma_f32_16x16x32_bf16 v[72:75], v[160:163], v[0:3], v[172:175]
	v_mfma_f32_16x16x32_bf16 v[134:137], v[160:163], v[200:203], v[176:179]
	v_mfma_f32_16x16x32_bf16 v[0:3], v[212:215], v[0:3], v[24:27]
	v_mfma_f32_16x16x32_bf16 v[24:27], v[212:215], v[200:203], v[28:31]
	v_mfma_f32_16x16x32_bf16 v[88:91], v[152:155], v[196:199], v[8:11]
	v_mfma_f32_16x16x32_bf16 v[28:31], v[152:155], v[204:207], v[12:15]
	v_mfma_f32_16x16x32_bf16 v[80:83], v[156:159], v[196:199], v[16:19]
	v_mfma_f32_16x16x32_bf16 v[16:19], v[156:159], v[204:207], v[64:67]
	v_mfma_f32_16x16x32_bf16 v[72:75], v[208:211], v[196:199], v[72:75]
	v_mfma_f32_16x16x32_bf16 v[12:15], v[208:211], v[204:207], v[134:137]
	v_mfma_f32_16x16x32_bf16 v[64:67], v[216:219], v[196:199], v[0:3]
	v_mfma_f32_16x16x32_bf16 v[0:3], v[216:219], v[204:207], v[24:27]
	v_mfma_f32_16x16x32_bf16 v[8:11], v[84:87], v[4:7], v[144:147]
	v_mfma_f32_16x16x32_bf16 v[20:23], v[84:87], v[76:79], v[20:23]
	v_mfma_f32_16x16x32_bf16 v[84:87], v[92:95], v[4:7], v[180:183]
	v_mfma_f32_16x16x32_bf16 v[134:137], v[92:95], v[76:79], v[164:167]
	v_mfma_f32_16x16x32_bf16 v[144:147], v[160:163], v[4:7], v[188:191]
	v_mfma_f32_16x16x32_bf16 v[148:151], v[160:163], v[76:79], v[184:187]
	v_mfma_f32_16x16x32_bf16 v[4:7], v[212:215], v[4:7], v[68:71]
	v_mfma_f32_16x16x32_bf16 v[160:163], v[212:215], v[76:79], v[192:195]
	v_mfma_f32_16x16x32_bf16 v[92:95], v[152:155], v[220:223], v[8:11]
	v_mfma_f32_16x16x32_bf16 v[24:27], v[152:155], v[224:227], v[20:23]
	v_mfma_f32_16x16x32_bf16 v[84:87], v[156:159], v[220:223], v[84:87]
	v_mfma_f32_16x16x32_bf16 v[20:23], v[156:159], v[224:227], v[134:137]
	v_mfma_f32_16x16x32_bf16 v[76:79], v[208:211], v[220:223], v[144:147]
	v_mfma_f32_16x16x32_bf16 v[8:11], v[208:211], v[224:227], v[148:151]
	v_mfma_f32_16x16x32_bf16 v[68:71], v[216:219], v[220:223], v[4:7]
	v_mfma_f32_16x16x32_bf16 v[4:7], v[216:219], v[224:227], v[160:163]
	v_cmp_gt_u32_e32 vcc, s62, v130
	s_barrier
	s_and_saveexec_b64 s[46:47], vcc
	s_cbranch_execz .LBB0_1245
	s_barrier
	s_branch .LBB0_1245

; #define STAGE(P, BASE, LD, br, kt) do { const char* _g = (const char*)((BASE) + (size_t)(br) * (LD) + (size_t)(kt) * 64); \
;     for (int _i = 0; _i < 2; ++_i) { int _b = tidx * 16 + _i * 8192; int _r, _c; stage_rc(_b, _r, _c); \
;       __builtin_amdgcn_global_load_lds((const unsigned*)(_g + (unsigned)((_r * (LD) + _c) * 2)), (unsigned*)((char*)(P) + _b), 16, 0, 0); } } while (0)
; #define LDA(dst, b, h) for (int m = 0; m < 4; ++m) for (int k = 0; k < 2; ++k) \
;     dst[m][k] = *reinterpret_cast<const bf16x8*>((char*)SA(b, h) + lds_byte(wr * 64 + m * 16 + fr, k * 32 + fq * 8))
; #define LDB(dst, b, h) for (int n = 0; n < 2; ++n) for (int k = 0; k < 2; ++k) \
;     dst[n][k] = *reinterpret_cast<const bf16x8*>((char*)SB(b, h) + lds_byte(wc * 32 + n * 16 + fr, k * 32 + fq * 8))
; #define MMA(ai, bj, At_, Bt_) do { __builtin_amdgcn_s_setprio(1); \
;     for (int k = 0; k < 2; ++k) for (int m = 0; m < 4; ++m) for (int n = 0; n < 2; ++n) \
;       acc[ai][bj][m][n] = __builtin_amdgcn_mfma_f32_16x16x32_bf16(At_[m][k], Bt_[n][k], acc[ai][bj][m][n], 0, 0, 0); \
;     __builtin_amdgcn_s_setprio(0); } while (0)
; #define WAIT_V(n) asm volatile("s_waitcnt vmcnt(" #n ")" ::: "memory")
; #define WAIT_L(n) asm volatile("s_waitcnt lgkmcnt(" #n ")" ::: "memory")
; #define BAR __builtin_amdgcn_s_barrier()
; #define SCHED __builtin_amdgcn_sched_barrier(0)
; template <int EPI, int lda, int ldb, int N, int K>
; __device__ __forceinline__ void gemm_phase(const u16* __restrict__ A, const u16* __restrict__ Bt, const GemmEpi ep, int wv) {
;     ...
;     WAIT_V(4); BAR;
;     STAGE(SB(1, 0), Bt, ldb, bcol, 1); STAGE(SA(1, 0), Ab, lda, brow, 1); STAGE(SB(1, 1), Bt, ldb, bcol + HALF, 1);
;     WAIT_V(6); BAR;
;     for (int t = 0; t < nt - 2; t += 2) {
;       LDB(B0, 0, 0); SCHED; LDA(At, 0, 0); STAGE(SA(1, 1), Ab, lda, brow + HALF, t + 1);
;       WAIT_L(8); BAR; WAIT_L(0); MMA(0, 0, At, B0); BAR; SCHED;
;       LDB(B1, 0, 1); STAGE(SB(0, 0), Bt, ldb, bcol, t + 2);
;       BAR; WAIT_L(0); MMA(0, 1, At, B1); BAR;
.LBB0_1349:
	s_or_b64 exec, exec, s[54:55]
	v_mov_b32_e32 v1, v129
	v_add_u32_e32 v7, s58, v6
	v_lshl_add_u64 v[12:13], s[46:47], 0, v[128:129]
	v_lshl_add_u64 v[14:15], s[46:47], 0, v[0:1]
	v_lshl_add_u64 v[2:3], s[52:53], 0, v[128:129]
	v_lshl_add_u64 v[0:1], s[52:53], 0, v[0:1]
	v_readfirstlane_b32 s53, v7
	v_add_u32_e32 v7, 0x2000, v7
	v_mov_b32_e32 v5, v129
	v_mov_b32_e32 v17, v129
	v_lshl_add_u64 v[26:27], v[12:13], 0, s[36:37]
	s_mov_b32 m0, s53
	v_readfirstlane_b32 s52, v7
	v_add_u32_e32 v7, 0x8000, v23
	v_lshl_add_u64 v[8:9], s[50:51], 0, v[4:5]
	v_lshl_add_u64 v[10:11], s[50:51], 0, v[16:17]
	s_waitcnt vmcnt(4)
	s_barrier
	global_load_lds_dwordx4 v[26:27], off
	v_lshl_add_u64 v[26:27], v[14:15], 0, s[36:37]
	s_mov_b32 m0, s52
	v_readfirstlane_b32 s51, v7
	v_add_u32_e32 v7, 0xa000, v23
	global_load_lds_dwordx4 v[26:27], off
	v_lshl_add_u64 v[26:27], v[8:9], 0, s[36:37]
	s_mov_b32 m0, s51
	v_readfirstlane_b32 s50, v7
	v_add_u32_e32 v25, s59, v6
	global_load_lds_dwordx4 v[26:27], off
	v_lshl_add_u64 v[26:27], v[10:11], 0, s[36:37]
	s_mov_b32 m0, s50
	v_readfirstlane_b32 s11, v25
	v_add_u32_e32 v25, 0x2000, v25
	global_load_lds_dwordx4 v[26:27], off
	v_lshl_add_u64 v[26:27], v[2:3], 0, s[36:37]
	s_mov_b32 m0, s11
	v_readfirstlane_b32 s5, v25
	global_load_lds_dwordx4 v[26:27], off
	v_lshl_add_u64 v[6:7], v[0:1], 0, s[36:37]
	s_mov_b32 m0, s5
	v_and_b32_e32 v132, 15, v20
	global_load_lds_dwordx4 v[6:7], off
	v_bfe_u32 v128, v20, 4, 2
	v_lshlrev_b32_e32 v7, 2, v20
	v_bfe_u32 v131, v130, 6, 2
	v_lshlrev_b32_e32 v25, 4, v128
	v_lshlrev_b32_e32 v6, 6, v132
	v_and_b32_e32 v50, 32, v7
	v_lshlrev_b32_e32 v126, 12, v131
	v_bitop3_b32 v127, v25, v50, v6 bitop3:0x36
	v_add3_u32 v133, s56, v127, v126
	s_waitcnt vmcnt(6)
	s_barrier
	ds_read_b128 v[26:29], v133
	ds_read_b128 v[30:33], v133 offset:1024
	ds_read_b128 v[34:37], v133 offset:2048
	ds_read_b128 v[38:41], v133 offset:3072
	v_lshl_add_u64 v[6:7], s[48:49], 0, v[4:5]
	v_lshl_add_u64 v[4:5], s[48:49], 0, v[16:17]
	v_lshlrev_b32_e32 v17, 6, v20
	v_and_b32_e32 v17, 0x3c0, v17
	v_add_u32_e32 v20, 0xc000, v23
	v_lshlrev_b32_e32 v16, 13, v139
	v_bitop3_b32 v17, v17, v50, v25 bitop3:0x36
	v_readfirstlane_b32 s47, v20
	v_add_u32_e32 v20, 0xe000, v23
	v_add3_u32 v228, 0, v127, v16
	v_add3_u32 v229, 0, v17, v16
	v_lshl_add_u64 v[16:17], v[6:7], 0, s[36:37]
	s_mov_b32 m0, s47
	v_readfirstlane_b32 s46, v20
	ds_read_b128 v[42:45], v228
	ds_read_b128 v[46:49], v228 offset:1024
	ds_read_b128 v[50:53], v229 offset:2048
	ds_read_b128 v[54:57], v229 offset:3072
	ds_read_b128 v[58:61], v229 offset:4096
	ds_read_b128 v[62:65], v229 offset:5120
	ds_read_b128 v[66:69], v229 offset:6144
	ds_read_b128 v[70:73], v229 offset:7168
	global_load_lds_dwordx4 v[16:17], off
	v_lshl_add_u64 v[16:17], v[4:5], 0, s[36:37]
	s_mov_b32 m0, s46
	s_nop 0
	global_load_lds_dwordx4 v[16:17], off
	s_waitcnt lgkmcnt(8)
	s_barrier
	s_waitcnt lgkmcnt(0)
	s_waitcnt lgkmcnt(0)
	v_mfma_f32_16x16x32_bf16 v[74:77], v[42:45], v[26:29], 0
	v_mfma_f32_16x16x32_bf16 v[78:81], v[42:45], v[34:37], 0
	v_mfma_f32_16x16x32_bf16 v[82:85], v[50:53], v[26:29], 0
	v_mfma_f32_16x16x32_bf16 v[86:89], v[50:53], v[34:37], 0
	v_mfma_f32_16x16x32_bf16 v[90:93], v[58:61], v[26:29], 0
	v_mfma_f32_16x16x32_bf16 v[94:97], v[58:61], v[34:37], 0
	v_mfma_f32_16x16x32_bf16 v[98:101], v[66:69], v[26:29], 0
	v_mfma_f32_16x16x32_bf16 v[102:105], v[66:69], v[34:37], 0
	v_mfma_f32_16x16x32_bf16 v[74:77], v[46:49], v[30:33], v[74:77]
	v_mfma_f32_16x16x32_bf16 v[78:81], v[46:49], v[38:41], v[78:81]
	v_mfma_f32_16x16x32_bf16 v[82:85], v[54:57], v[30:33], v[82:85]
	v_mfma_f32_16x16x32_bf16 v[86:89], v[54:57], v[38:41], v[86:89]
	v_mfma_f32_16x16x32_bf16 v[90:93], v[62:65], v[30:33], v[90:93]
	v_mfma_f32_16x16x32_bf16 v[94:97], v[62:65], v[38:41], v[94:97]
	v_mfma_f32_16x16x32_bf16 v[98:101], v[70:73], v[30:33], v[98:101]
	v_mfma_f32_16x16x32_bf16 v[102:105], v[70:73], v[38:41], v[102:105]
	s_barrier
	v_readfirstlane_b32 s48, v21
	v_add_u32_e32 v20, 0x2000, v21
	v_add3_u32 v224, s57, v127, v126
	v_lshl_add_u64 v[16:17], v[12:13], 0, s[38:39]
	s_mov_b32 m0, s48
	v_readfirstlane_b32 s48, v20
	ds_read_b128 v[106:109], v224
	ds_read_b128 v[110:113], v224 offset:1024
	ds_read_b128 v[114:117], v224 offset:2048
	ds_read_b128 v[118:121], v224 offset:3072
	global_load_lds_dwordx4 v[16:17], off
	v_lshl_add_u64 v[16:17], v[14:15], 0, s[38:39]
	s_mov_b32 m0, s48
	s_nop 0
	global_load_lds_dwordx4 v[16:17], off
	s_barrier
	s_waitcnt lgkmcnt(0)
	s_waitcnt lgkmcnt(0)
	v_mfma_f32_16x16x32_bf16 v[122:125], v[42:45], v[106:109], 0
	v_mfma_f32_16x16x32_bf16 v[42:45], v[42:45], v[114:117], 0
	v_mfma_f32_16x16x32_bf16 v[140:143], v[50:53], v[106:109], 0
	v_mfma_f32_16x16x32_bf16 v[50:53], v[50:53], v[114:117], 0
	v_mfma_f32_16x16x32_bf16 v[144:147], v[58:61], v[106:109], 0
	v_mfma_f32_16x16x32_bf16 v[58:61], v[58:61], v[114:117], 0
	v_mfma_f32_16x16x32_bf16 v[148:151], v[66:69], v[106:109], 0
	v_mfma_f32_16x16x32_bf16 v[66:69], v[66:69], v[114:117], 0
	v_mfma_f32_16x16x32_bf16 v[122:125], v[46:49], v[110:113], v[122:125]
	v_mfma_f32_16x16x32_bf16 v[42:45], v[46:49], v[118:121], v[42:45]
	v_mfma_f32_16x16x32_bf16 v[46:49], v[54:57], v[110:113], v[140:143]
	v_mfma_f32_16x16x32_bf16 v[50:53], v[54:57], v[118:121], v[50:53]
	v_mfma_f32_16x16x32_bf16 v[54:57], v[62:65], v[110:113], v[144:147]
	v_mfma_f32_16x16x32_bf16 v[58:61], v[62:65], v[118:121], v[58:61]
	v_mfma_f32_16x16x32_bf16 v[62:65], v[70:73], v[110:113], v[148:151]
	v_mfma_f32_16x16x32_bf16 v[66:69], v[70:73], v[118:121], v[66:69]
	v_readfirstlane_b32 s48, v23
	v_lshl_add_u64 v[16:17], v[8:9], 0, s[38:39]
	s_mov_b32 m0, s48
	v_readfirstlane_b32 s48, v24
	s_barrier
; #define STAGE(P, BASE, LD, br, kt) do { const char* _g = (const char*)((BASE) + (size_t)(br) * (LD) + (size_t)(kt) * 64); \
;     for (int _i = 0; _i < 2; ++_i) { int _b = tidx * 16 + _i * 8192; int _r, _c; stage_rc(_b, _r, _c); \
;       __builtin_amdgcn_global_load_lds((const unsigned*)(_g + (unsigned)((_r * (LD) + _c) * 2)), (unsigned*)((char*)(P) + _b), 16, 0, 0); } } while (0)
; #define LDA(dst, b, h) for (int m = 0; m < 4; ++m) for (int k = 0; k < 2; ++k) \
;     dst[m][k] = *reinterpret_cast<const bf16x8*>((char*)SA(b, h) + lds_byte(wr * 64 + m * 16 + fr, k * 32 + fq * 8))
; #define LDB(dst, b, h) for (int n = 0; n < 2; ++n) for (int k = 0; k < 2; ++k) \
;     dst[n][k] = *reinterpret_cast<const bf16x8*>((char*)SB(b, h) + lds_byte(wc * 32 + n * 16 + fr, k * 32 + fq * 8))
; #define MMA(ai, bj, At_, Bt_) do { __builtin_amdgcn_s_setprio(1); \
;     for (int k = 0; k < 2; ++k) for (int m = 0; m < 4; ++m) for (int n = 0; n < 2; ++n) \
;       acc[ai][bj][m][n] = __builtin_amdgcn_mfma_f32_16x16x32_bf16(At_[m][k], Bt_[n][k], acc[ai][bj][m][n], 0, 0, 0); \
;     __builtin_amdgcn_s_setprio(0); } while (0)
; #define WAIT_V(n) asm volatile("s_waitcnt vmcnt(" #n ")" ::: "memory")
; #define WAIT_L(n) asm volatile("s_waitcnt lgkmcnt(" #n ")" ::: "memory")
; #define BAR __builtin_amdgcn_s_barrier()
; #define SCHED __builtin_amdgcn_sched_barrier(0)
; template <int EPI, int lda, int ldb, int N, int K>
; __device__ __forceinline__ void gemm_phase(const u16* __restrict__ A, const u16* __restrict__ Bt, const GemmEpi ep, int wv) {
;     ...
;       LDA(At, 0, 1); STAGE(SA(0, 0), Ab, lda, brow, t + 2);
;       BAR; WAIT_L(0); MMA(1, 0, At, B0); BAR; SCHED;
;       STAGE(SB(0, 1), Bt, ldb, bcol + HALF, t + 2);
;       WAIT_V(6); BAR; MMA(1, 1, At, B1); BAR;
;       LDB(B0, 1, 0); SCHED; LDA(At, 1, 0); STAGE(SA(0, 1), Ab, lda, brow + HALF, t + 2);
;       WAIT_L(8); BAR; WAIT_L(0); MMA(0, 0, At, B0); BAR; SCHED;
;       LDB(B1, 1, 1); STAGE(SB(1, 0), Bt, ldb, bcol, t + 3);
	ds_read_b128 v[70:73], v228 offset:16384
	ds_read_b128 v[140:143], v228 offset:17408
	ds_read_b128 v[144:147], v229 offset:18432
	ds_read_b128 v[148:151], v229 offset:19456
	ds_read_b128 v[152:155], v229 offset:20480
	ds_read_b128 v[156:159], v229 offset:21504
	ds_read_b128 v[160:163], v229 offset:22528
	ds_read_b128 v[164:167], v229 offset:23552
	global_load_lds_dwordx4 v[16:17], off
	v_lshl_add_u64 v[16:17], v[10:11], 0, s[38:39]
	s_mov_b32 m0, s48
	s_nop 0
	global_load_lds_dwordx4 v[16:17], off
	s_barrier
	s_waitcnt lgkmcnt(0)
	s_waitcnt lgkmcnt(0)
	v_mfma_f32_16x16x32_bf16 v[168:171], v[70:73], v[26:29], 0
	v_mfma_f32_16x16x32_bf16 v[172:175], v[70:73], v[34:37], 0
	v_mfma_f32_16x16x32_bf16 v[176:179], v[144:147], v[26:29], 0
	v_mfma_f32_16x16x32_bf16 v[180:183], v[144:147], v[34:37], 0
	v_mfma_f32_16x16x32_bf16 v[184:187], v[152:155], v[26:29], 0
	v_mfma_f32_16x16x32_bf16 v[188:191], v[152:155], v[34:37], 0
	v_mfma_f32_16x16x32_bf16 v[24:27], v[160:163], v[26:29], 0
	v_mfma_f32_16x16x32_bf16 v[34:37], v[160:163], v[34:37], 0
	v_mfma_f32_16x16x32_bf16 v[168:171], v[140:143], v[30:33], v[168:171]
	v_mfma_f32_16x16x32_bf16 v[176:179], v[148:151], v[30:33], v[176:179]
	v_mfma_f32_16x16x32_bf16 v[184:187], v[156:159], v[30:33], v[184:187]
	v_mfma_f32_16x16x32_bf16 v[24:27], v[164:167], v[30:33], v[24:27]
	v_mfma_f32_16x16x32_bf16 v[28:31], v[164:167], v[38:41], v[34:37]
	v_mfma_f32_16x16x32_bf16 v[172:175], v[140:143], v[38:41], v[172:175]
	v_mfma_f32_16x16x32_bf16 v[180:183], v[148:151], v[38:41], v[180:183]
	v_mfma_f32_16x16x32_bf16 v[188:191], v[156:159], v[38:41], v[188:191]
	s_barrier
	v_readfirstlane_b32 s48, v22
	v_add_u32_e32 v20, 0x2000, v22
	v_lshl_add_u64 v[16:17], v[2:3], 0, s[38:39]
	s_mov_b32 m0, s48
	v_readfirstlane_b32 s48, v20
	global_load_lds_dwordx4 v[16:17], off
	v_lshl_add_u64 v[16:17], v[0:1], 0, s[38:39]
	s_mov_b32 m0, s48
	s_nop 0
	global_load_lds_dwordx4 v[16:17], off
	s_waitcnt vmcnt(6)
	s_barrier
	v_mfma_f32_16x16x32_bf16 v[20:23], v[70:73], v[106:109], 0
	v_mfma_f32_16x16x32_bf16 v[32:35], v[70:73], v[114:117], 0
	v_mfma_f32_16x16x32_bf16 v[36:39], v[144:147], v[106:109], 0
	v_mfma_f32_16x16x32_bf16 v[70:73], v[144:147], v[114:117], 0
	v_mfma_f32_16x16x32_bf16 v[144:147], v[152:155], v[106:109], 0
	v_mfma_f32_16x16x32_bf16 v[152:155], v[152:155], v[114:117], 0
	v_mfma_f32_16x16x32_bf16 v[106:109], v[160:163], v[106:109], 0
	v_mfma_f32_16x16x32_bf16 v[114:117], v[160:163], v[114:117], 0
	v_mfma_f32_16x16x32_bf16 v[20:23], v[140:143], v[110:113], v[20:23]
	v_mfma_f32_16x16x32_bf16 v[32:35], v[140:143], v[118:121], v[32:35]
	v_mfma_f32_16x16x32_bf16 v[36:39], v[148:151], v[110:113], v[36:39]
	v_mfma_f32_16x16x32_bf16 v[70:73], v[148:151], v[118:121], v[70:73]
	v_mfma_f32_16x16x32_bf16 v[140:143], v[156:159], v[110:113], v[144:147]
	v_mfma_f32_16x16x32_bf16 v[106:109], v[164:167], v[110:113], v[106:109]
	v_mfma_f32_16x16x32_bf16 v[110:113], v[164:167], v[118:121], v[114:117]
	v_mfma_f32_16x16x32_bf16 v[144:147], v[156:159], v[118:121], v[152:155]
	v_add3_u32 v225, s58, v127, v126
	s_barrier
	ds_read_b128 v[114:117], v225
	ds_read_b128 v[118:121], v225 offset:1024
	ds_read_b128 v[148:151], v225 offset:2048
	ds_read_b128 v[152:155], v225 offset:3072
	v_readfirstlane_b32 s48, v18
	v_lshl_add_u64 v[16:17], v[6:7], 0, s[38:39]
	s_mov_b32 m0, s48
	v_readfirstlane_b32 s48, v19
	ds_read_b128 v[156:159], v228 offset:32768
	ds_read_b128 v[160:163], v228 offset:33792
	ds_read_b128 v[164:167], v229 offset:34816
	ds_read_b128 v[192:195], v229 offset:35840
	ds_read_b128 v[196:199], v229 offset:36864
	ds_read_b128 v[200:203], v229 offset:37888
	ds_read_b128 v[204:207], v229 offset:38912
	ds_read_b128 v[208:211], v229 offset:39936
	global_load_lds_dwordx4 v[16:17], off
	v_lshl_add_u64 v[16:17], v[4:5], 0, s[38:39]
	s_mov_b32 m0, s48
	s_nop 0
	global_load_lds_dwordx4 v[16:17], off
	s_waitcnt lgkmcnt(8)
	s_barrier
	s_waitcnt lgkmcnt(0)
	s_waitcnt lgkmcnt(0)
	v_mfma_f32_16x16x32_bf16 v[16:19], v[156:159], v[114:117], v[74:77]
	v_mfma_f32_16x16x32_bf16 v[74:77], v[156:159], v[148:151], v[78:81]
	v_mfma_f32_16x16x32_bf16 v[78:81], v[164:167], v[114:117], v[82:85]
	v_mfma_f32_16x16x32_bf16 v[82:85], v[164:167], v[148:151], v[86:89]
	v_mfma_f32_16x16x32_bf16 v[86:89], v[196:199], v[114:117], v[90:93]
	v_mfma_f32_16x16x32_bf16 v[90:93], v[196:199], v[148:151], v[94:97]
	v_mfma_f32_16x16x32_bf16 v[94:97], v[204:207], v[114:117], v[98:101]
	v_mfma_f32_16x16x32_bf16 v[98:101], v[204:207], v[148:151], v[102:105]
	v_mfma_f32_16x16x32_bf16 v[16:19], v[160:163], v[118:121], v[16:19]
	v_mfma_f32_16x16x32_bf16 v[74:77], v[160:163], v[152:155], v[74:77]
	v_mfma_f32_16x16x32_bf16 v[78:81], v[192:195], v[118:121], v[78:81]
	v_mfma_f32_16x16x32_bf16 v[82:85], v[192:195], v[152:155], v[82:85]
	v_mfma_f32_16x16x32_bf16 v[86:89], v[200:203], v[118:121], v[86:89]
	v_mfma_f32_16x16x32_bf16 v[90:93], v[200:203], v[152:155], v[90:93]
	v_mfma_f32_16x16x32_bf16 v[94:97], v[208:211], v[118:121], v[94:97]
	v_mfma_f32_16x16x32_bf16 v[98:101], v[208:211], v[152:155], v[98:101]
	s_barrier
	s_mov_b32 m0, s53
	v_add3_u32 v226, s59, v127, v126
	v_lshl_add_u64 v[12:13], v[12:13], 0, s[40:41]
	ds_read_b128 v[102:105], v226
	ds_read_b128 v[212:215], v226 offset:1024
	ds_read_b128 v[216:219], v226 offset:2048
	ds_read_b128 v[220:223], v226 offset:3072
	global_load_lds_dwordx4 v[12:13], off
	v_lshl_add_u64 v[12:13], v[14:15], 0, s[40:41]
	s_mov_b32 m0, s52
	s_nop 0
	global_load_lds_dwordx4 v[12:13], off
	s_barrier
; #define STAGE(P, BASE, LD, br, kt) do { const char* _g = (const char*)((BASE) + (size_t)(br) * (LD) + (size_t)(kt) * 64); \
;     for (int _i = 0; _i < 2; ++_i) { int _b = tidx * 16 + _i * 8192; int _r, _c; stage_rc(_b, _r, _c); \
;       __builtin_amdgcn_global_load_lds((const unsigned*)(_g + (unsigned)((_r * (LD) + _c) * 2)), (unsigned*)((char*)(P) + _b), 16, 0, 0); } } while (0)
; #define LDA(dst, b, h) for (int m = 0; m < 4; ++m) for (int k = 0; k < 2; ++k) \
;     dst[m][k] = *reinterpret_cast<const bf16x8*>((char*)SA(b, h) + lds_byte(wr * 64 + m * 16 + fr, k * 32 + fq * 8))
; #define LDB(dst, b, h) for (int n = 0; n < 2; ++n) for (int k = 0; k < 2; ++k) \
;     dst[n][k] = *reinterpret_cast<const bf16x8*>((char*)SB(b, h) + lds_byte(wc * 32 + n * 16 + fr, k * 32 + fq * 8))
; #define MMA(ai, bj, At_, Bt_) do { __builtin_amdgcn_s_setprio(1); \
;     for (int k = 0; k < 2; ++k) for (int m = 0; m < 4; ++m) for (int n = 0; n < 2; ++n) \
;       acc[ai][bj][m][n] = __builtin_amdgcn_mfma_f32_16x16x32_bf16(At_[m][k], Bt_[n][k], acc[ai][bj][m][n], 0, 0, 0); \
;     __builtin_amdgcn_s_setprio(0); } while (0)
; #define WAIT_V(n) asm volatile("s_waitcnt vmcnt(" #n ")" ::: "memory")
; #define WAIT_L(n) asm volatile("s_waitcnt lgkmcnt(" #n ")" ::: "memory")
; #define BAR __builtin_amdgcn_s_barrier()
; #define SCHED __builtin_amdgcn_sched_barrier(0)
; template <int EPI, int lda, int ldb, int N, int K>
; __device__ __forceinline__ void gemm_phase(const u16* __restrict__ A, const u16* __restrict__ Bt, const GemmEpi ep, int wv) {
;     ...
;       BAR; WAIT_L(0); MMA(0, 1, At, B1); BAR;
;       LDA(At, 1, 1); STAGE(SA(1, 0), Ab, lda, brow, t + 3);
;       BAR; WAIT_L(0); MMA(1, 0, At, B0); BAR; SCHED;
;       STAGE(SB(1, 1), Bt, ldb, bcol + HALF, t + 3);
;       WAIT_V(6); BAR; MMA(1, 1, At, B1); BAR;
;     }
;     { LDB(B0, 0, 0); LDA(At, 0, 0); STAGE(SA(1, 1), Ab, lda, brow + HALF, nt - 1);
;       BAR; WAIT_L(0); MMA(0, 0, At, B0); BAR;
	s_waitcnt lgkmcnt(0)
	s_waitcnt lgkmcnt(0)
	v_mfma_f32_16x16x32_bf16 v[12:15], v[156:159], v[102:105], v[122:125]
	v_mfma_f32_16x16x32_bf16 v[40:43], v[156:159], v[216:219], v[42:45]
	v_mfma_f32_16x16x32_bf16 v[44:47], v[164:167], v[102:105], v[46:49]
	v_mfma_f32_16x16x32_bf16 v[48:51], v[164:167], v[216:219], v[50:53]
	v_mfma_f32_16x16x32_bf16 v[52:55], v[196:199], v[102:105], v[54:57]
	v_mfma_f32_16x16x32_bf16 v[56:59], v[196:199], v[216:219], v[58:61]
	v_mfma_f32_16x16x32_bf16 v[60:63], v[204:207], v[102:105], v[62:65]
	v_mfma_f32_16x16x32_bf16 v[64:67], v[204:207], v[216:219], v[66:69]
	v_mfma_f32_16x16x32_bf16 v[12:15], v[160:163], v[212:215], v[12:15]
	v_mfma_f32_16x16x32_bf16 v[40:43], v[160:163], v[220:223], v[40:43]
	v_mfma_f32_16x16x32_bf16 v[44:47], v[192:195], v[212:215], v[44:47]
	v_mfma_f32_16x16x32_bf16 v[48:51], v[192:195], v[220:223], v[48:51]
	v_mfma_f32_16x16x32_bf16 v[52:55], v[200:203], v[212:215], v[52:55]
	v_mfma_f32_16x16x32_bf16 v[56:59], v[200:203], v[220:223], v[56:59]
	v_mfma_f32_16x16x32_bf16 v[60:63], v[208:211], v[212:215], v[60:63]
	v_mfma_f32_16x16x32_bf16 v[64:67], v[208:211], v[220:223], v[64:67]
	s_mov_b32 m0, s51
	v_lshl_add_u64 v[8:9], v[8:9], 0, s[40:41]
	s_barrier
	ds_read_b128 v[122:125], v228 offset:49152
	ds_read_b128 v[156:159], v228 offset:50176
	ds_read_b128 v[160:163], v229 offset:51200
	ds_read_b128 v[164:167], v229 offset:52224
	ds_read_b128 v[192:195], v229 offset:53248
	ds_read_b128 v[196:199], v229 offset:54272
	ds_read_b128 v[200:203], v229 offset:55296
	ds_read_b128 v[204:207], v229 offset:56320
	global_load_lds_dwordx4 v[8:9], off
	v_lshl_add_u64 v[8:9], v[10:11], 0, s[40:41]
	s_mov_b32 m0, s50
	s_nop 0
	global_load_lds_dwordx4 v[8:9], off
	s_barrier
	s_waitcnt lgkmcnt(0)
	s_waitcnt lgkmcnt(0)
	v_mfma_f32_16x16x32_bf16 v[8:11], v[122:125], v[114:117], v[168:171]
	v_mfma_f32_16x16x32_bf16 v[168:171], v[122:125], v[148:151], v[172:175]
	v_mfma_f32_16x16x32_bf16 v[24:27], v[200:203], v[114:117], v[24:27]
	v_mfma_f32_16x16x32_bf16 v[28:31], v[200:203], v[148:151], v[28:31]
	v_mfma_f32_16x16x32_bf16 v[172:175], v[160:163], v[114:117], v[176:179]
	v_mfma_f32_16x16x32_bf16 v[176:179], v[160:163], v[148:151], v[180:183]
	v_mfma_f32_16x16x32_bf16 v[180:183], v[192:195], v[114:117], v[184:187]
	v_mfma_f32_16x16x32_bf16 v[184:187], v[192:195], v[148:151], v[188:191]
	v_mfma_f32_16x16x32_bf16 v[8:11], v[156:159], v[118:121], v[8:11]
	v_mfma_f32_16x16x32_bf16 v[114:117], v[156:159], v[152:155], v[168:171]
	v_mfma_f32_16x16x32_bf16 v[24:27], v[204:207], v[118:121], v[24:27]
	v_mfma_f32_16x16x32_bf16 v[28:31], v[204:207], v[152:155], v[28:31]
	v_mfma_f32_16x16x32_bf16 v[148:151], v[164:167], v[118:121], v[172:175]
	v_mfma_f32_16x16x32_bf16 v[168:171], v[164:167], v[152:155], v[176:179]
	v_mfma_f32_16x16x32_bf16 v[172:175], v[196:199], v[118:121], v[180:183]
	v_mfma_f32_16x16x32_bf16 v[176:179], v[196:199], v[152:155], v[184:187]
	s_barrier
	s_mov_b32 m0, s11
	v_lshl_add_u64 v[2:3], v[2:3], 0, s[40:41]
	global_load_lds_dwordx4 v[2:3], off
	v_lshl_add_u64 v[0:1], v[0:1], 0, s[40:41]
	s_mov_b32 m0, s5
	s_nop 0
	global_load_lds_dwordx4 v[0:1], off
	s_waitcnt vmcnt(6)
	s_barrier
	v_mfma_f32_16x16x32_bf16 v[0:3], v[122:125], v[102:105], v[20:23]
	v_mfma_f32_16x16x32_bf16 v[20:23], v[122:125], v[216:219], v[32:35]
	v_mfma_f32_16x16x32_bf16 v[32:35], v[160:163], v[102:105], v[36:39]
	v_mfma_f32_16x16x32_bf16 v[36:39], v[160:163], v[216:219], v[70:73]
	v_mfma_f32_16x16x32_bf16 v[68:71], v[192:195], v[102:105], v[140:143]
	v_mfma_f32_16x16x32_bf16 v[118:121], v[192:195], v[216:219], v[144:147]
	v_mfma_f32_16x16x32_bf16 v[102:105], v[200:203], v[102:105], v[106:109]
	v_mfma_f32_16x16x32_bf16 v[106:109], v[200:203], v[216:219], v[110:113]
	v_mfma_f32_16x16x32_bf16 v[0:3], v[156:159], v[212:215], v[0:3]
	v_mfma_f32_16x16x32_bf16 v[20:23], v[156:159], v[220:223], v[20:23]
	v_mfma_f32_16x16x32_bf16 v[32:35], v[164:167], v[212:215], v[32:35]
	v_mfma_f32_16x16x32_bf16 v[36:39], v[164:167], v[220:223], v[36:39]
	v_mfma_f32_16x16x32_bf16 v[68:71], v[196:199], v[212:215], v[68:71]
	v_mfma_f32_16x16x32_bf16 v[110:113], v[196:199], v[220:223], v[118:121]
	v_mfma_f32_16x16x32_bf16 v[102:105], v[204:207], v[212:215], v[102:105]
	v_mfma_f32_16x16x32_bf16 v[106:109], v[204:207], v[220:223], v[106:109]
	s_mov_b32 m0, s47
	v_lshl_add_u64 v[6:7], v[6:7], 0, s[40:41]
	s_barrier
	ds_read_b128 v[118:121], v133
	ds_read_b128 v[122:125], v133 offset:1024
	ds_read_b128 v[140:143], v133 offset:2048
	ds_read_b128 v[144:147], v133 offset:3072
	ds_read_b128 v[152:155], v228
	ds_read_b128 v[156:159], v228 offset:1024
	ds_read_b128 v[160:163], v229 offset:2048
	ds_read_b128 v[164:167], v229 offset:3072
	ds_read_b128 v[180:183], v229 offset:4096
	ds_read_b128 v[184:187], v229 offset:5120
	ds_read_b128 v[188:191], v229 offset:6144
	ds_read_b128 v[192:195], v229 offset:7168
	global_load_lds_dwordx4 v[6:7], off
	v_lshl_add_u64 v[4:5], v[4:5], 0, s[40:41]
	s_mov_b32 m0, s46
	s_nop 0
	global_load_lds_dwordx4 v[4:5], off
	s_barrier
	s_waitcnt lgkmcnt(0)
	s_waitcnt lgkmcnt(0)
	v_mfma_f32_16x16x32_bf16 v[4:7], v[152:155], v[118:121], v[16:19]
	v_mfma_f32_16x16x32_bf16 v[16:19], v[152:155], v[140:143], v[74:77]
	v_mfma_f32_16x16x32_bf16 v[72:75], v[160:163], v[118:121], v[78:81]
	v_mfma_f32_16x16x32_bf16 v[76:79], v[160:163], v[140:143], v[82:85]
	v_mfma_f32_16x16x32_bf16 v[80:83], v[180:183], v[118:121], v[86:89]
	v_mfma_f32_16x16x32_bf16 v[84:87], v[180:183], v[140:143], v[90:93]
	v_mfma_f32_16x16x32_bf16 v[88:91], v[188:191], v[118:121], v[94:97]
	v_mfma_f32_16x16x32_bf16 v[92:95], v[188:191], v[140:143], v[98:101]
	v_mfma_f32_16x16x32_bf16 v[4:7], v[156:159], v[122:125], v[4:7]
	v_mfma_f32_16x16x32_bf16 v[16:19], v[156:159], v[144:147], v[16:19]
	v_mfma_f32_16x16x32_bf16 v[72:75], v[164:167], v[122:125], v[72:75]
	v_mfma_f32_16x16x32_bf16 v[76:79], v[164:167], v[144:147], v[76:79]
	v_mfma_f32_16x16x32_bf16 v[80:83], v[184:187], v[122:125], v[80:83]
	v_mfma_f32_16x16x32_bf16 v[84:87], v[184:187], v[144:147], v[84:87]
	v_mfma_f32_16x16x32_bf16 v[88:91], v[192:195], v[122:125], v[88:91]
	v_mfma_f32_16x16x32_bf16 v[92:95], v[192:195], v[144:147], v[92:95]
	s_barrier
; #define LDA(dst, b, h) for (int m = 0; m < 4; ++m) for (int k = 0; k < 2; ++k) \
;     dst[m][k] = *reinterpret_cast<const bf16x8*>((char*)SA(b, h) + lds_byte(wr * 64 + m * 16 + fr, k * 32 + fq * 8))
; #define LDB(dst, b, h) for (int n = 0; n < 2; ++n) for (int k = 0; k < 2; ++k) \
;     dst[n][k] = *reinterpret_cast<const bf16x8*>((char*)SB(b, h) + lds_byte(wc * 32 + n * 16 + fr, k * 32 + fq * 8))
; #define MMA(ai, bj, At_, Bt_) do { __builtin_amdgcn_s_setprio(1); \
;     for (int k = 0; k < 2; ++k) for (int m = 0; m < 4; ++m) for (int n = 0; n < 2; ++n) \
;       acc[ai][bj][m][n] = __builtin_amdgcn_mfma_f32_16x16x32_bf16(At_[m][k], Bt_[n][k], acc[ai][bj][m][n], 0, 0, 0); \
;     __builtin_amdgcn_s_setprio(0); } while (0)
; #define WAIT_V(n) asm volatile("s_waitcnt vmcnt(" #n ")" ::: "memory")
; #define WAIT_L(n) asm volatile("s_waitcnt lgkmcnt(" #n ")" ::: "memory")
; #define BAR __builtin_amdgcn_s_barrier()
; template <int EPI, int lda, int ldb, int N, int K>
; __device__ __forceinline__ void gemm_phase(const u16* __restrict__ A, const u16* __restrict__ Bt, const GemmEpi ep, int wv) {
;     ...
;       LDB(B1, 0, 1); BAR; WAIT_L(0); MMA(0, 1, At, B1); BAR;
;       LDA(At, 0, 1); WAIT_V(4); BAR; WAIT_L(0); MMA(1, 0, At, B0); MMA(1, 1, At, B1); BAR; }
;     { LDB(B0, 1, 0); LDA(At, 1, 0); WAIT_V(2); BAR; WAIT_L(0); MMA(0, 0, At, B0); BAR;
	ds_read_b128 v[96:99], v224
	ds_read_b128 v[196:199], v224 offset:1024
	ds_read_b128 v[200:203], v224 offset:2048
	ds_read_b128 v[204:207], v224 offset:3072
	s_barrier
	s_waitcnt lgkmcnt(0)
	s_waitcnt lgkmcnt(0)
	v_mfma_f32_16x16x32_bf16 v[12:15], v[152:155], v[96:99], v[12:15]
	v_mfma_f32_16x16x32_bf16 v[40:43], v[152:155], v[200:203], v[40:43]
	v_mfma_f32_16x16x32_bf16 v[52:55], v[180:183], v[96:99], v[52:55]
	v_mfma_f32_16x16x32_bf16 v[56:59], v[180:183], v[200:203], v[56:59]
	v_mfma_f32_16x16x32_bf16 v[64:67], v[188:191], v[200:203], v[64:67]
	v_mfma_f32_16x16x32_bf16 v[44:47], v[160:163], v[96:99], v[44:47]
	v_mfma_f32_16x16x32_bf16 v[48:51], v[160:163], v[200:203], v[48:51]
	v_mfma_f32_16x16x32_bf16 v[60:63], v[188:191], v[96:99], v[60:63]
	v_mfma_f32_16x16x32_bf16 v[12:15], v[156:159], v[196:199], v[12:15]
	v_mfma_f32_16x16x32_bf16 v[40:43], v[156:159], v[204:207], v[40:43]
	v_mfma_f32_16x16x32_bf16 v[52:55], v[184:187], v[196:199], v[52:55]
	v_mfma_f32_16x16x32_bf16 v[56:59], v[184:187], v[204:207], v[56:59]
	v_mfma_f32_16x16x32_bf16 v[64:67], v[192:195], v[204:207], v[64:67]
	v_mfma_f32_16x16x32_bf16 v[152:155], v[164:167], v[196:199], v[44:47]
	v_mfma_f32_16x16x32_bf16 v[156:159], v[164:167], v[204:207], v[48:51]
	v_mfma_f32_16x16x32_bf16 v[160:163], v[192:195], v[196:199], v[60:63]
	s_barrier
	ds_read_b128 v[44:47], v228 offset:16384
	ds_read_b128 v[48:51], v228 offset:17408
	ds_read_b128 v[60:63], v229 offset:18432
	ds_read_b128 v[164:167], v229 offset:19456
	ds_read_b128 v[180:183], v229 offset:20480
	ds_read_b128 v[184:187], v229 offset:21504
	ds_read_b128 v[188:191], v229 offset:22528
	ds_read_b128 v[192:195], v229 offset:23552
	s_waitcnt vmcnt(4)
	s_barrier
	s_waitcnt lgkmcnt(0)
	s_waitcnt lgkmcnt(0)
	v_mfma_f32_16x16x32_bf16 v[8:11], v[44:47], v[118:121], v[8:11]
	v_mfma_f32_16x16x32_bf16 v[24:27], v[188:191], v[118:121], v[24:27]
	v_mfma_f32_16x16x32_bf16 v[28:31], v[188:191], v[140:143], v[28:31]
	v_mfma_f32_16x16x32_bf16 v[114:117], v[44:47], v[140:143], v[114:117]
	v_mfma_f32_16x16x32_bf16 v[148:151], v[60:63], v[118:121], v[148:151]
	v_mfma_f32_16x16x32_bf16 v[168:171], v[60:63], v[140:143], v[168:171]
	v_mfma_f32_16x16x32_bf16 v[172:175], v[180:183], v[118:121], v[172:175]
	v_mfma_f32_16x16x32_bf16 v[176:179], v[180:183], v[140:143], v[176:179]
	v_mfma_f32_16x16x32_bf16 v[8:11], v[48:51], v[122:125], v[8:11]
	v_mfma_f32_16x16x32_bf16 v[24:27], v[192:195], v[122:125], v[24:27]
	v_mfma_f32_16x16x32_bf16 v[28:31], v[192:195], v[144:147], v[28:31]
	v_mfma_f32_16x16x32_bf16 v[140:143], v[48:51], v[144:147], v[114:117]
	v_mfma_f32_16x16x32_bf16 v[148:151], v[164:167], v[122:125], v[148:151]
	v_mfma_f32_16x16x32_bf16 v[168:171], v[164:167], v[144:147], v[168:171]
	v_mfma_f32_16x16x32_bf16 v[172:175], v[184:187], v[122:125], v[172:175]
	v_mfma_f32_16x16x32_bf16 v[176:179], v[184:187], v[144:147], v[176:179]
	v_mfma_f32_16x16x32_bf16 v[0:3], v[44:47], v[96:99], v[0:3]
	v_mfma_f32_16x16x32_bf16 v[20:23], v[44:47], v[200:203], v[20:23]
	v_mfma_f32_16x16x32_bf16 v[44:47], v[180:183], v[96:99], v[68:71]
	v_mfma_f32_16x16x32_bf16 v[68:71], v[188:191], v[96:99], v[102:105]
	v_mfma_f32_16x16x32_bf16 v[32:35], v[60:63], v[96:99], v[32:35]
	v_mfma_f32_16x16x32_bf16 v[36:39], v[60:63], v[200:203], v[36:39]
	v_mfma_f32_16x16x32_bf16 v[60:63], v[180:183], v[200:203], v[110:113]
	v_mfma_f32_16x16x32_bf16 v[96:99], v[188:191], v[200:203], v[106:109]
	v_mfma_f32_16x16x32_bf16 v[20:23], v[48:51], v[204:207], v[20:23]
	v_mfma_f32_16x16x32_bf16 v[68:71], v[192:195], v[196:199], v[68:71]
	v_mfma_f32_16x16x32_bf16 v[144:147], v[48:51], v[196:199], v[0:3]
	v_mfma_f32_16x16x32_bf16 v[180:183], v[164:167], v[196:199], v[32:35]
	v_mfma_f32_16x16x32_bf16 v[164:167], v[164:167], v[204:207], v[36:39]
	v_mfma_f32_16x16x32_bf16 v[188:191], v[184:187], v[196:199], v[44:47]
	v_mfma_f32_16x16x32_bf16 v[184:187], v[184:187], v[204:207], v[60:63]
	v_mfma_f32_16x16x32_bf16 v[192:195], v[192:195], v[204:207], v[96:99]
	s_barrier
	ds_read_b128 v[0:3], v225
	ds_read_b128 v[196:199], v225 offset:1024
	ds_read_b128 v[200:203], v225 offset:2048
	ds_read_b128 v[204:207], v225 offset:3072
	ds_read_b128 v[36:39], v228 offset:32768
	ds_read_b128 v[100:103], v228 offset:33792
	ds_read_b128 v[108:111], v229 offset:34816
	ds_read_b128 v[208:211], v229 offset:35840
	ds_read_b128 v[116:119], v229 offset:36864
	ds_read_b128 v[212:215], v229 offset:37888
	ds_read_b128 v[124:127], v229 offset:38912
	ds_read_b128 v[216:219], v229 offset:39936
	s_waitcnt vmcnt(2)
	s_barrier
; #define LDA(dst, b, h) for (int m = 0; m < 4; ++m) for (int k = 0; k < 2; ++k) \
;     dst[m][k] = *reinterpret_cast<const bf16x8*>((char*)SA(b, h) + lds_byte(wr * 64 + m * 16 + fr, k * 32 + fq * 8))
; #define LDB(dst, b, h) for (int n = 0; n < 2; ++n) for (int k = 0; k < 2; ++k) \
;     dst[n][k] = *reinterpret_cast<const bf16x8*>((char*)SB(b, h) + lds_byte(wc * 32 + n * 16 + fr, k * 32 + fq * 8))
; #define MMA(ai, bj, At_, Bt_) do { __builtin_amdgcn_s_setprio(1); \
;     for (int k = 0; k < 2; ++k) for (int m = 0; m < 4; ++m) for (int n = 0; n < 2; ++n) \
;       acc[ai][bj][m][n] = __builtin_amdgcn_mfma_f32_16x16x32_bf16(At_[m][k], Bt_[n][k], acc[ai][bj][m][n], 0, 0, 0); \
;     __builtin_amdgcn_s_setprio(0); } while (0)
; #define WAIT_V(n) asm volatile("s_waitcnt vmcnt(" #n ")" ::: "memory")
; #define WAIT_L(n) asm volatile("s_waitcnt lgkmcnt(" #n ")" ::: "memory")
; #define BAR __builtin_amdgcn_s_barrier()
; template <int EPI, int lda, int ldb, int N, int K>
; __device__ __forceinline__ void gemm_phase(const u16* __restrict__ A, const u16* __restrict__ Bt, const GemmEpi ep, int wv) {
;     ...
;     { LDB(B0, 1, 0); LDA(At, 1, 0); WAIT_V(2); BAR; WAIT_L(0); MMA(0, 0, At, B0); BAR;
;       LDB(B1, 1, 1); WAIT_V(0); BAR; WAIT_L(0); MMA(0, 1, At, B1); BAR;
;       LDA(At, 1, 1); BAR; WAIT_L(0); MMA(1, 0, At, B0); MMA(1, 1, At, B1); BAR; }
;     if (wr == 0) BAR;
	s_waitcnt lgkmcnt(0)
	s_waitcnt lgkmcnt(0)
	v_mfma_f32_16x16x32_bf16 v[4:7], v[36:39], v[0:3], v[4:7]
	v_mfma_f32_16x16x32_bf16 v[16:19], v[36:39], v[200:203], v[16:19]
	v_mfma_f32_16x16x32_bf16 v[32:35], v[108:111], v[0:3], v[72:75]
	v_mfma_f32_16x16x32_bf16 v[44:47], v[108:111], v[200:203], v[76:79]
	v_mfma_f32_16x16x32_bf16 v[72:75], v[116:119], v[0:3], v[80:83]
	v_mfma_f32_16x16x32_bf16 v[76:79], v[116:119], v[200:203], v[84:87]
	v_mfma_f32_16x16x32_bf16 v[80:83], v[124:127], v[0:3], v[88:91]
	v_mfma_f32_16x16x32_bf16 v[84:87], v[124:127], v[200:203], v[92:95]
	v_mfma_f32_16x16x32_bf16 v[120:123], v[100:103], v[196:199], v[4:7]
	v_mfma_f32_16x16x32_bf16 v[60:63], v[100:103], v[204:207], v[16:19]
	v_mfma_f32_16x16x32_bf16 v[112:115], v[208:211], v[196:199], v[32:35]
	v_mfma_f32_16x16x32_bf16 v[48:51], v[208:211], v[204:207], v[44:47]
	v_mfma_f32_16x16x32_bf16 v[104:107], v[212:215], v[196:199], v[72:75]
	v_mfma_f32_16x16x32_bf16 v[44:47], v[212:215], v[204:207], v[76:79]
	v_mfma_f32_16x16x32_bf16 v[96:99], v[216:219], v[196:199], v[80:83]
	v_mfma_f32_16x16x32_bf16 v[32:35], v[216:219], v[204:207], v[84:87]
	s_barrier
	ds_read_b128 v[4:7], v226
	ds_read_b128 v[220:223], v226 offset:1024
	ds_read_b128 v[76:79], v226 offset:2048
	ds_read_b128 v[224:227], v226 offset:3072
	s_waitcnt vmcnt(0)
	s_barrier
	s_waitcnt lgkmcnt(0)
	s_waitcnt lgkmcnt(0)
	v_mfma_f32_16x16x32_bf16 v[12:15], v[36:39], v[4:7], v[12:15]
	v_mfma_f32_16x16x32_bf16 v[16:19], v[36:39], v[76:79], v[40:43]
	v_mfma_f32_16x16x32_bf16 v[36:39], v[108:111], v[4:7], v[152:155]
	v_mfma_f32_16x16x32_bf16 v[40:43], v[108:111], v[76:79], v[156:159]
	v_mfma_f32_16x16x32_bf16 v[72:75], v[116:119], v[4:7], v[52:55]
	v_mfma_f32_16x16x32_bf16 v[80:83], v[116:119], v[76:79], v[56:59]
	v_mfma_f32_16x16x32_bf16 v[84:87], v[124:127], v[4:7], v[160:163]
	v_mfma_f32_16x16x32_bf16 v[64:67], v[124:127], v[76:79], v[64:67]
	v_mfma_f32_16x16x32_bf16 v[124:127], v[100:103], v[220:223], v[12:15]
	v_mfma_f32_16x16x32_bf16 v[56:59], v[100:103], v[224:227], v[16:19]
	v_mfma_f32_16x16x32_bf16 v[116:119], v[208:211], v[220:223], v[36:39]
	v_mfma_f32_16x16x32_bf16 v[52:55], v[208:211], v[224:227], v[40:43]
	v_mfma_f32_16x16x32_bf16 v[108:111], v[212:215], v[220:223], v[72:75]
	v_mfma_f32_16x16x32_bf16 v[40:43], v[212:215], v[224:227], v[80:83]
	v_mfma_f32_16x16x32_bf16 v[100:103], v[216:219], v[220:223], v[84:87]
	v_mfma_f32_16x16x32_bf16 v[36:39], v[216:219], v[224:227], v[64:67]
	s_barrier
	ds_read_b128 v[84:87], v228 offset:49152
	ds_read_b128 v[152:155], v228 offset:50176
	ds_read_b128 v[92:95], v229 offset:51200
	ds_read_b128 v[156:159], v229 offset:52224
	ds_read_b128 v[160:163], v229 offset:53248
	ds_read_b128 v[208:211], v229 offset:54272
	ds_read_b128 v[212:215], v229 offset:55296
	ds_read_b128 v[216:219], v229 offset:56320
	s_barrier
	s_waitcnt lgkmcnt(0)
	s_waitcnt lgkmcnt(0)
	v_mfma_f32_16x16x32_bf16 v[8:11], v[84:87], v[0:3], v[8:11]
	v_mfma_f32_16x16x32_bf16 v[12:15], v[84:87], v[200:203], v[140:143]
	v_mfma_f32_16x16x32_bf16 v[16:19], v[92:95], v[0:3], v[148:151]
	v_mfma_f32_16x16x32_bf16 v[64:67], v[92:95], v[200:203], v[168:171]
	v_mfma_f32_16x16x32_bf16 v[72:75], v[160:163], v[0:3], v[172:175]
	v_mfma_f32_16x16x32_bf16 v[140:143], v[160:163], v[200:203], v[176:179]
	v_mfma_f32_16x16x32_bf16 v[0:3], v[212:215], v[0:3], v[24:27]
	v_mfma_f32_16x16x32_bf16 v[24:27], v[212:215], v[200:203], v[28:31]
	v_mfma_f32_16x16x32_bf16 v[88:91], v[152:155], v[196:199], v[8:11]
	v_mfma_f32_16x16x32_bf16 v[28:31], v[152:155], v[204:207], v[12:15]
	v_mfma_f32_16x16x32_bf16 v[80:83], v[156:159], v[196:199], v[16:19]
	v_mfma_f32_16x16x32_bf16 v[16:19], v[156:159], v[204:207], v[64:67]
	v_mfma_f32_16x16x32_bf16 v[72:75], v[208:211], v[196:199], v[72:75]
	v_mfma_f32_16x16x32_bf16 v[12:15], v[208:211], v[204:207], v[140:143]
	v_mfma_f32_16x16x32_bf16 v[64:67], v[216:219], v[196:199], v[0:3]
	v_mfma_f32_16x16x32_bf16 v[0:3], v[216:219], v[204:207], v[24:27]
	v_mfma_f32_16x16x32_bf16 v[8:11], v[84:87], v[4:7], v[144:147]
	v_mfma_f32_16x16x32_bf16 v[20:23], v[84:87], v[76:79], v[20:23]
	v_mfma_f32_16x16x32_bf16 v[84:87], v[92:95], v[4:7], v[180:183]
	v_mfma_f32_16x16x32_bf16 v[140:143], v[92:95], v[76:79], v[164:167]
	v_mfma_f32_16x16x32_bf16 v[144:147], v[160:163], v[4:7], v[188:191]
	v_mfma_f32_16x16x32_bf16 v[148:151], v[160:163], v[76:79], v[184:187]
	v_mfma_f32_16x16x32_bf16 v[4:7], v[212:215], v[4:7], v[68:71]
	v_mfma_f32_16x16x32_bf16 v[160:163], v[212:215], v[76:79], v[192:195]
	v_mfma_f32_16x16x32_bf16 v[92:95], v[152:155], v[220:223], v[8:11]
	v_mfma_f32_16x16x32_bf16 v[24:27], v[152:155], v[224:227], v[20:23]
	v_mfma_f32_16x16x32_bf16 v[84:87], v[156:159], v[220:223], v[84:87]
	v_mfma_f32_16x16x32_bf16 v[20:23], v[156:159], v[224:227], v[140:143]
	v_mfma_f32_16x16x32_bf16 v[76:79], v[208:211], v[220:223], v[144:147]
	v_mfma_f32_16x16x32_bf16 v[8:11], v[208:211], v[224:227], v[148:151]
	v_mfma_f32_16x16x32_bf16 v[68:71], v[216:219], v[220:223], v[4:7]
	v_mfma_f32_16x16x32_bf16 v[4:7], v[216:219], v[224:227], v[160:163]
	v_cmp_gt_u32_e32 vcc, s60, v130
	s_barrier
	s_and_saveexec_b64 s[46:47], vcc
	s_cbranch_execz .LBB0_1346
	s_barrier
	s_branch .LBB0_1346

; #define STAGE(P, BASE, LD, br, kt) do { const char* _g = (const char*)((BASE) + (size_t)(br) * (LD) + (size_t)(kt) * 64); \
;     for (int _i = 0; _i < 2; ++_i) { int _b = tidx * 16 + _i * 8192; int _r, _c; stage_rc(_b, _r, _c); \
;       __builtin_amdgcn_global_load_lds((const unsigned*)(_g + (unsigned)((_r * (LD) + _c) * 2)), (unsigned*)((char*)(P) + _b), 16, 0, 0); } } while (0)
; #define LDA(dst, b, h) for (int m = 0; m < 4; ++m) for (int k = 0; k < 2; ++k) \
;     dst[m][k] = *reinterpret_cast<const bf16x8*>((char*)SA(b, h) + lds_byte(wr * 64 + m * 16 + fr, k * 32 + fq * 8))
; #define LDB(dst, b, h) for (int n = 0; n < 2; ++n) for (int k = 0; k < 2; ++k) \
;     dst[n][k] = *reinterpret_cast<const bf16x8*>((char*)SB(b, h) + lds_byte(wc * 32 + n * 16 + fr, k * 32 + fq * 8))
; #define MMA(ai, bj, At_, Bt_) do { __builtin_amdgcn_s_setprio(1); \
;     for (int k = 0; k < 2; ++k) for (int m = 0; m < 4; ++m) for (int n = 0; n < 2; ++n) \
;       acc[ai][bj][m][n] = __builtin_amdgcn_mfma_f32_16x16x32_bf16(At_[m][k], Bt_[n][k], acc[ai][bj][m][n], 0, 0, 0); \
;     __builtin_amdgcn_s_setprio(0); } while (0)
; #define WAIT_V(n) asm volatile("s_waitcnt vmcnt(" #n ")" ::: "memory")
; #define WAIT_L(n) asm volatile("s_waitcnt lgkmcnt(" #n ")" ::: "memory")
; #define BAR __builtin_amdgcn_s_barrier()
; #define SCHED __builtin_amdgcn_sched_barrier(0)
; template <int EPI, int lda, int ldb, int N, int K>
; __device__ __forceinline__ void gemm_phase(const u16* __restrict__ A, const u16* __restrict__ Bt, const GemmEpi ep, int wv) {
;     ...
;     for (int t = 0; t < nt - 2; t += 2) {
;       LDB(B0, 0, 0); SCHED; LDA(At, 0, 0); STAGE(SA(1, 1), Ab, lda, brow + HALF, t + 1);
;       WAIT_L(8); BAR; WAIT_L(0); MMA(0, 0, At, B0); BAR; SCHED;
;       LDB(B1, 0, 1); STAGE(SB(0, 0), Bt, ldb, bcol, t + 2);
;       BAR; WAIT_L(0); MMA(0, 1, At, B1); BAR;
;       LDA(At, 0, 1); STAGE(SA(0, 0), Ab, lda, brow, t + 2);
;       BAR; WAIT_L(0); MMA(1, 0, At, B0); BAR; SCHED;
;       STAGE(SB(0, 1), Bt, ldb, bcol + HALF, t + 2);
;       WAIT_V(6); BAR; MMA(1, 1, At, B1); BAR;
;       LDB(B0, 1, 0); SCHED; LDA(At, 1, 0); STAGE(SA(0, 1), Ab, lda, brow + HALF, t + 2);
;       WAIT_L(8); BAR; WAIT_L(0); MMA(0, 0, At, B0); BAR; SCHED;
.LBB0_1448:
	ds_read_b128 v[164:167], v160
	ds_read_b128 v[170:173], v160 offset:1024
	ds_read_b128 v[174:177], v160 offset:2048
	ds_read_b128 v[178:181], v160 offset:3072
	v_add_u32_e32 v168, 0xc000, v143
	v_lshl_add_u64 v[234:235], v[138:139], 0, s[44:45]
	v_readfirstlane_b32 s47, v168
	v_add_u32_e32 v169, 0xe000, v143
	v_lshl_add_u64 v[162:163], v[234:235], 0, s[20:21]
	s_mov_b32 m0, s47
	v_lshl_add_u64 v[236:237], v[140:141], 0, s[44:45]
	v_readfirstlane_b32 s47, v169
	ds_read_b128 v[182:185], v151
	ds_read_b128 v[186:189], v151 offset:1024
	ds_read_b128 v[190:193], v150
	ds_read_b128 v[194:197], v150 offset:1024
	ds_read_b128 v[198:201], v149
	ds_read_b128 v[202:205], v149 offset:1024
	ds_read_b128 v[206:209], v148
	ds_read_b128 v[210:213], v148 offset:1024
	global_load_lds_dwordx4 v[162:163], off
	v_lshl_add_u64 v[162:163], v[236:237], 0, s[20:21]
	s_mov_b32 m0, s47
	s_nop 0
	global_load_lds_dwordx4 v[162:163], off
	s_waitcnt lgkmcnt(8)
	s_barrier
	s_waitcnt lgkmcnt(0)
	s_waitcnt lgkmcnt(0)
	v_mfma_f32_16x16x32_bf16 v[124:127], v[164:167], v[182:185], v[124:127]
	v_mfma_f32_16x16x32_bf16 v[120:123], v[174:177], v[182:185], v[120:123]
	v_mfma_f32_16x16x32_bf16 v[116:119], v[164:167], v[190:193], v[116:119]
	v_mfma_f32_16x16x32_bf16 v[112:115], v[174:177], v[190:193], v[112:115]
	v_mfma_f32_16x16x32_bf16 v[108:111], v[164:167], v[198:201], v[108:111]
	v_mfma_f32_16x16x32_bf16 v[104:107], v[174:177], v[198:201], v[104:107]
	v_mfma_f32_16x16x32_bf16 v[100:103], v[164:167], v[206:209], v[100:103]
	v_mfma_f32_16x16x32_bf16 v[96:99], v[174:177], v[206:209], v[96:99]
	v_mfma_f32_16x16x32_bf16 v[124:127], v[170:173], v[186:189], v[124:127]
	v_mfma_f32_16x16x32_bf16 v[120:123], v[178:181], v[186:189], v[120:123]
	v_mfma_f32_16x16x32_bf16 v[116:119], v[170:173], v[194:197], v[116:119]
	v_mfma_f32_16x16x32_bf16 v[112:115], v[178:181], v[194:197], v[112:115]
	v_mfma_f32_16x16x32_bf16 v[108:111], v[170:173], v[202:205], v[108:111]
	v_mfma_f32_16x16x32_bf16 v[104:107], v[178:181], v[202:205], v[104:107]
	v_mfma_f32_16x16x32_bf16 v[100:103], v[170:173], v[210:213], v[100:103]
	v_mfma_f32_16x16x32_bf16 v[96:99], v[178:181], v[210:213], v[96:99]
	s_barrier
	v_add_u32_e32 v161, s55, v153
	v_lshl_add_u64 v[238:239], v[134:135], 0, s[44:45]
	v_readfirstlane_b32 s47, v161
	v_lshl_add_u64 v[162:163], v[238:239], 0, s[22:23]
	s_mov_b32 m0, s47
	ds_read_b128 v[214:217], v159
	ds_read_b128 v[218:221], v159 offset:1024
	ds_read_b128 v[222:225], v159 offset:2048
	ds_read_b128 v[226:229], v159 offset:3072
	global_load_lds_dwordx4 v[162:163], off
	v_add_u32_e32 v162, 0x2000, v161
	v_lshl_add_u64 v[240:241], v[136:137], 0, s[44:45]
	v_readfirstlane_b32 s47, v162
	v_lshl_add_u64 v[230:231], v[240:241], 0, s[22:23]
	s_mov_b32 m0, s47
	s_nop 0
	global_load_lds_dwordx4 v[230:231], off
	s_barrier
	s_waitcnt lgkmcnt(0)
	s_waitcnt lgkmcnt(0)
	v_mfma_f32_16x16x32_bf16 v[92:95], v[214:217], v[182:185], v[92:95]
	v_mfma_f32_16x16x32_bf16 v[88:91], v[222:225], v[182:185], v[88:91]
	v_mfma_f32_16x16x32_bf16 v[84:87], v[214:217], v[190:193], v[84:87]
	v_mfma_f32_16x16x32_bf16 v[80:83], v[222:225], v[190:193], v[80:83]
	v_mfma_f32_16x16x32_bf16 v[76:79], v[214:217], v[198:201], v[76:79]
	v_mfma_f32_16x16x32_bf16 v[72:75], v[222:225], v[198:201], v[72:75]
	v_mfma_f32_16x16x32_bf16 v[68:71], v[214:217], v[206:209], v[68:71]
	v_mfma_f32_16x16x32_bf16 v[64:67], v[222:225], v[206:209], v[64:67]
	v_mfma_f32_16x16x32_bf16 v[92:95], v[218:221], v[186:189], v[92:95]
	v_mfma_f32_16x16x32_bf16 v[88:91], v[226:229], v[186:189], v[88:91]
	v_mfma_f32_16x16x32_bf16 v[84:87], v[218:221], v[194:197], v[84:87]
	v_mfma_f32_16x16x32_bf16 v[80:83], v[226:229], v[194:197], v[80:83]
	v_mfma_f32_16x16x32_bf16 v[76:79], v[218:221], v[202:205], v[76:79]
	v_mfma_f32_16x16x32_bf16 v[72:75], v[226:229], v[202:205], v[72:75]
	v_mfma_f32_16x16x32_bf16 v[68:71], v[218:221], v[210:213], v[68:71]
	v_mfma_f32_16x16x32_bf16 v[64:67], v[226:229], v[210:213], v[64:67]
	v_readfirstlane_b32 s47, v143
	v_add_u32_e32 v163, 0x2000, v143
	v_lshl_add_u64 v[230:231], v[234:235], 0, s[24:25]
	s_mov_b32 m0, s47
	v_readfirstlane_b32 s47, v163
	s_barrier
	ds_read_b128 v[182:185], v151 offset:16384
	ds_read_b128 v[186:189], v151 offset:17408
	ds_read_b128 v[190:193], v150 offset:16384
	ds_read_b128 v[194:197], v150 offset:17408
	ds_read_b128 v[198:201], v149 offset:16384
	ds_read_b128 v[202:205], v149 offset:17408
	ds_read_b128 v[206:209], v148 offset:16384
	ds_read_b128 v[210:213], v148 offset:17408
	global_load_lds_dwordx4 v[230:231], off
	v_lshl_add_u64 v[230:231], v[236:237], 0, s[24:25]
	s_mov_b32 m0, s47
	s_nop 0
	global_load_lds_dwordx4 v[230:231], off
	s_barrier
	s_waitcnt lgkmcnt(0)
	s_waitcnt lgkmcnt(0)
	v_mfma_f32_16x16x32_bf16 v[60:63], v[164:167], v[182:185], v[60:63]
	v_mfma_f32_16x16x32_bf16 v[56:59], v[174:177], v[182:185], v[56:59]
	v_mfma_f32_16x16x32_bf16 v[52:55], v[164:167], v[190:193], v[52:55]
	v_mfma_f32_16x16x32_bf16 v[48:51], v[174:177], v[190:193], v[48:51]
	v_mfma_f32_16x16x32_bf16 v[44:47], v[164:167], v[198:201], v[44:47]
	v_mfma_f32_16x16x32_bf16 v[40:43], v[174:177], v[198:201], v[40:43]
	v_mfma_f32_16x16x32_bf16 v[36:39], v[164:167], v[206:209], v[36:39]
	v_mfma_f32_16x16x32_bf16 v[32:35], v[174:177], v[206:209], v[32:35]
	v_mfma_f32_16x16x32_bf16 v[60:63], v[170:173], v[186:189], v[60:63]
	v_mfma_f32_16x16x32_bf16 v[56:59], v[178:181], v[186:189], v[56:59]
	v_mfma_f32_16x16x32_bf16 v[52:55], v[170:173], v[194:197], v[52:55]
	v_mfma_f32_16x16x32_bf16 v[48:51], v[178:181], v[194:197], v[48:51]
	v_mfma_f32_16x16x32_bf16 v[44:47], v[170:173], v[202:205], v[44:47]
	v_mfma_f32_16x16x32_bf16 v[40:43], v[178:181], v[202:205], v[40:43]
	v_mfma_f32_16x16x32_bf16 v[36:39], v[170:173], v[210:213], v[36:39]
	v_mfma_f32_16x16x32_bf16 v[32:35], v[178:181], v[210:213], v[32:35]
	s_barrier
; #define STAGE(P, BASE, LD, br, kt) do { const char* _g = (const char*)((BASE) + (size_t)(br) * (LD) + (size_t)(kt) * 64); \
;     for (int _i = 0; _i < 2; ++_i) { int _b = tidx * 16 + _i * 8192; int _r, _c; stage_rc(_b, _r, _c); \
;       __builtin_amdgcn_global_load_lds((const unsigned*)(_g + (unsigned)((_r * (LD) + _c) * 2)), (unsigned*)((char*)(P) + _b), 16, 0, 0); } } while (0)
; #define LDA(dst, b, h) for (int m = 0; m < 4; ++m) for (int k = 0; k < 2; ++k) \
;     dst[m][k] = *reinterpret_cast<const bf16x8*>((char*)SA(b, h) + lds_byte(wr * 64 + m * 16 + fr, k * 32 + fq * 8))
; #define LDB(dst, b, h) for (int n = 0; n < 2; ++n) for (int k = 0; k < 2; ++k) \
;     dst[n][k] = *reinterpret_cast<const bf16x8*>((char*)SB(b, h) + lds_byte(wc * 32 + n * 16 + fr, k * 32 + fq * 8))
; #define MMA(ai, bj, At_, Bt_) do { __builtin_amdgcn_s_setprio(1); \
;     for (int k = 0; k < 2; ++k) for (int m = 0; m < 4; ++m) for (int n = 0; n < 2; ++n) \
;       acc[ai][bj][m][n] = __builtin_amdgcn_mfma_f32_16x16x32_bf16(At_[m][k], Bt_[n][k], acc[ai][bj][m][n], 0, 0, 0); \
;     __builtin_amdgcn_s_setprio(0); } while (0)
; #define WAIT_V(n) asm volatile("s_waitcnt vmcnt(" #n ")" ::: "memory")
; #define WAIT_L(n) asm volatile("s_waitcnt lgkmcnt(" #n ")" ::: "memory")
; #define BAR __builtin_amdgcn_s_barrier()
; #define SCHED __builtin_amdgcn_sched_barrier(0)
; template <int EPI, int lda, int ldb, int N, int K>
; __device__ __forceinline__ void gemm_phase(const u16* __restrict__ A, const u16* __restrict__ Bt, const GemmEpi ep, int wv) {
;     ...
;       STAGE(SB(0, 1), Bt, ldb, bcol + HALF, t + 2);
;       WAIT_V(6); BAR; MMA(1, 1, At, B1); BAR;
;       LDB(B0, 1, 0); SCHED; LDA(At, 1, 0); STAGE(SA(0, 1), Ab, lda, brow + HALF, t + 2);
;       WAIT_L(8); BAR; WAIT_L(0); MMA(0, 0, At, B0); BAR; SCHED;
;       LDB(B1, 1, 1); STAGE(SB(1, 0), Bt, ldb, bcol, t + 3);
;       BAR; WAIT_L(0); MMA(0, 1, At, B1); BAR;
;       LDA(At, 1, 1); STAGE(SA(1, 0), Ab, lda, brow, t + 3);
;       BAR; WAIT_L(0); MMA(1, 0, At, B0); BAR; SCHED;
	v_add_u32_e32 v164, s56, v153
	v_add_u32_e32 v165, 0x2000, v164
	v_readfirstlane_b32 s47, v164
	v_lshl_add_u64 v[166:167], v[238:239], 0, s[26:27]
	s_mov_b32 m0, s47
	v_readfirstlane_b32 s47, v165
	global_load_lds_dwordx4 v[166:167], off
	v_lshl_add_u64 v[166:167], v[240:241], 0, s[26:27]
	s_mov_b32 m0, s47
	s_nop 0
	global_load_lds_dwordx4 v[166:167], off
	s_waitcnt vmcnt(6)
	s_barrier
	v_mfma_f32_16x16x32_bf16 v[28:31], v[214:217], v[182:185], v[28:31]
	v_mfma_f32_16x16x32_bf16 v[24:27], v[222:225], v[182:185], v[24:27]
	v_mfma_f32_16x16x32_bf16 v[20:23], v[214:217], v[190:193], v[20:23]
	v_mfma_f32_16x16x32_bf16 v[16:19], v[222:225], v[190:193], v[16:19]
	v_mfma_f32_16x16x32_bf16 v[12:15], v[214:217], v[198:201], v[12:15]
	v_mfma_f32_16x16x32_bf16 v[8:11], v[222:225], v[198:201], v[8:11]
	v_mfma_f32_16x16x32_bf16 v[4:7], v[214:217], v[206:209], v[4:7]
	v_mfma_f32_16x16x32_bf16 v[0:3], v[222:225], v[206:209], v[0:3]
	v_mfma_f32_16x16x32_bf16 v[28:31], v[218:221], v[186:189], v[28:31]
	v_mfma_f32_16x16x32_bf16 v[24:27], v[226:229], v[186:189], v[24:27]
	v_mfma_f32_16x16x32_bf16 v[20:23], v[218:221], v[194:197], v[20:23]
	v_mfma_f32_16x16x32_bf16 v[16:19], v[226:229], v[194:197], v[16:19]
	v_mfma_f32_16x16x32_bf16 v[12:15], v[218:221], v[202:205], v[12:15]
	v_mfma_f32_16x16x32_bf16 v[8:11], v[226:229], v[202:205], v[8:11]
	v_mfma_f32_16x16x32_bf16 v[4:7], v[218:221], v[210:213], v[4:7]
	v_mfma_f32_16x16x32_bf16 v[0:3], v[226:229], v[210:213], v[0:3]
	s_barrier
	ds_read_b128 v[170:173], v154
	ds_read_b128 v[174:177], v154 offset:1024
	ds_read_b128 v[178:181], v154 offset:2048
	ds_read_b128 v[182:185], v154 offset:3072
	v_add_u32_e32 v166, 0x4000, v143
	v_add_u32_e32 v167, 0x6000, v143
	v_readfirstlane_b32 s47, v166
	v_lshl_add_u64 v[218:219], v[234:235], 0, s[34:35]
	s_mov_b32 m0, s47
	v_readfirstlane_b32 s47, v167
	ds_read_b128 v[186:189], v151 offset:32768
	ds_read_b128 v[190:193], v151 offset:33792
	ds_read_b128 v[194:197], v150 offset:32768
	ds_read_b128 v[198:201], v150 offset:33792
	ds_read_b128 v[202:205], v149 offset:32768
	ds_read_b128 v[206:209], v149 offset:33792
	ds_read_b128 v[210:213], v148 offset:32768
	ds_read_b128 v[214:217], v148 offset:33792
	global_load_lds_dwordx4 v[218:219], off
	v_lshl_add_u64 v[218:219], v[236:237], 0, s[34:35]
	s_mov_b32 m0, s47
	s_nop 0
	global_load_lds_dwordx4 v[218:219], off
	s_waitcnt lgkmcnt(8)
	s_barrier
	s_waitcnt lgkmcnt(0)
	s_waitcnt lgkmcnt(0)
	v_mfma_f32_16x16x32_bf16 v[124:127], v[170:173], v[186:189], v[124:127]
	v_mfma_f32_16x16x32_bf16 v[120:123], v[178:181], v[186:189], v[120:123]
	v_mfma_f32_16x16x32_bf16 v[116:119], v[170:173], v[194:197], v[116:119]
	v_mfma_f32_16x16x32_bf16 v[112:115], v[178:181], v[194:197], v[112:115]
	v_mfma_f32_16x16x32_bf16 v[108:111], v[170:173], v[202:205], v[108:111]
	v_mfma_f32_16x16x32_bf16 v[104:107], v[178:181], v[202:205], v[104:107]
	v_mfma_f32_16x16x32_bf16 v[100:103], v[170:173], v[210:213], v[100:103]
	v_mfma_f32_16x16x32_bf16 v[96:99], v[178:181], v[210:213], v[96:99]
	v_mfma_f32_16x16x32_bf16 v[124:127], v[174:177], v[190:193], v[124:127]
	v_mfma_f32_16x16x32_bf16 v[120:123], v[182:185], v[190:193], v[120:123]
	v_mfma_f32_16x16x32_bf16 v[116:119], v[174:177], v[198:201], v[116:119]
	v_mfma_f32_16x16x32_bf16 v[112:115], v[182:185], v[198:201], v[112:115]
	v_mfma_f32_16x16x32_bf16 v[108:111], v[174:177], v[206:209], v[108:111]
	v_mfma_f32_16x16x32_bf16 v[104:107], v[182:185], v[206:209], v[104:107]
	v_mfma_f32_16x16x32_bf16 v[100:103], v[174:177], v[214:217], v[100:103]
	v_mfma_f32_16x16x32_bf16 v[96:99], v[182:185], v[214:217], v[96:99]
	s_barrier
	v_readfirstlane_b32 s47, v155
	v_add_u32_e32 v244, 0x2000, v155
	v_lshl_add_u64 v[242:243], v[238:239], 0, s[36:37]
	s_mov_b32 m0, s47
	v_readfirstlane_b32 s47, v244
	ds_read_b128 v[218:221], v152
	ds_read_b128 v[222:225], v152 offset:1024
	ds_read_b128 v[226:229], v152 offset:2048
	ds_read_b128 v[230:233], v152 offset:3072
	global_load_lds_dwordx4 v[242:243], off
	v_lshl_add_u64 v[242:243], v[240:241], 0, s[36:37]
	s_mov_b32 m0, s47
	s_nop 0
	global_load_lds_dwordx4 v[242:243], off
	s_barrier
	s_waitcnt lgkmcnt(0)
	s_waitcnt lgkmcnt(0)
	v_mfma_f32_16x16x32_bf16 v[92:95], v[218:221], v[186:189], v[92:95]
	v_mfma_f32_16x16x32_bf16 v[88:91], v[226:229], v[186:189], v[88:91]
	v_mfma_f32_16x16x32_bf16 v[84:87], v[218:221], v[194:197], v[84:87]
	v_mfma_f32_16x16x32_bf16 v[80:83], v[226:229], v[194:197], v[80:83]
	v_mfma_f32_16x16x32_bf16 v[76:79], v[218:221], v[202:205], v[76:79]
	v_mfma_f32_16x16x32_bf16 v[72:75], v[226:229], v[202:205], v[72:75]
	v_mfma_f32_16x16x32_bf16 v[68:71], v[218:221], v[210:213], v[68:71]
	v_mfma_f32_16x16x32_bf16 v[64:67], v[226:229], v[210:213], v[64:67]
	v_mfma_f32_16x16x32_bf16 v[92:95], v[222:225], v[190:193], v[92:95]
	v_mfma_f32_16x16x32_bf16 v[88:91], v[230:233], v[190:193], v[88:91]
	v_mfma_f32_16x16x32_bf16 v[84:87], v[222:225], v[198:201], v[84:87]
	v_mfma_f32_16x16x32_bf16 v[80:83], v[230:233], v[198:201], v[80:83]
	v_mfma_f32_16x16x32_bf16 v[76:79], v[222:225], v[206:209], v[76:79]
	v_mfma_f32_16x16x32_bf16 v[72:75], v[230:233], v[206:209], v[72:75]
	v_mfma_f32_16x16x32_bf16 v[68:71], v[222:225], v[214:217], v[68:71]
	v_mfma_f32_16x16x32_bf16 v[64:67], v[230:233], v[214:217], v[64:67]
	v_readfirstlane_b32 s47, v156
	v_lshl_add_u64 v[234:235], v[234:235], 0, s[38:39]
	s_mov_b32 m0, s47
	v_readfirstlane_b32 s47, v157
	s_barrier
; #define STAGE(P, BASE, LD, br, kt) do { const char* _g = (const char*)((BASE) + (size_t)(br) * (LD) + (size_t)(kt) * 64); \
;     for (int _i = 0; _i < 2; ++_i) { int _b = tidx * 16 + _i * 8192; int _r, _c; stage_rc(_b, _r, _c); \
;       __builtin_amdgcn_global_load_lds((const unsigned*)(_g + (unsigned)((_r * (LD) + _c) * 2)), (unsigned*)((char*)(P) + _b), 16, 0, 0); } } while (0)
; #define LDA(dst, b, h) for (int m = 0; m < 4; ++m) for (int k = 0; k < 2; ++k) \
;     dst[m][k] = *reinterpret_cast<const bf16x8*>((char*)SA(b, h) + lds_byte(wr * 64 + m * 16 + fr, k * 32 + fq * 8))
; #define LDB(dst, b, h) for (int n = 0; n < 2; ++n) for (int k = 0; k < 2; ++k) \
;     dst[n][k] = *reinterpret_cast<const bf16x8*>((char*)SB(b, h) + lds_byte(wc * 32 + n * 16 + fr, k * 32 + fq * 8))
; #define MMA(ai, bj, At_, Bt_) do { __builtin_amdgcn_s_setprio(1); \
;     for (int k = 0; k < 2; ++k) for (int m = 0; m < 4; ++m) for (int n = 0; n < 2; ++n) \
;       acc[ai][bj][m][n] = __builtin_amdgcn_mfma_f32_16x16x32_bf16(At_[m][k], Bt_[n][k], acc[ai][bj][m][n], 0, 0, 0); \
;     __builtin_amdgcn_s_setprio(0); } while (0)
; #define WAIT_V(n) asm volatile("s_waitcnt vmcnt(" #n ")" ::: "memory")
; #define WAIT_L(n) asm volatile("s_waitcnt lgkmcnt(" #n ")" ::: "memory")
; #define BAR __builtin_amdgcn_s_barrier()
; #define SCHED __builtin_amdgcn_sched_barrier(0)
; template <int EPI, int lda, int ldb, int N, int K>
; __device__ __forceinline__ void gemm_phase(const u16* __restrict__ A, const u16* __restrict__ Bt, const GemmEpi ep, int wv) {
;     ...
;       LDB(B1, 1, 1); STAGE(SB(1, 0), Bt, ldb, bcol, t + 3);
;       BAR; WAIT_L(0); MMA(0, 1, At, B1); BAR;
;       LDA(At, 1, 1); STAGE(SA(1, 0), Ab, lda, brow, t + 3);
;       BAR; WAIT_L(0); MMA(1, 0, At, B0); BAR; SCHED;
;       STAGE(SB(1, 1), Bt, ldb, bcol + HALF, t + 3);
;       WAIT_V(6); BAR; MMA(1, 1, At, B1); BAR;
;     }
;     { LDB(B0, 0, 0); LDA(At, 0, 0); STAGE(SA(1, 1), Ab, lda, brow + HALF, nt - 1);
;       BAR; WAIT_L(0); MMA(0, 0, At, B0); BAR;
;       LDB(B1, 0, 1); BAR; WAIT_L(0); MMA(0, 1, At, B1); BAR;
	ds_read_b128 v[186:189], v151 offset:49152
	ds_read_b128 v[190:193], v151 offset:50176
	ds_read_b128 v[194:197], v150 offset:49152
	ds_read_b128 v[198:201], v150 offset:50176
	ds_read_b128 v[202:205], v149 offset:49152
	ds_read_b128 v[206:209], v149 offset:50176
	ds_read_b128 v[210:213], v148 offset:49152
	ds_read_b128 v[214:217], v148 offset:50176
	global_load_lds_dwordx4 v[234:235], off
	v_lshl_add_u64 v[234:235], v[236:237], 0, s[38:39]
	s_mov_b32 m0, s47
	s_nop 0
	global_load_lds_dwordx4 v[234:235], off
	s_barrier
	s_waitcnt lgkmcnt(0)
	s_waitcnt lgkmcnt(0)
	v_mfma_f32_16x16x32_bf16 v[60:63], v[170:173], v[186:189], v[60:63]
	v_mfma_f32_16x16x32_bf16 v[56:59], v[178:181], v[186:189], v[56:59]
	v_mfma_f32_16x16x32_bf16 v[52:55], v[170:173], v[194:197], v[52:55]
	v_mfma_f32_16x16x32_bf16 v[48:51], v[178:181], v[194:197], v[48:51]
	v_mfma_f32_16x16x32_bf16 v[44:47], v[170:173], v[202:205], v[44:47]
	v_mfma_f32_16x16x32_bf16 v[40:43], v[178:181], v[202:205], v[40:43]
	v_mfma_f32_16x16x32_bf16 v[36:39], v[170:173], v[210:213], v[36:39]
	v_mfma_f32_16x16x32_bf16 v[32:35], v[178:181], v[210:213], v[32:35]
	v_mfma_f32_16x16x32_bf16 v[60:63], v[174:177], v[190:193], v[60:63]
	v_mfma_f32_16x16x32_bf16 v[56:59], v[182:185], v[190:193], v[56:59]
	v_mfma_f32_16x16x32_bf16 v[52:55], v[174:177], v[198:201], v[52:55]
	v_mfma_f32_16x16x32_bf16 v[48:51], v[182:185], v[198:201], v[48:51]
	v_mfma_f32_16x16x32_bf16 v[44:47], v[174:177], v[206:209], v[44:47]
	v_mfma_f32_16x16x32_bf16 v[40:43], v[182:185], v[206:209], v[40:43]
	v_mfma_f32_16x16x32_bf16 v[36:39], v[174:177], v[214:217], v[36:39]
	v_mfma_f32_16x16x32_bf16 v[32:35], v[182:185], v[214:217], v[32:35]
	s_barrier
	v_readfirstlane_b32 s47, v158
	v_add_u32_e32 v172, 0x2000, v158
	v_lshl_add_u64 v[170:171], v[238:239], 0, s[40:41]
	s_mov_b32 m0, s47
	v_readfirstlane_b32 s47, v172
	global_load_lds_dwordx4 v[170:171], off
	v_lshl_add_u64 v[170:171], v[240:241], 0, s[40:41]
	s_mov_b32 m0, s47
	s_nop 0
	global_load_lds_dwordx4 v[170:171], off
	s_waitcnt vmcnt(6)
	s_barrier
	v_mfma_f32_16x16x32_bf16 v[28:31], v[218:221], v[186:189], v[28:31]
	v_mfma_f32_16x16x32_bf16 v[24:27], v[226:229], v[186:189], v[24:27]
	v_mfma_f32_16x16x32_bf16 v[20:23], v[218:221], v[194:197], v[20:23]
	v_mfma_f32_16x16x32_bf16 v[16:19], v[226:229], v[194:197], v[16:19]
	v_mfma_f32_16x16x32_bf16 v[12:15], v[218:221], v[202:205], v[12:15]
	v_mfma_f32_16x16x32_bf16 v[8:11], v[226:229], v[202:205], v[8:11]
	v_mfma_f32_16x16x32_bf16 v[4:7], v[218:221], v[210:213], v[4:7]
	v_mfma_f32_16x16x32_bf16 v[0:3], v[226:229], v[210:213], v[0:3]
	v_mfma_f32_16x16x32_bf16 v[28:31], v[222:225], v[190:193], v[28:31]
	v_mfma_f32_16x16x32_bf16 v[24:27], v[230:233], v[190:193], v[24:27]
	v_mfma_f32_16x16x32_bf16 v[20:23], v[222:225], v[198:201], v[20:23]
	v_mfma_f32_16x16x32_bf16 v[16:19], v[230:233], v[198:201], v[16:19]
	v_mfma_f32_16x16x32_bf16 v[12:15], v[222:225], v[206:209], v[12:15]
	v_mfma_f32_16x16x32_bf16 v[8:11], v[230:233], v[206:209], v[8:11]
	v_mfma_f32_16x16x32_bf16 v[4:7], v[222:225], v[214:217], v[4:7]
	v_mfma_f32_16x16x32_bf16 v[0:3], v[230:233], v[214:217], v[0:3]
	s_add_i32 s46, s46, 2
	s_add_u32 s44, s44, 0x100
	s_addc_u32 s45, s45, 0
	s_cmp_gt_u32 s46, 27
	s_barrier
	s_cbranch_scc0 .LBB0_1448
	s_lshl_b64 s[44:45], s[16:17], 12
	s_add_u32 s44, s14, s44
	s_addc_u32 s45, s15, s45
	s_add_u32 s44, s44, 0x80000
	s_addc_u32 s45, s45, 0
	v_lshl_add_u64 v[156:157], s[44:45], 0, v[128:129]
	v_readfirstlane_b32 s46, v168
	v_lshl_add_u64 v[156:157], v[156:157], 0, s[42:43]
	s_mov_b32 m0, s46
	ds_read_b128 v[134:137], v160
	ds_read_b128 v[138:141], v160 offset:1024
	ds_read_b128 v[170:173], v160 offset:2048
	ds_read_b128 v[174:177], v160 offset:3072
	ds_read_b128 v[178:181], v151
	ds_read_b128 v[182:185], v151 offset:1024
	ds_read_b128 v[186:189], v150
	ds_read_b128 v[190:193], v150 offset:1024
	ds_read_b128 v[194:197], v149
	ds_read_b128 v[198:201], v149 offset:1024
	ds_read_b128 v[202:205], v148
	ds_read_b128 v[206:209], v148 offset:1024
	global_load_lds_dwordx4 v[156:157], off
	v_lshl_add_u64 v[156:157], s[44:45], 0, v[132:133]
	v_readfirstlane_b32 s44, v169
	v_lshl_add_u64 v[156:157], v[156:157], 0, s[42:43]
	s_mov_b32 m0, s44
	s_nop 0
	global_load_lds_dwordx4 v[156:157], off
	s_barrier
	s_waitcnt lgkmcnt(0)
	s_waitcnt lgkmcnt(0)
	v_mfma_f32_16x16x32_bf16 v[124:127], v[134:137], v[178:181], v[124:127]
	v_mfma_f32_16x16x32_bf16 v[120:123], v[170:173], v[178:181], v[120:123]
	v_mfma_f32_16x16x32_bf16 v[116:119], v[134:137], v[186:189], v[116:119]
	v_mfma_f32_16x16x32_bf16 v[112:115], v[170:173], v[186:189], v[112:115]
	v_mfma_f32_16x16x32_bf16 v[108:111], v[134:137], v[194:197], v[108:111]
	v_mfma_f32_16x16x32_bf16 v[104:107], v[170:173], v[194:197], v[104:107]
	v_mfma_f32_16x16x32_bf16 v[100:103], v[134:137], v[202:205], v[100:103]
	v_mfma_f32_16x16x32_bf16 v[96:99], v[170:173], v[202:205], v[96:99]
	v_mfma_f32_16x16x32_bf16 v[124:127], v[138:141], v[182:185], v[124:127]
	v_mfma_f32_16x16x32_bf16 v[120:123], v[174:177], v[182:185], v[120:123]
	v_mfma_f32_16x16x32_bf16 v[116:119], v[138:141], v[190:193], v[116:119]
	v_mfma_f32_16x16x32_bf16 v[112:115], v[174:177], v[190:193], v[112:115]
	v_mfma_f32_16x16x32_bf16 v[108:111], v[138:141], v[198:201], v[108:111]
	v_mfma_f32_16x16x32_bf16 v[104:107], v[174:177], v[198:201], v[104:107]
	v_mfma_f32_16x16x32_bf16 v[100:103], v[138:141], v[206:209], v[100:103]
	v_mfma_f32_16x16x32_bf16 v[96:99], v[174:177], v[206:209], v[96:99]
	s_barrier
	ds_read_b128 v[210:213], v159
	ds_read_b128 v[214:217], v159 offset:1024
	ds_read_b128 v[218:221], v159 offset:2048
	ds_read_b128 v[156:159], v159 offset:3072
	s_barrier
; #define LDA(dst, b, h) for (int m = 0; m < 4; ++m) for (int k = 0; k < 2; ++k) \
;     dst[m][k] = *reinterpret_cast<const bf16x8*>((char*)SA(b, h) + lds_byte(wr * 64 + m * 16 + fr, k * 32 + fq * 8))
; #define LDB(dst, b, h) for (int n = 0; n < 2; ++n) for (int k = 0; k < 2; ++k) \
;     dst[n][k] = *reinterpret_cast<const bf16x8*>((char*)SB(b, h) + lds_byte(wc * 32 + n * 16 + fr, k * 32 + fq * 8))
; #define MMA(ai, bj, At_, Bt_) do { __builtin_amdgcn_s_setprio(1); \
;     for (int k = 0; k < 2; ++k) for (int m = 0; m < 4; ++m) for (int n = 0; n < 2; ++n) \
;       acc[ai][bj][m][n] = __builtin_amdgcn_mfma_f32_16x16x32_bf16(At_[m][k], Bt_[n][k], acc[ai][bj][m][n], 0, 0, 0); \
;     __builtin_amdgcn_s_setprio(0); } while (0)
; #define WAIT_V(n) asm volatile("s_waitcnt vmcnt(" #n ")" ::: "memory")
; #define WAIT_L(n) asm volatile("s_waitcnt lgkmcnt(" #n ")" ::: "memory")
; #define BAR __builtin_amdgcn_s_barrier()
; template <int EPI, int lda, int ldb, int N, int K>
; __device__ __forceinline__ void gemm_phase(const u16* __restrict__ A, const u16* __restrict__ Bt, const GemmEpi ep, int wv) {
;     ...
;       LDB(B1, 0, 1); BAR; WAIT_L(0); MMA(0, 1, At, B1); BAR;
;       LDA(At, 0, 1); WAIT_V(4); BAR; WAIT_L(0); MMA(1, 0, At, B0); MMA(1, 1, At, B1); BAR; }
;     { LDB(B0, 1, 0); LDA(At, 1, 0); WAIT_V(2); BAR; WAIT_L(0); MMA(0, 0, At, B0); BAR;
	s_waitcnt lgkmcnt(0)
	s_waitcnt lgkmcnt(0)
	v_mfma_f32_16x16x32_bf16 v[92:95], v[210:213], v[178:181], v[92:95]
	v_mfma_f32_16x16x32_bf16 v[88:91], v[218:221], v[178:181], v[88:91]
	v_mfma_f32_16x16x32_bf16 v[76:79], v[210:213], v[194:197], v[76:79]
	v_mfma_f32_16x16x32_bf16 v[72:75], v[218:221], v[194:197], v[72:75]
	v_mfma_f32_16x16x32_bf16 v[84:87], v[210:213], v[186:189], v[84:87]
	v_mfma_f32_16x16x32_bf16 v[80:83], v[218:221], v[186:189], v[80:83]
	v_mfma_f32_16x16x32_bf16 v[68:71], v[210:213], v[202:205], v[68:71]
	v_mfma_f32_16x16x32_bf16 v[64:67], v[218:221], v[202:205], v[64:67]
	v_mfma_f32_16x16x32_bf16 v[92:95], v[214:217], v[182:185], v[92:95]
	v_mfma_f32_16x16x32_bf16 v[88:91], v[156:159], v[182:185], v[88:91]
	v_mfma_f32_16x16x32_bf16 v[76:79], v[214:217], v[198:201], v[76:79]
	v_mfma_f32_16x16x32_bf16 v[72:75], v[156:159], v[198:201], v[72:75]
	v_mfma_f32_16x16x32_bf16 v[178:181], v[214:217], v[190:193], v[84:87]
	v_mfma_f32_16x16x32_bf16 v[182:185], v[156:159], v[190:193], v[80:83]
	v_mfma_f32_16x16x32_bf16 v[186:189], v[214:217], v[206:209], v[68:71]
	v_mfma_f32_16x16x32_bf16 v[190:193], v[156:159], v[206:209], v[64:67]
	s_barrier
	s_nop 0
	ds_read_b128 v[64:67], v151 offset:16384
	ds_read_b128 v[68:71], v151 offset:17408
	ds_read_b128 v[80:83], v150 offset:16384
	ds_read_b128 v[84:87], v150 offset:17408
	ds_read_b128 v[194:197], v149 offset:16384
	ds_read_b128 v[198:201], v149 offset:17408
	ds_read_b128 v[202:205], v148 offset:16384
	ds_read_b128 v[206:209], v148 offset:17408
	s_waitcnt vmcnt(4)
	s_barrier
	s_waitcnt lgkmcnt(0)
	s_waitcnt lgkmcnt(0)
	v_mfma_f32_16x16x32_bf16 v[60:63], v[134:137], v[64:67], v[60:63]
	v_mfma_f32_16x16x32_bf16 v[56:59], v[170:173], v[64:67], v[56:59]
	v_mfma_f32_16x16x32_bf16 v[52:55], v[134:137], v[80:83], v[52:55]
	v_mfma_f32_16x16x32_bf16 v[48:51], v[170:173], v[80:83], v[48:51]
	v_mfma_f32_16x16x32_bf16 v[44:47], v[134:137], v[194:197], v[44:47]
	v_mfma_f32_16x16x32_bf16 v[40:43], v[170:173], v[194:197], v[40:43]
	v_mfma_f32_16x16x32_bf16 v[36:39], v[134:137], v[202:205], v[36:39]
	v_mfma_f32_16x16x32_bf16 v[32:35], v[170:173], v[202:205], v[32:35]
	v_mfma_f32_16x16x32_bf16 v[60:63], v[138:141], v[68:71], v[60:63]
	v_mfma_f32_16x16x32_bf16 v[56:59], v[174:177], v[68:71], v[56:59]
	v_mfma_f32_16x16x32_bf16 v[52:55], v[138:141], v[84:87], v[52:55]
	v_mfma_f32_16x16x32_bf16 v[48:51], v[174:177], v[84:87], v[48:51]
	v_mfma_f32_16x16x32_bf16 v[44:47], v[138:141], v[198:201], v[44:47]
	v_mfma_f32_16x16x32_bf16 v[40:43], v[174:177], v[198:201], v[40:43]
	v_mfma_f32_16x16x32_bf16 v[36:39], v[138:141], v[206:209], v[36:39]
	v_mfma_f32_16x16x32_bf16 v[32:35], v[174:177], v[206:209], v[32:35]
	v_mfma_f32_16x16x32_bf16 v[28:31], v[210:213], v[64:67], v[28:31]
	v_mfma_f32_16x16x32_bf16 v[20:23], v[210:213], v[80:83], v[20:23]
	v_mfma_f32_16x16x32_bf16 v[12:15], v[210:213], v[194:197], v[12:15]
	v_mfma_f32_16x16x32_bf16 v[4:7], v[210:213], v[202:205], v[4:7]
	v_mfma_f32_16x16x32_bf16 v[24:27], v[218:221], v[64:67], v[24:27]
	v_mfma_f32_16x16x32_bf16 v[16:19], v[218:221], v[80:83], v[16:19]
	v_mfma_f32_16x16x32_bf16 v[8:11], v[218:221], v[194:197], v[8:11]
	v_mfma_f32_16x16x32_bf16 v[0:3], v[218:221], v[202:205], v[0:3]
	v_mfma_f32_16x16x32_bf16 v[28:31], v[214:217], v[68:71], v[28:31]
	v_mfma_f32_16x16x32_bf16 v[20:23], v[214:217], v[84:87], v[20:23]
	v_mfma_f32_16x16x32_bf16 v[12:15], v[214:217], v[198:201], v[12:15]
	v_mfma_f32_16x16x32_bf16 v[4:7], v[214:217], v[206:209], v[4:7]
	v_mfma_f32_16x16x32_bf16 v[134:137], v[156:159], v[68:71], v[24:27]
	v_mfma_f32_16x16x32_bf16 v[138:141], v[156:159], v[84:87], v[16:19]
	v_mfma_f32_16x16x32_bf16 v[168:171], v[156:159], v[198:201], v[8:11]
	v_mfma_f32_16x16x32_bf16 v[156:159], v[156:159], v[206:209], v[0:3]
	s_barrier
	s_nop 0
	ds_read_b128 v[0:3], v154
	ds_read_b128 v[8:11], v154 offset:1024
	ds_read_b128 v[16:19], v154 offset:2048
	ds_read_b128 v[172:175], v154 offset:3072
	ds_read_b128 v[24:27], v151 offset:32768
	ds_read_b128 v[194:197], v151 offset:33792
	ds_read_b128 v[198:201], v150 offset:32768
	ds_read_b128 v[202:205], v150 offset:33792
	ds_read_b128 v[206:209], v149 offset:32768
	ds_read_b128 v[210:213], v149 offset:33792
	ds_read_b128 v[214:217], v148 offset:32768
	ds_read_b128 v[218:221], v148 offset:33792
	s_waitcnt vmcnt(2)
	s_barrier
; #define LDA(dst, b, h) for (int m = 0; m < 4; ++m) for (int k = 0; k < 2; ++k) \
;     dst[m][k] = *reinterpret_cast<const bf16x8*>((char*)SA(b, h) + lds_byte(wr * 64 + m * 16 + fr, k * 32 + fq * 8))
; #define LDB(dst, b, h) for (int n = 0; n < 2; ++n) for (int k = 0; k < 2; ++k) \
;     dst[n][k] = *reinterpret_cast<const bf16x8*>((char*)SB(b, h) + lds_byte(wc * 32 + n * 16 + fr, k * 32 + fq * 8))
; #define MMA(ai, bj, At_, Bt_) do { __builtin_amdgcn_s_setprio(1); \
;     for (int k = 0; k < 2; ++k) for (int m = 0; m < 4; ++m) for (int n = 0; n < 2; ++n) \
;       acc[ai][bj][m][n] = __builtin_amdgcn_mfma_f32_16x16x32_bf16(At_[m][k], Bt_[n][k], acc[ai][bj][m][n], 0, 0, 0); \
;     __builtin_amdgcn_s_setprio(0); } while (0)
; #define WAIT_V(n) asm volatile("s_waitcnt vmcnt(" #n ")" ::: "memory")
; #define WAIT_L(n) asm volatile("s_waitcnt lgkmcnt(" #n ")" ::: "memory")
; #define BAR __builtin_amdgcn_s_barrier()
; template <int EPI, int lda, int ldb, int N, int K>
; __device__ __forceinline__ void gemm_phase(const u16* __restrict__ A, const u16* __restrict__ Bt, const GemmEpi ep, int wv) {
;     ...
;     { LDB(B0, 1, 0); LDA(At, 1, 0); WAIT_V(2); BAR; WAIT_L(0); MMA(0, 0, At, B0); BAR;
;       LDB(B1, 1, 1); WAIT_V(0); BAR; WAIT_L(0); MMA(0, 1, At, B1); BAR;
;       LDA(At, 1, 1); BAR; WAIT_L(0); MMA(1, 0, At, B0); MMA(1, 1, At, B1); BAR; }
;     if (wr == 0) BAR;
	s_waitcnt lgkmcnt(0)
	s_waitcnt lgkmcnt(0)
	v_mfma_f32_16x16x32_bf16 v[64:67], v[0:3], v[24:27], v[124:127]
	v_mfma_f32_16x16x32_bf16 v[68:71], v[16:19], v[24:27], v[120:123]
	v_mfma_f32_16x16x32_bf16 v[80:83], v[0:3], v[198:201], v[116:119]
	v_mfma_f32_16x16x32_bf16 v[84:87], v[16:19], v[198:201], v[112:115]
	v_mfma_f32_16x16x32_bf16 v[108:111], v[0:3], v[206:209], v[108:111]
	v_mfma_f32_16x16x32_bf16 v[104:107], v[16:19], v[206:209], v[104:107]
	v_mfma_f32_16x16x32_bf16 v[120:123], v[0:3], v[214:217], v[100:103]
	v_mfma_f32_16x16x32_bf16 v[124:127], v[16:19], v[214:217], v[96:99]
	v_mfma_f32_16x16x32_bf16 v[116:119], v[8:11], v[194:197], v[64:67]
	v_mfma_f32_16x16x32_bf16 v[112:115], v[172:175], v[194:197], v[68:71]
	v_mfma_f32_16x16x32_bf16 v[100:103], v[8:11], v[202:205], v[80:83]
	v_mfma_f32_16x16x32_bf16 v[96:99], v[172:175], v[202:205], v[84:87]
	v_mfma_f32_16x16x32_bf16 v[84:87], v[8:11], v[210:213], v[108:111]
	v_mfma_f32_16x16x32_bf16 v[80:83], v[172:175], v[210:213], v[104:107]
	v_mfma_f32_16x16x32_bf16 v[68:71], v[8:11], v[218:221], v[120:123]
	v_mfma_f32_16x16x32_bf16 v[64:67], v[172:175], v[218:221], v[124:127]
	s_barrier
	ds_read_b128 v[222:225], v152
	ds_read_b128 v[226:229], v152 offset:1024
	ds_read_b128 v[230:233], v152 offset:2048
	ds_read_b128 v[152:155], v152 offset:3072
	s_waitcnt vmcnt(0)
	s_barrier
	s_waitcnt lgkmcnt(0)
	s_waitcnt lgkmcnt(0)
	v_mfma_f32_16x16x32_bf16 v[92:95], v[222:225], v[24:27], v[92:95]
	v_mfma_f32_16x16x32_bf16 v[24:27], v[230:233], v[24:27], v[88:91]
	v_mfma_f32_16x16x32_bf16 v[88:91], v[222:225], v[198:201], v[178:181]
	v_mfma_f32_16x16x32_bf16 v[104:107], v[230:233], v[198:201], v[182:185]
	v_mfma_f32_16x16x32_bf16 v[76:79], v[222:225], v[206:209], v[76:79]
	v_mfma_f32_16x16x32_bf16 v[72:75], v[230:233], v[206:209], v[72:75]
	v_mfma_f32_16x16x32_bf16 v[176:179], v[222:225], v[214:217], v[186:189]
	v_mfma_f32_16x16x32_bf16 v[180:183], v[230:233], v[214:217], v[190:193]
	v_mfma_f32_16x16x32_bf16 v[124:127], v[226:229], v[194:197], v[92:95]
	v_mfma_f32_16x16x32_bf16 v[120:123], v[152:155], v[194:197], v[24:27]
	v_mfma_f32_16x16x32_bf16 v[108:111], v[226:229], v[202:205], v[88:91]
	v_mfma_f32_16x16x32_bf16 v[104:107], v[152:155], v[202:205], v[104:107]
	v_mfma_f32_16x16x32_bf16 v[92:95], v[226:229], v[210:213], v[76:79]
	v_mfma_f32_16x16x32_bf16 v[88:91], v[152:155], v[210:213], v[72:75]
	v_mfma_f32_16x16x32_bf16 v[76:79], v[226:229], v[218:221], v[176:179]
	v_mfma_f32_16x16x32_bf16 v[72:75], v[152:155], v[218:221], v[180:183]
	s_barrier
	ds_read_b128 v[176:179], v151 offset:49152
	ds_read_b128 v[180:183], v151 offset:50176
	ds_read_b128 v[184:187], v150 offset:49152
	ds_read_b128 v[188:191], v150 offset:50176
	ds_read_b128 v[192:195], v149 offset:49152
	ds_read_b128 v[196:199], v149 offset:50176
	ds_read_b128 v[200:203], v148 offset:49152
	ds_read_b128 v[148:151], v148 offset:50176
	s_barrier
	s_waitcnt lgkmcnt(0)
	s_waitcnt lgkmcnt(0)
	v_mfma_f32_16x16x32_bf16 v[24:27], v[0:3], v[176:179], v[60:63]
	v_mfma_f32_16x16x32_bf16 v[60:63], v[16:19], v[176:179], v[56:59]
	v_mfma_f32_16x16x32_bf16 v[52:55], v[0:3], v[184:187], v[52:55]
	v_mfma_f32_16x16x32_bf16 v[204:207], v[16:19], v[184:187], v[48:51]
	v_mfma_f32_16x16x32_bf16 v[44:47], v[0:3], v[192:195], v[44:47]
	v_mfma_f32_16x16x32_bf16 v[208:211], v[16:19], v[192:195], v[40:43]
	v_mfma_f32_16x16x32_bf16 v[0:3], v[0:3], v[200:203], v[36:39]
	v_mfma_f32_16x16x32_bf16 v[36:39], v[16:19], v[200:203], v[32:35]
	v_mfma_f32_16x16x32_bf16 v[56:59], v[8:11], v[180:183], v[24:27]
	v_mfma_f32_16x16x32_bf16 v[48:51], v[172:175], v[180:183], v[60:63]
	v_mfma_f32_16x16x32_bf16 v[40:43], v[8:11], v[188:191], v[52:55]
	v_mfma_f32_16x16x32_bf16 v[32:35], v[172:175], v[188:191], v[204:207]
	v_mfma_f32_16x16x32_bf16 v[24:27], v[8:11], v[196:199], v[44:47]
	v_mfma_f32_16x16x32_bf16 v[16:19], v[172:175], v[196:199], v[208:211]
	v_mfma_f32_16x16x32_bf16 v[8:11], v[8:11], v[148:151], v[0:3]
	v_mfma_f32_16x16x32_bf16 v[0:3], v[172:175], v[148:151], v[36:39]
	v_mfma_f32_16x16x32_bf16 v[28:31], v[222:225], v[176:179], v[28:31]
	v_mfma_f32_16x16x32_bf16 v[36:39], v[230:233], v[176:179], v[134:137]
	v_mfma_f32_16x16x32_bf16 v[20:23], v[222:225], v[184:187], v[20:23]
	v_mfma_f32_16x16x32_bf16 v[134:137], v[230:233], v[184:187], v[138:141]
	v_mfma_f32_16x16x32_bf16 v[12:15], v[222:225], v[192:195], v[12:15]
	v_mfma_f32_16x16x32_bf16 v[138:141], v[230:233], v[192:195], v[168:171]
	v_mfma_f32_16x16x32_bf16 v[4:7], v[222:225], v[200:203], v[4:7]
	v_mfma_f32_16x16x32_bf16 v[156:159], v[230:233], v[200:203], v[156:159]
	v_mfma_f32_16x16x32_bf16 v[60:63], v[226:229], v[180:183], v[28:31]
	v_mfma_f32_16x16x32_bf16 v[52:55], v[152:155], v[180:183], v[36:39]
	v_mfma_f32_16x16x32_bf16 v[44:47], v[226:229], v[188:191], v[20:23]
	v_mfma_f32_16x16x32_bf16 v[36:39], v[152:155], v[188:191], v[134:137]
	v_mfma_f32_16x16x32_bf16 v[28:31], v[226:229], v[196:199], v[12:15]
	v_mfma_f32_16x16x32_bf16 v[20:23], v[152:155], v[196:199], v[138:141]
	v_mfma_f32_16x16x32_bf16 v[12:15], v[226:229], v[148:151], v[4:7]
	v_mfma_f32_16x16x32_bf16 v[4:7], v[152:155], v[148:151], v[156:159]
	v_cmp_gt_u32_e32 vcc, s60, v130
	s_barrier
	s_and_saveexec_b64 s[44:45], vcc
	s_cbranch_execz .LBB0_1451
	s_barrier

; #define STAGE(P, BASE, LD, br, kt) do { const char* _g = (const char*)((BASE) + (size_t)(br) * (LD) + (size_t)(kt) * 64); \
;     for (int _i = 0; _i < 2; ++_i) { int _b = tidx * 16 + _i * 8192; int _r, _c; stage_rc(_b, _r, _c); \
;       __builtin_amdgcn_global_load_lds((const unsigned*)(_g + (unsigned)((_r * (LD) + _c) * 2)), (unsigned*)((char*)(P) + _b), 16, 0, 0); } } while (0)
; #define LDA(dst, b, h) for (int m = 0; m < 4; ++m) for (int k = 0; k < 2; ++k) \
;     dst[m][k] = *reinterpret_cast<const bf16x8*>((char*)SA(b, h) + lds_byte(wr * 64 + m * 16 + fr, k * 32 + fq * 8))
; #define LDB(dst, b, h) for (int n = 0; n < 2; ++n) for (int k = 0; k < 2; ++k) \
;     dst[n][k] = *reinterpret_cast<const bf16x8*>((char*)SB(b, h) + lds_byte(wc * 32 + n * 16 + fr, k * 32 + fq * 8))
; #define MMA(ai, bj, At_, Bt_) do { __builtin_amdgcn_s_setprio(1); \
;     for (int k = 0; k < 2; ++k) for (int m = 0; m < 4; ++m) for (int n = 0; n < 2; ++n) \
;       acc[ai][bj][m][n] = __builtin_amdgcn_mfma_f32_16x16x32_bf16(At_[m][k], Bt_[n][k], acc[ai][bj][m][n], 0, 0, 0); \
;     __builtin_amdgcn_s_setprio(0); } while (0)
; #define WAIT_V(n) asm volatile("s_waitcnt vmcnt(" #n ")" ::: "memory")
; #define WAIT_L(n) asm volatile("s_waitcnt lgkmcnt(" #n ")" ::: "memory")
; #define BAR __builtin_amdgcn_s_barrier()
; #define SCHED __builtin_amdgcn_sched_barrier(0)
; template <int EPI, int lda, int ldb, int N, int K>
; __device__ __forceinline__ void gemm_phase(const u16* __restrict__ A, const u16* __restrict__ Bt, const GemmEpi ep, int wv) {
;     ...
;     for (int t = 0; t < nt - 2; t += 2) {
;       LDB(B0, 0, 0); SCHED; LDA(At, 0, 0); STAGE(SA(1, 1), Ab, lda, brow + HALF, t + 1);
;       WAIT_L(8); BAR; WAIT_L(0); MMA(0, 0, At, B0); BAR; SCHED;
;       LDB(B1, 0, 1); STAGE(SB(0, 0), Bt, ldb, bcol, t + 2);
;       BAR; WAIT_L(0); MMA(0, 1, At, B1); BAR;
;       LDA(At, 0, 1); STAGE(SA(0, 0), Ab, lda, brow, t + 2);
;       BAR; WAIT_L(0); MMA(1, 0, At, B0); BAR; SCHED;
;       STAGE(SB(0, 1), Bt, ldb, bcol + HALF, t + 2);
;       WAIT_V(6); BAR; MMA(1, 1, At, B1); BAR;
;       LDB(B0, 1, 0); SCHED; LDA(At, 1, 0); STAGE(SA(0, 1), Ab, lda, brow + HALF, t + 2);
;       WAIT_L(8); BAR; WAIT_L(0); MMA(0, 0, At, B0); BAR; SCHED;
.LBB0_1564:
	ds_read_b128 v[172:175], v161
	ds_read_b128 v[176:179], v161 offset:1024
	ds_read_b128 v[180:183], v161 offset:2048
	ds_read_b128 v[184:187], v161 offset:3072
	v_add_u32_e32 v169, 0xc000, v148
	v_lshl_add_u64 v[236:237], v[136:137], 0, s[40:41]
	v_readfirstlane_b32 s43, v169
	v_add_u32_e32 v170, 0xe000, v148
	v_lshl_add_u64 v[162:163], v[236:237], 0, s[14:15]
	s_mov_b32 m0, s43
	v_lshl_add_u64 v[238:239], v[134:135], 0, s[40:41]
	v_readfirstlane_b32 s43, v170
	ds_read_b128 v[164:167], v152
	ds_read_b128 v[188:191], v152 offset:1024
	ds_read_b128 v[192:195], v151
	ds_read_b128 v[196:199], v151 offset:1024
	ds_read_b128 v[200:203], v150
	ds_read_b128 v[204:207], v150 offset:1024
	ds_read_b128 v[208:211], v149
	ds_read_b128 v[212:215], v149 offset:1024
	global_load_lds_dwordx4 v[162:163], off
	v_lshl_add_u64 v[162:163], v[238:239], 0, s[14:15]
	s_mov_b32 m0, s43
	s_nop 0
	global_load_lds_dwordx4 v[162:163], off
	s_waitcnt lgkmcnt(8)
	s_barrier
	s_waitcnt lgkmcnt(0)
	s_waitcnt lgkmcnt(0)
	v_mfma_f32_16x16x32_bf16 v[124:127], v[172:175], v[164:167], v[124:127]
	v_mfma_f32_16x16x32_bf16 v[120:123], v[180:183], v[164:167], v[120:123]
	v_mfma_f32_16x16x32_bf16 v[116:119], v[172:175], v[192:195], v[116:119]
	v_mfma_f32_16x16x32_bf16 v[112:115], v[180:183], v[192:195], v[112:115]
	v_mfma_f32_16x16x32_bf16 v[108:111], v[172:175], v[200:203], v[108:111]
	v_mfma_f32_16x16x32_bf16 v[104:107], v[180:183], v[200:203], v[104:107]
	v_mfma_f32_16x16x32_bf16 v[100:103], v[172:175], v[208:211], v[100:103]
	v_mfma_f32_16x16x32_bf16 v[96:99], v[180:183], v[208:211], v[96:99]
	v_mfma_f32_16x16x32_bf16 v[124:127], v[176:179], v[188:191], v[124:127]
	v_mfma_f32_16x16x32_bf16 v[120:123], v[184:187], v[188:191], v[120:123]
	v_mfma_f32_16x16x32_bf16 v[116:119], v[176:179], v[196:199], v[116:119]
	v_mfma_f32_16x16x32_bf16 v[112:115], v[184:187], v[196:199], v[112:115]
	v_mfma_f32_16x16x32_bf16 v[108:111], v[176:179], v[204:207], v[108:111]
	v_mfma_f32_16x16x32_bf16 v[104:107], v[184:187], v[204:207], v[104:107]
	v_mfma_f32_16x16x32_bf16 v[100:103], v[176:179], v[212:215], v[100:103]
	v_mfma_f32_16x16x32_bf16 v[96:99], v[184:187], v[212:215], v[96:99]
	s_barrier
	v_add_u32_e32 v162, s52, v153
	v_lshl_add_u64 v[240:241], v[140:141], 0, s[40:41]
	v_readfirstlane_b32 s43, v162
	v_add_u32_e32 v163, 0x2000, v162
	v_lshl_add_u64 v[232:233], v[240:241], 0, s[16:17]
	s_mov_b32 m0, s43
	v_lshl_add_u64 v[242:243], v[138:139], 0, s[40:41]
	v_readfirstlane_b32 s43, v163
	ds_read_b128 v[216:219], v160
	ds_read_b128 v[220:223], v160 offset:1024
	ds_read_b128 v[224:227], v160 offset:2048
	ds_read_b128 v[228:231], v160 offset:3072
	global_load_lds_dwordx4 v[232:233], off
	v_lshl_add_u64 v[232:233], v[242:243], 0, s[16:17]
	s_mov_b32 m0, s43
	s_nop 0
	global_load_lds_dwordx4 v[232:233], off
	s_barrier
	s_waitcnt lgkmcnt(0)
	s_waitcnt lgkmcnt(0)
	v_mfma_f32_16x16x32_bf16 v[92:95], v[216:219], v[164:167], v[92:95]
	v_mfma_f32_16x16x32_bf16 v[88:91], v[224:227], v[164:167], v[88:91]
	v_mfma_f32_16x16x32_bf16 v[84:87], v[216:219], v[192:195], v[84:87]
	v_mfma_f32_16x16x32_bf16 v[80:83], v[224:227], v[192:195], v[80:83]
	v_mfma_f32_16x16x32_bf16 v[76:79], v[216:219], v[200:203], v[76:79]
	v_mfma_f32_16x16x32_bf16 v[72:75], v[224:227], v[200:203], v[72:75]
	v_mfma_f32_16x16x32_bf16 v[68:71], v[216:219], v[208:211], v[68:71]
	v_mfma_f32_16x16x32_bf16 v[64:67], v[224:227], v[208:211], v[64:67]
	v_mfma_f32_16x16x32_bf16 v[92:95], v[220:223], v[188:191], v[92:95]
	v_mfma_f32_16x16x32_bf16 v[88:91], v[228:231], v[188:191], v[88:91]
	v_mfma_f32_16x16x32_bf16 v[84:87], v[220:223], v[196:199], v[84:87]
	v_mfma_f32_16x16x32_bf16 v[80:83], v[228:231], v[196:199], v[80:83]
	v_mfma_f32_16x16x32_bf16 v[76:79], v[220:223], v[204:207], v[76:79]
	v_mfma_f32_16x16x32_bf16 v[72:75], v[228:231], v[204:207], v[72:75]
	v_mfma_f32_16x16x32_bf16 v[68:71], v[220:223], v[212:215], v[68:71]
	v_mfma_f32_16x16x32_bf16 v[64:67], v[228:231], v[212:215], v[64:67]
	v_readfirstlane_b32 s43, v148
	v_lshl_add_u64 v[164:165], v[236:237], 0, s[18:19]
	s_mov_b32 m0, s43
	s_barrier
	ds_read_b128 v[188:191], v152 offset:16384
	ds_read_b128 v[192:195], v152 offset:17408
	ds_read_b128 v[196:199], v151 offset:16384
	ds_read_b128 v[200:203], v151 offset:17408
	ds_read_b128 v[204:207], v150 offset:16384
	ds_read_b128 v[208:211], v150 offset:17408
	ds_read_b128 v[212:215], v149 offset:16384
	ds_read_b128 v[232:235], v149 offset:17408
	global_load_lds_dwordx4 v[164:165], off
	v_add_u32_e32 v164, 0x2000, v148
	v_lshl_add_u64 v[166:167], v[238:239], 0, s[18:19]
	v_readfirstlane_b32 s43, v164
	s_mov_b32 m0, s43
	s_nop 0
	global_load_lds_dwordx4 v[166:167], off
	s_barrier
	s_waitcnt lgkmcnt(0)
	s_waitcnt lgkmcnt(0)
	v_mfma_f32_16x16x32_bf16 v[60:63], v[172:175], v[188:191], v[60:63]
	v_mfma_f32_16x16x32_bf16 v[56:59], v[180:183], v[188:191], v[56:59]
	v_mfma_f32_16x16x32_bf16 v[52:55], v[172:175], v[196:199], v[52:55]
	v_mfma_f32_16x16x32_bf16 v[48:51], v[180:183], v[196:199], v[48:51]
	v_mfma_f32_16x16x32_bf16 v[44:47], v[172:175], v[204:207], v[44:47]
	v_mfma_f32_16x16x32_bf16 v[40:43], v[180:183], v[204:207], v[40:43]
	v_mfma_f32_16x16x32_bf16 v[36:39], v[172:175], v[212:215], v[36:39]
	v_mfma_f32_16x16x32_bf16 v[32:35], v[180:183], v[212:215], v[32:35]
	v_mfma_f32_16x16x32_bf16 v[60:63], v[176:179], v[192:195], v[60:63]
	v_mfma_f32_16x16x32_bf16 v[56:59], v[184:187], v[192:195], v[56:59]
	v_mfma_f32_16x16x32_bf16 v[52:55], v[176:179], v[200:203], v[52:55]
	v_mfma_f32_16x16x32_bf16 v[48:51], v[184:187], v[200:203], v[48:51]
	v_mfma_f32_16x16x32_bf16 v[44:47], v[176:179], v[208:211], v[44:47]
	v_mfma_f32_16x16x32_bf16 v[40:43], v[184:187], v[208:211], v[40:43]
	v_mfma_f32_16x16x32_bf16 v[36:39], v[176:179], v[232:235], v[36:39]
	v_mfma_f32_16x16x32_bf16 v[32:35], v[184:187], v[232:235], v[32:35]
	s_barrier
; #define STAGE(P, BASE, LD, br, kt) do { const char* _g = (const char*)((BASE) + (size_t)(br) * (LD) + (size_t)(kt) * 64); \
;     for (int _i = 0; _i < 2; ++_i) { int _b = tidx * 16 + _i * 8192; int _r, _c; stage_rc(_b, _r, _c); \
;       __builtin_amdgcn_global_load_lds((const unsigned*)(_g + (unsigned)((_r * (LD) + _c) * 2)), (unsigned*)((char*)(P) + _b), 16, 0, 0); } } while (0)
; #define LDA(dst, b, h) for (int m = 0; m < 4; ++m) for (int k = 0; k < 2; ++k) \
;     dst[m][k] = *reinterpret_cast<const bf16x8*>((char*)SA(b, h) + lds_byte(wr * 64 + m * 16 + fr, k * 32 + fq * 8))
; #define LDB(dst, b, h) for (int n = 0; n < 2; ++n) for (int k = 0; k < 2; ++k) \
;     dst[n][k] = *reinterpret_cast<const bf16x8*>((char*)SB(b, h) + lds_byte(wc * 32 + n * 16 + fr, k * 32 + fq * 8))
; #define MMA(ai, bj, At_, Bt_) do { __builtin_amdgcn_s_setprio(1); \
;     for (int k = 0; k < 2; ++k) for (int m = 0; m < 4; ++m) for (int n = 0; n < 2; ++n) \
;       acc[ai][bj][m][n] = __builtin_amdgcn_mfma_f32_16x16x32_bf16(At_[m][k], Bt_[n][k], acc[ai][bj][m][n], 0, 0, 0); \
;     __builtin_amdgcn_s_setprio(0); } while (0)
; #define WAIT_V(n) asm volatile("s_waitcnt vmcnt(" #n ")" ::: "memory")
; #define WAIT_L(n) asm volatile("s_waitcnt lgkmcnt(" #n ")" ::: "memory")
; #define BAR __builtin_amdgcn_s_barrier()
; #define SCHED __builtin_amdgcn_sched_barrier(0)
; template <int EPI, int lda, int ldb, int N, int K>
; __device__ __forceinline__ void gemm_phase(const u16* __restrict__ A, const u16* __restrict__ Bt, const GemmEpi ep, int wv) {
;     ...
;       STAGE(SB(0, 1), Bt, ldb, bcol + HALF, t + 2);
;       WAIT_V(6); BAR; MMA(1, 1, At, B1); BAR;
;       LDB(B0, 1, 0); SCHED; LDA(At, 1, 0); STAGE(SA(0, 1), Ab, lda, brow + HALF, t + 2);
;       WAIT_L(8); BAR; WAIT_L(0); MMA(0, 0, At, B0); BAR; SCHED;
;       LDB(B1, 1, 1); STAGE(SB(1, 0), Bt, ldb, bcol, t + 3);
;       BAR; WAIT_L(0); MMA(0, 1, At, B1); BAR;
;       LDA(At, 1, 1); STAGE(SA(1, 0), Ab, lda, brow, t + 3);
;       BAR; WAIT_L(0); MMA(1, 0, At, B0); BAR; SCHED;
	v_add_u32_e32 v165, s53, v153
	v_lshl_add_u64 v[166:167], v[240:241], 0, s[20:21]
	v_readfirstlane_b32 s43, v165
	s_mov_b32 m0, s43
	v_lshl_add_u64 v[172:173], v[242:243], 0, s[20:21]
	global_load_lds_dwordx4 v[166:167], off
	v_add_u32_e32 v166, 0x2000, v165
	s_nop 0
	v_readfirstlane_b32 s43, v166
	s_mov_b32 m0, s43
	s_nop 0
	global_load_lds_dwordx4 v[172:173], off
	s_waitcnt vmcnt(6)
	s_barrier
	v_mfma_f32_16x16x32_bf16 v[28:31], v[216:219], v[188:191], v[28:31]
	v_mfma_f32_16x16x32_bf16 v[24:27], v[224:227], v[188:191], v[24:27]
	v_mfma_f32_16x16x32_bf16 v[20:23], v[216:219], v[196:199], v[20:23]
	v_mfma_f32_16x16x32_bf16 v[16:19], v[224:227], v[196:199], v[16:19]
	v_mfma_f32_16x16x32_bf16 v[12:15], v[216:219], v[204:207], v[12:15]
	v_mfma_f32_16x16x32_bf16 v[8:11], v[224:227], v[204:207], v[8:11]
	v_mfma_f32_16x16x32_bf16 v[4:7], v[216:219], v[212:215], v[4:7]
	v_mfma_f32_16x16x32_bf16 v[0:3], v[224:227], v[212:215], v[0:3]
	v_mfma_f32_16x16x32_bf16 v[28:31], v[220:223], v[192:195], v[28:31]
	v_mfma_f32_16x16x32_bf16 v[24:27], v[228:231], v[192:195], v[24:27]
	v_mfma_f32_16x16x32_bf16 v[20:23], v[220:223], v[200:203], v[20:23]
	v_mfma_f32_16x16x32_bf16 v[16:19], v[228:231], v[200:203], v[16:19]
	v_mfma_f32_16x16x32_bf16 v[12:15], v[220:223], v[208:211], v[12:15]
	v_mfma_f32_16x16x32_bf16 v[8:11], v[228:231], v[208:211], v[8:11]
	v_mfma_f32_16x16x32_bf16 v[4:7], v[220:223], v[232:235], v[4:7]
	v_mfma_f32_16x16x32_bf16 v[0:3], v[228:231], v[232:235], v[0:3]
	s_barrier
	ds_read_b128 v[172:175], v156
	ds_read_b128 v[176:179], v156 offset:1024
	ds_read_b128 v[180:183], v156 offset:2048
	ds_read_b128 v[184:187], v156 offset:3072
	v_add_u32_e32 v167, 0x4000, v148
	v_add_u32_e32 v168, 0x6000, v148
	v_readfirstlane_b32 s43, v167
	v_lshl_add_u64 v[220:221], v[236:237], 0, s[22:23]
	s_mov_b32 m0, s43
	v_readfirstlane_b32 s43, v168
	ds_read_b128 v[188:191], v152 offset:32768
	ds_read_b128 v[192:195], v152 offset:33792
	ds_read_b128 v[196:199], v151 offset:32768
	ds_read_b128 v[200:203], v151 offset:33792
	ds_read_b128 v[204:207], v150 offset:32768
	ds_read_b128 v[208:211], v150 offset:33792
	ds_read_b128 v[212:215], v149 offset:32768
	ds_read_b128 v[216:219], v149 offset:33792
	global_load_lds_dwordx4 v[220:221], off
	v_lshl_add_u64 v[220:221], v[238:239], 0, s[22:23]
	s_mov_b32 m0, s43
	s_nop 0
	global_load_lds_dwordx4 v[220:221], off
	s_waitcnt lgkmcnt(8)
	s_barrier
	s_waitcnt lgkmcnt(0)
	s_waitcnt lgkmcnt(0)
	v_mfma_f32_16x16x32_bf16 v[124:127], v[172:175], v[188:191], v[124:127]
	v_mfma_f32_16x16x32_bf16 v[120:123], v[180:183], v[188:191], v[120:123]
	v_mfma_f32_16x16x32_bf16 v[116:119], v[172:175], v[196:199], v[116:119]
	v_mfma_f32_16x16x32_bf16 v[112:115], v[180:183], v[196:199], v[112:115]
	v_mfma_f32_16x16x32_bf16 v[108:111], v[172:175], v[204:207], v[108:111]
	v_mfma_f32_16x16x32_bf16 v[104:107], v[180:183], v[204:207], v[104:107]
	v_mfma_f32_16x16x32_bf16 v[100:103], v[172:175], v[212:215], v[100:103]
	v_mfma_f32_16x16x32_bf16 v[96:99], v[180:183], v[212:215], v[96:99]
	v_mfma_f32_16x16x32_bf16 v[124:127], v[176:179], v[192:195], v[124:127]
	v_mfma_f32_16x16x32_bf16 v[120:123], v[184:187], v[192:195], v[120:123]
	v_mfma_f32_16x16x32_bf16 v[116:119], v[176:179], v[200:203], v[116:119]
	v_mfma_f32_16x16x32_bf16 v[112:115], v[184:187], v[200:203], v[112:115]
	v_mfma_f32_16x16x32_bf16 v[108:111], v[176:179], v[208:211], v[108:111]
	v_mfma_f32_16x16x32_bf16 v[104:107], v[184:187], v[208:211], v[104:107]
	v_mfma_f32_16x16x32_bf16 v[100:103], v[176:179], v[216:219], v[100:103]
	v_mfma_f32_16x16x32_bf16 v[96:99], v[184:187], v[216:219], v[96:99]
	s_barrier
	v_readfirstlane_b32 s43, v155
	v_add_u32_e32 v171, 0x2000, v155
	v_lshl_add_u64 v[244:245], v[240:241], 0, s[24:25]
	s_mov_b32 m0, s43
	v_readfirstlane_b32 s43, v171
	ds_read_b128 v[220:223], v154
	ds_read_b128 v[224:227], v154 offset:1024
	ds_read_b128 v[228:231], v154 offset:2048
	ds_read_b128 v[232:235], v154 offset:3072
	global_load_lds_dwordx4 v[244:245], off
	v_lshl_add_u64 v[244:245], v[242:243], 0, s[24:25]
	s_mov_b32 m0, s43
	s_nop 0
	global_load_lds_dwordx4 v[244:245], off
	s_barrier
	s_waitcnt lgkmcnt(0)
	s_waitcnt lgkmcnt(0)
	v_mfma_f32_16x16x32_bf16 v[92:95], v[220:223], v[188:191], v[92:95]
	v_mfma_f32_16x16x32_bf16 v[88:91], v[228:231], v[188:191], v[88:91]
	v_mfma_f32_16x16x32_bf16 v[84:87], v[220:223], v[196:199], v[84:87]
	v_mfma_f32_16x16x32_bf16 v[80:83], v[228:231], v[196:199], v[80:83]
	v_mfma_f32_16x16x32_bf16 v[76:79], v[220:223], v[204:207], v[76:79]
	v_mfma_f32_16x16x32_bf16 v[72:75], v[228:231], v[204:207], v[72:75]
	v_mfma_f32_16x16x32_bf16 v[68:71], v[220:223], v[212:215], v[68:71]
	v_mfma_f32_16x16x32_bf16 v[64:67], v[228:231], v[212:215], v[64:67]
	v_mfma_f32_16x16x32_bf16 v[92:95], v[224:227], v[192:195], v[92:95]
	v_mfma_f32_16x16x32_bf16 v[88:91], v[232:235], v[192:195], v[88:91]
	v_mfma_f32_16x16x32_bf16 v[84:87], v[224:227], v[200:203], v[84:87]
	v_mfma_f32_16x16x32_bf16 v[80:83], v[232:235], v[200:203], v[80:83]
	v_mfma_f32_16x16x32_bf16 v[76:79], v[224:227], v[208:211], v[76:79]
	v_mfma_f32_16x16x32_bf16 v[72:75], v[232:235], v[208:211], v[72:75]
	v_mfma_f32_16x16x32_bf16 v[68:71], v[224:227], v[216:219], v[68:71]
	v_mfma_f32_16x16x32_bf16 v[64:67], v[232:235], v[216:219], v[64:67]
	v_readfirstlane_b32 s43, v157
	v_lshl_add_u64 v[236:237], v[236:237], 0, s[26:27]
	s_mov_b32 m0, s43
	v_readfirstlane_b32 s43, v158
	s_barrier
; #define STAGE(P, BASE, LD, br, kt) do { const char* _g = (const char*)((BASE) + (size_t)(br) * (LD) + (size_t)(kt) * 64); \
;     for (int _i = 0; _i < 2; ++_i) { int _b = tidx * 16 + _i * 8192; int _r, _c; stage_rc(_b, _r, _c); \
;       __builtin_amdgcn_global_load_lds((const unsigned*)(_g + (unsigned)((_r * (LD) + _c) * 2)), (unsigned*)((char*)(P) + _b), 16, 0, 0); } } while (0)
; #define LDA(dst, b, h) for (int m = 0; m < 4; ++m) for (int k = 0; k < 2; ++k) \
;     dst[m][k] = *reinterpret_cast<const bf16x8*>((char*)SA(b, h) + lds_byte(wr * 64 + m * 16 + fr, k * 32 + fq * 8))
; #define LDB(dst, b, h) for (int n = 0; n < 2; ++n) for (int k = 0; k < 2; ++k) \
;     dst[n][k] = *reinterpret_cast<const bf16x8*>((char*)SB(b, h) + lds_byte(wc * 32 + n * 16 + fr, k * 32 + fq * 8))
; #define MMA(ai, bj, At_, Bt_) do { __builtin_amdgcn_s_setprio(1); \
;     for (int k = 0; k < 2; ++k) for (int m = 0; m < 4; ++m) for (int n = 0; n < 2; ++n) \
;       acc[ai][bj][m][n] = __builtin_amdgcn_mfma_f32_16x16x32_bf16(At_[m][k], Bt_[n][k], acc[ai][bj][m][n], 0, 0, 0); \
;     __builtin_amdgcn_s_setprio(0); } while (0)
; #define WAIT_V(n) asm volatile("s_waitcnt vmcnt(" #n ")" ::: "memory")
; #define WAIT_L(n) asm volatile("s_waitcnt lgkmcnt(" #n ")" ::: "memory")
; #define BAR __builtin_amdgcn_s_barrier()
; #define SCHED __builtin_amdgcn_sched_barrier(0)
; template <int EPI, int lda, int ldb, int N, int K>
; __device__ __forceinline__ void gemm_phase(const u16* __restrict__ A, const u16* __restrict__ Bt, const GemmEpi ep, int wv) {
;     ...
;       LDB(B1, 1, 1); STAGE(SB(1, 0), Bt, ldb, bcol, t + 3);
;       BAR; WAIT_L(0); MMA(0, 1, At, B1); BAR;
;       LDA(At, 1, 1); STAGE(SA(1, 0), Ab, lda, brow, t + 3);
;       BAR; WAIT_L(0); MMA(1, 0, At, B0); BAR; SCHED;
;       STAGE(SB(1, 1), Bt, ldb, bcol + HALF, t + 3);
;       WAIT_V(6); BAR; MMA(1, 1, At, B1); BAR;
;     }
;     { LDB(B0, 0, 0); LDA(At, 0, 0); STAGE(SA(1, 1), Ab, lda, brow + HALF, nt - 1);
;       BAR; WAIT_L(0); MMA(0, 0, At, B0); BAR;
;       LDB(B1, 0, 1); BAR; WAIT_L(0); MMA(0, 1, At, B1); BAR;
	ds_read_b128 v[188:191], v152 offset:49152
	ds_read_b128 v[192:195], v152 offset:50176
	ds_read_b128 v[196:199], v151 offset:49152
	ds_read_b128 v[200:203], v151 offset:50176
	ds_read_b128 v[204:207], v150 offset:49152
	ds_read_b128 v[208:211], v150 offset:50176
	ds_read_b128 v[212:215], v149 offset:49152
	ds_read_b128 v[216:219], v149 offset:50176
	global_load_lds_dwordx4 v[236:237], off
	v_lshl_add_u64 v[236:237], v[238:239], 0, s[26:27]
	s_mov_b32 m0, s43
	s_nop 0
	global_load_lds_dwordx4 v[236:237], off
	s_barrier
	s_waitcnt lgkmcnt(0)
	s_waitcnt lgkmcnt(0)
	v_mfma_f32_16x16x32_bf16 v[60:63], v[172:175], v[188:191], v[60:63]
	v_mfma_f32_16x16x32_bf16 v[56:59], v[180:183], v[188:191], v[56:59]
	v_mfma_f32_16x16x32_bf16 v[52:55], v[172:175], v[196:199], v[52:55]
	v_mfma_f32_16x16x32_bf16 v[48:51], v[180:183], v[196:199], v[48:51]
	v_mfma_f32_16x16x32_bf16 v[44:47], v[172:175], v[204:207], v[44:47]
	v_mfma_f32_16x16x32_bf16 v[40:43], v[180:183], v[204:207], v[40:43]
	v_mfma_f32_16x16x32_bf16 v[36:39], v[172:175], v[212:215], v[36:39]
	v_mfma_f32_16x16x32_bf16 v[32:35], v[180:183], v[212:215], v[32:35]
	v_mfma_f32_16x16x32_bf16 v[60:63], v[176:179], v[192:195], v[60:63]
	v_mfma_f32_16x16x32_bf16 v[56:59], v[184:187], v[192:195], v[56:59]
	v_mfma_f32_16x16x32_bf16 v[52:55], v[176:179], v[200:203], v[52:55]
	v_mfma_f32_16x16x32_bf16 v[48:51], v[184:187], v[200:203], v[48:51]
	v_mfma_f32_16x16x32_bf16 v[44:47], v[176:179], v[208:211], v[44:47]
	v_mfma_f32_16x16x32_bf16 v[40:43], v[184:187], v[208:211], v[40:43]
	v_mfma_f32_16x16x32_bf16 v[36:39], v[176:179], v[216:219], v[36:39]
	v_mfma_f32_16x16x32_bf16 v[32:35], v[184:187], v[216:219], v[32:35]
	s_barrier
	v_readfirstlane_b32 s43, v159
	v_add_u32_e32 v171, 0x2000, v159
	v_lshl_add_u64 v[172:173], v[240:241], 0, s[34:35]
	s_mov_b32 m0, s43
	v_readfirstlane_b32 s43, v171
	global_load_lds_dwordx4 v[172:173], off
	v_lshl_add_u64 v[172:173], v[242:243], 0, s[34:35]
	s_mov_b32 m0, s43
	s_nop 0
	global_load_lds_dwordx4 v[172:173], off
	s_waitcnt vmcnt(6)
	s_barrier
	v_mfma_f32_16x16x32_bf16 v[28:31], v[220:223], v[188:191], v[28:31]
	v_mfma_f32_16x16x32_bf16 v[24:27], v[228:231], v[188:191], v[24:27]
	v_mfma_f32_16x16x32_bf16 v[20:23], v[220:223], v[196:199], v[20:23]
	v_mfma_f32_16x16x32_bf16 v[16:19], v[228:231], v[196:199], v[16:19]
	v_mfma_f32_16x16x32_bf16 v[12:15], v[220:223], v[204:207], v[12:15]
	v_mfma_f32_16x16x32_bf16 v[8:11], v[228:231], v[204:207], v[8:11]
	v_mfma_f32_16x16x32_bf16 v[4:7], v[220:223], v[212:215], v[4:7]
	v_mfma_f32_16x16x32_bf16 v[0:3], v[228:231], v[212:215], v[0:3]
	v_mfma_f32_16x16x32_bf16 v[28:31], v[224:227], v[192:195], v[28:31]
	v_mfma_f32_16x16x32_bf16 v[24:27], v[232:235], v[192:195], v[24:27]
	v_mfma_f32_16x16x32_bf16 v[20:23], v[224:227], v[200:203], v[20:23]
	v_mfma_f32_16x16x32_bf16 v[16:19], v[232:235], v[200:203], v[16:19]
	v_mfma_f32_16x16x32_bf16 v[12:15], v[224:227], v[208:211], v[12:15]
	v_mfma_f32_16x16x32_bf16 v[8:11], v[232:235], v[208:211], v[8:11]
	v_mfma_f32_16x16x32_bf16 v[4:7], v[224:227], v[216:219], v[4:7]
	v_mfma_f32_16x16x32_bf16 v[0:3], v[232:235], v[216:219], v[0:3]
	s_add_i32 s42, s42, 2
	s_add_u32 s40, s40, 0x100
	s_addc_u32 s41, s41, 0
	s_cmp_gt_u32 s42, 27
	s_barrier
	s_cbranch_scc0 .LBB0_1564
	s_add_i32 s40, s38, 0x80
	s_mul_hi_i32 s41, s40, 0x1080
	s_mulk_i32 s40, 0x1080
	s_add_u32 s40, s49, s40
	s_addc_u32 s41, s50, s41
	v_lshl_add_u64 v[158:159], s[40:41], 0, v[128:129]
	v_readfirstlane_b32 s42, v169
	v_lshl_add_u64 v[158:159], v[158:159], 0, s[36:37]
	s_mov_b32 m0, s42
	ds_read_b128 v[134:137], v161
	ds_read_b128 v[138:141], v161 offset:1024
	ds_read_b128 v[172:175], v161 offset:2048
	ds_read_b128 v[176:179], v161 offset:3072
	ds_read_b128 v[180:183], v152
	ds_read_b128 v[184:187], v152 offset:1024
	ds_read_b128 v[188:191], v151
	ds_read_b128 v[192:195], v151 offset:1024
	ds_read_b128 v[196:199], v150
	ds_read_b128 v[200:203], v150 offset:1024
	ds_read_b128 v[204:207], v149
	ds_read_b128 v[208:211], v149 offset:1024
	global_load_lds_dwordx4 v[158:159], off
	v_lshl_add_u64 v[158:159], s[40:41], 0, v[132:133]
	v_readfirstlane_b32 s40, v170
	v_lshl_add_u64 v[158:159], v[158:159], 0, s[36:37]
	s_mov_b32 m0, s40
	s_nop 0
	global_load_lds_dwordx4 v[158:159], off
	s_barrier
	s_waitcnt lgkmcnt(0)
	s_waitcnt lgkmcnt(0)
	v_mfma_f32_16x16x32_bf16 v[124:127], v[134:137], v[180:183], v[124:127]
	v_mfma_f32_16x16x32_bf16 v[120:123], v[172:175], v[180:183], v[120:123]
	v_mfma_f32_16x16x32_bf16 v[116:119], v[134:137], v[188:191], v[116:119]
	v_mfma_f32_16x16x32_bf16 v[112:115], v[172:175], v[188:191], v[112:115]
	v_mfma_f32_16x16x32_bf16 v[108:111], v[134:137], v[196:199], v[108:111]
	v_mfma_f32_16x16x32_bf16 v[104:107], v[172:175], v[196:199], v[104:107]
	v_mfma_f32_16x16x32_bf16 v[100:103], v[134:137], v[204:207], v[100:103]
	v_mfma_f32_16x16x32_bf16 v[96:99], v[172:175], v[204:207], v[96:99]
	v_mfma_f32_16x16x32_bf16 v[124:127], v[138:141], v[184:187], v[124:127]
	v_mfma_f32_16x16x32_bf16 v[120:123], v[176:179], v[184:187], v[120:123]
	v_mfma_f32_16x16x32_bf16 v[116:119], v[138:141], v[192:195], v[116:119]
	v_mfma_f32_16x16x32_bf16 v[112:115], v[176:179], v[192:195], v[112:115]
	v_mfma_f32_16x16x32_bf16 v[108:111], v[138:141], v[200:203], v[108:111]
	v_mfma_f32_16x16x32_bf16 v[104:107], v[176:179], v[200:203], v[104:107]
	v_mfma_f32_16x16x32_bf16 v[100:103], v[138:141], v[208:211], v[100:103]
	v_mfma_f32_16x16x32_bf16 v[96:99], v[176:179], v[208:211], v[96:99]
	s_barrier
	ds_read_b128 v[212:215], v160
	ds_read_b128 v[216:219], v160 offset:1024
	ds_read_b128 v[220:223], v160 offset:2048
	ds_read_b128 v[158:161], v160 offset:3072
	s_barrier
; #define LDA(dst, b, h) for (int m = 0; m < 4; ++m) for (int k = 0; k < 2; ++k) \
;     dst[m][k] = *reinterpret_cast<const bf16x8*>((char*)SA(b, h) + lds_byte(wr * 64 + m * 16 + fr, k * 32 + fq * 8))
; #define LDB(dst, b, h) for (int n = 0; n < 2; ++n) for (int k = 0; k < 2; ++k) \
;     dst[n][k] = *reinterpret_cast<const bf16x8*>((char*)SB(b, h) + lds_byte(wc * 32 + n * 16 + fr, k * 32 + fq * 8))
; #define MMA(ai, bj, At_, Bt_) do { __builtin_amdgcn_s_setprio(1); \
;     for (int k = 0; k < 2; ++k) for (int m = 0; m < 4; ++m) for (int n = 0; n < 2; ++n) \
;       acc[ai][bj][m][n] = __builtin_amdgcn_mfma_f32_16x16x32_bf16(At_[m][k], Bt_[n][k], acc[ai][bj][m][n], 0, 0, 0); \
;     __builtin_amdgcn_s_setprio(0); } while (0)
; #define WAIT_V(n) asm volatile("s_waitcnt vmcnt(" #n ")" ::: "memory")
; #define WAIT_L(n) asm volatile("s_waitcnt lgkmcnt(" #n ")" ::: "memory")
; #define BAR __builtin_amdgcn_s_barrier()
; template <int EPI, int lda, int ldb, int N, int K>
; __device__ __forceinline__ void gemm_phase(const u16* __restrict__ A, const u16* __restrict__ Bt, const GemmEpi ep, int wv) {
;     ...
;       LDB(B1, 0, 1); BAR; WAIT_L(0); MMA(0, 1, At, B1); BAR;
;       LDA(At, 0, 1); WAIT_V(4); BAR; WAIT_L(0); MMA(1, 0, At, B0); MMA(1, 1, At, B1); BAR; }
;     { LDB(B0, 1, 0); LDA(At, 1, 0); WAIT_V(2); BAR; WAIT_L(0); MMA(0, 0, At, B0); BAR;
	s_waitcnt lgkmcnt(0)
	s_waitcnt lgkmcnt(0)
	v_mfma_f32_16x16x32_bf16 v[92:95], v[212:215], v[180:183], v[92:95]
	v_mfma_f32_16x16x32_bf16 v[88:91], v[220:223], v[180:183], v[88:91]
	v_mfma_f32_16x16x32_bf16 v[76:79], v[212:215], v[196:199], v[76:79]
	v_mfma_f32_16x16x32_bf16 v[72:75], v[220:223], v[196:199], v[72:75]
	v_mfma_f32_16x16x32_bf16 v[84:87], v[212:215], v[188:191], v[84:87]
	v_mfma_f32_16x16x32_bf16 v[80:83], v[220:223], v[188:191], v[80:83]
	v_mfma_f32_16x16x32_bf16 v[68:71], v[212:215], v[204:207], v[68:71]
	v_mfma_f32_16x16x32_bf16 v[64:67], v[220:223], v[204:207], v[64:67]
	v_mfma_f32_16x16x32_bf16 v[92:95], v[216:219], v[184:187], v[92:95]
	v_mfma_f32_16x16x32_bf16 v[88:91], v[158:161], v[184:187], v[88:91]
	v_mfma_f32_16x16x32_bf16 v[76:79], v[216:219], v[200:203], v[76:79]
	v_mfma_f32_16x16x32_bf16 v[72:75], v[158:161], v[200:203], v[72:75]
	v_mfma_f32_16x16x32_bf16 v[180:183], v[216:219], v[192:195], v[84:87]
	v_mfma_f32_16x16x32_bf16 v[184:187], v[158:161], v[192:195], v[80:83]
	v_mfma_f32_16x16x32_bf16 v[188:191], v[216:219], v[208:211], v[68:71]
	v_mfma_f32_16x16x32_bf16 v[192:195], v[158:161], v[208:211], v[64:67]
	s_barrier
	s_nop 0
	ds_read_b128 v[64:67], v152 offset:16384
	ds_read_b128 v[68:71], v152 offset:17408
	ds_read_b128 v[80:83], v151 offset:16384
	ds_read_b128 v[84:87], v151 offset:17408
	ds_read_b128 v[196:199], v150 offset:16384
	ds_read_b128 v[200:203], v150 offset:17408
	ds_read_b128 v[204:207], v149 offset:16384
	ds_read_b128 v[208:211], v149 offset:17408
	s_waitcnt vmcnt(4)
	s_barrier
	s_waitcnt lgkmcnt(0)
	s_waitcnt lgkmcnt(0)
	v_mfma_f32_16x16x32_bf16 v[60:63], v[134:137], v[64:67], v[60:63]
	v_mfma_f32_16x16x32_bf16 v[56:59], v[172:175], v[64:67], v[56:59]
	v_mfma_f32_16x16x32_bf16 v[52:55], v[134:137], v[80:83], v[52:55]
	v_mfma_f32_16x16x32_bf16 v[48:51], v[172:175], v[80:83], v[48:51]
	v_mfma_f32_16x16x32_bf16 v[44:47], v[134:137], v[196:199], v[44:47]
	v_mfma_f32_16x16x32_bf16 v[40:43], v[172:175], v[196:199], v[40:43]
	v_mfma_f32_16x16x32_bf16 v[36:39], v[134:137], v[204:207], v[36:39]
	v_mfma_f32_16x16x32_bf16 v[32:35], v[172:175], v[204:207], v[32:35]
	v_mfma_f32_16x16x32_bf16 v[60:63], v[138:141], v[68:71], v[60:63]
	v_mfma_f32_16x16x32_bf16 v[56:59], v[176:179], v[68:71], v[56:59]
	v_mfma_f32_16x16x32_bf16 v[52:55], v[138:141], v[84:87], v[52:55]
	v_mfma_f32_16x16x32_bf16 v[48:51], v[176:179], v[84:87], v[48:51]
	v_mfma_f32_16x16x32_bf16 v[44:47], v[138:141], v[200:203], v[44:47]
	v_mfma_f32_16x16x32_bf16 v[40:43], v[176:179], v[200:203], v[40:43]
	v_mfma_f32_16x16x32_bf16 v[36:39], v[138:141], v[208:211], v[36:39]
	v_mfma_f32_16x16x32_bf16 v[32:35], v[176:179], v[208:211], v[32:35]
	v_mfma_f32_16x16x32_bf16 v[28:31], v[212:215], v[64:67], v[28:31]
	v_mfma_f32_16x16x32_bf16 v[24:27], v[220:223], v[64:67], v[24:27]
	v_mfma_f32_16x16x32_bf16 v[12:15], v[212:215], v[196:199], v[12:15]
	v_mfma_f32_16x16x32_bf16 v[8:11], v[220:223], v[196:199], v[8:11]
	v_mfma_f32_16x16x32_bf16 v[20:23], v[212:215], v[80:83], v[20:23]
	v_mfma_f32_16x16x32_bf16 v[16:19], v[220:223], v[80:83], v[16:19]
	v_mfma_f32_16x16x32_bf16 v[4:7], v[212:215], v[204:207], v[4:7]
	v_mfma_f32_16x16x32_bf16 v[0:3], v[220:223], v[204:207], v[0:3]
	v_mfma_f32_16x16x32_bf16 v[28:31], v[216:219], v[68:71], v[28:31]
	v_mfma_f32_16x16x32_bf16 v[24:27], v[158:161], v[68:71], v[24:27]
	v_mfma_f32_16x16x32_bf16 v[12:15], v[216:219], v[200:203], v[12:15]
	v_mfma_f32_16x16x32_bf16 v[8:11], v[158:161], v[200:203], v[8:11]
	v_mfma_f32_16x16x32_bf16 v[134:137], v[216:219], v[84:87], v[20:23]
	v_mfma_f32_16x16x32_bf16 v[138:141], v[158:161], v[84:87], v[16:19]
	v_mfma_f32_16x16x32_bf16 v[170:173], v[216:219], v[208:211], v[4:7]
	v_mfma_f32_16x16x32_bf16 v[158:161], v[158:161], v[208:211], v[0:3]
	s_barrier
	s_nop 0
	ds_read_b128 v[0:3], v156
	ds_read_b128 v[4:7], v156 offset:1024
	ds_read_b128 v[16:19], v156 offset:2048
	ds_read_b128 v[174:177], v156 offset:3072
	ds_read_b128 v[20:23], v152 offset:32768
	ds_read_b128 v[196:199], v152 offset:33792
	ds_read_b128 v[200:203], v151 offset:32768
	ds_read_b128 v[204:207], v151 offset:33792
	ds_read_b128 v[208:211], v150 offset:32768
	ds_read_b128 v[212:215], v150 offset:33792
	ds_read_b128 v[216:219], v149 offset:32768
	ds_read_b128 v[220:223], v149 offset:33792
	s_waitcnt vmcnt(2)
	s_barrier
; #define LDA(dst, b, h) for (int m = 0; m < 4; ++m) for (int k = 0; k < 2; ++k) \
;     dst[m][k] = *reinterpret_cast<const bf16x8*>((char*)SA(b, h) + lds_byte(wr * 64 + m * 16 + fr, k * 32 + fq * 8))
; #define LDB(dst, b, h) for (int n = 0; n < 2; ++n) for (int k = 0; k < 2; ++k) \
;     dst[n][k] = *reinterpret_cast<const bf16x8*>((char*)SB(b, h) + lds_byte(wc * 32 + n * 16 + fr, k * 32 + fq * 8))
; #define MMA(ai, bj, At_, Bt_) do { __builtin_amdgcn_s_setprio(1); \
;     for (int k = 0; k < 2; ++k) for (int m = 0; m < 4; ++m) for (int n = 0; n < 2; ++n) \
;       acc[ai][bj][m][n] = __builtin_amdgcn_mfma_f32_16x16x32_bf16(At_[m][k], Bt_[n][k], acc[ai][bj][m][n], 0, 0, 0); \
;     __builtin_amdgcn_s_setprio(0); } while (0)
; #define WAIT_V(n) asm volatile("s_waitcnt vmcnt(" #n ")" ::: "memory")
; #define WAIT_L(n) asm volatile("s_waitcnt lgkmcnt(" #n ")" ::: "memory")
; #define BAR __builtin_amdgcn_s_barrier()
; template <int EPI, int lda, int ldb, int N, int K>
; __device__ __forceinline__ void gemm_phase(const u16* __restrict__ A, const u16* __restrict__ Bt, const GemmEpi ep, int wv) {
;     ...
;     { LDB(B0, 1, 0); LDA(At, 1, 0); WAIT_V(2); BAR; WAIT_L(0); MMA(0, 0, At, B0); BAR;
;       LDB(B1, 1, 1); WAIT_V(0); BAR; WAIT_L(0); MMA(0, 1, At, B1); BAR;
;       LDA(At, 1, 1); BAR; WAIT_L(0); MMA(1, 0, At, B0); MMA(1, 1, At, B1); BAR; }
;     if (wr == 0) BAR;
	s_waitcnt lgkmcnt(0)
	s_waitcnt lgkmcnt(0)
	v_mfma_f32_16x16x32_bf16 v[64:67], v[0:3], v[20:23], v[124:127]
	v_mfma_f32_16x16x32_bf16 v[68:71], v[16:19], v[20:23], v[120:123]
	v_mfma_f32_16x16x32_bf16 v[80:83], v[0:3], v[200:203], v[116:119]
	v_mfma_f32_16x16x32_bf16 v[84:87], v[16:19], v[200:203], v[112:115]
	v_mfma_f32_16x16x32_bf16 v[108:111], v[0:3], v[208:211], v[108:111]
	v_mfma_f32_16x16x32_bf16 v[104:107], v[16:19], v[208:211], v[104:107]
	v_mfma_f32_16x16x32_bf16 v[120:123], v[0:3], v[216:219], v[100:103]
	v_mfma_f32_16x16x32_bf16 v[124:127], v[16:19], v[216:219], v[96:99]
	v_mfma_f32_16x16x32_bf16 v[116:119], v[4:7], v[196:199], v[64:67]
	v_mfma_f32_16x16x32_bf16 v[112:115], v[174:177], v[196:199], v[68:71]
	v_mfma_f32_16x16x32_bf16 v[100:103], v[4:7], v[204:207], v[80:83]
	v_mfma_f32_16x16x32_bf16 v[96:99], v[174:177], v[204:207], v[84:87]
	v_mfma_f32_16x16x32_bf16 v[84:87], v[4:7], v[212:215], v[108:111]
	v_mfma_f32_16x16x32_bf16 v[80:83], v[174:177], v[212:215], v[104:107]
	v_mfma_f32_16x16x32_bf16 v[68:71], v[4:7], v[220:223], v[120:123]
	v_mfma_f32_16x16x32_bf16 v[64:67], v[174:177], v[220:223], v[124:127]
	s_barrier
	ds_read_b128 v[224:227], v154
	ds_read_b128 v[228:231], v154 offset:1024
	ds_read_b128 v[232:235], v154 offset:2048
	ds_read_b128 v[154:157], v154 offset:3072
	s_waitcnt vmcnt(0)
	s_barrier
	s_waitcnt lgkmcnt(0)
	s_waitcnt lgkmcnt(0)
	v_mfma_f32_16x16x32_bf16 v[92:95], v[224:227], v[20:23], v[92:95]
	v_mfma_f32_16x16x32_bf16 v[20:23], v[232:235], v[20:23], v[88:91]
	v_mfma_f32_16x16x32_bf16 v[88:91], v[224:227], v[200:203], v[180:183]
	v_mfma_f32_16x16x32_bf16 v[104:107], v[232:235], v[200:203], v[184:187]
	v_mfma_f32_16x16x32_bf16 v[76:79], v[224:227], v[208:211], v[76:79]
	v_mfma_f32_16x16x32_bf16 v[72:75], v[232:235], v[208:211], v[72:75]
	v_mfma_f32_16x16x32_bf16 v[178:181], v[224:227], v[216:219], v[188:191]
	v_mfma_f32_16x16x32_bf16 v[182:185], v[232:235], v[216:219], v[192:195]
	v_mfma_f32_16x16x32_bf16 v[124:127], v[228:231], v[196:199], v[92:95]
	v_mfma_f32_16x16x32_bf16 v[120:123], v[154:157], v[196:199], v[20:23]
	v_mfma_f32_16x16x32_bf16 v[108:111], v[228:231], v[204:207], v[88:91]
	v_mfma_f32_16x16x32_bf16 v[104:107], v[154:157], v[204:207], v[104:107]
	v_mfma_f32_16x16x32_bf16 v[92:95], v[228:231], v[212:215], v[76:79]
	v_mfma_f32_16x16x32_bf16 v[88:91], v[154:157], v[212:215], v[72:75]
	v_mfma_f32_16x16x32_bf16 v[76:79], v[228:231], v[220:223], v[178:181]
	v_mfma_f32_16x16x32_bf16 v[72:75], v[154:157], v[220:223], v[182:185]
	s_barrier
	ds_read_b128 v[178:181], v152 offset:49152
	ds_read_b128 v[182:185], v152 offset:50176
	ds_read_b128 v[186:189], v151 offset:49152
	ds_read_b128 v[190:193], v151 offset:50176
	ds_read_b128 v[194:197], v150 offset:49152
	ds_read_b128 v[150:153], v150 offset:50176
	ds_read_b128 v[198:201], v149 offset:49152
	ds_read_b128 v[202:205], v149 offset:50176
	s_barrier
	s_waitcnt lgkmcnt(0)
	s_waitcnt lgkmcnt(0)
	v_mfma_f32_16x16x32_bf16 v[20:23], v[0:3], v[178:181], v[60:63]
	v_mfma_f32_16x16x32_bf16 v[56:59], v[16:19], v[178:181], v[56:59]
	v_mfma_f32_16x16x32_bf16 v[60:63], v[0:3], v[186:189], v[52:55]
	v_mfma_f32_16x16x32_bf16 v[206:209], v[16:19], v[186:189], v[48:51]
	v_mfma_f32_16x16x32_bf16 v[44:47], v[0:3], v[194:197], v[44:47]
	v_mfma_f32_16x16x32_bf16 v[40:43], v[16:19], v[194:197], v[40:43]
	v_mfma_f32_16x16x32_bf16 v[0:3], v[0:3], v[198:201], v[36:39]
	v_mfma_f32_16x16x32_bf16 v[210:213], v[16:19], v[198:201], v[32:35]
	v_mfma_f32_16x16x32_bf16 v[52:55], v[4:7], v[182:185], v[20:23]
	v_mfma_f32_16x16x32_bf16 v[48:51], v[174:177], v[182:185], v[56:59]
	v_mfma_f32_16x16x32_bf16 v[36:39], v[4:7], v[190:193], v[60:63]
	v_mfma_f32_16x16x32_bf16 v[32:35], v[174:177], v[190:193], v[206:209]
	v_mfma_f32_16x16x32_bf16 v[20:23], v[4:7], v[150:153], v[44:47]
	v_mfma_f32_16x16x32_bf16 v[16:19], v[174:177], v[150:153], v[40:43]
	v_mfma_f32_16x16x32_bf16 v[4:7], v[4:7], v[202:205], v[0:3]
	v_mfma_f32_16x16x32_bf16 v[0:3], v[174:177], v[202:205], v[210:213]
	v_mfma_f32_16x16x32_bf16 v[28:31], v[224:227], v[178:181], v[28:31]
	v_mfma_f32_16x16x32_bf16 v[24:27], v[232:235], v[178:181], v[24:27]
	v_mfma_f32_16x16x32_bf16 v[40:43], v[224:227], v[186:189], v[134:137]
	v_mfma_f32_16x16x32_bf16 v[134:137], v[232:235], v[186:189], v[138:141]
	v_mfma_f32_16x16x32_bf16 v[12:15], v[224:227], v[194:197], v[12:15]
	v_mfma_f32_16x16x32_bf16 v[8:11], v[232:235], v[194:197], v[8:11]
	v_mfma_f32_16x16x32_bf16 v[138:141], v[224:227], v[198:201], v[170:173]
	v_mfma_f32_16x16x32_bf16 v[158:161], v[232:235], v[198:201], v[158:161]
	v_mfma_f32_16x16x32_bf16 v[60:63], v[228:231], v[182:185], v[28:31]
	v_mfma_f32_16x16x32_bf16 v[56:59], v[154:157], v[182:185], v[24:27]
	v_mfma_f32_16x16x32_bf16 v[44:47], v[228:231], v[190:193], v[40:43]
	v_mfma_f32_16x16x32_bf16 v[40:43], v[154:157], v[190:193], v[134:137]
	v_mfma_f32_16x16x32_bf16 v[28:31], v[228:231], v[150:153], v[12:15]
	v_mfma_f32_16x16x32_bf16 v[24:27], v[154:157], v[150:153], v[8:11]
	v_mfma_f32_16x16x32_bf16 v[12:15], v[228:231], v[202:205], v[138:141]
	v_mfma_f32_16x16x32_bf16 v[8:11], v[154:157], v[202:205], v[158:161]
	v_cmp_gt_u32_e32 vcc, s54, v130
	s_barrier
	s_and_saveexec_b64 s[40:41], vcc
	s_cbranch_execz .LBB0_1567
	s_barrier

; #define STAGE(P, BASE, LD, br, kt) do { const char* _g = (const char*)((BASE) + (size_t)(br) * (LD) + (size_t)(kt) * 64); \
;     for (int _i = 0; _i < 2; ++_i) { int _b = tidx * 16 + _i * 8192; int _r, _c; stage_rc(_b, _r, _c); \
;       __builtin_amdgcn_global_load_lds((const unsigned*)(_g + (unsigned)((_r * (LD) + _c) * 2)), (unsigned*)((char*)(P) + _b), 16, 0, 0); } } while (0)
; #define LDA(dst, b, h) for (int m = 0; m < 4; ++m) for (int k = 0; k < 2; ++k) \
;     dst[m][k] = *reinterpret_cast<const bf16x8*>((char*)SA(b, h) + lds_byte(wr * 64 + m * 16 + fr, k * 32 + fq * 8))
; #define LDB(dst, b, h) for (int n = 0; n < 2; ++n) for (int k = 0; k < 2; ++k) \
;     dst[n][k] = *reinterpret_cast<const bf16x8*>((char*)SB(b, h) + lds_byte(wc * 32 + n * 16 + fr, k * 32 + fq * 8))
; #define MMA(ai, bj, At_, Bt_) do { __builtin_amdgcn_s_setprio(1); \
;     for (int k = 0; k < 2; ++k) for (int m = 0; m < 4; ++m) for (int n = 0; n < 2; ++n) \
;       acc[ai][bj][m][n] = __builtin_amdgcn_mfma_f32_16x16x32_bf16(At_[m][k], Bt_[n][k], acc[ai][bj][m][n], 0, 0, 0); \
;     __builtin_amdgcn_s_setprio(0); } while (0)
; #define WAIT_V(n) asm volatile("s_waitcnt vmcnt(" #n ")" ::: "memory")
; #define WAIT_L(n) asm volatile("s_waitcnt lgkmcnt(" #n ")" ::: "memory")
; #define BAR __builtin_amdgcn_s_barrier()
; #define SCHED __builtin_amdgcn_sched_barrier(0)
; template <int EPI, int lda, int ldb, int N, int K>
; __device__ __forceinline__ void gemm_phase(const u16* __restrict__ A, const u16* __restrict__ Bt, const GemmEpi ep, int wv) {
;     ...
;     for (int t = 0; t < nt - 2; t += 2) {
;       LDB(B0, 0, 0); SCHED; LDA(At, 0, 0); STAGE(SA(1, 1), Ab, lda, brow + HALF, t + 1);
;       WAIT_L(8); BAR; WAIT_L(0); MMA(0, 0, At, B0); BAR; SCHED;
;       LDB(B1, 0, 1); STAGE(SB(0, 0), Bt, ldb, bcol, t + 2);
;       BAR; WAIT_L(0); MMA(0, 1, At, B1); BAR;
;       LDA(At, 0, 1); STAGE(SA(0, 0), Ab, lda, brow, t + 2);
;       BAR; WAIT_L(0); MMA(1, 0, At, B0); BAR; SCHED;
;       STAGE(SB(0, 1), Bt, ldb, bcol + HALF, t + 2);
;       WAIT_V(6); BAR; MMA(1, 1, At, B1); BAR;
;       LDB(B0, 1, 0); SCHED; LDA(At, 1, 0); STAGE(SA(0, 1), Ab, lda, brow + HALF, t + 2);
;       WAIT_L(8); BAR; WAIT_L(0); MMA(0, 0, At, B0); BAR; SCHED;
.LBB0_1624:
	ds_read_b128 v[174:177], v163
	ds_read_b128 v[178:181], v163 offset:1024
	ds_read_b128 v[182:185], v163 offset:2048
	ds_read_b128 v[186:189], v163 offset:3072
	v_add_u32_e32 v171, 0xc000, v149
	v_lshl_add_u64 v[238:239], v[134:135], 0, s[28:29]
	v_readfirstlane_b32 s50, v171
	v_add_u32_e32 v172, 0xe000, v149
	v_lshl_add_u64 v[164:165], v[238:239], 0, s[10:11]
	s_mov_b32 m0, s50
	v_lshl_add_u64 v[240:241], v[132:133], 0, s[28:29]
	v_readfirstlane_b32 s50, v172
	ds_read_b128 v[166:169], v154
	ds_read_b128 v[190:193], v154 offset:1024
	ds_read_b128 v[194:197], v153
	ds_read_b128 v[198:201], v153 offset:1024
	ds_read_b128 v[202:205], v151
	ds_read_b128 v[206:209], v151 offset:1024
	ds_read_b128 v[210:213], v150
	ds_read_b128 v[214:217], v150 offset:1024
	global_load_lds_dwordx4 v[164:165], off
	v_lshl_add_u64 v[164:165], v[240:241], 0, s[10:11]
	s_mov_b32 m0, s50
	s_nop 0
	global_load_lds_dwordx4 v[164:165], off
	s_waitcnt lgkmcnt(8)
	s_barrier
	s_waitcnt lgkmcnt(0)
	s_waitcnt lgkmcnt(0)
	v_mfma_f32_16x16x32_bf16 v[124:127], v[166:169], v[174:177], v[124:127]
	v_mfma_f32_16x16x32_bf16 v[120:123], v[166:169], v[182:185], v[120:123]
	v_mfma_f32_16x16x32_bf16 v[116:119], v[194:197], v[174:177], v[116:119]
	v_mfma_f32_16x16x32_bf16 v[112:115], v[194:197], v[182:185], v[112:115]
	v_mfma_f32_16x16x32_bf16 v[108:111], v[202:205], v[174:177], v[108:111]
	v_mfma_f32_16x16x32_bf16 v[104:107], v[202:205], v[182:185], v[104:107]
	v_mfma_f32_16x16x32_bf16 v[100:103], v[210:213], v[174:177], v[100:103]
	v_mfma_f32_16x16x32_bf16 v[96:99], v[210:213], v[182:185], v[96:99]
	v_mfma_f32_16x16x32_bf16 v[124:127], v[190:193], v[178:181], v[124:127]
	v_mfma_f32_16x16x32_bf16 v[120:123], v[190:193], v[186:189], v[120:123]
	v_mfma_f32_16x16x32_bf16 v[116:119], v[198:201], v[178:181], v[116:119]
	v_mfma_f32_16x16x32_bf16 v[112:115], v[198:201], v[186:189], v[112:115]
	v_mfma_f32_16x16x32_bf16 v[108:111], v[206:209], v[178:181], v[108:111]
	v_mfma_f32_16x16x32_bf16 v[104:107], v[206:209], v[186:189], v[104:107]
	v_mfma_f32_16x16x32_bf16 v[100:103], v[214:217], v[178:181], v[100:103]
	v_mfma_f32_16x16x32_bf16 v[96:99], v[214:217], v[186:189], v[96:99]
	s_barrier
	v_add_u32_e32 v164, s40, v155
	v_lshl_add_u64 v[242:243], v[142:143], 0, s[28:29]
	v_readfirstlane_b32 s50, v164
	v_add_u32_e32 v165, 0x2000, v164
	v_lshl_add_u64 v[234:235], v[242:243], 0, s[12:13]
	s_mov_b32 m0, s50
	v_lshl_add_u64 v[244:245], v[140:141], 0, s[28:29]
	v_readfirstlane_b32 s50, v165
	ds_read_b128 v[218:221], v162
	ds_read_b128 v[222:225], v162 offset:1024
	ds_read_b128 v[226:229], v162 offset:2048
	ds_read_b128 v[230:233], v162 offset:3072
	global_load_lds_dwordx4 v[234:235], off
	v_lshl_add_u64 v[234:235], v[244:245], 0, s[12:13]
	s_mov_b32 m0, s50
	s_nop 0
	global_load_lds_dwordx4 v[234:235], off
	s_barrier
	s_waitcnt lgkmcnt(0)
	s_waitcnt lgkmcnt(0)
	v_mfma_f32_16x16x32_bf16 v[92:95], v[166:169], v[218:221], v[92:95]
	v_mfma_f32_16x16x32_bf16 v[88:91], v[166:169], v[226:229], v[88:91]
	v_mfma_f32_16x16x32_bf16 v[84:87], v[194:197], v[218:221], v[84:87]
	v_mfma_f32_16x16x32_bf16 v[80:83], v[194:197], v[226:229], v[80:83]
	v_mfma_f32_16x16x32_bf16 v[76:79], v[202:205], v[218:221], v[76:79]
	v_mfma_f32_16x16x32_bf16 v[72:75], v[202:205], v[226:229], v[72:75]
	v_mfma_f32_16x16x32_bf16 v[68:71], v[210:213], v[218:221], v[68:71]
	v_mfma_f32_16x16x32_bf16 v[64:67], v[210:213], v[226:229], v[64:67]
	v_mfma_f32_16x16x32_bf16 v[92:95], v[190:193], v[222:225], v[92:95]
	v_mfma_f32_16x16x32_bf16 v[88:91], v[190:193], v[230:233], v[88:91]
	v_mfma_f32_16x16x32_bf16 v[84:87], v[198:201], v[222:225], v[84:87]
	v_mfma_f32_16x16x32_bf16 v[80:83], v[198:201], v[230:233], v[80:83]
	v_mfma_f32_16x16x32_bf16 v[76:79], v[206:209], v[222:225], v[76:79]
	v_mfma_f32_16x16x32_bf16 v[72:75], v[206:209], v[230:233], v[72:75]
	v_mfma_f32_16x16x32_bf16 v[68:71], v[214:217], v[222:225], v[68:71]
	v_mfma_f32_16x16x32_bf16 v[64:67], v[214:217], v[230:233], v[64:67]
	v_readfirstlane_b32 s50, v149
	v_lshl_add_u64 v[166:167], v[238:239], 0, s[14:15]
	s_mov_b32 m0, s50
	s_barrier
	ds_read_b128 v[190:193], v154 offset:16384
	ds_read_b128 v[194:197], v154 offset:17408
	ds_read_b128 v[198:201], v153 offset:16384
	ds_read_b128 v[202:205], v153 offset:17408
	ds_read_b128 v[206:209], v151 offset:16384
	ds_read_b128 v[210:213], v151 offset:17408
	ds_read_b128 v[214:217], v150 offset:16384
	ds_read_b128 v[234:237], v150 offset:17408
	global_load_lds_dwordx4 v[166:167], off
	v_add_u32_e32 v166, 0x2000, v149
	v_lshl_add_u64 v[168:169], v[240:241], 0, s[14:15]
	v_readfirstlane_b32 s50, v166
	s_mov_b32 m0, s50
	s_nop 0
	global_load_lds_dwordx4 v[168:169], off
	s_barrier
	s_waitcnt lgkmcnt(0)
	s_waitcnt lgkmcnt(0)
	v_mfma_f32_16x16x32_bf16 v[60:63], v[190:193], v[174:177], v[60:63]
	v_mfma_f32_16x16x32_bf16 v[56:59], v[190:193], v[182:185], v[56:59]
	v_mfma_f32_16x16x32_bf16 v[52:55], v[198:201], v[174:177], v[52:55]
	v_mfma_f32_16x16x32_bf16 v[48:51], v[198:201], v[182:185], v[48:51]
	v_mfma_f32_16x16x32_bf16 v[44:47], v[206:209], v[174:177], v[44:47]
	v_mfma_f32_16x16x32_bf16 v[40:43], v[206:209], v[182:185], v[40:43]
	v_mfma_f32_16x16x32_bf16 v[36:39], v[214:217], v[174:177], v[36:39]
	v_mfma_f32_16x16x32_bf16 v[32:35], v[214:217], v[182:185], v[32:35]
	v_mfma_f32_16x16x32_bf16 v[60:63], v[194:197], v[178:181], v[60:63]
	v_mfma_f32_16x16x32_bf16 v[56:59], v[194:197], v[186:189], v[56:59]
	v_mfma_f32_16x16x32_bf16 v[52:55], v[202:205], v[178:181], v[52:55]
	v_mfma_f32_16x16x32_bf16 v[48:51], v[202:205], v[186:189], v[48:51]
	v_mfma_f32_16x16x32_bf16 v[44:47], v[210:213], v[178:181], v[44:47]
	v_mfma_f32_16x16x32_bf16 v[40:43], v[210:213], v[186:189], v[40:43]
	v_mfma_f32_16x16x32_bf16 v[36:39], v[234:237], v[178:181], v[36:39]
	v_mfma_f32_16x16x32_bf16 v[32:35], v[234:237], v[186:189], v[32:35]
	s_barrier
; #define STAGE(P, BASE, LD, br, kt) do { const char* _g = (const char*)((BASE) + (size_t)(br) * (LD) + (size_t)(kt) * 64); \
;     for (int _i = 0; _i < 2; ++_i) { int _b = tidx * 16 + _i * 8192; int _r, _c; stage_rc(_b, _r, _c); \
;       __builtin_amdgcn_global_load_lds((const unsigned*)(_g + (unsigned)((_r * (LD) + _c) * 2)), (unsigned*)((char*)(P) + _b), 16, 0, 0); } } while (0)
; #define LDA(dst, b, h) for (int m = 0; m < 4; ++m) for (int k = 0; k < 2; ++k) \
;     dst[m][k] = *reinterpret_cast<const bf16x8*>((char*)SA(b, h) + lds_byte(wr * 64 + m * 16 + fr, k * 32 + fq * 8))
; #define LDB(dst, b, h) for (int n = 0; n < 2; ++n) for (int k = 0; k < 2; ++k) \
;     dst[n][k] = *reinterpret_cast<const bf16x8*>((char*)SB(b, h) + lds_byte(wc * 32 + n * 16 + fr, k * 32 + fq * 8))
; #define MMA(ai, bj, At_, Bt_) do { __builtin_amdgcn_s_setprio(1); \
;     for (int k = 0; k < 2; ++k) for (int m = 0; m < 4; ++m) for (int n = 0; n < 2; ++n) \
;       acc[ai][bj][m][n] = __builtin_amdgcn_mfma_f32_16x16x32_bf16(At_[m][k], Bt_[n][k], acc[ai][bj][m][n], 0, 0, 0); \
;     __builtin_amdgcn_s_setprio(0); } while (0)
; #define WAIT_V(n) asm volatile("s_waitcnt vmcnt(" #n ")" ::: "memory")
; #define WAIT_L(n) asm volatile("s_waitcnt lgkmcnt(" #n ")" ::: "memory")
; #define BAR __builtin_amdgcn_s_barrier()
; #define SCHED __builtin_amdgcn_sched_barrier(0)
; template <int EPI, int lda, int ldb, int N, int K>
; __device__ __forceinline__ void gemm_phase(const u16* __restrict__ A, const u16* __restrict__ Bt, const GemmEpi ep, int wv) {
;     ...
;       STAGE(SB(0, 1), Bt, ldb, bcol + HALF, t + 2);
;       WAIT_V(6); BAR; MMA(1, 1, At, B1); BAR;
;       LDB(B0, 1, 0); SCHED; LDA(At, 1, 0); STAGE(SA(0, 1), Ab, lda, brow + HALF, t + 2);
;       WAIT_L(8); BAR; WAIT_L(0); MMA(0, 0, At, B0); BAR; SCHED;
;       LDB(B1, 1, 1); STAGE(SB(1, 0), Bt, ldb, bcol, t + 3);
;       BAR; WAIT_L(0); MMA(0, 1, At, B1); BAR;
;       LDA(At, 1, 1); STAGE(SA(1, 0), Ab, lda, brow, t + 3);
;       BAR; WAIT_L(0); MMA(1, 0, At, B0); BAR; SCHED;
	v_add_u32_e32 v167, s41, v155
	v_lshl_add_u64 v[246:247], v[138:139], 0, s[28:29]
	v_readfirstlane_b32 s50, v167
	v_lshl_add_u64 v[168:169], v[246:247], 0, s[16:17]
	s_mov_b32 m0, s50
	v_lshl_add_u64 v[248:249], v[136:137], 0, s[28:29]
	global_load_lds_dwordx4 v[168:169], off
	v_add_u32_e32 v168, 0x2000, v167
	v_lshl_add_u64 v[174:175], v[248:249], 0, s[16:17]
	v_readfirstlane_b32 s50, v168
	s_mov_b32 m0, s50
	s_nop 0
	global_load_lds_dwordx4 v[174:175], off
	s_waitcnt vmcnt(6)
	s_barrier
	v_mfma_f32_16x16x32_bf16 v[28:31], v[190:193], v[218:221], v[28:31]
	v_mfma_f32_16x16x32_bf16 v[24:27], v[190:193], v[226:229], v[24:27]
	v_mfma_f32_16x16x32_bf16 v[20:23], v[198:201], v[218:221], v[20:23]
	v_mfma_f32_16x16x32_bf16 v[16:19], v[198:201], v[226:229], v[16:19]
	v_mfma_f32_16x16x32_bf16 v[12:15], v[206:209], v[218:221], v[12:15]
	v_mfma_f32_16x16x32_bf16 v[8:11], v[206:209], v[226:229], v[8:11]
	v_mfma_f32_16x16x32_bf16 v[4:7], v[214:217], v[218:221], v[4:7]
	v_mfma_f32_16x16x32_bf16 v[0:3], v[214:217], v[226:229], v[0:3]
	v_mfma_f32_16x16x32_bf16 v[28:31], v[194:197], v[222:225], v[28:31]
	v_mfma_f32_16x16x32_bf16 v[24:27], v[194:197], v[230:233], v[24:27]
	v_mfma_f32_16x16x32_bf16 v[20:23], v[202:205], v[222:225], v[20:23]
	v_mfma_f32_16x16x32_bf16 v[16:19], v[202:205], v[230:233], v[16:19]
	v_mfma_f32_16x16x32_bf16 v[12:15], v[210:213], v[222:225], v[12:15]
	v_mfma_f32_16x16x32_bf16 v[8:11], v[210:213], v[230:233], v[8:11]
	v_mfma_f32_16x16x32_bf16 v[4:7], v[234:237], v[222:225], v[4:7]
	v_mfma_f32_16x16x32_bf16 v[0:3], v[234:237], v[230:233], v[0:3]
	s_barrier
	ds_read_b128 v[174:177], v158
	ds_read_b128 v[178:181], v158 offset:1024
	ds_read_b128 v[182:185], v158 offset:2048
	ds_read_b128 v[186:189], v158 offset:3072
	v_add_u32_e32 v169, 0x4000, v149
	v_add_u32_e32 v170, 0x6000, v149
	v_readfirstlane_b32 s50, v169
	v_lshl_add_u64 v[222:223], v[238:239], 0, s[18:19]
	s_mov_b32 m0, s50
	v_readfirstlane_b32 s50, v170
	ds_read_b128 v[190:193], v154 offset:32768
	ds_read_b128 v[194:197], v154 offset:33792
	ds_read_b128 v[198:201], v153 offset:32768
	ds_read_b128 v[202:205], v153 offset:33792
	ds_read_b128 v[206:209], v151 offset:32768
	ds_read_b128 v[210:213], v151 offset:33792
	ds_read_b128 v[214:217], v150 offset:32768
	ds_read_b128 v[218:221], v150 offset:33792
	global_load_lds_dwordx4 v[222:223], off
	v_lshl_add_u64 v[222:223], v[240:241], 0, s[18:19]
	s_mov_b32 m0, s50
	s_nop 0
	global_load_lds_dwordx4 v[222:223], off
	s_waitcnt lgkmcnt(8)
	s_barrier
	s_waitcnt lgkmcnt(0)
	s_waitcnt lgkmcnt(0)
	v_mfma_f32_16x16x32_bf16 v[124:127], v[190:193], v[174:177], v[124:127]
	v_mfma_f32_16x16x32_bf16 v[120:123], v[190:193], v[182:185], v[120:123]
	v_mfma_f32_16x16x32_bf16 v[116:119], v[198:201], v[174:177], v[116:119]
	v_mfma_f32_16x16x32_bf16 v[112:115], v[198:201], v[182:185], v[112:115]
	v_mfma_f32_16x16x32_bf16 v[108:111], v[206:209], v[174:177], v[108:111]
	v_mfma_f32_16x16x32_bf16 v[104:107], v[206:209], v[182:185], v[104:107]
	v_mfma_f32_16x16x32_bf16 v[100:103], v[214:217], v[174:177], v[100:103]
	v_mfma_f32_16x16x32_bf16 v[96:99], v[214:217], v[182:185], v[96:99]
	v_mfma_f32_16x16x32_bf16 v[124:127], v[194:197], v[178:181], v[124:127]
	v_mfma_f32_16x16x32_bf16 v[120:123], v[194:197], v[186:189], v[120:123]
	v_mfma_f32_16x16x32_bf16 v[116:119], v[202:205], v[178:181], v[116:119]
	v_mfma_f32_16x16x32_bf16 v[112:115], v[202:205], v[186:189], v[112:115]
	v_mfma_f32_16x16x32_bf16 v[108:111], v[210:213], v[178:181], v[108:111]
	v_mfma_f32_16x16x32_bf16 v[104:107], v[210:213], v[186:189], v[104:107]
	v_mfma_f32_16x16x32_bf16 v[100:103], v[218:221], v[178:181], v[100:103]
	v_mfma_f32_16x16x32_bf16 v[96:99], v[218:221], v[186:189], v[96:99]
	s_barrier
	v_readfirstlane_b32 s50, v157
	v_add_u32_e32 v173, 0x2000, v157
	v_lshl_add_u64 v[242:243], v[242:243], 0, s[20:21]
	s_mov_b32 m0, s50
	v_readfirstlane_b32 s50, v173
	ds_read_b128 v[222:225], v156
	ds_read_b128 v[226:229], v156 offset:1024
	ds_read_b128 v[230:233], v156 offset:2048
	ds_read_b128 v[234:237], v156 offset:3072
	global_load_lds_dwordx4 v[242:243], off
	v_lshl_add_u64 v[242:243], v[244:245], 0, s[20:21]
	s_mov_b32 m0, s50
	s_nop 0
	global_load_lds_dwordx4 v[242:243], off
	s_barrier
	s_waitcnt lgkmcnt(0)
	s_waitcnt lgkmcnt(0)
	v_mfma_f32_16x16x32_bf16 v[92:95], v[190:193], v[222:225], v[92:95]
	v_mfma_f32_16x16x32_bf16 v[88:91], v[190:193], v[230:233], v[88:91]
	v_mfma_f32_16x16x32_bf16 v[84:87], v[198:201], v[222:225], v[84:87]
	v_mfma_f32_16x16x32_bf16 v[80:83], v[198:201], v[230:233], v[80:83]
	v_mfma_f32_16x16x32_bf16 v[76:79], v[206:209], v[222:225], v[76:79]
	v_mfma_f32_16x16x32_bf16 v[72:75], v[206:209], v[230:233], v[72:75]
	v_mfma_f32_16x16x32_bf16 v[68:71], v[214:217], v[222:225], v[68:71]
	v_mfma_f32_16x16x32_bf16 v[64:67], v[214:217], v[230:233], v[64:67]
	v_mfma_f32_16x16x32_bf16 v[92:95], v[194:197], v[226:229], v[92:95]
	v_mfma_f32_16x16x32_bf16 v[88:91], v[194:197], v[234:237], v[88:91]
	v_mfma_f32_16x16x32_bf16 v[84:87], v[202:205], v[226:229], v[84:87]
	v_mfma_f32_16x16x32_bf16 v[80:83], v[202:205], v[234:237], v[80:83]
	v_mfma_f32_16x16x32_bf16 v[76:79], v[210:213], v[226:229], v[76:79]
	v_mfma_f32_16x16x32_bf16 v[72:75], v[210:213], v[234:237], v[72:75]
	v_mfma_f32_16x16x32_bf16 v[68:71], v[218:221], v[226:229], v[68:71]
	v_mfma_f32_16x16x32_bf16 v[64:67], v[218:221], v[234:237], v[64:67]
	v_readfirstlane_b32 s50, v159
	v_lshl_add_u64 v[238:239], v[238:239], 0, s[22:23]
	s_mov_b32 m0, s50
	v_readfirstlane_b32 s50, v160
	s_barrier
; #define STAGE(P, BASE, LD, br, kt) do { const char* _g = (const char*)((BASE) + (size_t)(br) * (LD) + (size_t)(kt) * 64); \
;     for (int _i = 0; _i < 2; ++_i) { int _b = tidx * 16 + _i * 8192; int _r, _c; stage_rc(_b, _r, _c); \
;       __builtin_amdgcn_global_load_lds((const unsigned*)(_g + (unsigned)((_r * (LD) + _c) * 2)), (unsigned*)((char*)(P) + _b), 16, 0, 0); } } while (0)
; #define LDA(dst, b, h) for (int m = 0; m < 4; ++m) for (int k = 0; k < 2; ++k) \
;     dst[m][k] = *reinterpret_cast<const bf16x8*>((char*)SA(b, h) + lds_byte(wr * 64 + m * 16 + fr, k * 32 + fq * 8))
; #define LDB(dst, b, h) for (int n = 0; n < 2; ++n) for (int k = 0; k < 2; ++k) \
;     dst[n][k] = *reinterpret_cast<const bf16x8*>((char*)SB(b, h) + lds_byte(wc * 32 + n * 16 + fr, k * 32 + fq * 8))
; #define MMA(ai, bj, At_, Bt_) do { __builtin_amdgcn_s_setprio(1); \
;     for (int k = 0; k < 2; ++k) for (int m = 0; m < 4; ++m) for (int n = 0; n < 2; ++n) \
;       acc[ai][bj][m][n] = __builtin_amdgcn_mfma_f32_16x16x32_bf16(At_[m][k], Bt_[n][k], acc[ai][bj][m][n], 0, 0, 0); \
;     __builtin_amdgcn_s_setprio(0); } while (0)
; #define WAIT_V(n) asm volatile("s_waitcnt vmcnt(" #n ")" ::: "memory")
; #define WAIT_L(n) asm volatile("s_waitcnt lgkmcnt(" #n ")" ::: "memory")
; #define BAR __builtin_amdgcn_s_barrier()
; #define SCHED __builtin_amdgcn_sched_barrier(0)
; template <int EPI, int lda, int ldb, int N, int K>
; __device__ __forceinline__ void gemm_phase(const u16* __restrict__ A, const u16* __restrict__ Bt, const GemmEpi ep, int wv) {
;     ...
;       LDB(B1, 1, 1); STAGE(SB(1, 0), Bt, ldb, bcol, t + 3);
;       BAR; WAIT_L(0); MMA(0, 1, At, B1); BAR;
;       LDA(At, 1, 1); STAGE(SA(1, 0), Ab, lda, brow, t + 3);
;       BAR; WAIT_L(0); MMA(1, 0, At, B0); BAR; SCHED;
;       STAGE(SB(1, 1), Bt, ldb, bcol + HALF, t + 3);
;       WAIT_V(6); BAR; MMA(1, 1, At, B1); BAR;
;     }
;     { LDB(B0, 0, 0); LDA(At, 0, 0); STAGE(SA(1, 1), Ab, lda, brow + HALF, nt - 1);
;       BAR; WAIT_L(0); MMA(0, 0, At, B0); BAR;
;       LDB(B1, 0, 1); BAR; WAIT_L(0); MMA(0, 1, At, B1); BAR;
	ds_read_b128 v[190:193], v154 offset:49152
	ds_read_b128 v[194:197], v154 offset:50176
	ds_read_b128 v[198:201], v153 offset:49152
	ds_read_b128 v[202:205], v153 offset:50176
	ds_read_b128 v[206:209], v151 offset:49152
	ds_read_b128 v[210:213], v151 offset:50176
	ds_read_b128 v[214:217], v150 offset:49152
	ds_read_b128 v[218:221], v150 offset:50176
	global_load_lds_dwordx4 v[238:239], off
	v_lshl_add_u64 v[238:239], v[240:241], 0, s[22:23]
	s_mov_b32 m0, s50
	s_nop 0
	global_load_lds_dwordx4 v[238:239], off
	s_barrier
	s_waitcnt lgkmcnt(0)
	s_waitcnt lgkmcnt(0)
	v_mfma_f32_16x16x32_bf16 v[60:63], v[190:193], v[174:177], v[60:63]
	v_mfma_f32_16x16x32_bf16 v[56:59], v[190:193], v[182:185], v[56:59]
	v_mfma_f32_16x16x32_bf16 v[52:55], v[198:201], v[174:177], v[52:55]
	v_mfma_f32_16x16x32_bf16 v[48:51], v[198:201], v[182:185], v[48:51]
	v_mfma_f32_16x16x32_bf16 v[44:47], v[206:209], v[174:177], v[44:47]
	v_mfma_f32_16x16x32_bf16 v[40:43], v[206:209], v[182:185], v[40:43]
	v_mfma_f32_16x16x32_bf16 v[36:39], v[214:217], v[174:177], v[36:39]
	v_mfma_f32_16x16x32_bf16 v[32:35], v[214:217], v[182:185], v[32:35]
	v_mfma_f32_16x16x32_bf16 v[60:63], v[194:197], v[178:181], v[60:63]
	v_mfma_f32_16x16x32_bf16 v[56:59], v[194:197], v[186:189], v[56:59]
	v_mfma_f32_16x16x32_bf16 v[52:55], v[202:205], v[178:181], v[52:55]
	v_mfma_f32_16x16x32_bf16 v[48:51], v[202:205], v[186:189], v[48:51]
	v_mfma_f32_16x16x32_bf16 v[44:47], v[210:213], v[178:181], v[44:47]
	v_mfma_f32_16x16x32_bf16 v[40:43], v[210:213], v[186:189], v[40:43]
	v_mfma_f32_16x16x32_bf16 v[36:39], v[218:221], v[178:181], v[36:39]
	v_mfma_f32_16x16x32_bf16 v[32:35], v[218:221], v[186:189], v[32:35]
	s_barrier
	v_readfirstlane_b32 s50, v161
	v_add_u32_e32 v173, 0x2000, v161
	v_lshl_add_u64 v[174:175], v[246:247], 0, s[24:25]
	s_mov_b32 m0, s50
	v_readfirstlane_b32 s50, v173
	global_load_lds_dwordx4 v[174:175], off
	v_lshl_add_u64 v[174:175], v[248:249], 0, s[24:25]
	s_mov_b32 m0, s50
	s_nop 0
	global_load_lds_dwordx4 v[174:175], off
	s_waitcnt vmcnt(6)
	s_barrier
	v_mfma_f32_16x16x32_bf16 v[28:31], v[190:193], v[222:225], v[28:31]
	v_mfma_f32_16x16x32_bf16 v[24:27], v[190:193], v[230:233], v[24:27]
	v_mfma_f32_16x16x32_bf16 v[20:23], v[198:201], v[222:225], v[20:23]
	v_mfma_f32_16x16x32_bf16 v[16:19], v[198:201], v[230:233], v[16:19]
	v_mfma_f32_16x16x32_bf16 v[12:15], v[206:209], v[222:225], v[12:15]
	v_mfma_f32_16x16x32_bf16 v[8:11], v[206:209], v[230:233], v[8:11]
	v_mfma_f32_16x16x32_bf16 v[4:7], v[214:217], v[222:225], v[4:7]
	v_mfma_f32_16x16x32_bf16 v[0:3], v[214:217], v[230:233], v[0:3]
	v_mfma_f32_16x16x32_bf16 v[28:31], v[194:197], v[226:229], v[28:31]
	v_mfma_f32_16x16x32_bf16 v[24:27], v[194:197], v[234:237], v[24:27]
	v_mfma_f32_16x16x32_bf16 v[20:23], v[202:205], v[226:229], v[20:23]
	v_mfma_f32_16x16x32_bf16 v[16:19], v[202:205], v[234:237], v[16:19]
	v_mfma_f32_16x16x32_bf16 v[12:15], v[210:213], v[226:229], v[12:15]
	v_mfma_f32_16x16x32_bf16 v[8:11], v[210:213], v[234:237], v[8:11]
	v_mfma_f32_16x16x32_bf16 v[4:7], v[218:221], v[226:229], v[4:7]
	v_mfma_f32_16x16x32_bf16 v[0:3], v[218:221], v[234:237], v[0:3]
	s_add_i32 s49, s49, 2
	s_add_u32 s28, s28, 0x100
	s_addc_u32 s29, s29, 0
	s_cmpk_gt_u32 s49, 0x51
	s_barrier
	s_cbranch_scc0 .LBB0_1624
	s_add_i32 s28, s48, 0x80
	s_mul_hi_i32 s29, s28, 0x2b00
	s_mulk_i32 s28, 0x2b00
	s_add_u32 s28, s34, s28
	s_addc_u32 s29, s35, s29
	s_add_u32 s28, s28, 0x2a80
	s_addc_u32 s29, s29, 0
	v_readfirstlane_b32 s49, v171
	v_lshl_add_u64 v[160:161], s[28:29], 0, v[128:129]
	s_mov_b32 m0, s49
	ds_read_b128 v[132:135], v163
	ds_read_b128 v[136:139], v163 offset:1024
	ds_read_b128 v[140:143], v163 offset:2048
	ds_read_b128 v[174:177], v163 offset:3072
	ds_read_b128 v[178:181], v154
	ds_read_b128 v[182:185], v154 offset:1024
	ds_read_b128 v[186:189], v153
	ds_read_b128 v[190:193], v153 offset:1024
	ds_read_b128 v[194:197], v151
	ds_read_b128 v[198:201], v151 offset:1024
	ds_read_b128 v[202:205], v150
	ds_read_b128 v[206:209], v150 offset:1024
	global_load_lds_dwordx4 v[160:161], off
	v_lshl_add_u64 v[160:161], s[28:29], 0, v[130:131]
	v_readfirstlane_b32 s28, v172
	s_mov_b32 m0, s28
	s_nop 0
	global_load_lds_dwordx4 v[160:161], off
	s_barrier
	s_waitcnt lgkmcnt(0)
	s_waitcnt lgkmcnt(0)
	v_mfma_f32_16x16x32_bf16 v[124:127], v[178:181], v[132:135], v[124:127]
	v_mfma_f32_16x16x32_bf16 v[120:123], v[178:181], v[140:143], v[120:123]
	v_mfma_f32_16x16x32_bf16 v[116:119], v[186:189], v[132:135], v[116:119]
	v_mfma_f32_16x16x32_bf16 v[112:115], v[186:189], v[140:143], v[112:115]
	v_mfma_f32_16x16x32_bf16 v[108:111], v[194:197], v[132:135], v[108:111]
	v_mfma_f32_16x16x32_bf16 v[104:107], v[194:197], v[140:143], v[104:107]
	v_mfma_f32_16x16x32_bf16 v[100:103], v[202:205], v[132:135], v[100:103]
	v_mfma_f32_16x16x32_bf16 v[96:99], v[202:205], v[140:143], v[96:99]
	v_mfma_f32_16x16x32_bf16 v[124:127], v[182:185], v[136:139], v[124:127]
	v_mfma_f32_16x16x32_bf16 v[120:123], v[182:185], v[174:177], v[120:123]
	v_mfma_f32_16x16x32_bf16 v[116:119], v[190:193], v[136:139], v[116:119]
	v_mfma_f32_16x16x32_bf16 v[112:115], v[190:193], v[174:177], v[112:115]
	v_mfma_f32_16x16x32_bf16 v[108:111], v[198:201], v[136:139], v[108:111]
	v_mfma_f32_16x16x32_bf16 v[104:107], v[198:201], v[174:177], v[104:107]
	v_mfma_f32_16x16x32_bf16 v[100:103], v[206:209], v[136:139], v[100:103]
	v_mfma_f32_16x16x32_bf16 v[96:99], v[206:209], v[174:177], v[96:99]
	s_barrier
	ds_read_b128 v[210:213], v162
	ds_read_b128 v[214:217], v162 offset:1024
	ds_read_b128 v[218:221], v162 offset:2048
	ds_read_b128 v[160:163], v162 offset:3072
	s_barrier
; #define LDA(dst, b, h) for (int m = 0; m < 4; ++m) for (int k = 0; k < 2; ++k) \
;     dst[m][k] = *reinterpret_cast<const bf16x8*>((char*)SA(b, h) + lds_byte(wr * 64 + m * 16 + fr, k * 32 + fq * 8))
; #define LDB(dst, b, h) for (int n = 0; n < 2; ++n) for (int k = 0; k < 2; ++k) \
;     dst[n][k] = *reinterpret_cast<const bf16x8*>((char*)SB(b, h) + lds_byte(wc * 32 + n * 16 + fr, k * 32 + fq * 8))
; #define MMA(ai, bj, At_, Bt_) do { __builtin_amdgcn_s_setprio(1); \
;     for (int k = 0; k < 2; ++k) for (int m = 0; m < 4; ++m) for (int n = 0; n < 2; ++n) \
;       acc[ai][bj][m][n] = __builtin_amdgcn_mfma_f32_16x16x32_bf16(At_[m][k], Bt_[n][k], acc[ai][bj][m][n], 0, 0, 0); \
;     __builtin_amdgcn_s_setprio(0); } while (0)
; #define WAIT_V(n) asm volatile("s_waitcnt vmcnt(" #n ")" ::: "memory")
; #define WAIT_L(n) asm volatile("s_waitcnt lgkmcnt(" #n ")" ::: "memory")
; #define BAR __builtin_amdgcn_s_barrier()
; template <int EPI, int lda, int ldb, int N, int K>
; __device__ __forceinline__ void gemm_phase(const u16* __restrict__ A, const u16* __restrict__ Bt, const GemmEpi ep, int wv) {
;     ...
;       LDB(B1, 0, 1); BAR; WAIT_L(0); MMA(0, 1, At, B1); BAR;
;       LDA(At, 0, 1); WAIT_V(4); BAR; WAIT_L(0); MMA(1, 0, At, B0); MMA(1, 1, At, B1); BAR; }
;     { LDB(B0, 1, 0); LDA(At, 1, 0); WAIT_V(2); BAR; WAIT_L(0); MMA(0, 0, At, B0); BAR;
	s_waitcnt lgkmcnt(0)
	s_waitcnt lgkmcnt(0)
	v_mfma_f32_16x16x32_bf16 v[92:95], v[178:181], v[210:213], v[92:95]
	v_mfma_f32_16x16x32_bf16 v[88:91], v[178:181], v[218:221], v[88:91]
	v_mfma_f32_16x16x32_bf16 v[72:75], v[194:197], v[218:221], v[72:75]
	v_mfma_f32_16x16x32_bf16 v[68:71], v[202:205], v[210:213], v[68:71]
	v_mfma_f32_16x16x32_bf16 v[84:87], v[186:189], v[210:213], v[84:87]
	v_mfma_f32_16x16x32_bf16 v[80:83], v[186:189], v[218:221], v[80:83]
	v_mfma_f32_16x16x32_bf16 v[76:79], v[194:197], v[210:213], v[76:79]
	v_mfma_f32_16x16x32_bf16 v[64:67], v[202:205], v[218:221], v[64:67]
	v_mfma_f32_16x16x32_bf16 v[92:95], v[182:185], v[214:217], v[92:95]
	v_mfma_f32_16x16x32_bf16 v[88:91], v[182:185], v[160:163], v[88:91]
	v_mfma_f32_16x16x32_bf16 v[72:75], v[198:201], v[160:163], v[72:75]
	v_mfma_f32_16x16x32_bf16 v[68:71], v[206:209], v[214:217], v[68:71]
	v_mfma_f32_16x16x32_bf16 v[178:181], v[190:193], v[214:217], v[84:87]
	v_mfma_f32_16x16x32_bf16 v[182:185], v[190:193], v[160:163], v[80:83]
	v_mfma_f32_16x16x32_bf16 v[186:189], v[198:201], v[214:217], v[76:79]
	v_mfma_f32_16x16x32_bf16 v[190:193], v[206:209], v[160:163], v[64:67]
	s_barrier
	s_nop 0
	ds_read_b128 v[64:67], v154 offset:16384
	ds_read_b128 v[76:79], v154 offset:17408
	ds_read_b128 v[80:83], v153 offset:16384
	ds_read_b128 v[84:87], v153 offset:17408
	ds_read_b128 v[194:197], v151 offset:16384
	ds_read_b128 v[198:201], v151 offset:17408
	ds_read_b128 v[202:205], v150 offset:16384
	ds_read_b128 v[206:209], v150 offset:17408
	s_waitcnt vmcnt(4)
	s_barrier
	s_waitcnt lgkmcnt(0)
	s_waitcnt lgkmcnt(0)
	v_mfma_f32_16x16x32_bf16 v[60:63], v[64:67], v[132:135], v[60:63]
	v_mfma_f32_16x16x32_bf16 v[56:59], v[64:67], v[140:143], v[56:59]
	v_mfma_f32_16x16x32_bf16 v[52:55], v[80:83], v[132:135], v[52:55]
	v_mfma_f32_16x16x32_bf16 v[48:51], v[80:83], v[140:143], v[48:51]
	v_mfma_f32_16x16x32_bf16 v[44:47], v[194:197], v[132:135], v[44:47]
	v_mfma_f32_16x16x32_bf16 v[40:43], v[194:197], v[140:143], v[40:43]
	v_mfma_f32_16x16x32_bf16 v[36:39], v[202:205], v[132:135], v[36:39]
	v_mfma_f32_16x16x32_bf16 v[32:35], v[202:205], v[140:143], v[32:35]
	v_mfma_f32_16x16x32_bf16 v[60:63], v[76:79], v[136:139], v[60:63]
	v_mfma_f32_16x16x32_bf16 v[56:59], v[76:79], v[174:177], v[56:59]
	v_mfma_f32_16x16x32_bf16 v[52:55], v[84:87], v[136:139], v[52:55]
	v_mfma_f32_16x16x32_bf16 v[48:51], v[84:87], v[174:177], v[48:51]
	v_mfma_f32_16x16x32_bf16 v[44:47], v[198:201], v[136:139], v[44:47]
	v_mfma_f32_16x16x32_bf16 v[40:43], v[198:201], v[174:177], v[40:43]
	v_mfma_f32_16x16x32_bf16 v[36:39], v[206:209], v[136:139], v[36:39]
	v_mfma_f32_16x16x32_bf16 v[32:35], v[206:209], v[174:177], v[32:35]
	v_mfma_f32_16x16x32_bf16 v[28:31], v[64:67], v[210:213], v[28:31]
	v_mfma_f32_16x16x32_bf16 v[24:27], v[64:67], v[218:221], v[24:27]
	v_mfma_f32_16x16x32_bf16 v[12:15], v[194:197], v[210:213], v[12:15]
	v_mfma_f32_16x16x32_bf16 v[8:11], v[194:197], v[218:221], v[8:11]
	v_mfma_f32_16x16x32_bf16 v[20:23], v[80:83], v[210:213], v[20:23]
	v_mfma_f32_16x16x32_bf16 v[16:19], v[80:83], v[218:221], v[16:19]
	v_mfma_f32_16x16x32_bf16 v[4:7], v[202:205], v[210:213], v[4:7]
	v_mfma_f32_16x16x32_bf16 v[0:3], v[202:205], v[218:221], v[0:3]
	v_mfma_f32_16x16x32_bf16 v[28:31], v[76:79], v[214:217], v[28:31]
	v_mfma_f32_16x16x32_bf16 v[24:27], v[76:79], v[160:163], v[24:27]
	v_mfma_f32_16x16x32_bf16 v[12:15], v[198:201], v[214:217], v[12:15]
	v_mfma_f32_16x16x32_bf16 v[8:11], v[198:201], v[160:163], v[8:11]
	v_mfma_f32_16x16x32_bf16 v[132:135], v[84:87], v[214:217], v[20:23]
	v_mfma_f32_16x16x32_bf16 v[136:139], v[84:87], v[160:163], v[16:19]
	v_mfma_f32_16x16x32_bf16 v[140:143], v[206:209], v[214:217], v[4:7]
	v_mfma_f32_16x16x32_bf16 v[160:163], v[206:209], v[160:163], v[0:3]
	s_barrier
	s_nop 0
	ds_read_b128 v[0:3], v158
	ds_read_b128 v[4:7], v158 offset:1024
	ds_read_b128 v[16:19], v158 offset:2048
	ds_read_b128 v[172:175], v158 offset:3072
	ds_read_b128 v[20:23], v154 offset:32768
	ds_read_b128 v[194:197], v154 offset:33792
	ds_read_b128 v[198:201], v153 offset:32768
	ds_read_b128 v[202:205], v153 offset:33792
	ds_read_b128 v[206:209], v151 offset:32768
	ds_read_b128 v[210:213], v151 offset:33792
	ds_read_b128 v[214:217], v150 offset:32768
	ds_read_b128 v[218:221], v150 offset:33792
	s_waitcnt vmcnt(2)
	s_barrier
; #define LDA(dst, b, h) for (int m = 0; m < 4; ++m) for (int k = 0; k < 2; ++k) \
;     dst[m][k] = *reinterpret_cast<const bf16x8*>((char*)SA(b, h) + lds_byte(wr * 64 + m * 16 + fr, k * 32 + fq * 8))
; #define LDB(dst, b, h) for (int n = 0; n < 2; ++n) for (int k = 0; k < 2; ++k) \
;     dst[n][k] = *reinterpret_cast<const bf16x8*>((char*)SB(b, h) + lds_byte(wc * 32 + n * 16 + fr, k * 32 + fq * 8))
; #define MMA(ai, bj, At_, Bt_) do { __builtin_amdgcn_s_setprio(1); \
;     for (int k = 0; k < 2; ++k) for (int m = 0; m < 4; ++m) for (int n = 0; n < 2; ++n) \
;       acc[ai][bj][m][n] = __builtin_amdgcn_mfma_f32_16x16x32_bf16(At_[m][k], Bt_[n][k], acc[ai][bj][m][n], 0, 0, 0); \
;     __builtin_amdgcn_s_setprio(0); } while (0)
; #define WAIT_V(n) asm volatile("s_waitcnt vmcnt(" #n ")" ::: "memory")
; #define WAIT_L(n) asm volatile("s_waitcnt lgkmcnt(" #n ")" ::: "memory")
; #define BAR __builtin_amdgcn_s_barrier()
; template <int EPI, int lda, int ldb, int N, int K>
; __device__ __forceinline__ void gemm_phase(const u16* __restrict__ A, const u16* __restrict__ Bt, const GemmEpi ep, int wv) {
;     ...
;     { LDB(B0, 1, 0); LDA(At, 1, 0); WAIT_V(2); BAR; WAIT_L(0); MMA(0, 0, At, B0); BAR;
;       LDB(B1, 1, 1); WAIT_V(0); BAR; WAIT_L(0); MMA(0, 1, At, B1); BAR;
;       LDA(At, 1, 1); BAR; WAIT_L(0); MMA(1, 0, At, B0); MMA(1, 1, At, B1); BAR; }
;     if (wr == 0) BAR;
	s_waitcnt lgkmcnt(0)
	s_waitcnt lgkmcnt(0)
	v_mfma_f32_16x16x32_bf16 v[64:67], v[20:23], v[0:3], v[124:127]
	v_mfma_f32_16x16x32_bf16 v[76:79], v[20:23], v[16:19], v[120:123]
	v_mfma_f32_16x16x32_bf16 v[80:83], v[198:201], v[0:3], v[116:119]
	v_mfma_f32_16x16x32_bf16 v[84:87], v[198:201], v[16:19], v[112:115]
	v_mfma_f32_16x16x32_bf16 v[108:111], v[206:209], v[0:3], v[108:111]
	v_mfma_f32_16x16x32_bf16 v[104:107], v[206:209], v[16:19], v[104:107]
	v_mfma_f32_16x16x32_bf16 v[120:123], v[214:217], v[0:3], v[100:103]
	v_mfma_f32_16x16x32_bf16 v[124:127], v[214:217], v[16:19], v[96:99]
	v_mfma_f32_16x16x32_bf16 v[116:119], v[194:197], v[4:7], v[64:67]
	v_mfma_f32_16x16x32_bf16 v[112:115], v[194:197], v[172:175], v[76:79]
	v_mfma_f32_16x16x32_bf16 v[100:103], v[202:205], v[4:7], v[80:83]
	v_mfma_f32_16x16x32_bf16 v[96:99], v[202:205], v[172:175], v[84:87]
	v_mfma_f32_16x16x32_bf16 v[84:87], v[210:213], v[4:7], v[108:111]
	v_mfma_f32_16x16x32_bf16 v[80:83], v[210:213], v[172:175], v[104:107]
	v_mfma_f32_16x16x32_bf16 v[76:79], v[218:221], v[4:7], v[120:123]
	v_mfma_f32_16x16x32_bf16 v[64:67], v[218:221], v[172:175], v[124:127]
	s_barrier
	ds_read_b128 v[222:225], v156
	ds_read_b128 v[226:229], v156 offset:1024
	ds_read_b128 v[230:233], v156 offset:2048
	ds_read_b128 v[156:159], v156 offset:3072
	s_waitcnt vmcnt(0)
	s_barrier
	s_waitcnt lgkmcnt(0)
	s_waitcnt lgkmcnt(0)
	v_mfma_f32_16x16x32_bf16 v[92:95], v[20:23], v[222:225], v[92:95]
	v_mfma_f32_16x16x32_bf16 v[20:23], v[20:23], v[230:233], v[88:91]
	v_mfma_f32_16x16x32_bf16 v[88:91], v[198:201], v[222:225], v[178:181]
	v_mfma_f32_16x16x32_bf16 v[104:107], v[198:201], v[230:233], v[182:185]
	v_mfma_f32_16x16x32_bf16 v[176:179], v[206:209], v[222:225], v[186:189]
	v_mfma_f32_16x16x32_bf16 v[72:75], v[206:209], v[230:233], v[72:75]
	v_mfma_f32_16x16x32_bf16 v[68:71], v[214:217], v[222:225], v[68:71]
	v_mfma_f32_16x16x32_bf16 v[180:183], v[214:217], v[230:233], v[190:193]
	v_mfma_f32_16x16x32_bf16 v[124:127], v[194:197], v[226:229], v[92:95]
	v_mfma_f32_16x16x32_bf16 v[120:123], v[194:197], v[156:159], v[20:23]
	v_mfma_f32_16x16x32_bf16 v[108:111], v[202:205], v[226:229], v[88:91]
	v_mfma_f32_16x16x32_bf16 v[104:107], v[202:205], v[156:159], v[104:107]
	v_mfma_f32_16x16x32_bf16 v[92:95], v[210:213], v[226:229], v[176:179]
	v_mfma_f32_16x16x32_bf16 v[88:91], v[210:213], v[156:159], v[72:75]
	v_mfma_f32_16x16x32_bf16 v[72:75], v[218:221], v[226:229], v[68:71]
	v_mfma_f32_16x16x32_bf16 v[68:71], v[218:221], v[156:159], v[180:183]
	s_barrier
	ds_read_b128 v[176:179], v154 offset:49152
	ds_read_b128 v[180:183], v154 offset:50176
	ds_read_b128 v[184:187], v153 offset:49152
	ds_read_b128 v[188:191], v153 offset:50176
	ds_read_b128 v[192:195], v151 offset:49152
	ds_read_b128 v[196:199], v151 offset:50176
	ds_read_b128 v[200:203], v150 offset:49152
	ds_read_b128 v[204:207], v150 offset:50176
	s_barrier
	s_waitcnt lgkmcnt(0)
	s_waitcnt lgkmcnt(0)
	v_mfma_f32_16x16x32_bf16 v[20:23], v[176:179], v[0:3], v[60:63]
	v_mfma_f32_16x16x32_bf16 v[56:59], v[176:179], v[16:19], v[56:59]
	v_mfma_f32_16x16x32_bf16 v[60:63], v[184:187], v[0:3], v[52:55]
	v_mfma_f32_16x16x32_bf16 v[208:211], v[184:187], v[16:19], v[48:51]
	v_mfma_f32_16x16x32_bf16 v[44:47], v[192:195], v[0:3], v[44:47]
	v_mfma_f32_16x16x32_bf16 v[40:43], v[192:195], v[16:19], v[40:43]
	v_mfma_f32_16x16x32_bf16 v[0:3], v[200:203], v[0:3], v[36:39]
	v_mfma_f32_16x16x32_bf16 v[212:215], v[200:203], v[16:19], v[32:35]
	v_mfma_f32_16x16x32_bf16 v[52:55], v[180:183], v[4:7], v[20:23]
	v_mfma_f32_16x16x32_bf16 v[48:51], v[180:183], v[172:175], v[56:59]
	v_mfma_f32_16x16x32_bf16 v[36:39], v[188:191], v[4:7], v[60:63]
	v_mfma_f32_16x16x32_bf16 v[32:35], v[188:191], v[172:175], v[208:211]
	v_mfma_f32_16x16x32_bf16 v[20:23], v[196:199], v[4:7], v[44:47]
	v_mfma_f32_16x16x32_bf16 v[16:19], v[196:199], v[172:175], v[40:43]
	v_mfma_f32_16x16x32_bf16 v[4:7], v[204:207], v[4:7], v[0:3]
	v_mfma_f32_16x16x32_bf16 v[0:3], v[204:207], v[172:175], v[212:215]
	v_mfma_f32_16x16x32_bf16 v[28:31], v[176:179], v[222:225], v[28:31]
	v_mfma_f32_16x16x32_bf16 v[24:27], v[176:179], v[230:233], v[24:27]
	v_mfma_f32_16x16x32_bf16 v[40:43], v[184:187], v[222:225], v[132:135]
	v_mfma_f32_16x16x32_bf16 v[132:135], v[184:187], v[230:233], v[136:139]
	v_mfma_f32_16x16x32_bf16 v[12:15], v[192:195], v[222:225], v[12:15]
	v_mfma_f32_16x16x32_bf16 v[8:11], v[192:195], v[230:233], v[8:11]
	v_mfma_f32_16x16x32_bf16 v[136:139], v[200:203], v[222:225], v[140:143]
	v_mfma_f32_16x16x32_bf16 v[140:143], v[200:203], v[230:233], v[160:163]
	v_mfma_f32_16x16x32_bf16 v[60:63], v[180:183], v[226:229], v[28:31]
	v_mfma_f32_16x16x32_bf16 v[56:59], v[180:183], v[156:159], v[24:27]
	v_mfma_f32_16x16x32_bf16 v[44:47], v[188:191], v[226:229], v[40:43]
	v_mfma_f32_16x16x32_bf16 v[40:43], v[188:191], v[156:159], v[132:135]
	v_mfma_f32_16x16x32_bf16 v[28:31], v[196:199], v[226:229], v[12:15]
	v_mfma_f32_16x16x32_bf16 v[24:27], v[196:199], v[156:159], v[8:11]
	v_mfma_f32_16x16x32_bf16 v[12:15], v[204:207], v[226:229], v[136:139]
	v_mfma_f32_16x16x32_bf16 v[8:11], v[204:207], v[156:159], v[140:143]
	v_cmp_gt_u32_e32 vcc, s46, v147
	s_barrier
	s_and_saveexec_b64 s[28:29], vcc
	s_cbranch_execz .LBB0_1627
	s_barrier
